# hand-written top-256 selection (radix select + ordered scatter) replacing hipcc's unrolled code; dead readlane elimination; topk prefetch wait moved to staging stores
# speedup vs baseline: 1.0465x; 1.0465x over previous
; DI unsigned xb_ld(unsigned* p) { return __hip_atomic_load(p, __ATOMIC_RELAXED, __HIP_MEMORY_SCOPE_AGENT); }
; DI unsigned xb_add(unsigned* p, unsigned v) { return __hip_atomic_fetch_add(p, v, __ATOMIC_RELAXED, __HIP_MEMORY_SCOPE_AGENT); }
; DI int t5_bucket(int n) {
;   if (n < 16) return n;
;   int lg = 16 + (int)(logf((float)n / 16.f) / logf(8.f) * 16.f);
;   return lg < 31 ? lg : 31;
; }
; DI XcdBarrier xcd_barrier_post(unsigned* bar, volatile unsigned* st) {
;   XcdBarrier b; b.bar = bar; b.x = xb_xcc_id(); b.st = st;
;   if (threadIdx.x == 0) (void)xb_add(&bar[XB_XCNT(b.x)], 1u);
;   return b;
; }
; DI void xcd_barrier_complete(unsigned* bar, unsigned x, unsigned& nloc, unsigned& nx) {
;   const unsigned G = gridDim.x * gridDim.y * gridDim.z;
;   unsigned sum, cnt, mine, sp = 0u;
;   for (;;) {
;     sum = 0u; cnt = 0u; mine = 0u;
; #pragma unroll
;     for (unsigned j = 0; j < 16; ++j) { const unsigned c = xb_ld(&bar[XB_XCNT(j)]); sum += c; cnt += (c > 0u) ? 1u : 0u; mine = (j == x) ? c : mine; }
;     if (sum == G) break;
;     __builtin_amdgcn_s_sleep(1);
;     if ((++sp & 255u) == 0u) { if (xb_ld(&bar[XB_TMO])) break; if (sp > XB_SPIN_CAP) { atomicAdd(&bar[XB_TMO], 1u); break; } }
;   }
;   nloc = mine > 0u ? mine : 1u; nx = cnt > 0u ? cnt : 1u;
; }
; DI void xcd_barrier(const XcdBarrier& b) {
;   asm volatile("s_waitcnt vmcnt(0)" ::: "memory");
;   __syncthreads();
;   if (threadIdx.x == 0) {
;     unsigned* bar = b.bar;
;     __builtin_amdgcn_s_waitcnt(0);
;     unsigned nloc = b.st[0], nx = b.st[1];
;     if (nloc == 0u) { xcd_barrier_complete(bar, b.x, nloc, nx); b.st[0] = nloc; b.st[1] = nx; }
;     const unsigned old = xb_add(&bar[XB_XSUB(b.x)], 1u);
;     const unsigned gen = old / nloc;
;     if (old + 1u == (gen + 1u) * nloc) {
;       __builtin_amdgcn_fence(__ATOMIC_RELEASE, "agent");
;       asm volatile("s_waitcnt vmcnt(0)" ::: "memory");
;       const unsigned og = xb_add(&bar[XB_TOP], 1u);
;       const unsigned tg = og / nx;
;       if (og + 1u == (tg + 1u) * nx) xb_add(&bar[XB_TOPGEN], 1u);
;       else XB_SPIN(xb_ld(&bar[XB_TOPGEN]) == tg, bar);
;       __builtin_amdgcn_fence(__ATOMIC_ACQUIRE, "agent");
;       xb_add(&bar[XB_XGEN(b.x)], 1u);
;       asm volatile("s_waitcnt vmcnt(0)" ::: "memory");
;     } else {
;       XB_SPIN(xb_ld(&bar[XB_XGEN(b.x)]) == gen, bar);
.LBB0_316:
	s_or_b64 exec, exec, s[0:1]
	v_readlane_b32 s52, v241, 40
	s_cmpk_lt_i32 s35, 0xc60
	v_readlane_b32 s56, v241, 44
	s_cselect_b64 s[0:1], -1, 0
	v_readlane_b32 s57, v241, 45
	s_add_u32 s94, s56, 0x200
	v_writelane_b32 v240, s0, 17
	s_addc_u32 s95, s57, 0
	v_cvt_f32_u32_e32 v0, v152
	v_writelane_b32 v240, s1, 18
	s_add_u32 s0, s56, 0x1000
	s_addc_u32 s1, s57, 0
	v_writelane_b32 v240, s0, 19
	v_mul_f32_e32 v0, 0x3d800000, v0
	s_mov_b32 s89, 0x7f800000
	v_writelane_b32 v240, s1, 20
	s_add_u32 s0, s56, 0x1100
	s_addc_u32 s1, s57, 0
	v_writelane_b32 v240, s0, 21
	v_mov_b32_e32 v188, 0x41b17218
	s_mov_b32 s6, 0x40051592
	v_writelane_b32 v240, s1, 22
	s_add_u32 s0, s56, 0x1200
	s_addc_u32 s1, s57, 0
	v_writelane_b32 v240, s0, 23
	v_readlane_b32 s58, v241, 46
	v_writelane_b32 v240, s1, 24
	s_mov_b32 s0, 0x800000
	v_cmp_gt_f32_e32 vcc, s0, v0
	s_add_u32 s0, s56, 0x1300
	s_addc_u32 s1, s57, 0
	v_cndmask_b32_e64 v1, 0, 32, vcc
	v_ldexp_f32 v0, v0, v1
	v_log_f32_e32 v0, v0
	v_writelane_b32 v240, s0, 25
	s_cmp_eq_u32 s5, 15
	v_readlane_b32 s48, v241, 28
	v_writelane_b32 v240, s1, 26
	s_mov_b32 s0, 0x3f317217
	v_mul_f32_e32 v1, 0x3f317217, v0
	v_fma_f32 v1, v0, s0, -v1
	v_fmac_f32_e32 v1, 0x3377d1cf, v0
	v_fmac_f32_e32 v1, 0x3f317217, v0
	v_cmp_lt_f32_e64 s[0:1], |v0|, s89
	v_readlane_b32 s49, v241, 29
	v_readlane_b32 s38, v241, 18
	v_cndmask_b32_e64 v0, v0, v1, s[0:1]
	v_cndmask_b32_e32 v1, 0, v188, vcc
	v_sub_f32_e32 v4, v0, v1
	v_div_scale_f32 v0, s[0:1], s6, s6, v4
	s_cselect_b64 s[0:1], -1, 0
	s_nop 0
	v_writelane_b32 v240, s0, 27
	s_cmp_eq_u32 s5, 14
	v_rcp_f32_e32 v1, v0
	v_writelane_b32 v240, s1, 28
	s_cselect_b64 s[0:1], -1, 0
	v_writelane_b32 v240, s0, 29
	s_cmp_eq_u32 s5, 13
	v_fma_f32 v2, -v0, v1, 1.0
	v_writelane_b32 v240, s1, 30
	s_cselect_b64 s[0:1], -1, 0
	v_writelane_b32 v240, s0, 31
	s_cmp_eq_u32 s5, 12
	v_fmac_f32_e32 v1, v2, v1
	v_writelane_b32 v240, s1, 32
	s_cselect_b64 s[0:1], -1, 0
	v_writelane_b32 v240, s0, 33
	s_cmp_eq_u32 s5, 11
	v_div_scale_f32 v2, vcc, v4, s6, v4
	v_writelane_b32 v240, s1, 34
	s_cselect_b64 s[0:1], -1, 0
	v_writelane_b32 v240, s0, 35
	s_cmp_eq_u32 s5, 10
	v_mul_f32_e32 v3, v2, v1
	v_writelane_b32 v240, s1, 36
	s_cselect_b64 s[0:1], -1, 0
	v_writelane_b32 v240, s0, 37
	s_cmp_eq_u32 s5, 9
	v_fma_f32 v5, -v0, v3, v2
	v_writelane_b32 v240, s1, 38
	s_cselect_b64 s[0:1], -1, 0
	v_writelane_b32 v240, s0, 39
	s_cmp_eq_u32 s5, 8
	v_fmac_f32_e32 v3, v5, v1
	v_writelane_b32 v240, s1, 40
	s_cselect_b64 s[0:1], -1, 0
	v_writelane_b32 v240, s0, 41
	s_cmp_eq_u32 s5, 7
	v_fma_f32 v0, -v0, v3, v2
	v_writelane_b32 v240, s1, 42
	s_cselect_b64 s[0:1], -1, 0
	v_writelane_b32 v240, s0, 43
	s_cmp_eq_u32 s5, 6
	v_div_fmas_f32 v5, v0, v1, v3
	v_writelane_b32 v240, s1, 44
	s_cselect_b64 s[0:1], -1, 0
	v_writelane_b32 v240, s0, 45
	s_cmp_eq_u32 s5, 5
	v_lshlrev_b32_e32 v0, 1, v152
	v_writelane_b32 v240, s1, 46
	s_cselect_b64 s[0:1], -1, 0
	v_writelane_b32 v240, s0, 47
	s_cmp_eq_u32 s5, 4
	v_and_b32_e32 v1, 7, v152
	v_writelane_b32 v240, s1, 48
	s_cselect_b64 s[0:1], -1, 0
	v_writelane_b32 v240, s0, 49
	s_cmp_eq_u32 s5, 3
	v_readlane_b32 s39, v241, 19
	v_writelane_b32 v240, s1, 50
	s_cselect_b64 s[0:1], -1, 0
	v_writelane_b32 v240, s0, 51
	s_cmp_eq_u32 s5, 2
	v_mov_b32_e32 v3, 0
	v_writelane_b32 v240, s1, 52
	s_cselect_b64 s[0:1], -1, 0
	v_writelane_b32 v240, s0, 53
	s_cmp_eq_u32 s5, 1
	v_readlane_b32 s53, v241, 41
	v_writelane_b32 v240, s1, 54
	s_cselect_b64 s[0:1], -1, 0
	v_writelane_b32 v240, s0, 55
	s_cmp_eq_u32 s5, 0
	v_cmp_gt_u32_e32 vcc, 16, v152
	v_writelane_b32 v240, s1, 56
	s_cselect_b64 s[0:1], -1, 0
	v_writelane_b32 v240, s0, 57
	v_readlane_b32 s59, v241, 47
	v_readlane_b32 s46, v241, 26
	v_writelane_b32 v240, s1, 58
	s_lshl_b32 s0, s4, 2
	s_add_u32 s0, s56, s0
	s_addc_u32 s1, s57, 0
	s_add_u32 s2, s0, 0x1400
	s_addc_u32 s3, s1, 0
	v_writelane_b32 v240, s2, 59
	s_add_u32 s0, s0, 0x2400
	s_addc_u32 s1, s1, 0
	v_writelane_b32 v240, s3, 60
	v_writelane_b32 v240, s0, 61
	v_readlane_b32 s47, v241, 27
	s_movk_i32 s33, 0x80
	v_writelane_b32 v240, s1, 62
	s_movk_i32 s0, 0x7f0
	v_and_or_b32 v0, v0, s0, v1
	s_add_u32 s0, s56, 0x3400
	s_addc_u32 s1, s57, 0
	v_writelane_b32 v240, s0, 63
	v_lshlrev_b32_e32 v2, 2, v0
	v_writelane_b32 v239, s1, 0
	s_add_u32 s0, s56, 0x3500
	s_addc_u32 s1, s57, 0
	s_add_i32 s7, 0, 0x23000
	s_add_i32 s4, 0, 0x23400
	v_writelane_b32 v239, s0, 1
	s_cmpk_lt_i32 s35, 0x200
	v_writelane_b32 v239, s1, 2
	s_cselect_b64 s[0:1], -1, 0
	v_writelane_b32 v239, s0, 3
	s_add_i32 s3, s35, 0x5c0
	v_mov_b32_e32 v192, 0x3ecc95a3
	v_writelane_b32 v239, s1, 4
	v_sub_co_u32_e64 v1, s[0:1], s35, 64
	s_xor_b64 s[0:1], s[0:1], -1
	s_nop 0
	v_writelane_b32 v239, s0, 5
	v_mov_b32_e32 v193, 0x260
	v_mov_b32_e32 v194, 1
	v_writelane_b32 v239, s1, 6
	s_sub_i32 s0, s58, 64
	s_cmpk_lt_i32 s35, 0x290
	v_writelane_b32 v239, s0, 7
	s_cselect_b64 s[0:1], -1, 0
	v_writelane_b32 v239, s0, 8
	s_cmp_gt_i32 s35, 63
	v_mov_b32_e32 v195, -1
	v_writelane_b32 v239, s1, 9
	s_cselect_b64 s[0:1], -1, 0
	v_writelane_b32 v239, s0, 10
	s_cmpk_gt_u32 s3, 0x7ff
	v_mov_b32_e32 v196, 0x3727c5ac
	v_writelane_b32 v239, s1, 11
	s_cselect_b64 s[0:1], -1, 0
	v_writelane_b32 v239, s0, 12
	s_cmpk_gt_u32 s3, 0x82f
	s_cselect_b64 s[8:9], -1, 0
	v_writelane_b32 v239, s1, 13
	s_mul_hi_i32 s0, s3, 0x2aaaaaab
	s_lshr_b32 s1, s0, 31
	s_ashr_i32 s0, s0, 4
	s_add_i32 s5, s0, s1
	s_lshr_b32 s0, s35, 1
	s_and_b32 s0, s0, 6
	s_lshr_b32 s1, s35, 5
	v_writelane_b32 v239, s8, 14
	s_or_b32 s2, s0, s1
	s_add_i32 s0, s35, 0xfffffd90
	v_writelane_b32 v239, s9, 15
	s_lshr_b32 s0, s0, 4
	v_writelane_b32 v239, s0, 16
	s_and_b32 s0, s3, 0xff
	s_mulk_i32 s0, 0xab
; DI void conv_weights(const Params& p, int l, char* lds, int t_first, int t_stride, int t_end) {
;     ...
;   auto loadtile = [&](int tI, float* rv, TD& d) {
;     const float* src; const float* ksc = nullptr; int ldsrc, kind, kt, ntile;
;     ...
;     else if (tI < 2048) { int u = tI - 1536; kind = 1; kt = u / 16; ntile = u % 16; src = p.w_out + (size_t)l * 2048 * DM; ldsrc = DM; d.K = 2048; d.dst = p.Wt_out + (size_t)(l & 1) * DM * 2048; }
;     else if (tI < 2096) { int u = tI - 2048; kind = 2; kt = u / 12; ntile = u % 12; src = p.w_uq + (size_t)l * 256 * 768; ldsrc = 768; d.K = 256; d.dst = p.Wt_uq; ksc = p.gq + l * 256; }
;     else { int u = tI - 2096; kind = 3; kt = u / 16; ntile = u % 16; src = p.w_ukv + (size_t)l * 128 * 1024; ldsrc = 1024; d.K = 128; d.dst = p.Wt_ukv; ksc = p.gkv + l * 128; }
;     d.k0 = kt * 64; d.n0 = ntile * 64;
;     const int n = d.n0 + nn_l;
;     int sc;
;     if (kind == 0) sc = map_in(n);
;     else if (kind == 3) sc = (n < 512) ? ((n >> 6) * 128 + (n & 63)) : (((n - 512) >> 6) * 128 + 64 + (n & 63));
;     else sc = n;
; __global__ void __launch_bounds__(NTHREADS) mega(Params p) {
;     ...
;     for (int rep = 0; rep < REP_P1; ++rep) {
;       for (int j = blockIdx.x; j < 66 * 48; j += gridDim.x) inproj_tile(p, l, j / 48, j % 48, lds);
;       if (l < 3 && rep == 0) {
;         const int nbusy = 66 * 48 - (66 * 48 / (int)gridDim.x) * (int)gridDim.x;
;         const int nidle = (int)gridDim.x - nbusy;
;         if ((int)blockIdx.x >= nbusy && nidle > 0) conv_weights(p, l + 1, lds, (int)blockIdx.x - nbusy, nidle, 1536);
	s_lshr_b32 s0, s0, 11
	v_writelane_b32 v239, s0, 17
	s_mul_i32 s0, s0, 12
	s_sub_i32 s0, s3, s0
	s_and_b32 s0, s0, 0xff
	v_writelane_b32 v239, s0, 18
	v_readfirstlane_b32 s0, v1
	s_lshr_b32 s0, s0, 4
	v_mov_b32_e32 v197, 0x7f800000
	v_writelane_b32 v239, s0, 19
	v_writelane_b32 v239, s5, 20
	s_mul_i32 s0, s5, 0x60
	v_writelane_b32 v239, s3, 21
	s_sub_i32 s0, s3, s0
	v_writelane_b32 v239, s0, 22
	s_lshl_b32 s0, s35, 4
	s_and_b32 s1, s0, 0x100
	s_and_b32 s0, s35, 15
	v_writelane_b32 v239, s0, 23
	v_writelane_b32 v239, s1, 24
	s_bitset1_b32 s1, 14
	s_and_b32 s0, s35, 3
	v_writelane_b32 v239, s1, 25
	s_lshl_b32 s1, s1, 12
	s_add_u32 s1, s48, s1
	s_addc_u32 s3, s49, 0
	s_lshl_b32 s5, s0, 10
	s_add_u32 s8, s1, s5
	s_addc_u32 s9, s3, 0
	s_lshl_b32 s1, s2, 19
	s_add_u32 s1, s38, s1
	v_writelane_b32 v239, s8, 26
	s_addc_u32 s3, s39, 0
	s_add_u32 s1, s1, s5
	v_writelane_b32 v239, s9, 27
	v_writelane_b32 v239, s1, 28
	v_readlane_b32 s16, v241, 8
	v_readlane_b32 s17, v241, 9
	s_addc_u32 s1, s3, 0
	v_writelane_b32 v239, s1, 29
	v_lshl_add_u64 v[154:155], s[16:17], 0, v[2:3]
	v_sub_co_u32_e64 v2, s[0:1], s0, 1
	s_xor_b64 s[0:1], s[0:1], -1
	s_nop 0
	v_writelane_b32 v239, s0, 30
	v_lshlrev_b64 v[0:1], 21, v[2:3]
	v_lshl_add_u64 v[0:1], s[52:53], 0, v[0:1]
	v_writelane_b32 v239, s1, 31
	s_lshl_b32 s0, s2, 7
	s_mov_b32 s1, s61
	v_writelane_b32 v239, s0, 32
	v_writelane_b32 v239, s1, 33
	s_lshl_b64 s[0:1], s[0:1], 2
	v_lshl_add_u64 v[156:157], v[0:1], 0, s[0:1]
	v_div_fixup_f32 v0, v5, s6, v4
	v_mul_f32_e32 v0, 0x41800000, v0
	v_cvt_i32_f32_e32 v0, v0
	s_add_u32 s0, s74, s0
	s_addc_u32 s1, s75, s1
	v_writelane_b32 v239, s0, 34
	v_min_i32_e32 v0, 15, v0
	v_add_u32_e32 v0, 16, v0
	v_writelane_b32 v239, s1, 35
	s_abs_i32 s0, s58
	v_cndmask_b32_e32 v189, v0, v152, vcc
	v_cvt_f32_u32_e32 v0, s0
	s_sub_i32 s1, 0, s0
	s_mov_b32 s18, s76
	v_mov_b32_e32 v199, 0x43000000
	v_rcp_iflag_f32_e32 v0, v0
	v_mov_b32_e32 v200, 0x43800000
	v_bfrev_b32_e32 v201, 0.5
	v_mov_b32_e32 v202, 0x70
	v_mul_f32_e32 v0, 0x4f7ffffe, v0
	v_cvt_u32_f32_e32 v0, v0
	v_mov_b32_e32 v203, 0xf149f2ca
	v_mov_b32_e32 v204, 0x1200
	v_mov_b32_e32 v205, 0x80
	v_readfirstlane_b32 s2, v0
	s_mul_i32 s1, s1, s2
	s_mul_hi_u32 s1, s2, s1
	s_add_i32 s2, s2, s1
	s_mul_hi_u32 s1, s2, 0xc60
	s_mul_i32 s1, s1, s0
	s_sub_i32 s1, 0xc60, s1
	s_sub_i32 s2, s1, s0
	s_cmp_ge_u32 s1, s0
	s_cselect_b32 s1, s2, s1
	s_sub_i32 s2, s1, s0
	s_cmp_ge_u32 s1, s0
	s_cselect_b32 s5, s2, s1
	s_sub_i32 s91, s58, s5
	s_cmp_ge_i32 s35, s5
	s_cselect_b64 s[0:1], -1, 0
	s_cmp_gt_i32 s91, 0
	s_cselect_b64 s[2:3], -1, 0
	s_and_b64 s[0:1], s[0:1], s[2:3]
	v_writelane_b32 v239, s0, 36
	s_sub_i32 s2, s35, s5
	v_lshlrev_b32_e32 v0, 2, v152
	v_writelane_b32 v239, s1, 37
	s_mul_i32 s0, s59, s58
	s_mul_i32 s96, s0, s28
	s_sext_i32_i16 s0, s2
	s_cmpk_lt_i32 s2, 0x600
	s_mulk_i32 s0, 0x2aab
	v_add_u32_e32 v190, s4, v0
	s_cselect_b64 s[4:5], -1, 0
	s_lshr_b32 s1, s0, 31
	s_ashr_i32 s0, s0, 20
	s_add_i32 s0, s0, s1
	s_sext_i32_i16 s1, s0
	s_mulk_i32 s0, 0x60
	s_sub_i32 s0, s2, s0
	v_writelane_b32 v239, s4, 38
	s_sext_i32_i16 s0, s0
	s_lshl_b32 s1, s1, 6
	v_writelane_b32 v239, s5, 39
	s_lshl_b32 s0, s0, 6
	v_writelane_b32 v239, s7, 40
	s_cmpk_gt_u32 s0, 0x5ff
	v_writelane_b32 v239, s2, 41
	s_cselect_b64 s[2:3], -1, 0
	v_writelane_b32 v239, s2, 42
	s_cmpk_gt_u32 s0, 0x6ff
	v_add_u32_e32 v191, s7, v0
	v_writelane_b32 v239, s3, 43
	s_cselect_b64 s[2:3], -1, 0
	v_writelane_b32 v239, s2, 44
	s_cmpk_gt_u32 s0, 0x77f
	v_mov_b32_e32 v206, 0x1a00
	v_writelane_b32 v239, s3, 45
	s_cselect_b64 s[2:3], -1, 0
; DI int opaque_tid() { int t = threadIdx.x; asm volatile("" : "+v"(t)); return t; }
; DI int map_in(int n) {
;   if (n < 512) return n;
;   if (n < 1024) return n;
;   if (n < 1536) return 1544 + (n - 1024);
;   if (n < 1792) return 2056 + (n - 1536);
;   if (n < 1920) return 2312 + (n - 1792);
;   if (n < 2432) return 2472 + (n - 1920);
;   if (n < 2944) return 2984 + (n - 2432);
;   if (n < 3072) return 3496 + (n - 2944);
;   if (n < 3200) return 3624 + (n - 3072);
;   if (n < 3712) return 3752 + (n - 3200);
;   if (n < 4224) return 4336 + (n - 3712);
;   if (n < 4736) return 4848 + (n - 4224);
;   if (n < 4864) return 5360 + (n - 4736);
;   if (n < 5376) return 5616 + (n - 4864);
;   if (n < 5408) return 2440 + (n - 5376);
;   if (n < 5472) return 4264 + (n - 5408);
;   if (n < 5480) return 1536 + (n - 5472);
;   if (n < 5488) return 4328 + (n - 5480);
;   if (n < 5504) return -1;
;   if (n < 6016) return 1024 + (n - 5504);
;   return 5488 + (n - 6016);
; }
; DI void conv_weights(const Params& p, int l, char* lds, int t_first, int t_stride, int t_end) {
;   const int tid = opaque_tid();
;   float* tile = (float*)lds;
;   struct TD { u16* dst; int K, k0, n0; };
;   const int nn_l = tid & 63;
;   auto loadtile = [&](int tI, float* rv, TD& d) {
;     const float* src; const float* ksc = nullptr; int ldsrc, kind, kt, ntile;
;     ...
;     else if (tI < 2048) { int u = tI - 1536; kind = 1; kt = u / 16; ntile = u % 16; src = p.w_out + (size_t)l * 2048 * DM; ldsrc = DM; d.K = 2048; d.dst = p.Wt_out + (size_t)(l & 1) * DM * 2048; }
;     else if (tI < 2096) { int u = tI - 2048; kind = 2; kt = u / 12; ntile = u % 12; src = p.w_uq + (size_t)l * 256 * 768; ldsrc = 768; d.K = 256; d.dst = p.Wt_uq; ksc = p.gq + l * 256; }
;     else { int u = tI - 2096; kind = 3; kt = u / 16; ntile = u % 16; src = p.w_ukv + (size_t)l * 128 * 1024; ldsrc = 1024; d.K = 128; d.dst = p.Wt_ukv; ksc = p.gkv + l * 128; }
;     d.k0 = kt * 64; d.n0 = ntile * 64;
;     const int n = d.n0 + nn_l;
;     int sc;
;     if (kind == 0) sc = map_in(n);
;     else if (kind == 3) sc = (n < 512) ? ((n >> 6) * 128 + (n & 63)) : (((n - 512) >> 6) * 128 + 64 + (n & 63));
;     else sc = n;
	v_writelane_b32 v239, s2, 46
	s_cmpk_gt_u32 s0, 0x97f
	v_mbcnt_lo_u32_b32 v0, -1, 0
	v_writelane_b32 v239, s3, 47
	s_cselect_b64 s[2:3], -1, 0
	v_writelane_b32 v239, s2, 48
	s_cmpk_gt_u32 s0, 0xb7f
	v_mbcnt_hi_u32_b32 v198, -1, v0
	v_writelane_b32 v239, s3, 49
	s_cselect_b64 s[2:3], -1, 0
	v_writelane_b32 v239, s2, 50
	s_cmpk_gt_u32 s0, 0xbff
	s_mov_b32 s60, 0x20000
	v_writelane_b32 v239, s3, 51
	s_cselect_b64 s[2:3], -1, 0
	v_writelane_b32 v239, s2, 52
	s_cmpk_gt_u32 s0, 0xc7f
	s_movk_i32 s57, 0x90
	v_writelane_b32 v239, s3, 53
	s_cselect_b64 s[2:3], -1, 0
	v_writelane_b32 v239, s2, 54
	s_cmpk_gt_u32 s0, 0xe7f
	s_movk_i32 s53, 0x2a00
	v_writelane_b32 v239, s3, 55
	s_cselect_b64 s[2:3], -1, 0
	v_writelane_b32 v239, s2, 56
	s_cmpk_gt_u32 s0, 0x107f
	s_movk_i32 s86, 0x6f
	v_writelane_b32 v239, s3, 57
	s_cselect_b64 s[2:3], -1, 0
	v_writelane_b32 v239, s2, 58
	s_cmpk_gt_u32 s0, 0x127f
	s_mov_b32 s38, 0
	v_writelane_b32 v239, s3, 59
	s_cselect_b64 s[2:3], -1, 0
	v_writelane_b32 v239, s2, 60
	s_cmpk_gt_u32 s0, 0x12ff
	s_mov_b32 s52, 0x3e38aa3b
	v_writelane_b32 v239, s3, 61
	s_cselect_b64 s[2:3], -1, 0
	v_writelane_b32 v239, s2, 62
	s_cmpk_gt_u32 s0, 0x14ff
	s_mov_b64 s[54:55], 0x100
	v_writelane_b32 v239, s3, 63
	s_cselect_b64 s[2:3], -1, 0
	v_writelane_b32 v238, s2, 0
	s_cmpk_gt_u32 s0, 0x157f
	v_writelane_b32 v238, s3, 1
	s_cselect_b64 s[2:3], -1, 0
	v_writelane_b32 v238, s2, 2
	s_cmpk_gt_u32 s0, 0x177f
	v_writelane_b32 v238, s3, 3
	v_writelane_b32 v238, s0, 4
	s_cselect_b64 s[2:3], -1, 0
	v_writelane_b32 v238, s2, 5
	s_or_b32 s0, s1, 8
	s_ashr_i32 s19, s76, 31
	v_writelane_b32 v238, s3, 6
	v_writelane_b32 v238, s0, 7
	s_or_b32 s0, s1, 16
	v_writelane_b32 v238, s0, 8
	s_or_b32 s0, s1, 24
	v_writelane_b32 v238, s0, 9
	s_or_b32 s0, s1, 32
	v_writelane_b32 v238, s0, 10
	s_or_b32 s0, s1, 40
	v_writelane_b32 v238, s0, 11
	s_or_b32 s0, s1, 48
	v_writelane_b32 v238, s0, 12
	v_writelane_b32 v238, s1, 13
	s_or_b32 s0, s1, 56
	v_writelane_b32 v238, s0, 14
	s_lshl_b32 s0, s35, 1
	v_writelane_b32 v238, s0, 15
	v_writelane_b32 v238, s35, 16
	s_lshl_b32 s0, s35, 7
	v_writelane_b32 v238, s0, 17
	s_lshl_b32 s0, s58, 1
	v_writelane_b32 v238, s0, 18
	v_readlane_b32 s0, v241, 48
	s_add_i32 s1, s0, 0xffffff80
	v_writelane_b32 v238, s1, 19
	s_add_i32 s0, s0, s76
	v_writelane_b32 v238, s0, 20
	s_lshl_b64 s[0:1], s[18:19], 12
	v_writelane_b32 v238, s0, 21
	v_writelane_b32 v238, s1, 22
	s_add_u32 s0, s46, 0x400
	s_addc_u32 s1, s47, 0
	v_writelane_b32 v238, s0, 23
	s_add_i32 s59, 0, 0x16800
	v_writelane_b32 v238, s1, 24
	s_add_i32 s1, 0, 0xd800
	v_writelane_b32 v238, s1, 25
	s_add_i32 s1, 0, 0x10000
	v_writelane_b32 v238, s1, 26
	s_add_i32 s1, 0, 0x400
	s_movk_i32 s0, 0x100
	v_writelane_b32 v238, s1, 27
	s_add_i32 s1, 0, 0x23010
	v_writelane_b32 v238, s1, 28
	v_cmp_gt_u32_e64 s[0:1], s0, v152
	s_nop 0
	s_nop 0
	v_writelane_b32 v238, s0, 29
	v_writelane_b32 v238, s1, 30
	v_cmp_gt_u32_e64 s[0:1], s33, v152
	s_nop 0
	s_nop 0
	v_writelane_b32 v238, s0, 31
	s_nop 0
	s_nop 0
	v_writelane_b32 v238, s1, 32
	s_lshl_b64 s[0:1], s[18:19], 11
	v_writelane_b32 v238, s0, 33
	v_writelane_b32 v238, s1, 34
	s_mov_b64 s[0:1], 0
	v_writelane_b32 v238, s0, 35
	v_writelane_b32 v238, s1, 36
	v_writelane_b32 v238, s92, 37
	v_readlane_b32 s22, v241, 14
	v_writelane_b32 v238, s93, 38
	v_writelane_b32 v238, s94, 39
	v_readlane_b32 s23, v241, 15
	s_nop 0
	v_writelane_b32 v238, s95, 40
	v_writelane_b32 v238, s91, 41
	v_writelane_b32 v238, s96, 42
	v_writelane_b32 v238, s18, 43
	s_nop 1
	v_writelane_b32 v238, s19, 44
	s_branch .LBB0_320

; #define MFMA32(a, b, c) __builtin_amdgcn_mfma_f32_32x32x16_bf16((a), (b), (c), 0, 0, 0)
; DI void topk_job(const Params& p, int b, int t0, char* lds) {
;     ...
; #pragma unroll
;     for (int i = 0; i < 17; ++i) {
;       const int c = 1 + w + 8 * i;
;       if (c <= cmax) {
;         const bool more = c + 8 <= cmax;
;         if (more) {
;           const u16* kp = ikb + (size_t)(c + 8) * 64 * 64;
; #pragma unroll
;           for (int j = 0; j < 8; ++j) st[j] = *(const u32x4*)(kp + (size_t)j * 8 * 64);
;         }
;         bf16x8 b0[4], b1[4];
; #pragma unroll
;         for (int ks = 0; ks < 4; ++ks) {
;           b0[ks] = *(const bf16x8*)(wb + r * 144 + ks * 32 + h * 16);
;           b1[ks] = *(const bf16x8*)(wb + (32 + r) * 144 + ks * 32 + h * 16);
;         }
;         __builtin_amdgcn_sched_barrier(0);
;         f32x16 a0, a1;
; #pragma unroll
;         for (int e = 0; e < 16; ++e) { a0[e] = 0.f; a1[e] = 0.f; }
; #pragma unroll
;         for (int ks = 0; ks < 4; ++ks) { a0 = MFMA32(af[ks], b0[ks], a0); a1 = MFMA32(af[ks], b1[ks], a1); }
;         const int key = c * 64 + lane;
; #pragma unroll
;         for (int qi = 0; qi < 4; ++qi) {
;           f32x2 pp2 = {0.f, 0.f};
; #pragma unroll
;           for (int e = 0; e < 4; ++e) {
;             const f32x2 rl = {fmaxf(a0[4 * qi + e], 0.f), fmaxf(a1[4 * qi + e], 0.f)};
;             const f32x2 wv = {iw[qi][e], iw[qi][e]};
;             pp2 += rl * wv;
;           }
;           const float p0 = pp2[0], p1 = pp2[1];
;           const u32x2 sw = __builtin_amdgcn_permlane32_swap(__float_as_uint(p0), __float_as_uint(p1), false, false);
;           float mine = __uint_as_float(sw[0]) + __uint_as_float(sw[1]);
;           mine += 0.0f;
;           unsigned u = __float_as_uint(mine);
;           u = (u & 0x80000000u) ? ~u : (u | 0x80000000u);
;           if (key > t0 + qi || key < LEAD) u = 0u;
;           sc[i][qi] = u;
;         }
;         if (more) {
; #pragma unroll
;           for (int j = 0; j < 8; ++j) *(u32x4*)(wb + (lrow + 8 * j) * 144 + lpc * 16) = st[j];
;         }
.LBB0_654:
	s_or_b64 exec, exec, s[0:1]
	s_waitcnt vmcnt(0)
	v_and_b32_e32 v2, 31, v100
	v_mul_u32_u24_e32 v2, 0x90, v2
	v_and_b32_e32 v101, 63, v100
	v_add3_u32 v210, v5, v2, v4
	v_add_u32_e32 v2, v5, v8
	v_add_u32_e32 v132, 9, v137
	v_mov_b32_e32 v175, 0
	v_mov_b32_e32 v208, 0
	v_mov_b32_e32 v138, 0
	v_mov_b32_e32 v161, 0
	s_and_saveexec_b64 s[18:19], s[28:29]
	s_cbranch_execz .LBB0_660
	v_cmp_ge_i32_e64 s[0:1], s90, v132
	s_and_saveexec_b64 s[2:3], s[0:1]
	s_cbranch_execz .LBB0_657
	v_ashrrev_i32_e32 v133, 31, v132
	v_lshlrev_b64 v[4:5], 13, v[132:133]
	v_lshl_add_u64 v[4:5], v[0:1], 0, v[4:5]
	global_load_dwordx4 v[68:71], v[4:5], off
	global_load_dwordx4 v[72:75], v[4:5], off offset:1024
	global_load_dwordx4 v[76:79], v[4:5], off offset:2048
	global_load_dwordx4 v[80:83], v[4:5], off offset:3072
	v_add_co_u32_e32 v4, vcc, 0x1000, v4
	s_nop 1
	v_addc_co_u32_e32 v5, vcc, 0, v5, vcc
	global_load_dwordx4 v[84:87], v[4:5], off
	global_load_dwordx4 v[88:91], v[4:5], off offset:1024
	global_load_dwordx4 v[92:95], v[4:5], off offset:2048
	global_load_dwordx4 v[96:99], v[4:5], off offset:3072
.LBB0_657:
	s_or_b64 exec, exec, s[2:3]
	ds_read_b128 v[4:7], v210 offset:16384
	ds_read_b128 v[102:105], v210 offset:16416
	s_waitcnt vmcnt(8)
	ds_read_b128 v[8:11], v210 offset:20992
	ds_read_b128 v[106:109], v210 offset:21024
	ds_read_b128 v[110:113], v210 offset:16448
	ds_read_b128 v[114:117], v210 offset:16480
	ds_read_b128 v[118:121], v210 offset:21056
	ds_read_b128 v[122:125], v210 offset:21088
	s_waitcnt lgkmcnt(7)
	v_mfma_f32_32x32x16_bf16 v[20:35], v[64:67], v[4:7], 0
	s_sub_i32 s2, 0x209d, s23
	s_sub_i32 s10, 0x209e, s23
	s_waitcnt lgkmcnt(5)
	v_mfma_f32_32x32x16_bf16 v[4:19], v[64:67], v[8:11], 0
	v_mfma_f32_32x32x16_bf16 v[20:35], v[60:63], v[102:105], v[20:35]
	v_lshl_or_b32 v104, v134, 6, v101
	v_cmp_gt_i32_e32 vcc, s25, v104
	v_cmp_lt_i32_e64 s[6:7], s24, v104
	v_cmp_lt_i32_e64 s[2:3], s2, v104
	v_cmp_lt_i32_e64 s[14:15], s10, v104
	v_cmp_lt_i32_e64 s[10:11], s22, v104
	s_waitcnt lgkmcnt(4)
	v_mfma_f32_32x32x16_bf16 v[4:19], v[60:63], v[106:109], v[4:19]
	s_waitcnt lgkmcnt(3)
	v_mfma_f32_32x32x16_bf16 v[20:35], v[56:59], v[110:113], v[20:35]
	s_waitcnt lgkmcnt(1)
	v_mfma_f32_32x32x16_bf16 v[4:19], v[56:59], v[118:121], v[4:19]
	v_mfma_f32_32x32x16_bf16 v[20:35], v[52:55], v[114:117], v[20:35]
	s_waitcnt lgkmcnt(0)
	v_mfma_f32_32x32x16_bf16 v[4:19], v[52:55], v[122:125], v[4:19]
	s_nop 9
	v_max_f32_e32 v20, v20, v20
	v_max_f32_e32 v102, 0, v20
	v_max_f32_e32 v20, v22, v22
	v_max_f32_e32 v20, 0, v20
	v_max_f32_e32 v4, v4, v4
	v_max_f32_e32 v103, 0, v4
	v_max_f32_e32 v4, v21, v21
	v_max_f32_e32 v5, v5, v5
	v_pk_fma_f32 v[102:103], v[48:49], v[102:103], 0 op_sel_hi:[0,1,0]
	v_max_f32_e32 v4, 0, v4
	v_max_f32_e32 v5, 0, v5
	v_max_f32_e32 v6, v6, v6
	v_pk_fma_f32 v[4:5], v[48:49], v[4:5], v[102:103] op_sel:[1,0,0]
	v_max_f32_e32 v21, 0, v6
	v_max_f32_e32 v6, v23, v23
	v_max_f32_e32 v7, v7, v7
	v_pk_fma_f32 v[4:5], v[50:51], v[20:21], v[4:5] op_sel_hi:[0,1,1]
	v_max_f32_e32 v6, 0, v6
	v_max_f32_e32 v7, 0, v7
	v_mov_b32_e32 v20, v51
	v_pk_fma_f32 v[4:5], v[20:21], v[6:7], v[4:5] op_sel_hi:[0,1,1]
	v_mov_b32_e32 v6, v5
	v_max_f32_e32 v5, v24, v24
	v_max_f32_e32 v20, 0, v5
	v_max_f32_e32 v5, v8, v8
	v_max_f32_e32 v21, 0, v5
	v_max_f32_e32 v5, v25, v25
	v_max_f32_e32 v8, 0, v5
	v_max_f32_e32 v5, v9, v9
	v_pk_fma_f32 v[20:21], v[44:45], v[20:21], 0 op_sel_hi:[0,1,0]
	v_max_f32_e32 v9, 0, v5
	v_max_f32_e32 v5, v26, v26
	v_pk_fma_f32 v[8:9], v[44:45], v[8:9], v[20:21] op_sel:[1,0,0]
	v_max_f32_e32 v20, 0, v5
	v_max_f32_e32 v5, v10, v10
	v_max_f32_e32 v21, 0, v5
	v_max_f32_e32 v5, v27, v27
	v_max_f32_e32 v10, 0, v5
	v_max_f32_e32 v5, v11, v11
	v_pk_fma_f32 v[8:9], v[46:47], v[20:21], v[8:9] op_sel_hi:[0,1,1]
	v_max_f32_e32 v11, 0, v5
	v_mov_b32_e32 v20, v47
	v_pk_fma_f32 v[8:9], v[20:21], v[10:11], v[8:9] op_sel_hi:[0,1,1]
	v_mov_b32_e32 v7, v9
	s_nop 1
	v_permlane32_swap_b32_e32 v8, v7
	v_permlane32_swap_b32_e32 v4, v6
	v_mov_b32_e32 v5, v8
	v_pk_add_f32 v[4:5], v[4:5], v[6:7]
	v_max_f32_e32 v6, v28, v28
	v_max_f32_e32 v7, v12, v12
	v_max_f32_e32 v6, 0, v6
	v_max_f32_e32 v7, 0, v7
	v_max_f32_e32 v8, v29, v29
	v_max_f32_e32 v9, v13, v13
	v_pk_fma_f32 v[6:7], v[40:41], v[6:7], 0 op_sel_hi:[0,1,0]
	v_max_f32_e32 v8, 0, v8
	v_max_f32_e32 v9, 0, v9
	v_pk_fma_f32 v[6:7], v[40:41], v[8:9], v[6:7] op_sel:[1,0,0]
	v_max_f32_e32 v8, v30, v30
	v_max_f32_e32 v9, v14, v14
	v_max_f32_e32 v8, 0, v8
	v_max_f32_e32 v9, 0, v9
	v_pk_fma_f32 v[6:7], v[42:43], v[8:9], v[6:7] op_sel_hi:[0,1,1]
	v_max_f32_e32 v8, v31, v31
	v_max_f32_e32 v9, v15, v15
	v_max_f32_e32 v8, 0, v8
	v_max_f32_e32 v9, 0, v9
	v_mov_b32_e32 v10, v43
	v_pk_fma_f32 v[6:7], v[10:11], v[8:9], v[6:7] op_sel_hi:[0,1,1]
	v_mov_b32_e32 v8, v7
	v_max_f32_e32 v7, v32, v32
	v_max_f32_e32 v10, 0, v7
	v_max_f32_e32 v7, v16, v16
	v_max_f32_e32 v11, 0, v7
	v_max_f32_e32 v7, v33, v33
	v_max_f32_e32 v12, 0, v7
	v_max_f32_e32 v7, v17, v17
	v_pk_fma_f32 v[10:11], v[36:37], v[10:11], 0 op_sel_hi:[0,1,0]
	v_max_f32_e32 v13, 0, v7
	v_max_f32_e32 v7, v34, v34
	v_pk_fma_f32 v[10:11], v[36:37], v[12:13], v[10:11] op_sel:[1,0,0]
	v_max_f32_e32 v12, 0, v7
	v_max_f32_e32 v7, v18, v18
	v_max_f32_e32 v13, 0, v7
	v_max_f32_e32 v7, v35, v35
	v_pk_fma_f32 v[10:11], v[38:39], v[12:13], v[10:11] op_sel_hi:[0,1,1]
	v_max_f32_e32 v12, 0, v7
	v_max_f32_e32 v7, v19, v19
	v_max_f32_e32 v13, 0, v7
	v_mov_b32_e32 v14, v39
	v_pk_fma_f32 v[10:11], v[14:15], v[12:13], v[10:11] op_sel_hi:[0,1,1]
	v_mov_b32_e32 v9, v11
	s_nop 1
	v_permlane32_swap_b32_e32 v10, v9
	v_permlane32_swap_b32_e32 v6, v8
	v_mov_b32_e32 v7, v10
	v_pk_add_f32 v[6:7], v[6:7], v[8:9]
	v_pk_add_f32 v[4:5], v[4:5], 0 op_sel_hi:[1,0]
	v_pk_add_f32 v[6:7], v[6:7], 0 op_sel_hi:[1,0]
	v_cmp_gt_i32_e64 s[4:5], 0, v4
	v_cmp_gt_i32_e64 s[8:9], 0, v5
	v_cmp_gt_i32_e64 s[12:13], 0, v6
	v_cmp_gt_i32_e64 s[16:17], 0, v7
	s_and_saveexec_b64 s[20:21], s[0:1]
	s_cbranch_execz .LBB0_659
	v_mad_u32_u24 v8, v209, s57, v2
	s_waitcnt vmcnt(0)
	ds_write_b128 v8, v[68:71] offset:16384
	ds_write_b128 v8, v[72:75] offset:17536
	ds_write_b128 v8, v[76:79] offset:18688
	ds_write_b128 v8, v[80:83] offset:19840
	ds_write_b128 v8, v[84:87] offset:20992
	ds_write_b128 v8, v[88:91] offset:22144
	ds_write_b128 v8, v[92:95] offset:23296
	ds_write_b128 v8, v[96:99] offset:24448

; #define MFMA32(a, b, c) __builtin_amdgcn_mfma_f32_32x32x16_bf16((a), (b), (c), 0, 0, 0)
; DI void topk_job(const Params& p, int b, int t0, char* lds) {
;     ...
; #pragma unroll
;     for (int i = 0; i < 17; ++i) {
;       const int c = 1 + w + 8 * i;
;       if (c <= cmax) {
;         const bool more = c + 8 <= cmax;
;         if (more) {
;           const u16* kp = ikb + (size_t)(c + 8) * 64 * 64;
; #pragma unroll
;           for (int j = 0; j < 8; ++j) st[j] = *(const u32x4*)(kp + (size_t)j * 8 * 64);
;         }
;         bf16x8 b0[4], b1[4];
; #pragma unroll
;         for (int ks = 0; ks < 4; ++ks) {
;           b0[ks] = *(const bf16x8*)(wb + r * 144 + ks * 32 + h * 16);
;           b1[ks] = *(const bf16x8*)(wb + (32 + r) * 144 + ks * 32 + h * 16);
;         }
;         __builtin_amdgcn_sched_barrier(0);
;         f32x16 a0, a1;
; #pragma unroll
;         for (int e = 0; e < 16; ++e) { a0[e] = 0.f; a1[e] = 0.f; }
; #pragma unroll
;         for (int ks = 0; ks < 4; ++ks) { a0 = MFMA32(af[ks], b0[ks], a0); a1 = MFMA32(af[ks], b1[ks], a1); }
;         const int key = c * 64 + lane;
; #pragma unroll
;         for (int qi = 0; qi < 4; ++qi) {
;           f32x2 pp2 = {0.f, 0.f};
; #pragma unroll
;           for (int e = 0; e < 4; ++e) {
;             const f32x2 rl = {fmaxf(a0[4 * qi + e], 0.f), fmaxf(a1[4 * qi + e], 0.f)};
;             const f32x2 wv = {iw[qi][e], iw[qi][e]};
;             pp2 += rl * wv;
;           }
;           const float p0 = pp2[0], p1 = pp2[1];
;           const u32x2 sw = __builtin_amdgcn_permlane32_swap(__float_as_uint(p0), __float_as_uint(p1), false, false);
;           float mine = __uint_as_float(sw[0]) + __uint_as_float(sw[1]);
;           mine += 0.0f;
;           unsigned u = __float_as_uint(mine);
;           u = (u & 0x80000000u) ? ~u : (u | 0x80000000u);
;           if (key > t0 + qi || key < LEAD) u = 0u;
;           sc[i][qi] = u;
;         }
;         if (more) {
; #pragma unroll
;           for (int j = 0; j < 8; ++j) *(u32x4*)(wb + (lrow + 8 * j) * 144 + lpc * 16) = st[j];
;         }
.LBB0_663:
	s_or_b64 exec, exec, s[2:3]
	ds_read_b128 v[4:7], v210 offset:16384
	ds_read_b128 v[102:105], v210 offset:16416
	s_waitcnt vmcnt(8)
	ds_read_b128 v[8:11], v210 offset:20992
	ds_read_b128 v[106:109], v210 offset:21024
	ds_read_b128 v[110:113], v210 offset:16448
	ds_read_b128 v[114:117], v210 offset:16480
	ds_read_b128 v[118:121], v210 offset:21056
	ds_read_b128 v[122:125], v210 offset:21088
	s_waitcnt lgkmcnt(7)
	v_mfma_f32_32x32x16_bf16 v[20:35], v[64:67], v[4:7], 0
	s_sub_i32 s2, 0x209d, s23
	s_sub_i32 s10, 0x209e, s23
	s_waitcnt lgkmcnt(5)
	v_mfma_f32_32x32x16_bf16 v[4:19], v[64:67], v[8:11], 0
	v_mfma_f32_32x32x16_bf16 v[20:35], v[60:63], v[102:105], v[20:35]
	v_lshl_or_b32 v104, v132, 6, v101
	v_cmp_gt_i32_e32 vcc, s25, v104
	v_cmp_lt_i32_e64 s[6:7], s24, v104
	v_cmp_lt_i32_e64 s[2:3], s2, v104
	v_cmp_lt_i32_e64 s[14:15], s10, v104
	v_cmp_lt_i32_e64 s[10:11], s22, v104
	s_waitcnt lgkmcnt(4)
	v_mfma_f32_32x32x16_bf16 v[4:19], v[60:63], v[106:109], v[4:19]
	s_waitcnt lgkmcnt(3)
	v_mfma_f32_32x32x16_bf16 v[20:35], v[56:59], v[110:113], v[20:35]
	s_waitcnt lgkmcnt(1)
	v_mfma_f32_32x32x16_bf16 v[4:19], v[56:59], v[118:121], v[4:19]
	v_mfma_f32_32x32x16_bf16 v[20:35], v[52:55], v[114:117], v[20:35]
	s_waitcnt lgkmcnt(0)
	v_mfma_f32_32x32x16_bf16 v[4:19], v[52:55], v[122:125], v[4:19]
	s_nop 9
	v_max_f32_e32 v20, v20, v20
	v_max_f32_e32 v102, 0, v20
	v_max_f32_e32 v20, v22, v22
	v_max_f32_e32 v20, 0, v20
	v_max_f32_e32 v4, v4, v4
	v_max_f32_e32 v103, 0, v4
	v_max_f32_e32 v4, v21, v21
	v_max_f32_e32 v5, v5, v5
	v_pk_fma_f32 v[102:103], v[48:49], v[102:103], 0 op_sel_hi:[0,1,0]
	v_max_f32_e32 v4, 0, v4
	v_max_f32_e32 v5, 0, v5
	v_max_f32_e32 v6, v6, v6
	v_pk_fma_f32 v[4:5], v[48:49], v[4:5], v[102:103] op_sel:[1,0,0]
	v_max_f32_e32 v21, 0, v6
	v_max_f32_e32 v6, v23, v23
	v_max_f32_e32 v7, v7, v7
	v_pk_fma_f32 v[4:5], v[50:51], v[20:21], v[4:5] op_sel_hi:[0,1,1]
	v_max_f32_e32 v6, 0, v6
	v_max_f32_e32 v7, 0, v7
	v_mov_b32_e32 v20, v51
	v_pk_fma_f32 v[4:5], v[20:21], v[6:7], v[4:5] op_sel_hi:[0,1,1]
	v_mov_b32_e32 v6, v5
	v_max_f32_e32 v5, v24, v24
	v_max_f32_e32 v20, 0, v5
	v_max_f32_e32 v5, v8, v8
	v_max_f32_e32 v21, 0, v5
	v_max_f32_e32 v5, v25, v25
	v_max_f32_e32 v8, 0, v5
	v_max_f32_e32 v5, v9, v9
	v_pk_fma_f32 v[20:21], v[44:45], v[20:21], 0 op_sel_hi:[0,1,0]
	v_max_f32_e32 v9, 0, v5
	v_max_f32_e32 v5, v26, v26
	v_pk_fma_f32 v[8:9], v[44:45], v[8:9], v[20:21] op_sel:[1,0,0]
	v_max_f32_e32 v20, 0, v5
	v_max_f32_e32 v5, v10, v10
	v_max_f32_e32 v21, 0, v5
	v_max_f32_e32 v5, v27, v27
	v_max_f32_e32 v10, 0, v5
	v_max_f32_e32 v5, v11, v11
	v_pk_fma_f32 v[8:9], v[46:47], v[20:21], v[8:9] op_sel_hi:[0,1,1]
	v_max_f32_e32 v11, 0, v5
	v_mov_b32_e32 v20, v47
	v_pk_fma_f32 v[8:9], v[20:21], v[10:11], v[8:9] op_sel_hi:[0,1,1]
	v_mov_b32_e32 v7, v9
	s_nop 1
	v_permlane32_swap_b32_e32 v8, v7
	v_permlane32_swap_b32_e32 v4, v6
	v_mov_b32_e32 v5, v8
	v_pk_add_f32 v[4:5], v[4:5], v[6:7]
	v_max_f32_e32 v6, v28, v28
	v_max_f32_e32 v7, v12, v12
	v_max_f32_e32 v6, 0, v6
	v_max_f32_e32 v7, 0, v7
	v_max_f32_e32 v8, v29, v29
	v_max_f32_e32 v9, v13, v13
	v_pk_fma_f32 v[6:7], v[40:41], v[6:7], 0 op_sel_hi:[0,1,0]
	v_max_f32_e32 v8, 0, v8
	v_max_f32_e32 v9, 0, v9
	v_pk_fma_f32 v[6:7], v[40:41], v[8:9], v[6:7] op_sel:[1,0,0]
	v_max_f32_e32 v8, v30, v30
	v_max_f32_e32 v9, v14, v14
	v_max_f32_e32 v8, 0, v8
	v_max_f32_e32 v9, 0, v9
	v_pk_fma_f32 v[6:7], v[42:43], v[8:9], v[6:7] op_sel_hi:[0,1,1]
	v_max_f32_e32 v8, v31, v31
	v_max_f32_e32 v9, v15, v15
	v_max_f32_e32 v8, 0, v8
	v_max_f32_e32 v9, 0, v9
	v_mov_b32_e32 v10, v43
	v_pk_fma_f32 v[6:7], v[10:11], v[8:9], v[6:7] op_sel_hi:[0,1,1]
	v_mov_b32_e32 v8, v7
	v_max_f32_e32 v7, v32, v32
	v_max_f32_e32 v10, 0, v7
	v_max_f32_e32 v7, v16, v16
	v_max_f32_e32 v11, 0, v7
	v_max_f32_e32 v7, v33, v33
	v_max_f32_e32 v12, 0, v7
	v_max_f32_e32 v7, v17, v17
	v_pk_fma_f32 v[10:11], v[36:37], v[10:11], 0 op_sel_hi:[0,1,0]
	v_max_f32_e32 v13, 0, v7
	v_max_f32_e32 v7, v34, v34
	v_pk_fma_f32 v[10:11], v[36:37], v[12:13], v[10:11] op_sel:[1,0,0]
	v_max_f32_e32 v12, 0, v7
	v_max_f32_e32 v7, v18, v18
	v_max_f32_e32 v13, 0, v7
	v_max_f32_e32 v7, v35, v35
	v_pk_fma_f32 v[10:11], v[38:39], v[12:13], v[10:11] op_sel_hi:[0,1,1]
	v_max_f32_e32 v12, 0, v7
	v_max_f32_e32 v7, v19, v19
	v_max_f32_e32 v13, 0, v7
	v_mov_b32_e32 v14, v39
	v_pk_fma_f32 v[10:11], v[14:15], v[12:13], v[10:11] op_sel_hi:[0,1,1]
	v_mov_b32_e32 v9, v11
	s_nop 1
	v_permlane32_swap_b32_e32 v10, v9
	v_permlane32_swap_b32_e32 v6, v8
	v_mov_b32_e32 v7, v10
	v_pk_add_f32 v[6:7], v[6:7], v[8:9]
	v_pk_add_f32 v[4:5], v[4:5], 0 op_sel_hi:[1,0]
	v_pk_add_f32 v[6:7], v[6:7], 0 op_sel_hi:[1,0]
	v_cmp_gt_i32_e64 s[4:5], 0, v4
	v_cmp_gt_i32_e64 s[8:9], 0, v5
	v_cmp_gt_i32_e64 s[12:13], 0, v6
	v_cmp_gt_i32_e64 s[16:17], 0, v7
	s_and_saveexec_b64 s[20:21], s[0:1]
	s_cbranch_execz .LBB0_665
	v_mad_u32_u24 v8, v209, s57, v2
	s_waitcnt vmcnt(0)
	ds_write_b128 v8, v[68:71] offset:16384
	ds_write_b128 v8, v[72:75] offset:17536
	ds_write_b128 v8, v[76:79] offset:18688
	ds_write_b128 v8, v[80:83] offset:19840
	ds_write_b128 v8, v[84:87] offset:20992
	ds_write_b128 v8, v[88:91] offset:22144
	ds_write_b128 v8, v[92:95] offset:23296
	ds_write_b128 v8, v[96:99] offset:24448

; #define MFMA32(a, b, c) __builtin_amdgcn_mfma_f32_32x32x16_bf16((a), (b), (c), 0, 0, 0)
; DI void topk_job(const Params& p, int b, int t0, char* lds) {
;     ...
; #pragma unroll
;     for (int i = 0; i < 17; ++i) {
;       const int c = 1 + w + 8 * i;
;       if (c <= cmax) {
;         const bool more = c + 8 <= cmax;
;         if (more) {
;           const u16* kp = ikb + (size_t)(c + 8) * 64 * 64;
; #pragma unroll
;           for (int j = 0; j < 8; ++j) st[j] = *(const u32x4*)(kp + (size_t)j * 8 * 64);
;         }
;         bf16x8 b0[4], b1[4];
; #pragma unroll
;         for (int ks = 0; ks < 4; ++ks) {
;           b0[ks] = *(const bf16x8*)(wb + r * 144 + ks * 32 + h * 16);
;           b1[ks] = *(const bf16x8*)(wb + (32 + r) * 144 + ks * 32 + h * 16);
;         }
;         __builtin_amdgcn_sched_barrier(0);
;         f32x16 a0, a1;
; #pragma unroll
;         for (int e = 0; e < 16; ++e) { a0[e] = 0.f; a1[e] = 0.f; }
; #pragma unroll
;         for (int ks = 0; ks < 4; ++ks) { a0 = MFMA32(af[ks], b0[ks], a0); a1 = MFMA32(af[ks], b1[ks], a1); }
;         const int key = c * 64 + lane;
; #pragma unroll
;         for (int qi = 0; qi < 4; ++qi) {
;           f32x2 pp2 = {0.f, 0.f};
; #pragma unroll
;           for (int e = 0; e < 4; ++e) {
;             const f32x2 rl = {fmaxf(a0[4 * qi + e], 0.f), fmaxf(a1[4 * qi + e], 0.f)};
;             const f32x2 wv = {iw[qi][e], iw[qi][e]};
;             pp2 += rl * wv;
;           }
;           const float p0 = pp2[0], p1 = pp2[1];
;           const u32x2 sw = __builtin_amdgcn_permlane32_swap(__float_as_uint(p0), __float_as_uint(p1), false, false);
;           float mine = __uint_as_float(sw[0]) + __uint_as_float(sw[1]);
;           mine += 0.0f;
;           unsigned u = __float_as_uint(mine);
;           u = (u & 0x80000000u) ? ~u : (u | 0x80000000u);
;           if (key > t0 + qi || key < LEAD) u = 0u;
;           sc[i][qi] = u;
;         }
;         if (more) {
; #pragma unroll
;           for (int j = 0; j < 8; ++j) *(u32x4*)(wb + (lrow + 8 * j) * 144 + lpc * 16) = st[j];
;         }
.LBB0_669:
	s_or_b64 exec, exec, s[2:3]
	ds_read_b128 v[4:7], v210 offset:16384
	ds_read_b128 v[102:105], v210 offset:16416
	s_waitcnt vmcnt(8)
	ds_read_b128 v[8:11], v210 offset:20992
	ds_read_b128 v[106:109], v210 offset:21024
	ds_read_b128 v[110:113], v210 offset:16448
	ds_read_b128 v[114:117], v210 offset:16480
	ds_read_b128 v[118:121], v210 offset:21056
	ds_read_b128 v[122:125], v210 offset:21088
	s_waitcnt lgkmcnt(7)
	v_mfma_f32_32x32x16_bf16 v[20:35], v[64:67], v[4:7], 0
	s_sub_i32 s2, 0x209d, s23
	s_sub_i32 s10, 0x209e, s23
	s_waitcnt lgkmcnt(5)
	v_mfma_f32_32x32x16_bf16 v[4:19], v[64:67], v[8:11], 0
	v_mfma_f32_32x32x16_bf16 v[20:35], v[60:63], v[102:105], v[20:35]
	v_lshl_or_b32 v104, v130, 6, v101
	v_cmp_gt_i32_e32 vcc, s25, v104
	v_cmp_lt_i32_e64 s[6:7], s24, v104
	v_cmp_lt_i32_e64 s[2:3], s2, v104
	v_cmp_lt_i32_e64 s[14:15], s10, v104
	v_cmp_lt_i32_e64 s[10:11], s22, v104
	s_waitcnt lgkmcnt(4)
	v_mfma_f32_32x32x16_bf16 v[4:19], v[60:63], v[106:109], v[4:19]
	s_waitcnt lgkmcnt(3)
	v_mfma_f32_32x32x16_bf16 v[20:35], v[56:59], v[110:113], v[20:35]
	s_waitcnt lgkmcnt(1)
	v_mfma_f32_32x32x16_bf16 v[4:19], v[56:59], v[118:121], v[4:19]
	v_mfma_f32_32x32x16_bf16 v[20:35], v[52:55], v[114:117], v[20:35]
	s_waitcnt lgkmcnt(0)
	v_mfma_f32_32x32x16_bf16 v[4:19], v[52:55], v[122:125], v[4:19]
	s_nop 9
	v_max_f32_e32 v20, v20, v20
	v_max_f32_e32 v102, 0, v20
	v_max_f32_e32 v20, v22, v22
	v_max_f32_e32 v20, 0, v20
	v_max_f32_e32 v4, v4, v4
	v_max_f32_e32 v103, 0, v4
	v_max_f32_e32 v4, v21, v21
	v_max_f32_e32 v5, v5, v5
	v_pk_fma_f32 v[102:103], v[48:49], v[102:103], 0 op_sel_hi:[0,1,0]
	v_max_f32_e32 v4, 0, v4
	v_max_f32_e32 v5, 0, v5
	v_max_f32_e32 v6, v6, v6
	v_pk_fma_f32 v[4:5], v[48:49], v[4:5], v[102:103] op_sel:[1,0,0]
	v_max_f32_e32 v21, 0, v6
	v_max_f32_e32 v6, v23, v23
	v_max_f32_e32 v7, v7, v7
	v_pk_fma_f32 v[4:5], v[50:51], v[20:21], v[4:5] op_sel_hi:[0,1,1]
	v_max_f32_e32 v6, 0, v6
	v_max_f32_e32 v7, 0, v7
	v_mov_b32_e32 v20, v51
	v_pk_fma_f32 v[4:5], v[20:21], v[6:7], v[4:5] op_sel_hi:[0,1,1]
	v_mov_b32_e32 v6, v5
	v_max_f32_e32 v5, v24, v24
	v_max_f32_e32 v20, 0, v5
	v_max_f32_e32 v5, v8, v8
	v_max_f32_e32 v21, 0, v5
	v_max_f32_e32 v5, v25, v25
	v_max_f32_e32 v8, 0, v5
	v_max_f32_e32 v5, v9, v9
	v_pk_fma_f32 v[20:21], v[44:45], v[20:21], 0 op_sel_hi:[0,1,0]
	v_max_f32_e32 v9, 0, v5
	v_max_f32_e32 v5, v26, v26
	v_pk_fma_f32 v[8:9], v[44:45], v[8:9], v[20:21] op_sel:[1,0,0]
	v_max_f32_e32 v20, 0, v5
	v_max_f32_e32 v5, v10, v10
	v_max_f32_e32 v21, 0, v5
	v_max_f32_e32 v5, v27, v27
	v_max_f32_e32 v10, 0, v5
	v_max_f32_e32 v5, v11, v11
	v_pk_fma_f32 v[8:9], v[46:47], v[20:21], v[8:9] op_sel_hi:[0,1,1]
	v_max_f32_e32 v11, 0, v5
	v_mov_b32_e32 v20, v47
	v_pk_fma_f32 v[8:9], v[20:21], v[10:11], v[8:9] op_sel_hi:[0,1,1]
	v_mov_b32_e32 v7, v9
	s_nop 1
	v_permlane32_swap_b32_e32 v8, v7
	v_permlane32_swap_b32_e32 v4, v6
	v_mov_b32_e32 v5, v8
	v_pk_add_f32 v[4:5], v[4:5], v[6:7]
	v_max_f32_e32 v6, v28, v28
	v_max_f32_e32 v7, v12, v12
	v_max_f32_e32 v6, 0, v6
	v_max_f32_e32 v7, 0, v7
	v_max_f32_e32 v8, v29, v29
	v_max_f32_e32 v9, v13, v13
	v_pk_fma_f32 v[6:7], v[40:41], v[6:7], 0 op_sel_hi:[0,1,0]
	v_max_f32_e32 v8, 0, v8
	v_max_f32_e32 v9, 0, v9
	v_pk_fma_f32 v[6:7], v[40:41], v[8:9], v[6:7] op_sel:[1,0,0]
	v_max_f32_e32 v8, v30, v30
	v_max_f32_e32 v9, v14, v14
	v_max_f32_e32 v8, 0, v8
	v_max_f32_e32 v9, 0, v9
	v_pk_fma_f32 v[6:7], v[42:43], v[8:9], v[6:7] op_sel_hi:[0,1,1]
	v_max_f32_e32 v8, v31, v31
	v_max_f32_e32 v9, v15, v15
	v_max_f32_e32 v8, 0, v8
	v_max_f32_e32 v9, 0, v9
	v_mov_b32_e32 v10, v43
	v_pk_fma_f32 v[6:7], v[10:11], v[8:9], v[6:7] op_sel_hi:[0,1,1]
	v_mov_b32_e32 v8, v7
	v_max_f32_e32 v7, v32, v32
	v_max_f32_e32 v10, 0, v7
	v_max_f32_e32 v7, v16, v16
	v_max_f32_e32 v11, 0, v7
	v_max_f32_e32 v7, v33, v33
	v_max_f32_e32 v12, 0, v7
	v_max_f32_e32 v7, v17, v17
	v_pk_fma_f32 v[10:11], v[36:37], v[10:11], 0 op_sel_hi:[0,1,0]
	v_max_f32_e32 v13, 0, v7
	v_max_f32_e32 v7, v34, v34
	v_pk_fma_f32 v[10:11], v[36:37], v[12:13], v[10:11] op_sel:[1,0,0]
	v_max_f32_e32 v12, 0, v7
	v_max_f32_e32 v7, v18, v18
	v_max_f32_e32 v13, 0, v7
	v_max_f32_e32 v7, v35, v35
	v_pk_fma_f32 v[10:11], v[38:39], v[12:13], v[10:11] op_sel_hi:[0,1,1]
	v_max_f32_e32 v12, 0, v7
	v_max_f32_e32 v7, v19, v19
	v_max_f32_e32 v13, 0, v7
	v_mov_b32_e32 v14, v39
	v_pk_fma_f32 v[10:11], v[14:15], v[12:13], v[10:11] op_sel_hi:[0,1,1]
	v_mov_b32_e32 v9, v11
	s_nop 1
	v_permlane32_swap_b32_e32 v10, v9
	v_permlane32_swap_b32_e32 v6, v8
	v_mov_b32_e32 v7, v10
	v_pk_add_f32 v[6:7], v[6:7], v[8:9]
	v_pk_add_f32 v[4:5], v[4:5], 0 op_sel_hi:[1,0]
	v_pk_add_f32 v[6:7], v[6:7], 0 op_sel_hi:[1,0]
	v_cmp_gt_i32_e64 s[4:5], 0, v4
	v_cmp_gt_i32_e64 s[8:9], 0, v5
	v_cmp_gt_i32_e64 s[12:13], 0, v6
	v_cmp_gt_i32_e64 s[16:17], 0, v7
	s_and_saveexec_b64 s[20:21], s[0:1]
	s_cbranch_execz .LBB0_671
	v_mad_u32_u24 v8, v209, s57, v2
	s_waitcnt vmcnt(0)
	ds_write_b128 v8, v[68:71] offset:16384
	ds_write_b128 v8, v[72:75] offset:17536
	ds_write_b128 v8, v[76:79] offset:18688
	ds_write_b128 v8, v[80:83] offset:19840
	ds_write_b128 v8, v[84:87] offset:20992
	ds_write_b128 v8, v[88:91] offset:22144
	ds_write_b128 v8, v[92:95] offset:23296
	ds_write_b128 v8, v[96:99] offset:24448

; #define MFMA32(a, b, c) __builtin_amdgcn_mfma_f32_32x32x16_bf16((a), (b), (c), 0, 0, 0)
; DI void topk_job(const Params& p, int b, int t0, char* lds) {
;     ...
; #pragma unroll
;     for (int i = 0; i < 17; ++i) {
;       const int c = 1 + w + 8 * i;
;       if (c <= cmax) {
;         const bool more = c + 8 <= cmax;
;         if (more) {
;           const u16* kp = ikb + (size_t)(c + 8) * 64 * 64;
; #pragma unroll
;           for (int j = 0; j < 8; ++j) st[j] = *(const u32x4*)(kp + (size_t)j * 8 * 64);
;         }
;         bf16x8 b0[4], b1[4];
; #pragma unroll
;         for (int ks = 0; ks < 4; ++ks) {
;           b0[ks] = *(const bf16x8*)(wb + r * 144 + ks * 32 + h * 16);
;           b1[ks] = *(const bf16x8*)(wb + (32 + r) * 144 + ks * 32 + h * 16);
;         }
;         __builtin_amdgcn_sched_barrier(0);
;         f32x16 a0, a1;
; #pragma unroll
;         for (int e = 0; e < 16; ++e) { a0[e] = 0.f; a1[e] = 0.f; }
; #pragma unroll
;         for (int ks = 0; ks < 4; ++ks) { a0 = MFMA32(af[ks], b0[ks], a0); a1 = MFMA32(af[ks], b1[ks], a1); }
;         const int key = c * 64 + lane;
; #pragma unroll
;         for (int qi = 0; qi < 4; ++qi) {
;           f32x2 pp2 = {0.f, 0.f};
; #pragma unroll
;           for (int e = 0; e < 4; ++e) {
;             const f32x2 rl = {fmaxf(a0[4 * qi + e], 0.f), fmaxf(a1[4 * qi + e], 0.f)};
;             const f32x2 wv = {iw[qi][e], iw[qi][e]};
;             pp2 += rl * wv;
;           }
;           const float p0 = pp2[0], p1 = pp2[1];
;           const u32x2 sw = __builtin_amdgcn_permlane32_swap(__float_as_uint(p0), __float_as_uint(p1), false, false);
;           float mine = __uint_as_float(sw[0]) + __uint_as_float(sw[1]);
;           mine += 0.0f;
;           unsigned u = __float_as_uint(mine);
;           u = (u & 0x80000000u) ? ~u : (u | 0x80000000u);
;           if (key > t0 + qi || key < LEAD) u = 0u;
;           sc[i][qi] = u;
;         }
;         if (more) {
; #pragma unroll
;           for (int j = 0; j < 8; ++j) *(u32x4*)(wb + (lrow + 8 * j) * 144 + lpc * 16) = st[j];
;         }
.LBB0_675:
	s_or_b64 exec, exec, s[2:3]
	ds_read_b128 v[4:7], v210 offset:16384
	ds_read_b128 v[102:105], v210 offset:16416
	s_waitcnt vmcnt(8)
	ds_read_b128 v[8:11], v210 offset:20992
	ds_read_b128 v[106:109], v210 offset:21024
	ds_read_b128 v[110:113], v210 offset:16448
	ds_read_b128 v[114:117], v210 offset:16480
	ds_read_b128 v[118:121], v210 offset:21056
	ds_read_b128 v[122:125], v210 offset:21088
	s_waitcnt lgkmcnt(7)
	v_mfma_f32_32x32x16_bf16 v[20:35], v[64:67], v[4:7], 0
	s_sub_i32 s2, 0x209d, s23
	s_sub_i32 s10, 0x209e, s23
	s_waitcnt lgkmcnt(5)
	v_mfma_f32_32x32x16_bf16 v[4:19], v[64:67], v[8:11], 0
	v_mfma_f32_32x32x16_bf16 v[20:35], v[60:63], v[102:105], v[20:35]
	v_lshl_or_b32 v104, v128, 6, v101
	v_cmp_gt_i32_e32 vcc, s25, v104
	v_cmp_lt_i32_e64 s[6:7], s24, v104
	v_cmp_lt_i32_e64 s[2:3], s2, v104
	v_cmp_lt_i32_e64 s[14:15], s10, v104
	v_cmp_lt_i32_e64 s[10:11], s22, v104
	s_waitcnt lgkmcnt(4)
	v_mfma_f32_32x32x16_bf16 v[4:19], v[60:63], v[106:109], v[4:19]
	s_waitcnt lgkmcnt(3)
	v_mfma_f32_32x32x16_bf16 v[20:35], v[56:59], v[110:113], v[20:35]
	s_waitcnt lgkmcnt(1)
	v_mfma_f32_32x32x16_bf16 v[4:19], v[56:59], v[118:121], v[4:19]
	v_mfma_f32_32x32x16_bf16 v[20:35], v[52:55], v[114:117], v[20:35]
	s_waitcnt lgkmcnt(0)
	v_mfma_f32_32x32x16_bf16 v[4:19], v[52:55], v[122:125], v[4:19]
	s_nop 9
	v_max_f32_e32 v20, v20, v20
	v_max_f32_e32 v102, 0, v20
	v_max_f32_e32 v20, v22, v22
	v_max_f32_e32 v20, 0, v20
	v_max_f32_e32 v4, v4, v4
	v_max_f32_e32 v103, 0, v4
	v_max_f32_e32 v4, v21, v21
	v_max_f32_e32 v5, v5, v5
	v_pk_fma_f32 v[102:103], v[48:49], v[102:103], 0 op_sel_hi:[0,1,0]
	v_max_f32_e32 v4, 0, v4
	v_max_f32_e32 v5, 0, v5
	v_max_f32_e32 v6, v6, v6
	v_pk_fma_f32 v[4:5], v[48:49], v[4:5], v[102:103] op_sel:[1,0,0]
	v_max_f32_e32 v21, 0, v6
	v_max_f32_e32 v6, v23, v23
	v_max_f32_e32 v7, v7, v7
	v_pk_fma_f32 v[4:5], v[50:51], v[20:21], v[4:5] op_sel_hi:[0,1,1]
	v_max_f32_e32 v6, 0, v6
	v_max_f32_e32 v7, 0, v7
	v_mov_b32_e32 v20, v51
	v_pk_fma_f32 v[4:5], v[20:21], v[6:7], v[4:5] op_sel_hi:[0,1,1]
	v_mov_b32_e32 v6, v5
	v_max_f32_e32 v5, v24, v24
	v_max_f32_e32 v20, 0, v5
	v_max_f32_e32 v5, v8, v8
	v_max_f32_e32 v21, 0, v5
	v_max_f32_e32 v5, v25, v25
	v_max_f32_e32 v8, 0, v5
	v_max_f32_e32 v5, v9, v9
	v_pk_fma_f32 v[20:21], v[44:45], v[20:21], 0 op_sel_hi:[0,1,0]
	v_max_f32_e32 v9, 0, v5
	v_max_f32_e32 v5, v26, v26
	v_pk_fma_f32 v[8:9], v[44:45], v[8:9], v[20:21] op_sel:[1,0,0]
	v_max_f32_e32 v20, 0, v5
	v_max_f32_e32 v5, v10, v10
	v_max_f32_e32 v21, 0, v5
	v_max_f32_e32 v5, v27, v27
	v_max_f32_e32 v10, 0, v5
	v_max_f32_e32 v5, v11, v11
	v_pk_fma_f32 v[8:9], v[46:47], v[20:21], v[8:9] op_sel_hi:[0,1,1]
	v_max_f32_e32 v11, 0, v5
	v_mov_b32_e32 v20, v47
	v_pk_fma_f32 v[8:9], v[20:21], v[10:11], v[8:9] op_sel_hi:[0,1,1]
	v_mov_b32_e32 v7, v9
	s_nop 1
	v_permlane32_swap_b32_e32 v8, v7
	v_permlane32_swap_b32_e32 v4, v6
	v_mov_b32_e32 v5, v8
	v_pk_add_f32 v[4:5], v[4:5], v[6:7]
	v_max_f32_e32 v6, v28, v28
	v_max_f32_e32 v7, v12, v12
	v_max_f32_e32 v6, 0, v6
	v_max_f32_e32 v7, 0, v7
	v_max_f32_e32 v8, v29, v29
	v_max_f32_e32 v9, v13, v13
	v_pk_fma_f32 v[6:7], v[40:41], v[6:7], 0 op_sel_hi:[0,1,0]
	v_max_f32_e32 v8, 0, v8
	v_max_f32_e32 v9, 0, v9
	v_pk_fma_f32 v[6:7], v[40:41], v[8:9], v[6:7] op_sel:[1,0,0]
	v_max_f32_e32 v8, v30, v30
	v_max_f32_e32 v9, v14, v14
	v_max_f32_e32 v8, 0, v8
	v_max_f32_e32 v9, 0, v9
	v_pk_fma_f32 v[6:7], v[42:43], v[8:9], v[6:7] op_sel_hi:[0,1,1]
	v_max_f32_e32 v8, v31, v31
	v_max_f32_e32 v9, v15, v15
	v_max_f32_e32 v8, 0, v8
	v_max_f32_e32 v9, 0, v9
	v_mov_b32_e32 v10, v43
	v_pk_fma_f32 v[6:7], v[10:11], v[8:9], v[6:7] op_sel_hi:[0,1,1]
	v_mov_b32_e32 v8, v7
	v_max_f32_e32 v7, v32, v32
	v_max_f32_e32 v10, 0, v7
	v_max_f32_e32 v7, v16, v16
	v_max_f32_e32 v11, 0, v7
	v_max_f32_e32 v7, v33, v33
	v_max_f32_e32 v12, 0, v7
	v_max_f32_e32 v7, v17, v17
	v_pk_fma_f32 v[10:11], v[36:37], v[10:11], 0 op_sel_hi:[0,1,0]
	v_max_f32_e32 v13, 0, v7
	v_max_f32_e32 v7, v34, v34
	v_pk_fma_f32 v[10:11], v[36:37], v[12:13], v[10:11] op_sel:[1,0,0]
	v_max_f32_e32 v12, 0, v7
	v_max_f32_e32 v7, v18, v18
	v_max_f32_e32 v13, 0, v7
	v_max_f32_e32 v7, v35, v35
	v_pk_fma_f32 v[10:11], v[38:39], v[12:13], v[10:11] op_sel_hi:[0,1,1]
	v_max_f32_e32 v12, 0, v7
	v_max_f32_e32 v7, v19, v19
	v_max_f32_e32 v13, 0, v7
	v_mov_b32_e32 v14, v39
	v_pk_fma_f32 v[10:11], v[14:15], v[12:13], v[10:11] op_sel_hi:[0,1,1]
	v_mov_b32_e32 v9, v11
	s_nop 1
	v_permlane32_swap_b32_e32 v10, v9
	v_permlane32_swap_b32_e32 v6, v8
	v_mov_b32_e32 v7, v10
	v_pk_add_f32 v[6:7], v[6:7], v[8:9]
	v_pk_add_f32 v[4:5], v[4:5], 0 op_sel_hi:[1,0]
	v_pk_add_f32 v[6:7], v[6:7], 0 op_sel_hi:[1,0]
	v_cmp_gt_i32_e64 s[4:5], 0, v4
	v_cmp_gt_i32_e64 s[8:9], 0, v5
	v_cmp_gt_i32_e64 s[12:13], 0, v6
	v_cmp_gt_i32_e64 s[16:17], 0, v7
	s_and_saveexec_b64 s[20:21], s[0:1]
	s_cbranch_execz .LBB0_677
	v_mad_u32_u24 v8, v209, s57, v2
	s_waitcnt vmcnt(0)
	ds_write_b128 v8, v[68:71] offset:16384
	ds_write_b128 v8, v[72:75] offset:17536
	ds_write_b128 v8, v[76:79] offset:18688
	ds_write_b128 v8, v[80:83] offset:19840
	ds_write_b128 v8, v[84:87] offset:20992
	ds_write_b128 v8, v[88:91] offset:22144
	ds_write_b128 v8, v[92:95] offset:23296
	ds_write_b128 v8, v[96:99] offset:24448

; #define MFMA32(a, b, c) __builtin_amdgcn_mfma_f32_32x32x16_bf16((a), (b), (c), 0, 0, 0)
; DI void topk_job(const Params& p, int b, int t0, char* lds) {
;     ...
; #pragma unroll
;     for (int i = 0; i < 17; ++i) {
;       const int c = 1 + w + 8 * i;
;       if (c <= cmax) {
;         const bool more = c + 8 <= cmax;
;         if (more) {
;           const u16* kp = ikb + (size_t)(c + 8) * 64 * 64;
; #pragma unroll
;           for (int j = 0; j < 8; ++j) st[j] = *(const u32x4*)(kp + (size_t)j * 8 * 64);
;         }
;         bf16x8 b0[4], b1[4];
; #pragma unroll
;         for (int ks = 0; ks < 4; ++ks) {
;           b0[ks] = *(const bf16x8*)(wb + r * 144 + ks * 32 + h * 16);
;           b1[ks] = *(const bf16x8*)(wb + (32 + r) * 144 + ks * 32 + h * 16);
;         }
;         __builtin_amdgcn_sched_barrier(0);
;         f32x16 a0, a1;
; #pragma unroll
;         for (int e = 0; e < 16; ++e) { a0[e] = 0.f; a1[e] = 0.f; }
; #pragma unroll
;         for (int ks = 0; ks < 4; ++ks) { a0 = MFMA32(af[ks], b0[ks], a0); a1 = MFMA32(af[ks], b1[ks], a1); }
;         const int key = c * 64 + lane;
; #pragma unroll
;         for (int qi = 0; qi < 4; ++qi) {
;           f32x2 pp2 = {0.f, 0.f};
; #pragma unroll
;           for (int e = 0; e < 4; ++e) {
;             const f32x2 rl = {fmaxf(a0[4 * qi + e], 0.f), fmaxf(a1[4 * qi + e], 0.f)};
;             const f32x2 wv = {iw[qi][e], iw[qi][e]};
;             pp2 += rl * wv;
;           }
;           const float p0 = pp2[0], p1 = pp2[1];
;           const u32x2 sw = __builtin_amdgcn_permlane32_swap(__float_as_uint(p0), __float_as_uint(p1), false, false);
;           float mine = __uint_as_float(sw[0]) + __uint_as_float(sw[1]);
;           mine += 0.0f;
;           unsigned u = __float_as_uint(mine);
;           u = (u & 0x80000000u) ? ~u : (u | 0x80000000u);
;           if (key > t0 + qi || key < LEAD) u = 0u;
;           sc[i][qi] = u;
;         }
;         if (more) {
; #pragma unroll
;           for (int j = 0; j < 8; ++j) *(u32x4*)(wb + (lrow + 8 * j) * 144 + lpc * 16) = st[j];
;         }
.LBB0_681:
	s_or_b64 exec, exec, s[2:3]
	ds_read_b128 v[4:7], v210 offset:16384
	ds_read_b128 v[102:105], v210 offset:16416
	s_waitcnt vmcnt(8)
	ds_read_b128 v[8:11], v210 offset:20992
	ds_read_b128 v[106:109], v210 offset:21024
	ds_read_b128 v[110:113], v210 offset:16448
	ds_read_b128 v[114:117], v210 offset:16480
	ds_read_b128 v[118:121], v210 offset:21056
	ds_read_b128 v[140:143], v210 offset:21088
	s_waitcnt lgkmcnt(7)
	v_mfma_f32_32x32x16_bf16 v[20:35], v[64:67], v[4:7], 0
	s_sub_i32 s2, 0x209d, s23
	s_sub_i32 s10, 0x209e, s23
	s_waitcnt lgkmcnt(5)
	v_mfma_f32_32x32x16_bf16 v[4:19], v[64:67], v[8:11], 0
	v_mfma_f32_32x32x16_bf16 v[20:35], v[60:63], v[102:105], v[20:35]
	v_lshl_or_b32 v104, v126, 6, v101
	v_cmp_gt_i32_e32 vcc, s25, v104
	v_cmp_lt_i32_e64 s[6:7], s24, v104
	v_cmp_lt_i32_e64 s[2:3], s2, v104
	v_cmp_lt_i32_e64 s[14:15], s10, v104
	v_cmp_lt_i32_e64 s[10:11], s22, v104
	s_waitcnt lgkmcnt(4)
	v_mfma_f32_32x32x16_bf16 v[4:19], v[60:63], v[106:109], v[4:19]
	s_waitcnt lgkmcnt(3)
	v_mfma_f32_32x32x16_bf16 v[20:35], v[56:59], v[110:113], v[20:35]
	s_waitcnt lgkmcnt(1)
	v_mfma_f32_32x32x16_bf16 v[4:19], v[56:59], v[118:121], v[4:19]
	v_mfma_f32_32x32x16_bf16 v[20:35], v[52:55], v[114:117], v[20:35]
	s_waitcnt lgkmcnt(0)
	v_mfma_f32_32x32x16_bf16 v[4:19], v[52:55], v[140:143], v[4:19]
	s_nop 9
	v_max_f32_e32 v20, v20, v20
	v_max_f32_e32 v102, 0, v20
	v_max_f32_e32 v20, v22, v22
	v_max_f32_e32 v20, 0, v20
	v_max_f32_e32 v4, v4, v4
	v_max_f32_e32 v103, 0, v4
	v_max_f32_e32 v4, v21, v21
	v_max_f32_e32 v5, v5, v5
	v_pk_fma_f32 v[102:103], v[48:49], v[102:103], 0 op_sel_hi:[0,1,0]
	v_max_f32_e32 v4, 0, v4
	v_max_f32_e32 v5, 0, v5
	v_max_f32_e32 v6, v6, v6
	v_pk_fma_f32 v[4:5], v[48:49], v[4:5], v[102:103] op_sel:[1,0,0]
	v_max_f32_e32 v21, 0, v6
	v_max_f32_e32 v6, v23, v23
	v_max_f32_e32 v7, v7, v7
	v_pk_fma_f32 v[4:5], v[50:51], v[20:21], v[4:5] op_sel_hi:[0,1,1]
	v_max_f32_e32 v6, 0, v6
	v_max_f32_e32 v7, 0, v7
	v_mov_b32_e32 v20, v51
	v_pk_fma_f32 v[4:5], v[20:21], v[6:7], v[4:5] op_sel_hi:[0,1,1]
	v_mov_b32_e32 v6, v5
	v_max_f32_e32 v5, v24, v24
	v_max_f32_e32 v20, 0, v5
	v_max_f32_e32 v5, v8, v8
	v_max_f32_e32 v21, 0, v5
	v_max_f32_e32 v5, v25, v25
	v_max_f32_e32 v8, 0, v5
	v_max_f32_e32 v5, v9, v9
	v_pk_fma_f32 v[20:21], v[44:45], v[20:21], 0 op_sel_hi:[0,1,0]
	v_max_f32_e32 v9, 0, v5
	v_max_f32_e32 v5, v26, v26
	v_pk_fma_f32 v[8:9], v[44:45], v[8:9], v[20:21] op_sel:[1,0,0]
	v_max_f32_e32 v20, 0, v5
	v_max_f32_e32 v5, v10, v10
	v_max_f32_e32 v21, 0, v5
	v_max_f32_e32 v5, v27, v27
	v_max_f32_e32 v10, 0, v5
	v_max_f32_e32 v5, v11, v11
	v_pk_fma_f32 v[8:9], v[46:47], v[20:21], v[8:9] op_sel_hi:[0,1,1]
	v_max_f32_e32 v11, 0, v5
	v_mov_b32_e32 v20, v47
	v_pk_fma_f32 v[8:9], v[20:21], v[10:11], v[8:9] op_sel_hi:[0,1,1]
	v_mov_b32_e32 v7, v9
	s_nop 1
	v_permlane32_swap_b32_e32 v8, v7
	v_permlane32_swap_b32_e32 v4, v6
	v_mov_b32_e32 v5, v8
	v_pk_add_f32 v[4:5], v[4:5], v[6:7]
	v_max_f32_e32 v6, v28, v28
	v_max_f32_e32 v7, v12, v12
	v_max_f32_e32 v6, 0, v6
	v_max_f32_e32 v7, 0, v7
	v_max_f32_e32 v8, v29, v29
	v_max_f32_e32 v9, v13, v13
	v_pk_fma_f32 v[6:7], v[40:41], v[6:7], 0 op_sel_hi:[0,1,0]
	v_max_f32_e32 v8, 0, v8
	v_max_f32_e32 v9, 0, v9
	v_pk_fma_f32 v[6:7], v[40:41], v[8:9], v[6:7] op_sel:[1,0,0]
	v_max_f32_e32 v8, v30, v30
	v_max_f32_e32 v9, v14, v14
	v_max_f32_e32 v8, 0, v8
	v_max_f32_e32 v9, 0, v9
	v_pk_fma_f32 v[6:7], v[42:43], v[8:9], v[6:7] op_sel_hi:[0,1,1]
	v_max_f32_e32 v8, v31, v31
	v_max_f32_e32 v9, v15, v15
	v_max_f32_e32 v8, 0, v8
	v_max_f32_e32 v9, 0, v9
	v_mov_b32_e32 v10, v43
	v_pk_fma_f32 v[6:7], v[10:11], v[8:9], v[6:7] op_sel_hi:[0,1,1]
	v_mov_b32_e32 v8, v7
	v_max_f32_e32 v7, v32, v32
	v_max_f32_e32 v10, 0, v7
	v_max_f32_e32 v7, v16, v16
	v_max_f32_e32 v11, 0, v7
	v_max_f32_e32 v7, v33, v33
	v_max_f32_e32 v12, 0, v7
	v_max_f32_e32 v7, v17, v17
	v_pk_fma_f32 v[10:11], v[36:37], v[10:11], 0 op_sel_hi:[0,1,0]
	v_max_f32_e32 v13, 0, v7
	v_max_f32_e32 v7, v34, v34
	v_pk_fma_f32 v[10:11], v[36:37], v[12:13], v[10:11] op_sel:[1,0,0]
	v_max_f32_e32 v12, 0, v7
	v_max_f32_e32 v7, v18, v18
	v_max_f32_e32 v13, 0, v7
	v_max_f32_e32 v7, v35, v35
	v_pk_fma_f32 v[10:11], v[38:39], v[12:13], v[10:11] op_sel_hi:[0,1,1]
	v_max_f32_e32 v12, 0, v7
	v_max_f32_e32 v7, v19, v19
	v_max_f32_e32 v13, 0, v7
	v_mov_b32_e32 v14, v39
	v_pk_fma_f32 v[10:11], v[14:15], v[12:13], v[10:11] op_sel_hi:[0,1,1]
	v_mov_b32_e32 v9, v11
	s_nop 1
	v_permlane32_swap_b32_e32 v10, v9
	v_permlane32_swap_b32_e32 v6, v8
	v_mov_b32_e32 v7, v10
	v_pk_add_f32 v[6:7], v[6:7], v[8:9]
	v_pk_add_f32 v[4:5], v[4:5], 0 op_sel_hi:[1,0]
	v_pk_add_f32 v[6:7], v[6:7], 0 op_sel_hi:[1,0]
	v_cmp_gt_i32_e64 s[4:5], 0, v4
	v_cmp_gt_i32_e64 s[8:9], 0, v5
	v_cmp_gt_i32_e64 s[12:13], 0, v6
	v_cmp_gt_i32_e64 s[16:17], 0, v7
	s_and_saveexec_b64 s[20:21], s[0:1]
	s_cbranch_execz .LBB0_683
	v_mad_u32_u24 v8, v209, s57, v2
	s_waitcnt vmcnt(0)
	ds_write_b128 v8, v[68:71] offset:16384
	ds_write_b128 v8, v[72:75] offset:17536
	ds_write_b128 v8, v[76:79] offset:18688
	ds_write_b128 v8, v[80:83] offset:19840
	ds_write_b128 v8, v[84:87] offset:20992
	ds_write_b128 v8, v[88:91] offset:22144
	ds_write_b128 v8, v[92:95] offset:23296
	ds_write_b128 v8, v[96:99] offset:24448

; #define MFMA32(a, b, c) __builtin_amdgcn_mfma_f32_32x32x16_bf16((a), (b), (c), 0, 0, 0)
; DI void topk_job(const Params& p, int b, int t0, char* lds) {
;     ...
; #pragma unroll
;     for (int i = 0; i < 17; ++i) {
;       const int c = 1 + w + 8 * i;
;       if (c <= cmax) {
;         const bool more = c + 8 <= cmax;
;         if (more) {
;           const u16* kp = ikb + (size_t)(c + 8) * 64 * 64;
; #pragma unroll
;           for (int j = 0; j < 8; ++j) st[j] = *(const u32x4*)(kp + (size_t)j * 8 * 64);
;         }
;         bf16x8 b0[4], b1[4];
; #pragma unroll
;         for (int ks = 0; ks < 4; ++ks) {
;           b0[ks] = *(const bf16x8*)(wb + r * 144 + ks * 32 + h * 16);
;           b1[ks] = *(const bf16x8*)(wb + (32 + r) * 144 + ks * 32 + h * 16);
;         }
;         __builtin_amdgcn_sched_barrier(0);
;         f32x16 a0, a1;
; #pragma unroll
;         for (int e = 0; e < 16; ++e) { a0[e] = 0.f; a1[e] = 0.f; }
; #pragma unroll
;         for (int ks = 0; ks < 4; ++ks) { a0 = MFMA32(af[ks], b0[ks], a0); a1 = MFMA32(af[ks], b1[ks], a1); }
;         const int key = c * 64 + lane;
; #pragma unroll
;         for (int qi = 0; qi < 4; ++qi) {
;           f32x2 pp2 = {0.f, 0.f};
; #pragma unroll
;           for (int e = 0; e < 4; ++e) {
;             const f32x2 rl = {fmaxf(a0[4 * qi + e], 0.f), fmaxf(a1[4 * qi + e], 0.f)};
;             const f32x2 wv = {iw[qi][e], iw[qi][e]};
;             pp2 += rl * wv;
;           }
;           const float p0 = pp2[0], p1 = pp2[1];
;           const u32x2 sw = __builtin_amdgcn_permlane32_swap(__float_as_uint(p0), __float_as_uint(p1), false, false);
;           float mine = __uint_as_float(sw[0]) + __uint_as_float(sw[1]);
;           mine += 0.0f;
;           unsigned u = __float_as_uint(mine);
;           u = (u & 0x80000000u) ? ~u : (u | 0x80000000u);
;           if (key > t0 + qi || key < LEAD) u = 0u;
;           sc[i][qi] = u;
;         }
;         if (more) {
; #pragma unroll
;           for (int j = 0; j < 8; ++j) *(u32x4*)(wb + (lrow + 8 * j) * 144 + lpc * 16) = st[j];
;         }
.LBB0_687:
	s_or_b64 exec, exec, s[2:3]
	ds_read_b128 v[4:7], v210 offset:16384
	ds_read_b128 v[102:105], v210 offset:16416
	s_waitcnt vmcnt(8)
	ds_read_b128 v[8:11], v210 offset:20992
	ds_read_b128 v[106:109], v210 offset:21024
	ds_read_b128 v[110:113], v210 offset:16448
	ds_read_b128 v[114:117], v210 offset:16480
	ds_read_b128 v[118:121], v210 offset:21056
	ds_read_b128 v[140:143], v210 offset:21088
	s_waitcnt lgkmcnt(7)
	v_mfma_f32_32x32x16_bf16 v[20:35], v[64:67], v[4:7], 0
	s_sub_i32 s2, 0x209d, s23
	s_sub_i32 s10, 0x209e, s23
	s_waitcnt lgkmcnt(5)
	v_mfma_f32_32x32x16_bf16 v[4:19], v[64:67], v[8:11], 0
	v_mfma_f32_32x32x16_bf16 v[20:35], v[60:63], v[102:105], v[20:35]
	v_lshl_or_b32 v104, v124, 6, v101
	v_cmp_gt_i32_e32 vcc, s25, v104
	v_cmp_lt_i32_e64 s[6:7], s24, v104
	v_cmp_lt_i32_e64 s[2:3], s2, v104
	v_cmp_lt_i32_e64 s[14:15], s10, v104
	v_cmp_lt_i32_e64 s[10:11], s22, v104
	s_waitcnt lgkmcnt(4)
	v_mfma_f32_32x32x16_bf16 v[4:19], v[60:63], v[106:109], v[4:19]
	s_waitcnt lgkmcnt(3)
	v_mfma_f32_32x32x16_bf16 v[20:35], v[56:59], v[110:113], v[20:35]
	s_waitcnt lgkmcnt(1)
	v_mfma_f32_32x32x16_bf16 v[4:19], v[56:59], v[118:121], v[4:19]
	v_mfma_f32_32x32x16_bf16 v[20:35], v[52:55], v[114:117], v[20:35]
	s_waitcnt lgkmcnt(0)
	v_mfma_f32_32x32x16_bf16 v[4:19], v[52:55], v[140:143], v[4:19]
	s_nop 9
	v_max_f32_e32 v20, v20, v20
	v_max_f32_e32 v102, 0, v20
	v_max_f32_e32 v20, v22, v22
	v_max_f32_e32 v20, 0, v20
	v_max_f32_e32 v4, v4, v4
	v_max_f32_e32 v103, 0, v4
	v_max_f32_e32 v4, v21, v21
	v_max_f32_e32 v5, v5, v5
	v_pk_fma_f32 v[102:103], v[48:49], v[102:103], 0 op_sel_hi:[0,1,0]
	v_max_f32_e32 v4, 0, v4
	v_max_f32_e32 v5, 0, v5
	v_max_f32_e32 v6, v6, v6
	v_pk_fma_f32 v[4:5], v[48:49], v[4:5], v[102:103] op_sel:[1,0,0]
	v_max_f32_e32 v21, 0, v6
	v_max_f32_e32 v6, v23, v23
	v_max_f32_e32 v7, v7, v7
	v_pk_fma_f32 v[4:5], v[50:51], v[20:21], v[4:5] op_sel_hi:[0,1,1]
	v_max_f32_e32 v6, 0, v6
	v_max_f32_e32 v7, 0, v7
	v_mov_b32_e32 v20, v51
	v_pk_fma_f32 v[4:5], v[20:21], v[6:7], v[4:5] op_sel_hi:[0,1,1]
	v_mov_b32_e32 v6, v5
	v_max_f32_e32 v5, v24, v24
	v_max_f32_e32 v20, 0, v5
	v_max_f32_e32 v5, v8, v8
	v_max_f32_e32 v21, 0, v5
	v_max_f32_e32 v5, v25, v25
	v_max_f32_e32 v8, 0, v5
	v_max_f32_e32 v5, v9, v9
	v_pk_fma_f32 v[20:21], v[44:45], v[20:21], 0 op_sel_hi:[0,1,0]
	v_max_f32_e32 v9, 0, v5
	v_max_f32_e32 v5, v26, v26
	v_pk_fma_f32 v[8:9], v[44:45], v[8:9], v[20:21] op_sel:[1,0,0]
	v_max_f32_e32 v20, 0, v5
	v_max_f32_e32 v5, v10, v10
	v_max_f32_e32 v21, 0, v5
	v_max_f32_e32 v5, v27, v27
	v_max_f32_e32 v10, 0, v5
	v_max_f32_e32 v5, v11, v11
	v_pk_fma_f32 v[8:9], v[46:47], v[20:21], v[8:9] op_sel_hi:[0,1,1]
	v_max_f32_e32 v11, 0, v5
	v_mov_b32_e32 v20, v47
	v_pk_fma_f32 v[8:9], v[20:21], v[10:11], v[8:9] op_sel_hi:[0,1,1]
	v_mov_b32_e32 v7, v9
	s_nop 1
	v_permlane32_swap_b32_e32 v8, v7
	v_permlane32_swap_b32_e32 v4, v6
	v_mov_b32_e32 v5, v8
	v_pk_add_f32 v[4:5], v[4:5], v[6:7]
	v_max_f32_e32 v6, v28, v28
	v_max_f32_e32 v7, v12, v12
	v_max_f32_e32 v6, 0, v6
	v_max_f32_e32 v7, 0, v7
	v_max_f32_e32 v8, v29, v29
	v_max_f32_e32 v9, v13, v13
	v_pk_fma_f32 v[6:7], v[40:41], v[6:7], 0 op_sel_hi:[0,1,0]
	v_max_f32_e32 v8, 0, v8
	v_max_f32_e32 v9, 0, v9
	v_pk_fma_f32 v[6:7], v[40:41], v[8:9], v[6:7] op_sel:[1,0,0]
	v_max_f32_e32 v8, v30, v30
	v_max_f32_e32 v9, v14, v14
	v_max_f32_e32 v8, 0, v8
	v_max_f32_e32 v9, 0, v9
	v_pk_fma_f32 v[6:7], v[42:43], v[8:9], v[6:7] op_sel_hi:[0,1,1]
	v_max_f32_e32 v8, v31, v31
	v_max_f32_e32 v9, v15, v15
	v_max_f32_e32 v8, 0, v8
	v_max_f32_e32 v9, 0, v9
	v_mov_b32_e32 v10, v43
	v_pk_fma_f32 v[6:7], v[10:11], v[8:9], v[6:7] op_sel_hi:[0,1,1]
	v_mov_b32_e32 v8, v7
	v_max_f32_e32 v7, v32, v32
	v_max_f32_e32 v10, 0, v7
	v_max_f32_e32 v7, v16, v16
	v_max_f32_e32 v11, 0, v7
	v_max_f32_e32 v7, v33, v33
	v_max_f32_e32 v12, 0, v7
	v_max_f32_e32 v7, v17, v17
	v_pk_fma_f32 v[10:11], v[36:37], v[10:11], 0 op_sel_hi:[0,1,0]
	v_max_f32_e32 v13, 0, v7
	v_max_f32_e32 v7, v34, v34
	v_pk_fma_f32 v[10:11], v[36:37], v[12:13], v[10:11] op_sel:[1,0,0]
	v_max_f32_e32 v12, 0, v7
	v_max_f32_e32 v7, v18, v18
	v_max_f32_e32 v13, 0, v7
	v_max_f32_e32 v7, v35, v35
	v_pk_fma_f32 v[10:11], v[38:39], v[12:13], v[10:11] op_sel_hi:[0,1,1]
	v_max_f32_e32 v12, 0, v7
	v_max_f32_e32 v7, v19, v19
	v_max_f32_e32 v13, 0, v7
	v_mov_b32_e32 v14, v39
	v_pk_fma_f32 v[10:11], v[14:15], v[12:13], v[10:11] op_sel_hi:[0,1,1]
	v_mov_b32_e32 v9, v11
	s_nop 1
	v_permlane32_swap_b32_e32 v10, v9
	v_permlane32_swap_b32_e32 v6, v8
	v_mov_b32_e32 v7, v10
	v_pk_add_f32 v[6:7], v[6:7], v[8:9]
	v_pk_add_f32 v[4:5], v[4:5], 0 op_sel_hi:[1,0]
	v_pk_add_f32 v[6:7], v[6:7], 0 op_sel_hi:[1,0]
	v_cmp_gt_i32_e64 s[4:5], 0, v4
	v_cmp_gt_i32_e64 s[8:9], 0, v5
	v_cmp_gt_i32_e64 s[12:13], 0, v6
	v_cmp_gt_i32_e64 s[16:17], 0, v7
	s_and_saveexec_b64 s[20:21], s[0:1]
	s_cbranch_execz .LBB0_689
	v_mad_u32_u24 v8, v209, s57, v2
	s_waitcnt vmcnt(0)
	ds_write_b128 v8, v[68:71] offset:16384
	ds_write_b128 v8, v[72:75] offset:17536
	ds_write_b128 v8, v[76:79] offset:18688
	ds_write_b128 v8, v[80:83] offset:19840
	ds_write_b128 v8, v[84:87] offset:20992
	ds_write_b128 v8, v[88:91] offset:22144
	ds_write_b128 v8, v[92:95] offset:23296
	ds_write_b128 v8, v[96:99] offset:24448

; #define MFMA32(a, b, c) __builtin_amdgcn_mfma_f32_32x32x16_bf16((a), (b), (c), 0, 0, 0)
; DI void topk_job(const Params& p, int b, int t0, char* lds) {
;     ...
; #pragma unroll
;     for (int i = 0; i < 17; ++i) {
;       const int c = 1 + w + 8 * i;
;       if (c <= cmax) {
;         const bool more = c + 8 <= cmax;
;         if (more) {
;           const u16* kp = ikb + (size_t)(c + 8) * 64 * 64;
; #pragma unroll
;           for (int j = 0; j < 8; ++j) st[j] = *(const u32x4*)(kp + (size_t)j * 8 * 64);
;         }
;         bf16x8 b0[4], b1[4];
; #pragma unroll
;         for (int ks = 0; ks < 4; ++ks) {
;           b0[ks] = *(const bf16x8*)(wb + r * 144 + ks * 32 + h * 16);
;           b1[ks] = *(const bf16x8*)(wb + (32 + r) * 144 + ks * 32 + h * 16);
;         }
;         __builtin_amdgcn_sched_barrier(0);
;         f32x16 a0, a1;
; #pragma unroll
;         for (int e = 0; e < 16; ++e) { a0[e] = 0.f; a1[e] = 0.f; }
; #pragma unroll
;         for (int ks = 0; ks < 4; ++ks) { a0 = MFMA32(af[ks], b0[ks], a0); a1 = MFMA32(af[ks], b1[ks], a1); }
;         const int key = c * 64 + lane;
; #pragma unroll
;         for (int qi = 0; qi < 4; ++qi) {
;           f32x2 pp2 = {0.f, 0.f};
; #pragma unroll
;           for (int e = 0; e < 4; ++e) {
;             const f32x2 rl = {fmaxf(a0[4 * qi + e], 0.f), fmaxf(a1[4 * qi + e], 0.f)};
;             const f32x2 wv = {iw[qi][e], iw[qi][e]};
;             pp2 += rl * wv;
;           }
;           const float p0 = pp2[0], p1 = pp2[1];
;           const u32x2 sw = __builtin_amdgcn_permlane32_swap(__float_as_uint(p0), __float_as_uint(p1), false, false);
;           float mine = __uint_as_float(sw[0]) + __uint_as_float(sw[1]);
;           mine += 0.0f;
;           unsigned u = __float_as_uint(mine);
;           u = (u & 0x80000000u) ? ~u : (u | 0x80000000u);
;           if (key > t0 + qi || key < LEAD) u = 0u;
;           sc[i][qi] = u;
;         }
;         if (more) {
; #pragma unroll
;           for (int j = 0; j < 8; ++j) *(u32x4*)(wb + (lrow + 8 * j) * 144 + lpc * 16) = st[j];
;         }
.LBB0_693:
	s_or_b64 exec, exec, s[2:3]
	ds_read_b128 v[4:7], v210 offset:16384
	ds_read_b128 v[102:105], v210 offset:16416
	s_waitcnt vmcnt(8)
	ds_read_b128 v[8:11], v210 offset:20992
	ds_read_b128 v[106:109], v210 offset:21024
	ds_read_b128 v[110:113], v210 offset:16448
	ds_read_b128 v[114:117], v210 offset:16480
	ds_read_b128 v[140:143], v210 offset:21056
	ds_read_b128 v[144:147], v210 offset:21088
	s_waitcnt lgkmcnt(7)
	v_mfma_f32_32x32x16_bf16 v[20:35], v[64:67], v[4:7], 0
	s_sub_i32 s2, 0x209d, s23
	s_sub_i32 s10, 0x209e, s23
	s_waitcnt lgkmcnt(5)
	v_mfma_f32_32x32x16_bf16 v[4:19], v[64:67], v[8:11], 0
	v_mfma_f32_32x32x16_bf16 v[20:35], v[60:63], v[102:105], v[20:35]
	v_lshl_or_b32 v104, v122, 6, v101
	v_cmp_gt_i32_e32 vcc, s25, v104
	v_cmp_lt_i32_e64 s[6:7], s24, v104
	v_cmp_lt_i32_e64 s[2:3], s2, v104
	v_cmp_lt_i32_e64 s[14:15], s10, v104
	v_cmp_lt_i32_e64 s[10:11], s22, v104
	s_waitcnt lgkmcnt(4)
	v_mfma_f32_32x32x16_bf16 v[4:19], v[60:63], v[106:109], v[4:19]
	s_waitcnt lgkmcnt(3)
	v_mfma_f32_32x32x16_bf16 v[20:35], v[56:59], v[110:113], v[20:35]
	s_waitcnt lgkmcnt(1)
	v_mfma_f32_32x32x16_bf16 v[4:19], v[56:59], v[140:143], v[4:19]
	v_mfma_f32_32x32x16_bf16 v[20:35], v[52:55], v[114:117], v[20:35]
	s_waitcnt lgkmcnt(0)
	v_mfma_f32_32x32x16_bf16 v[4:19], v[52:55], v[144:147], v[4:19]
	s_nop 9
	v_max_f32_e32 v20, v20, v20
	v_max_f32_e32 v102, 0, v20
	v_max_f32_e32 v20, v22, v22
	v_max_f32_e32 v20, 0, v20
	v_max_f32_e32 v4, v4, v4
	v_max_f32_e32 v103, 0, v4
	v_max_f32_e32 v4, v21, v21
	v_max_f32_e32 v5, v5, v5
	v_pk_fma_f32 v[102:103], v[48:49], v[102:103], 0 op_sel_hi:[0,1,0]
	v_max_f32_e32 v4, 0, v4
	v_max_f32_e32 v5, 0, v5
	v_max_f32_e32 v6, v6, v6
	v_pk_fma_f32 v[4:5], v[48:49], v[4:5], v[102:103] op_sel:[1,0,0]
	v_max_f32_e32 v21, 0, v6
	v_max_f32_e32 v6, v23, v23
	v_max_f32_e32 v7, v7, v7
	v_pk_fma_f32 v[4:5], v[50:51], v[20:21], v[4:5] op_sel_hi:[0,1,1]
	v_max_f32_e32 v6, 0, v6
	v_max_f32_e32 v7, 0, v7
	v_mov_b32_e32 v20, v51
	v_pk_fma_f32 v[4:5], v[20:21], v[6:7], v[4:5] op_sel_hi:[0,1,1]
	v_mov_b32_e32 v6, v5
	v_max_f32_e32 v5, v24, v24
	v_max_f32_e32 v20, 0, v5
	v_max_f32_e32 v5, v8, v8
	v_max_f32_e32 v21, 0, v5
	v_max_f32_e32 v5, v25, v25
	v_max_f32_e32 v8, 0, v5
	v_max_f32_e32 v5, v9, v9
	v_pk_fma_f32 v[20:21], v[44:45], v[20:21], 0 op_sel_hi:[0,1,0]
	v_max_f32_e32 v9, 0, v5
	v_max_f32_e32 v5, v26, v26
	v_pk_fma_f32 v[8:9], v[44:45], v[8:9], v[20:21] op_sel:[1,0,0]
	v_max_f32_e32 v20, 0, v5
	v_max_f32_e32 v5, v10, v10
	v_max_f32_e32 v21, 0, v5
	v_max_f32_e32 v5, v27, v27
	v_max_f32_e32 v10, 0, v5
	v_max_f32_e32 v5, v11, v11
	v_pk_fma_f32 v[8:9], v[46:47], v[20:21], v[8:9] op_sel_hi:[0,1,1]
	v_max_f32_e32 v11, 0, v5
	v_mov_b32_e32 v20, v47
	v_pk_fma_f32 v[8:9], v[20:21], v[10:11], v[8:9] op_sel_hi:[0,1,1]
	v_mov_b32_e32 v7, v9
	s_nop 1
	v_permlane32_swap_b32_e32 v8, v7
	v_permlane32_swap_b32_e32 v4, v6
	v_mov_b32_e32 v5, v8
	v_pk_add_f32 v[4:5], v[4:5], v[6:7]
	v_max_f32_e32 v6, v28, v28
	v_max_f32_e32 v7, v12, v12
	v_max_f32_e32 v6, 0, v6
	v_max_f32_e32 v7, 0, v7
	v_max_f32_e32 v8, v29, v29
	v_max_f32_e32 v9, v13, v13
	v_pk_fma_f32 v[6:7], v[40:41], v[6:7], 0 op_sel_hi:[0,1,0]
	v_max_f32_e32 v8, 0, v8
	v_max_f32_e32 v9, 0, v9
	v_pk_fma_f32 v[6:7], v[40:41], v[8:9], v[6:7] op_sel:[1,0,0]
	v_max_f32_e32 v8, v30, v30
	v_max_f32_e32 v9, v14, v14
	v_max_f32_e32 v8, 0, v8
	v_max_f32_e32 v9, 0, v9
	v_pk_fma_f32 v[6:7], v[42:43], v[8:9], v[6:7] op_sel_hi:[0,1,1]
	v_max_f32_e32 v8, v31, v31
	v_max_f32_e32 v9, v15, v15
	v_max_f32_e32 v8, 0, v8
	v_max_f32_e32 v9, 0, v9
	v_mov_b32_e32 v10, v43
	v_pk_fma_f32 v[6:7], v[10:11], v[8:9], v[6:7] op_sel_hi:[0,1,1]
	v_mov_b32_e32 v8, v7
	v_max_f32_e32 v7, v32, v32
	v_max_f32_e32 v10, 0, v7
	v_max_f32_e32 v7, v16, v16
	v_max_f32_e32 v11, 0, v7
	v_max_f32_e32 v7, v33, v33
	v_max_f32_e32 v12, 0, v7
	v_max_f32_e32 v7, v17, v17
	v_pk_fma_f32 v[10:11], v[36:37], v[10:11], 0 op_sel_hi:[0,1,0]
	v_max_f32_e32 v13, 0, v7
	v_max_f32_e32 v7, v34, v34
	v_pk_fma_f32 v[10:11], v[36:37], v[12:13], v[10:11] op_sel:[1,0,0]
	v_max_f32_e32 v12, 0, v7
	v_max_f32_e32 v7, v18, v18
	v_max_f32_e32 v13, 0, v7
	v_max_f32_e32 v7, v35, v35
	v_pk_fma_f32 v[10:11], v[38:39], v[12:13], v[10:11] op_sel_hi:[0,1,1]
	v_max_f32_e32 v12, 0, v7
	v_max_f32_e32 v7, v19, v19
	v_max_f32_e32 v13, 0, v7
	v_mov_b32_e32 v14, v39
	v_pk_fma_f32 v[10:11], v[14:15], v[12:13], v[10:11] op_sel_hi:[0,1,1]
	v_mov_b32_e32 v9, v11
	s_nop 1
	v_permlane32_swap_b32_e32 v10, v9
	v_permlane32_swap_b32_e32 v6, v8
	v_mov_b32_e32 v7, v10
	v_pk_add_f32 v[6:7], v[6:7], v[8:9]
	v_pk_add_f32 v[4:5], v[4:5], 0 op_sel_hi:[1,0]
	v_pk_add_f32 v[6:7], v[6:7], 0 op_sel_hi:[1,0]
	v_cmp_gt_i32_e64 s[4:5], 0, v4
	v_cmp_gt_i32_e64 s[8:9], 0, v5
	v_cmp_gt_i32_e64 s[12:13], 0, v6
	v_cmp_gt_i32_e64 s[16:17], 0, v7
	s_and_saveexec_b64 s[20:21], s[0:1]
	s_cbranch_execz .LBB0_695
	v_mad_u32_u24 v8, v209, s57, v2
	s_waitcnt vmcnt(0)
	ds_write_b128 v8, v[68:71] offset:16384
	ds_write_b128 v8, v[72:75] offset:17536
	ds_write_b128 v8, v[76:79] offset:18688
	ds_write_b128 v8, v[80:83] offset:19840
	ds_write_b128 v8, v[84:87] offset:20992
	ds_write_b128 v8, v[88:91] offset:22144
	ds_write_b128 v8, v[92:95] offset:23296
	ds_write_b128 v8, v[96:99] offset:24448

; #define MFMA32(a, b, c) __builtin_amdgcn_mfma_f32_32x32x16_bf16((a), (b), (c), 0, 0, 0)
; DI void topk_job(const Params& p, int b, int t0, char* lds) {
;     ...
; #pragma unroll
;     for (int i = 0; i < 17; ++i) {
;       const int c = 1 + w + 8 * i;
;       if (c <= cmax) {
;         const bool more = c + 8 <= cmax;
;         if (more) {
;           const u16* kp = ikb + (size_t)(c + 8) * 64 * 64;
; #pragma unroll
;           for (int j = 0; j < 8; ++j) st[j] = *(const u32x4*)(kp + (size_t)j * 8 * 64);
;         }
;         bf16x8 b0[4], b1[4];
; #pragma unroll
;         for (int ks = 0; ks < 4; ++ks) {
;           b0[ks] = *(const bf16x8*)(wb + r * 144 + ks * 32 + h * 16);
;           b1[ks] = *(const bf16x8*)(wb + (32 + r) * 144 + ks * 32 + h * 16);
;         }
;         __builtin_amdgcn_sched_barrier(0);
;         f32x16 a0, a1;
; #pragma unroll
;         for (int e = 0; e < 16; ++e) { a0[e] = 0.f; a1[e] = 0.f; }
; #pragma unroll
;         for (int ks = 0; ks < 4; ++ks) { a0 = MFMA32(af[ks], b0[ks], a0); a1 = MFMA32(af[ks], b1[ks], a1); }
;         const int key = c * 64 + lane;
; #pragma unroll
;         for (int qi = 0; qi < 4; ++qi) {
;           f32x2 pp2 = {0.f, 0.f};
; #pragma unroll
;           for (int e = 0; e < 4; ++e) {
;             const f32x2 rl = {fmaxf(a0[4 * qi + e], 0.f), fmaxf(a1[4 * qi + e], 0.f)};
;             const f32x2 wv = {iw[qi][e], iw[qi][e]};
;             pp2 += rl * wv;
;           }
;           const float p0 = pp2[0], p1 = pp2[1];
;           const u32x2 sw = __builtin_amdgcn_permlane32_swap(__float_as_uint(p0), __float_as_uint(p1), false, false);
;           float mine = __uint_as_float(sw[0]) + __uint_as_float(sw[1]);
;           mine += 0.0f;
;           unsigned u = __float_as_uint(mine);
;           u = (u & 0x80000000u) ? ~u : (u | 0x80000000u);
;           if (key > t0 + qi || key < LEAD) u = 0u;
;           sc[i][qi] = u;
;         }
;         if (more) {
; #pragma unroll
;           for (int j = 0; j < 8; ++j) *(u32x4*)(wb + (lrow + 8 * j) * 144 + lpc * 16) = st[j];
;         }
.LBB0_699:
	s_or_b64 exec, exec, s[2:3]
	ds_read_b128 v[4:7], v210 offset:16384
	ds_read_b128 v[102:105], v210 offset:16416
	s_waitcnt vmcnt(8)
	ds_read_b128 v[8:11], v210 offset:20992
	ds_read_b128 v[106:109], v210 offset:21024
	ds_read_b128 v[110:113], v210 offset:16448
	ds_read_b128 v[114:117], v210 offset:16480
	ds_read_b128 v[140:143], v210 offset:21056
	ds_read_b128 v[162:165], v210 offset:21088
	s_waitcnt lgkmcnt(7)
	v_mfma_f32_32x32x16_bf16 v[20:35], v[64:67], v[4:7], 0
	s_sub_i32 s2, 0x209d, s23
	s_sub_i32 s10, 0x209e, s23
	s_waitcnt lgkmcnt(5)
	v_mfma_f32_32x32x16_bf16 v[4:19], v[64:67], v[8:11], 0
	v_mfma_f32_32x32x16_bf16 v[20:35], v[60:63], v[102:105], v[20:35]
	v_lshl_or_b32 v104, v120, 6, v101
	v_cmp_gt_i32_e32 vcc, s25, v104
	v_cmp_lt_i32_e64 s[6:7], s24, v104
	v_cmp_lt_i32_e64 s[2:3], s2, v104
	v_cmp_lt_i32_e64 s[14:15], s10, v104
	v_cmp_lt_i32_e64 s[10:11], s22, v104
	s_waitcnt lgkmcnt(4)
	v_mfma_f32_32x32x16_bf16 v[4:19], v[60:63], v[106:109], v[4:19]
	s_waitcnt lgkmcnt(3)
	v_mfma_f32_32x32x16_bf16 v[20:35], v[56:59], v[110:113], v[20:35]
	s_waitcnt lgkmcnt(1)
	v_mfma_f32_32x32x16_bf16 v[4:19], v[56:59], v[140:143], v[4:19]
	v_mfma_f32_32x32x16_bf16 v[20:35], v[52:55], v[114:117], v[20:35]
	s_waitcnt lgkmcnt(0)
	v_mfma_f32_32x32x16_bf16 v[4:19], v[52:55], v[162:165], v[4:19]
	s_nop 9
	v_max_f32_e32 v20, v20, v20
	v_max_f32_e32 v102, 0, v20
	v_max_f32_e32 v20, v22, v22
	v_max_f32_e32 v20, 0, v20
	v_max_f32_e32 v4, v4, v4
	v_max_f32_e32 v103, 0, v4
	v_max_f32_e32 v4, v21, v21
	v_max_f32_e32 v5, v5, v5
	v_pk_fma_f32 v[102:103], v[48:49], v[102:103], 0 op_sel_hi:[0,1,0]
	v_max_f32_e32 v4, 0, v4
	v_max_f32_e32 v5, 0, v5
	v_max_f32_e32 v6, v6, v6
	v_pk_fma_f32 v[4:5], v[48:49], v[4:5], v[102:103] op_sel:[1,0,0]
	v_max_f32_e32 v21, 0, v6
	v_max_f32_e32 v6, v23, v23
	v_max_f32_e32 v7, v7, v7
	v_pk_fma_f32 v[4:5], v[50:51], v[20:21], v[4:5] op_sel_hi:[0,1,1]
	v_max_f32_e32 v6, 0, v6
	v_max_f32_e32 v7, 0, v7
	v_mov_b32_e32 v20, v51
	v_pk_fma_f32 v[4:5], v[20:21], v[6:7], v[4:5] op_sel_hi:[0,1,1]
	v_mov_b32_e32 v6, v5
	v_max_f32_e32 v5, v24, v24
	v_max_f32_e32 v20, 0, v5
	v_max_f32_e32 v5, v8, v8
	v_max_f32_e32 v21, 0, v5
	v_max_f32_e32 v5, v25, v25
	v_max_f32_e32 v8, 0, v5
	v_max_f32_e32 v5, v9, v9
	v_pk_fma_f32 v[20:21], v[44:45], v[20:21], 0 op_sel_hi:[0,1,0]
	v_max_f32_e32 v9, 0, v5
	v_max_f32_e32 v5, v26, v26
	v_pk_fma_f32 v[8:9], v[44:45], v[8:9], v[20:21] op_sel:[1,0,0]
	v_max_f32_e32 v20, 0, v5
	v_max_f32_e32 v5, v10, v10
	v_max_f32_e32 v21, 0, v5
	v_max_f32_e32 v5, v27, v27
	v_max_f32_e32 v10, 0, v5
	v_max_f32_e32 v5, v11, v11
	v_pk_fma_f32 v[8:9], v[46:47], v[20:21], v[8:9] op_sel_hi:[0,1,1]
	v_max_f32_e32 v11, 0, v5
	v_mov_b32_e32 v20, v47
	v_pk_fma_f32 v[8:9], v[20:21], v[10:11], v[8:9] op_sel_hi:[0,1,1]
	v_mov_b32_e32 v7, v9
	s_nop 1
	v_permlane32_swap_b32_e32 v8, v7
	v_permlane32_swap_b32_e32 v4, v6
	v_mov_b32_e32 v5, v8
	v_pk_add_f32 v[4:5], v[4:5], v[6:7]
	v_max_f32_e32 v6, v28, v28
	v_max_f32_e32 v7, v12, v12
	v_max_f32_e32 v6, 0, v6
	v_max_f32_e32 v7, 0, v7
	v_max_f32_e32 v8, v29, v29
	v_max_f32_e32 v9, v13, v13
	v_pk_fma_f32 v[6:7], v[40:41], v[6:7], 0 op_sel_hi:[0,1,0]
	v_max_f32_e32 v8, 0, v8
	v_max_f32_e32 v9, 0, v9
	v_pk_fma_f32 v[6:7], v[40:41], v[8:9], v[6:7] op_sel:[1,0,0]
	v_max_f32_e32 v8, v30, v30
	v_max_f32_e32 v9, v14, v14
	v_max_f32_e32 v8, 0, v8
	v_max_f32_e32 v9, 0, v9
	v_pk_fma_f32 v[6:7], v[42:43], v[8:9], v[6:7] op_sel_hi:[0,1,1]
	v_max_f32_e32 v8, v31, v31
	v_max_f32_e32 v9, v15, v15
	v_max_f32_e32 v8, 0, v8
	v_max_f32_e32 v9, 0, v9
	v_mov_b32_e32 v10, v43
	v_pk_fma_f32 v[6:7], v[10:11], v[8:9], v[6:7] op_sel_hi:[0,1,1]
	v_mov_b32_e32 v8, v7
	v_max_f32_e32 v7, v32, v32
	v_max_f32_e32 v10, 0, v7
	v_max_f32_e32 v7, v16, v16
	v_max_f32_e32 v11, 0, v7
	v_max_f32_e32 v7, v33, v33
	v_max_f32_e32 v12, 0, v7
	v_max_f32_e32 v7, v17, v17
	v_pk_fma_f32 v[10:11], v[36:37], v[10:11], 0 op_sel_hi:[0,1,0]
	v_max_f32_e32 v13, 0, v7
	v_max_f32_e32 v7, v34, v34
	v_pk_fma_f32 v[10:11], v[36:37], v[12:13], v[10:11] op_sel:[1,0,0]
	v_max_f32_e32 v12, 0, v7
	v_max_f32_e32 v7, v18, v18
	v_max_f32_e32 v13, 0, v7
	v_max_f32_e32 v7, v35, v35
	v_pk_fma_f32 v[10:11], v[38:39], v[12:13], v[10:11] op_sel_hi:[0,1,1]
	v_max_f32_e32 v12, 0, v7
	v_max_f32_e32 v7, v19, v19
	v_max_f32_e32 v13, 0, v7
	v_mov_b32_e32 v14, v39
	v_pk_fma_f32 v[10:11], v[14:15], v[12:13], v[10:11] op_sel_hi:[0,1,1]
	v_mov_b32_e32 v9, v11
	s_nop 1
	v_permlane32_swap_b32_e32 v10, v9
	v_permlane32_swap_b32_e32 v6, v8
	v_mov_b32_e32 v7, v10
	v_pk_add_f32 v[6:7], v[6:7], v[8:9]
	v_pk_add_f32 v[4:5], v[4:5], 0 op_sel_hi:[1,0]
	v_pk_add_f32 v[6:7], v[6:7], 0 op_sel_hi:[1,0]
	v_cmp_gt_i32_e64 s[4:5], 0, v4
	v_cmp_gt_i32_e64 s[8:9], 0, v5
	v_cmp_gt_i32_e64 s[12:13], 0, v6
	v_cmp_gt_i32_e64 s[16:17], 0, v7
	s_and_saveexec_b64 s[20:21], s[0:1]
	s_cbranch_execz .LBB0_701
	v_mad_u32_u24 v8, v209, s57, v2
	s_waitcnt vmcnt(0)
	ds_write_b128 v8, v[68:71] offset:16384
	ds_write_b128 v8, v[72:75] offset:17536
	ds_write_b128 v8, v[76:79] offset:18688
	ds_write_b128 v8, v[80:83] offset:19840
	ds_write_b128 v8, v[84:87] offset:20992
	ds_write_b128 v8, v[88:91] offset:22144
	ds_write_b128 v8, v[92:95] offset:23296
	ds_write_b128 v8, v[96:99] offset:24448

; #define MFMA32(a, b, c) __builtin_amdgcn_mfma_f32_32x32x16_bf16((a), (b), (c), 0, 0, 0)
; DI void topk_job(const Params& p, int b, int t0, char* lds) {
;     ...
; #pragma unroll
;     for (int i = 0; i < 17; ++i) {
;       const int c = 1 + w + 8 * i;
;       if (c <= cmax) {
;         const bool more = c + 8 <= cmax;
;         if (more) {
;           const u16* kp = ikb + (size_t)(c + 8) * 64 * 64;
; #pragma unroll
;           for (int j = 0; j < 8; ++j) st[j] = *(const u32x4*)(kp + (size_t)j * 8 * 64);
;         }
;         bf16x8 b0[4], b1[4];
; #pragma unroll
;         for (int ks = 0; ks < 4; ++ks) {
;           b0[ks] = *(const bf16x8*)(wb + r * 144 + ks * 32 + h * 16);
;           b1[ks] = *(const bf16x8*)(wb + (32 + r) * 144 + ks * 32 + h * 16);
;         }
;         __builtin_amdgcn_sched_barrier(0);
;         f32x16 a0, a1;
; #pragma unroll
;         for (int e = 0; e < 16; ++e) { a0[e] = 0.f; a1[e] = 0.f; }
; #pragma unroll
;         for (int ks = 0; ks < 4; ++ks) { a0 = MFMA32(af[ks], b0[ks], a0); a1 = MFMA32(af[ks], b1[ks], a1); }
;         const int key = c * 64 + lane;
; #pragma unroll
;         for (int qi = 0; qi < 4; ++qi) {
;           f32x2 pp2 = {0.f, 0.f};
; #pragma unroll
;           for (int e = 0; e < 4; ++e) {
;             const f32x2 rl = {fmaxf(a0[4 * qi + e], 0.f), fmaxf(a1[4 * qi + e], 0.f)};
;             const f32x2 wv = {iw[qi][e], iw[qi][e]};
;             pp2 += rl * wv;
;           }
;           const float p0 = pp2[0], p1 = pp2[1];
;           const u32x2 sw = __builtin_amdgcn_permlane32_swap(__float_as_uint(p0), __float_as_uint(p1), false, false);
;           float mine = __uint_as_float(sw[0]) + __uint_as_float(sw[1]);
;           mine += 0.0f;
;           unsigned u = __float_as_uint(mine);
;           u = (u & 0x80000000u) ? ~u : (u | 0x80000000u);
;           if (key > t0 + qi || key < LEAD) u = 0u;
;           sc[i][qi] = u;
;         }
;         if (more) {
; #pragma unroll
;           for (int j = 0; j < 8; ++j) *(u32x4*)(wb + (lrow + 8 * j) * 144 + lpc * 16) = st[j];
;         }
.LBB0_705:
	s_or_b64 exec, exec, s[2:3]
	ds_read_b128 v[4:7], v210 offset:16384
	ds_read_b128 v[102:105], v210 offset:16416
	s_waitcnt vmcnt(8)
	ds_read_b128 v[8:11], v210 offset:20992
	ds_read_b128 v[106:109], v210 offset:21024
	ds_read_b128 v[110:113], v210 offset:16448
	ds_read_b128 v[140:143], v210 offset:16480
	ds_read_b128 v[162:165], v210 offset:21056
	ds_read_b128 v[176:179], v210 offset:21088
	s_waitcnt lgkmcnt(7)
	v_mfma_f32_32x32x16_bf16 v[20:35], v[64:67], v[4:7], 0
	s_sub_i32 s2, 0x209d, s23
	s_sub_i32 s10, 0x209e, s23
	s_waitcnt lgkmcnt(5)
	v_mfma_f32_32x32x16_bf16 v[4:19], v[64:67], v[8:11], 0
	v_mfma_f32_32x32x16_bf16 v[20:35], v[60:63], v[102:105], v[20:35]
	v_lshl_or_b32 v104, v118, 6, v101
	v_cmp_gt_i32_e32 vcc, s25, v104
	v_cmp_lt_i32_e64 s[6:7], s24, v104
	v_cmp_lt_i32_e64 s[2:3], s2, v104
	v_cmp_lt_i32_e64 s[14:15], s10, v104
	v_cmp_lt_i32_e64 s[10:11], s22, v104
	s_waitcnt lgkmcnt(4)
	v_mfma_f32_32x32x16_bf16 v[4:19], v[60:63], v[106:109], v[4:19]
	s_waitcnt lgkmcnt(3)
	v_mfma_f32_32x32x16_bf16 v[20:35], v[56:59], v[110:113], v[20:35]
	s_waitcnt lgkmcnt(1)
	v_mfma_f32_32x32x16_bf16 v[4:19], v[56:59], v[162:165], v[4:19]
	v_mfma_f32_32x32x16_bf16 v[20:35], v[52:55], v[140:143], v[20:35]
	s_waitcnt lgkmcnt(0)
	v_mfma_f32_32x32x16_bf16 v[4:19], v[52:55], v[176:179], v[4:19]
	s_nop 9
	v_max_f32_e32 v20, v20, v20
	v_max_f32_e32 v102, 0, v20
	v_max_f32_e32 v20, v22, v22
	v_max_f32_e32 v20, 0, v20
	v_max_f32_e32 v4, v4, v4
	v_max_f32_e32 v103, 0, v4
	v_max_f32_e32 v4, v21, v21
	v_max_f32_e32 v5, v5, v5
	v_pk_fma_f32 v[102:103], v[48:49], v[102:103], 0 op_sel_hi:[0,1,0]
	v_max_f32_e32 v4, 0, v4
	v_max_f32_e32 v5, 0, v5
	v_max_f32_e32 v6, v6, v6
	v_pk_fma_f32 v[4:5], v[48:49], v[4:5], v[102:103] op_sel:[1,0,0]
	v_max_f32_e32 v21, 0, v6
	v_max_f32_e32 v6, v23, v23
	v_max_f32_e32 v7, v7, v7
	v_pk_fma_f32 v[4:5], v[50:51], v[20:21], v[4:5] op_sel_hi:[0,1,1]
	v_max_f32_e32 v6, 0, v6
	v_max_f32_e32 v7, 0, v7
	v_mov_b32_e32 v20, v51
	v_pk_fma_f32 v[4:5], v[20:21], v[6:7], v[4:5] op_sel_hi:[0,1,1]
	v_mov_b32_e32 v6, v5
	v_max_f32_e32 v5, v24, v24
	v_max_f32_e32 v20, 0, v5
	v_max_f32_e32 v5, v8, v8
	v_max_f32_e32 v21, 0, v5
	v_max_f32_e32 v5, v25, v25
	v_max_f32_e32 v8, 0, v5
	v_max_f32_e32 v5, v9, v9
	v_pk_fma_f32 v[20:21], v[44:45], v[20:21], 0 op_sel_hi:[0,1,0]
	v_max_f32_e32 v9, 0, v5
	v_max_f32_e32 v5, v26, v26
	v_pk_fma_f32 v[8:9], v[44:45], v[8:9], v[20:21] op_sel:[1,0,0]
	v_max_f32_e32 v20, 0, v5
	v_max_f32_e32 v5, v10, v10
	v_max_f32_e32 v21, 0, v5
	v_max_f32_e32 v5, v27, v27
	v_max_f32_e32 v10, 0, v5
	v_max_f32_e32 v5, v11, v11
	v_pk_fma_f32 v[8:9], v[46:47], v[20:21], v[8:9] op_sel_hi:[0,1,1]
	v_max_f32_e32 v11, 0, v5
	v_mov_b32_e32 v20, v47
	v_pk_fma_f32 v[8:9], v[20:21], v[10:11], v[8:9] op_sel_hi:[0,1,1]
	v_mov_b32_e32 v7, v9
	s_nop 1
	v_permlane32_swap_b32_e32 v8, v7
	v_permlane32_swap_b32_e32 v4, v6
	v_mov_b32_e32 v5, v8
	v_pk_add_f32 v[4:5], v[4:5], v[6:7]
	v_max_f32_e32 v6, v28, v28
	v_max_f32_e32 v7, v12, v12
	v_max_f32_e32 v6, 0, v6
	v_max_f32_e32 v7, 0, v7
	v_max_f32_e32 v8, v29, v29
	v_max_f32_e32 v9, v13, v13
	v_pk_fma_f32 v[6:7], v[40:41], v[6:7], 0 op_sel_hi:[0,1,0]
	v_max_f32_e32 v8, 0, v8
	v_max_f32_e32 v9, 0, v9
	v_pk_fma_f32 v[6:7], v[40:41], v[8:9], v[6:7] op_sel:[1,0,0]
	v_max_f32_e32 v8, v30, v30
	v_max_f32_e32 v9, v14, v14
	v_max_f32_e32 v8, 0, v8
	v_max_f32_e32 v9, 0, v9
	v_pk_fma_f32 v[6:7], v[42:43], v[8:9], v[6:7] op_sel_hi:[0,1,1]
	v_max_f32_e32 v8, v31, v31
	v_max_f32_e32 v9, v15, v15
	v_max_f32_e32 v8, 0, v8
	v_max_f32_e32 v9, 0, v9
	v_mov_b32_e32 v10, v43
	v_pk_fma_f32 v[6:7], v[10:11], v[8:9], v[6:7] op_sel_hi:[0,1,1]
	v_mov_b32_e32 v8, v7
	v_max_f32_e32 v7, v32, v32
	v_max_f32_e32 v10, 0, v7
	v_max_f32_e32 v7, v16, v16
	v_max_f32_e32 v11, 0, v7
	v_max_f32_e32 v7, v33, v33
	v_max_f32_e32 v12, 0, v7
	v_max_f32_e32 v7, v17, v17
	v_pk_fma_f32 v[10:11], v[36:37], v[10:11], 0 op_sel_hi:[0,1,0]
	v_max_f32_e32 v13, 0, v7
	v_max_f32_e32 v7, v34, v34
	v_pk_fma_f32 v[10:11], v[36:37], v[12:13], v[10:11] op_sel:[1,0,0]
	v_max_f32_e32 v12, 0, v7
	v_max_f32_e32 v7, v18, v18
	v_max_f32_e32 v13, 0, v7
	v_max_f32_e32 v7, v35, v35
	v_pk_fma_f32 v[10:11], v[38:39], v[12:13], v[10:11] op_sel_hi:[0,1,1]
	v_max_f32_e32 v12, 0, v7
	v_max_f32_e32 v7, v19, v19
	v_max_f32_e32 v13, 0, v7
	v_mov_b32_e32 v14, v39
	v_pk_fma_f32 v[10:11], v[14:15], v[12:13], v[10:11] op_sel_hi:[0,1,1]
	v_mov_b32_e32 v9, v11
	s_nop 1
	v_permlane32_swap_b32_e32 v10, v9
	v_permlane32_swap_b32_e32 v6, v8
	v_mov_b32_e32 v7, v10
	v_pk_add_f32 v[6:7], v[6:7], v[8:9]
	v_pk_add_f32 v[4:5], v[4:5], 0 op_sel_hi:[1,0]
	v_pk_add_f32 v[6:7], v[6:7], 0 op_sel_hi:[1,0]
	v_cmp_gt_i32_e64 s[4:5], 0, v4
	v_cmp_gt_i32_e64 s[8:9], 0, v5
	v_cmp_gt_i32_e64 s[12:13], 0, v6
	v_cmp_gt_i32_e64 s[16:17], 0, v7
	s_and_saveexec_b64 s[20:21], s[0:1]
	s_cbranch_execz .LBB0_707
	v_mad_u32_u24 v8, v209, s57, v2
	s_waitcnt vmcnt(0)
	ds_write_b128 v8, v[68:71] offset:16384
	ds_write_b128 v8, v[72:75] offset:17536
	ds_write_b128 v8, v[76:79] offset:18688
	ds_write_b128 v8, v[80:83] offset:19840
	ds_write_b128 v8, v[84:87] offset:20992
	ds_write_b128 v8, v[88:91] offset:22144
	ds_write_b128 v8, v[92:95] offset:23296
	ds_write_b128 v8, v[96:99] offset:24448

; #define MFMA32(a, b, c) __builtin_amdgcn_mfma_f32_32x32x16_bf16((a), (b), (c), 0, 0, 0)
; DI void topk_job(const Params& p, int b, int t0, char* lds) {
;     ...
; #pragma unroll
;     for (int i = 0; i < 17; ++i) {
;       const int c = 1 + w + 8 * i;
;       if (c <= cmax) {
;         const bool more = c + 8 <= cmax;
;         if (more) {
;           const u16* kp = ikb + (size_t)(c + 8) * 64 * 64;
; #pragma unroll
;           for (int j = 0; j < 8; ++j) st[j] = *(const u32x4*)(kp + (size_t)j * 8 * 64);
;         }
;         bf16x8 b0[4], b1[4];
; #pragma unroll
;         for (int ks = 0; ks < 4; ++ks) {
;           b0[ks] = *(const bf16x8*)(wb + r * 144 + ks * 32 + h * 16);
;           b1[ks] = *(const bf16x8*)(wb + (32 + r) * 144 + ks * 32 + h * 16);
;         }
;         __builtin_amdgcn_sched_barrier(0);
;         f32x16 a0, a1;
; #pragma unroll
;         for (int e = 0; e < 16; ++e) { a0[e] = 0.f; a1[e] = 0.f; }
; #pragma unroll
;         for (int ks = 0; ks < 4; ++ks) { a0 = MFMA32(af[ks], b0[ks], a0); a1 = MFMA32(af[ks], b1[ks], a1); }
;         const int key = c * 64 + lane;
; #pragma unroll
;         for (int qi = 0; qi < 4; ++qi) {
;           f32x2 pp2 = {0.f, 0.f};
; #pragma unroll
;           for (int e = 0; e < 4; ++e) {
;             const f32x2 rl = {fmaxf(a0[4 * qi + e], 0.f), fmaxf(a1[4 * qi + e], 0.f)};
;             const f32x2 wv = {iw[qi][e], iw[qi][e]};
;             pp2 += rl * wv;
;           }
;           const float p0 = pp2[0], p1 = pp2[1];
;           const u32x2 sw = __builtin_amdgcn_permlane32_swap(__float_as_uint(p0), __float_as_uint(p1), false, false);
;           float mine = __uint_as_float(sw[0]) + __uint_as_float(sw[1]);
;           mine += 0.0f;
;           unsigned u = __float_as_uint(mine);
;           u = (u & 0x80000000u) ? ~u : (u | 0x80000000u);
;           if (key > t0 + qi || key < LEAD) u = 0u;
;           sc[i][qi] = u;
;         }
;         if (more) {
; #pragma unroll
;           for (int j = 0; j < 8; ++j) *(u32x4*)(wb + (lrow + 8 * j) * 144 + lpc * 16) = st[j];
;         }
.LBB0_711:
	s_or_b64 exec, exec, s[2:3]
	ds_read_b128 v[4:7], v210 offset:16384
	ds_read_b128 v[102:105], v210 offset:16416
	s_waitcnt vmcnt(8)
	ds_read_b128 v[8:11], v210 offset:20992
	ds_read_b128 v[106:109], v210 offset:21024
	ds_read_b128 v[140:143], v210 offset:16448
	ds_read_b128 v[176:179], v210 offset:16480
	ds_read_b128 v[212:215], v210 offset:21056
	ds_read_b128 v[216:219], v210 offset:21088
	s_waitcnt lgkmcnt(7)
	v_mfma_f32_32x32x16_bf16 v[20:35], v[64:67], v[4:7], 0
	s_sub_i32 s2, 0x209d, s23
	s_sub_i32 s10, 0x209e, s23
	s_waitcnt lgkmcnt(5)
	v_mfma_f32_32x32x16_bf16 v[4:19], v[64:67], v[8:11], 0
	v_mfma_f32_32x32x16_bf16 v[20:35], v[60:63], v[102:105], v[20:35]
	v_lshl_or_b32 v104, v114, 6, v101
	v_cmp_gt_i32_e32 vcc, s25, v104
	v_cmp_lt_i32_e64 s[6:7], s24, v104
	v_cmp_lt_i32_e64 s[2:3], s2, v104
	v_cmp_lt_i32_e64 s[14:15], s10, v104
	v_cmp_lt_i32_e64 s[10:11], s22, v104
	s_waitcnt lgkmcnt(4)
	v_mfma_f32_32x32x16_bf16 v[4:19], v[60:63], v[106:109], v[4:19]
	s_waitcnt lgkmcnt(3)
	v_mfma_f32_32x32x16_bf16 v[20:35], v[56:59], v[140:143], v[20:35]
	s_waitcnt lgkmcnt(1)
	v_mfma_f32_32x32x16_bf16 v[4:19], v[56:59], v[212:215], v[4:19]
	v_mfma_f32_32x32x16_bf16 v[20:35], v[52:55], v[176:179], v[20:35]
	s_waitcnt lgkmcnt(0)
	v_mfma_f32_32x32x16_bf16 v[4:19], v[52:55], v[216:219], v[4:19]
	s_nop 9
	v_max_f32_e32 v20, v20, v20
	v_max_f32_e32 v102, 0, v20
	v_max_f32_e32 v20, v22, v22
	v_max_f32_e32 v20, 0, v20
	v_max_f32_e32 v4, v4, v4
	v_max_f32_e32 v103, 0, v4
	v_max_f32_e32 v4, v21, v21
	v_max_f32_e32 v5, v5, v5
	v_pk_fma_f32 v[102:103], v[48:49], v[102:103], 0 op_sel_hi:[0,1,0]
	v_max_f32_e32 v4, 0, v4
	v_max_f32_e32 v5, 0, v5
	v_max_f32_e32 v6, v6, v6
	v_pk_fma_f32 v[4:5], v[48:49], v[4:5], v[102:103] op_sel:[1,0,0]
	v_max_f32_e32 v21, 0, v6
	v_max_f32_e32 v6, v23, v23
	v_max_f32_e32 v7, v7, v7
	v_pk_fma_f32 v[4:5], v[50:51], v[20:21], v[4:5] op_sel_hi:[0,1,1]
	v_max_f32_e32 v6, 0, v6
	v_max_f32_e32 v7, 0, v7
	v_mov_b32_e32 v20, v51
	v_pk_fma_f32 v[4:5], v[20:21], v[6:7], v[4:5] op_sel_hi:[0,1,1]
	v_mov_b32_e32 v6, v5
	v_max_f32_e32 v5, v24, v24
	v_max_f32_e32 v20, 0, v5
	v_max_f32_e32 v5, v8, v8
	v_max_f32_e32 v21, 0, v5
	v_max_f32_e32 v5, v25, v25
	v_max_f32_e32 v8, 0, v5
	v_max_f32_e32 v5, v9, v9
	v_pk_fma_f32 v[20:21], v[44:45], v[20:21], 0 op_sel_hi:[0,1,0]
	v_max_f32_e32 v9, 0, v5
	v_max_f32_e32 v5, v26, v26
	v_pk_fma_f32 v[8:9], v[44:45], v[8:9], v[20:21] op_sel:[1,0,0]
	v_max_f32_e32 v20, 0, v5
	v_max_f32_e32 v5, v10, v10
	v_max_f32_e32 v21, 0, v5
	v_max_f32_e32 v5, v27, v27
	v_max_f32_e32 v10, 0, v5
	v_max_f32_e32 v5, v11, v11
	v_pk_fma_f32 v[8:9], v[46:47], v[20:21], v[8:9] op_sel_hi:[0,1,1]
	v_max_f32_e32 v11, 0, v5
	v_mov_b32_e32 v20, v47
	v_pk_fma_f32 v[8:9], v[20:21], v[10:11], v[8:9] op_sel_hi:[0,1,1]
	v_mov_b32_e32 v7, v9
	s_nop 1
	v_permlane32_swap_b32_e32 v8, v7
	v_permlane32_swap_b32_e32 v4, v6
	v_mov_b32_e32 v5, v8
	v_pk_add_f32 v[4:5], v[4:5], v[6:7]
	v_max_f32_e32 v6, v28, v28
	v_max_f32_e32 v7, v12, v12
	v_max_f32_e32 v6, 0, v6
	v_max_f32_e32 v7, 0, v7
	v_max_f32_e32 v8, v29, v29
	v_max_f32_e32 v9, v13, v13
	v_pk_fma_f32 v[6:7], v[40:41], v[6:7], 0 op_sel_hi:[0,1,0]
	v_max_f32_e32 v8, 0, v8
	v_max_f32_e32 v9, 0, v9
	v_pk_fma_f32 v[6:7], v[40:41], v[8:9], v[6:7] op_sel:[1,0,0]
	v_max_f32_e32 v8, v30, v30
	v_max_f32_e32 v9, v14, v14
	v_max_f32_e32 v8, 0, v8
	v_max_f32_e32 v9, 0, v9
	v_pk_fma_f32 v[6:7], v[42:43], v[8:9], v[6:7] op_sel_hi:[0,1,1]
	v_max_f32_e32 v8, v31, v31
	v_max_f32_e32 v9, v15, v15
	v_max_f32_e32 v8, 0, v8
	v_max_f32_e32 v9, 0, v9
	v_mov_b32_e32 v10, v43
	v_pk_fma_f32 v[6:7], v[10:11], v[8:9], v[6:7] op_sel_hi:[0,1,1]
	v_mov_b32_e32 v8, v7
	v_max_f32_e32 v7, v32, v32
	v_max_f32_e32 v10, 0, v7
	v_max_f32_e32 v7, v16, v16
	v_max_f32_e32 v11, 0, v7
	v_max_f32_e32 v7, v33, v33
	v_max_f32_e32 v12, 0, v7
	v_max_f32_e32 v7, v17, v17
	v_pk_fma_f32 v[10:11], v[36:37], v[10:11], 0 op_sel_hi:[0,1,0]
	v_max_f32_e32 v13, 0, v7
	v_max_f32_e32 v7, v34, v34
	v_pk_fma_f32 v[10:11], v[36:37], v[12:13], v[10:11] op_sel:[1,0,0]
	v_max_f32_e32 v12, 0, v7
	v_max_f32_e32 v7, v18, v18
	v_max_f32_e32 v13, 0, v7
	v_max_f32_e32 v7, v35, v35
	v_pk_fma_f32 v[10:11], v[38:39], v[12:13], v[10:11] op_sel_hi:[0,1,1]
	v_max_f32_e32 v12, 0, v7
	v_max_f32_e32 v7, v19, v19
	v_max_f32_e32 v13, 0, v7
	v_mov_b32_e32 v14, v39
	v_pk_fma_f32 v[10:11], v[14:15], v[12:13], v[10:11] op_sel_hi:[0,1,1]
	v_mov_b32_e32 v9, v11
	s_nop 1
	v_permlane32_swap_b32_e32 v10, v9
	v_permlane32_swap_b32_e32 v6, v8
	v_mov_b32_e32 v7, v10
	v_pk_add_f32 v[6:7], v[6:7], v[8:9]
	v_pk_add_f32 v[4:5], v[4:5], 0 op_sel_hi:[1,0]
	v_pk_add_f32 v[6:7], v[6:7], 0 op_sel_hi:[1,0]
	v_cmp_gt_i32_e64 s[4:5], 0, v4
	v_cmp_gt_i32_e64 s[8:9], 0, v5
	v_cmp_gt_i32_e64 s[12:13], 0, v6
	v_cmp_gt_i32_e64 s[16:17], 0, v7
	s_and_saveexec_b64 s[20:21], s[0:1]
	s_cbranch_execz .LBB0_713
	v_mad_u32_u24 v8, v209, s57, v2
	s_waitcnt vmcnt(0)
	ds_write_b128 v8, v[68:71] offset:16384
	ds_write_b128 v8, v[72:75] offset:17536
	ds_write_b128 v8, v[76:79] offset:18688
	ds_write_b128 v8, v[80:83] offset:19840
	ds_write_b128 v8, v[84:87] offset:20992
	ds_write_b128 v8, v[88:91] offset:22144
	ds_write_b128 v8, v[92:95] offset:23296
	ds_write_b128 v8, v[96:99] offset:24448

; #define MFMA32(a, b, c) __builtin_amdgcn_mfma_f32_32x32x16_bf16((a), (b), (c), 0, 0, 0)
; DI void topk_job(const Params& p, int b, int t0, char* lds) {
;     ...
; #pragma unroll
;     for (int i = 0; i < 17; ++i) {
;       const int c = 1 + w + 8 * i;
;       if (c <= cmax) {
;         const bool more = c + 8 <= cmax;
;         if (more) {
;           const u16* kp = ikb + (size_t)(c + 8) * 64 * 64;
; #pragma unroll
;           for (int j = 0; j < 8; ++j) st[j] = *(const u32x4*)(kp + (size_t)j * 8 * 64);
;         }
;         bf16x8 b0[4], b1[4];
; #pragma unroll
;         for (int ks = 0; ks < 4; ++ks) {
;           b0[ks] = *(const bf16x8*)(wb + r * 144 + ks * 32 + h * 16);
;           b1[ks] = *(const bf16x8*)(wb + (32 + r) * 144 + ks * 32 + h * 16);
;         }
;         __builtin_amdgcn_sched_barrier(0);
;         f32x16 a0, a1;
; #pragma unroll
;         for (int e = 0; e < 16; ++e) { a0[e] = 0.f; a1[e] = 0.f; }
; #pragma unroll
;         for (int ks = 0; ks < 4; ++ks) { a0 = MFMA32(af[ks], b0[ks], a0); a1 = MFMA32(af[ks], b1[ks], a1); }
;         const int key = c * 64 + lane;
; #pragma unroll
;         for (int qi = 0; qi < 4; ++qi) {
;           f32x2 pp2 = {0.f, 0.f};
; #pragma unroll
;           for (int e = 0; e < 4; ++e) {
;             const f32x2 rl = {fmaxf(a0[4 * qi + e], 0.f), fmaxf(a1[4 * qi + e], 0.f)};
;             const f32x2 wv = {iw[qi][e], iw[qi][e]};
;             pp2 += rl * wv;
;           }
;           const float p0 = pp2[0], p1 = pp2[1];
;           const u32x2 sw = __builtin_amdgcn_permlane32_swap(__float_as_uint(p0), __float_as_uint(p1), false, false);
;           float mine = __uint_as_float(sw[0]) + __uint_as_float(sw[1]);
;           mine += 0.0f;
;           unsigned u = __float_as_uint(mine);
;           u = (u & 0x80000000u) ? ~u : (u | 0x80000000u);
;           if (key > t0 + qi || key < LEAD) u = 0u;
;           sc[i][qi] = u;
;         }
;         if (more) {
; #pragma unroll
;           for (int j = 0; j < 8; ++j) *(u32x4*)(wb + (lrow + 8 * j) * 144 + lpc * 16) = st[j];
;         }
.LBB0_717:
	s_or_b64 exec, exec, s[2:3]
	ds_read_b128 v[4:7], v210 offset:16384
	ds_read_b128 v[102:105], v210 offset:16416
	s_waitcnt vmcnt(8)
	ds_read_b128 v[8:11], v210 offset:20992
	ds_read_b128 v[106:109], v210 offset:21024
	ds_read_b128 v[176:179], v210 offset:16448
	ds_read_b128 v[212:215], v210 offset:16480
	ds_read_b128 v[216:219], v210 offset:21056
	ds_read_b128 v[220:223], v210 offset:21088
	s_waitcnt lgkmcnt(7)
	v_mfma_f32_32x32x16_bf16 v[20:35], v[64:67], v[4:7], 0
	s_sub_i32 s2, 0x209d, s23
	s_sub_i32 s10, 0x209e, s23
	s_waitcnt lgkmcnt(5)
	v_mfma_f32_32x32x16_bf16 v[4:19], v[64:67], v[8:11], 0
	v_mfma_f32_32x32x16_bf16 v[20:35], v[60:63], v[102:105], v[20:35]
	v_lshl_or_b32 v104, v112, 6, v101
	v_cmp_gt_i32_e32 vcc, s25, v104
	v_cmp_lt_i32_e64 s[6:7], s24, v104
	v_cmp_lt_i32_e64 s[2:3], s2, v104
	v_cmp_lt_i32_e64 s[14:15], s10, v104
	v_cmp_lt_i32_e64 s[10:11], s22, v104
	s_waitcnt lgkmcnt(4)
	v_mfma_f32_32x32x16_bf16 v[4:19], v[60:63], v[106:109], v[4:19]
	s_waitcnt lgkmcnt(3)
	v_mfma_f32_32x32x16_bf16 v[20:35], v[56:59], v[176:179], v[20:35]
	s_waitcnt lgkmcnt(1)
	v_mfma_f32_32x32x16_bf16 v[4:19], v[56:59], v[216:219], v[4:19]
	v_mfma_f32_32x32x16_bf16 v[20:35], v[52:55], v[212:215], v[20:35]
	s_waitcnt lgkmcnt(0)
	v_mfma_f32_32x32x16_bf16 v[4:19], v[52:55], v[220:223], v[4:19]
	s_nop 9
	v_max_f32_e32 v20, v20, v20
	v_max_f32_e32 v102, 0, v20
	v_max_f32_e32 v20, v22, v22
	v_max_f32_e32 v20, 0, v20
	v_max_f32_e32 v4, v4, v4
	v_max_f32_e32 v103, 0, v4
	v_max_f32_e32 v4, v21, v21
	v_max_f32_e32 v5, v5, v5
	v_pk_fma_f32 v[102:103], v[48:49], v[102:103], 0 op_sel_hi:[0,1,0]
	v_max_f32_e32 v4, 0, v4
	v_max_f32_e32 v5, 0, v5
	v_max_f32_e32 v6, v6, v6
	v_pk_fma_f32 v[4:5], v[48:49], v[4:5], v[102:103] op_sel:[1,0,0]
	v_max_f32_e32 v21, 0, v6
	v_max_f32_e32 v6, v23, v23
	v_max_f32_e32 v7, v7, v7
	v_pk_fma_f32 v[4:5], v[50:51], v[20:21], v[4:5] op_sel_hi:[0,1,1]
	v_max_f32_e32 v6, 0, v6
	v_max_f32_e32 v7, 0, v7
	v_mov_b32_e32 v20, v51
	v_pk_fma_f32 v[4:5], v[20:21], v[6:7], v[4:5] op_sel_hi:[0,1,1]
	v_mov_b32_e32 v6, v5
	v_max_f32_e32 v5, v24, v24
	v_max_f32_e32 v20, 0, v5
	v_max_f32_e32 v5, v8, v8
	v_max_f32_e32 v21, 0, v5
	v_max_f32_e32 v5, v25, v25
	v_max_f32_e32 v8, 0, v5
	v_max_f32_e32 v5, v9, v9
	v_pk_fma_f32 v[20:21], v[44:45], v[20:21], 0 op_sel_hi:[0,1,0]
	v_max_f32_e32 v9, 0, v5
	v_max_f32_e32 v5, v26, v26
	v_pk_fma_f32 v[8:9], v[44:45], v[8:9], v[20:21] op_sel:[1,0,0]
	v_max_f32_e32 v20, 0, v5
	v_max_f32_e32 v5, v10, v10
	v_max_f32_e32 v21, 0, v5
	v_max_f32_e32 v5, v27, v27
	v_max_f32_e32 v10, 0, v5
	v_max_f32_e32 v5, v11, v11
	v_pk_fma_f32 v[8:9], v[46:47], v[20:21], v[8:9] op_sel_hi:[0,1,1]
	v_max_f32_e32 v11, 0, v5
	v_mov_b32_e32 v20, v47
	v_pk_fma_f32 v[8:9], v[20:21], v[10:11], v[8:9] op_sel_hi:[0,1,1]
	v_mov_b32_e32 v7, v9
	s_nop 1
	v_permlane32_swap_b32_e32 v8, v7
	v_permlane32_swap_b32_e32 v4, v6
	v_mov_b32_e32 v5, v8
	v_pk_add_f32 v[4:5], v[4:5], v[6:7]
	v_max_f32_e32 v6, v28, v28
	v_max_f32_e32 v7, v12, v12
	v_max_f32_e32 v6, 0, v6
	v_max_f32_e32 v7, 0, v7
	v_max_f32_e32 v8, v29, v29
	v_max_f32_e32 v9, v13, v13
	v_pk_fma_f32 v[6:7], v[40:41], v[6:7], 0 op_sel_hi:[0,1,0]
	v_max_f32_e32 v8, 0, v8
	v_max_f32_e32 v9, 0, v9
	v_pk_fma_f32 v[6:7], v[40:41], v[8:9], v[6:7] op_sel:[1,0,0]
	v_max_f32_e32 v8, v30, v30
	v_max_f32_e32 v9, v14, v14
	v_max_f32_e32 v8, 0, v8
	v_max_f32_e32 v9, 0, v9
	v_pk_fma_f32 v[6:7], v[42:43], v[8:9], v[6:7] op_sel_hi:[0,1,1]
	v_max_f32_e32 v8, v31, v31
	v_max_f32_e32 v9, v15, v15
	v_max_f32_e32 v8, 0, v8
	v_max_f32_e32 v9, 0, v9
	v_mov_b32_e32 v10, v43
	v_pk_fma_f32 v[6:7], v[10:11], v[8:9], v[6:7] op_sel_hi:[0,1,1]
	v_mov_b32_e32 v8, v7
	v_max_f32_e32 v7, v32, v32
	v_max_f32_e32 v10, 0, v7
	v_max_f32_e32 v7, v16, v16
	v_max_f32_e32 v11, 0, v7
	v_max_f32_e32 v7, v33, v33
	v_max_f32_e32 v12, 0, v7
	v_max_f32_e32 v7, v17, v17
	v_pk_fma_f32 v[10:11], v[36:37], v[10:11], 0 op_sel_hi:[0,1,0]
	v_max_f32_e32 v13, 0, v7
	v_max_f32_e32 v7, v34, v34
	v_pk_fma_f32 v[10:11], v[36:37], v[12:13], v[10:11] op_sel:[1,0,0]
	v_max_f32_e32 v12, 0, v7
	v_max_f32_e32 v7, v18, v18
	v_max_f32_e32 v13, 0, v7
	v_max_f32_e32 v7, v35, v35
	v_pk_fma_f32 v[10:11], v[38:39], v[12:13], v[10:11] op_sel_hi:[0,1,1]
	v_max_f32_e32 v12, 0, v7
	v_max_f32_e32 v7, v19, v19
	v_max_f32_e32 v13, 0, v7
	v_mov_b32_e32 v14, v39
	v_pk_fma_f32 v[10:11], v[14:15], v[12:13], v[10:11] op_sel_hi:[0,1,1]
	v_mov_b32_e32 v9, v11
	s_nop 1
	v_permlane32_swap_b32_e32 v10, v9
	v_permlane32_swap_b32_e32 v6, v8
	v_mov_b32_e32 v7, v10
	v_pk_add_f32 v[6:7], v[6:7], v[8:9]
	v_pk_add_f32 v[4:5], v[4:5], 0 op_sel_hi:[1,0]
	v_pk_add_f32 v[6:7], v[6:7], 0 op_sel_hi:[1,0]
	v_cmp_gt_i32_e64 s[4:5], 0, v4
	v_cmp_gt_i32_e64 s[8:9], 0, v5
	v_cmp_gt_i32_e64 s[12:13], 0, v6
	v_cmp_gt_i32_e64 s[16:17], 0, v7
	s_and_saveexec_b64 s[20:21], s[0:1]
	s_cbranch_execz .LBB0_719
	v_mad_u32_u24 v8, v209, s57, v2
	s_waitcnt vmcnt(0)
	ds_write_b128 v8, v[68:71] offset:16384
	ds_write_b128 v8, v[72:75] offset:17536
	ds_write_b128 v8, v[76:79] offset:18688
	ds_write_b128 v8, v[80:83] offset:19840
	ds_write_b128 v8, v[84:87] offset:20992
	ds_write_b128 v8, v[88:91] offset:22144
	ds_write_b128 v8, v[92:95] offset:23296
	ds_write_b128 v8, v[96:99] offset:24448

; #define MFMA32(a, b, c) __builtin_amdgcn_mfma_f32_32x32x16_bf16((a), (b), (c), 0, 0, 0)
; DI void topk_job(const Params& p, int b, int t0, char* lds) {
;     ...
; #pragma unroll
;     for (int i = 0; i < 17; ++i) {
;       const int c = 1 + w + 8 * i;
;       if (c <= cmax) {
;         const bool more = c + 8 <= cmax;
;         if (more) {
;           const u16* kp = ikb + (size_t)(c + 8) * 64 * 64;
; #pragma unroll
;           for (int j = 0; j < 8; ++j) st[j] = *(const u32x4*)(kp + (size_t)j * 8 * 64);
;         }
;         bf16x8 b0[4], b1[4];
; #pragma unroll
;         for (int ks = 0; ks < 4; ++ks) {
;           b0[ks] = *(const bf16x8*)(wb + r * 144 + ks * 32 + h * 16);
;           b1[ks] = *(const bf16x8*)(wb + (32 + r) * 144 + ks * 32 + h * 16);
;         }
;         __builtin_amdgcn_sched_barrier(0);
;         f32x16 a0, a1;
; #pragma unroll
;         for (int e = 0; e < 16; ++e) { a0[e] = 0.f; a1[e] = 0.f; }
; #pragma unroll
;         for (int ks = 0; ks < 4; ++ks) { a0 = MFMA32(af[ks], b0[ks], a0); a1 = MFMA32(af[ks], b1[ks], a1); }
;         const int key = c * 64 + lane;
; #pragma unroll
;         for (int qi = 0; qi < 4; ++qi) {
;           f32x2 pp2 = {0.f, 0.f};
; #pragma unroll
;           for (int e = 0; e < 4; ++e) {
;             const f32x2 rl = {fmaxf(a0[4 * qi + e], 0.f), fmaxf(a1[4 * qi + e], 0.f)};
;             const f32x2 wv = {iw[qi][e], iw[qi][e]};
;             pp2 += rl * wv;
;           }
;           const float p0 = pp2[0], p1 = pp2[1];
;           const u32x2 sw = __builtin_amdgcn_permlane32_swap(__float_as_uint(p0), __float_as_uint(p1), false, false);
;           float mine = __uint_as_float(sw[0]) + __uint_as_float(sw[1]);
;           mine += 0.0f;
;           unsigned u = __float_as_uint(mine);
;           u = (u & 0x80000000u) ? ~u : (u | 0x80000000u);
;           if (key > t0 + qi || key < LEAD) u = 0u;
;           sc[i][qi] = u;
;         }
;         if (more) {
; #pragma unroll
;           for (int j = 0; j < 8; ++j) *(u32x4*)(wb + (lrow + 8 * j) * 144 + lpc * 16) = st[j];
;         }
.LBB0_723:
	s_or_b64 exec, exec, s[2:3]
	ds_read_b128 v[4:7], v210 offset:16384
	ds_read_b128 v[102:105], v210 offset:16416
	s_waitcnt vmcnt(8)
	ds_read_b128 v[8:11], v210 offset:20992
	ds_read_b128 v[106:109], v210 offset:21024
	ds_read_b128 v[212:215], v210 offset:16448
	ds_read_b128 v[216:219], v210 offset:16480
	ds_read_b128 v[220:223], v210 offset:21056
	ds_read_b128 v[224:227], v210 offset:21088
	s_waitcnt lgkmcnt(7)
	v_mfma_f32_32x32x16_bf16 v[20:35], v[64:67], v[4:7], 0
	s_sub_i32 s2, 0x209d, s23
	s_sub_i32 s10, 0x209e, s23
	s_waitcnt lgkmcnt(5)
	v_mfma_f32_32x32x16_bf16 v[4:19], v[64:67], v[8:11], 0
	v_mfma_f32_32x32x16_bf16 v[20:35], v[60:63], v[102:105], v[20:35]
	v_lshl_or_b32 v104, v116, 6, v101
	v_cmp_gt_i32_e32 vcc, s25, v104
	v_cmp_lt_i32_e64 s[6:7], s24, v104
	v_cmp_lt_i32_e64 s[2:3], s2, v104
	v_cmp_lt_i32_e64 s[14:15], s10, v104
	v_cmp_lt_i32_e64 s[10:11], s22, v104
	s_waitcnt lgkmcnt(4)
	v_mfma_f32_32x32x16_bf16 v[4:19], v[60:63], v[106:109], v[4:19]
	s_waitcnt lgkmcnt(3)
	v_mfma_f32_32x32x16_bf16 v[20:35], v[56:59], v[212:215], v[20:35]
	s_waitcnt lgkmcnt(1)
	v_mfma_f32_32x32x16_bf16 v[4:19], v[56:59], v[220:223], v[4:19]
	v_mfma_f32_32x32x16_bf16 v[20:35], v[52:55], v[216:219], v[20:35]
	s_waitcnt lgkmcnt(0)
	v_mfma_f32_32x32x16_bf16 v[4:19], v[52:55], v[224:227], v[4:19]
	s_nop 9
	v_max_f32_e32 v20, v20, v20
	v_max_f32_e32 v102, 0, v20
	v_max_f32_e32 v20, v22, v22
	v_max_f32_e32 v20, 0, v20
	v_max_f32_e32 v4, v4, v4
	v_max_f32_e32 v103, 0, v4
	v_max_f32_e32 v4, v21, v21
	v_max_f32_e32 v5, v5, v5
	v_pk_fma_f32 v[102:103], v[48:49], v[102:103], 0 op_sel_hi:[0,1,0]
	v_max_f32_e32 v4, 0, v4
	v_max_f32_e32 v5, 0, v5
	v_max_f32_e32 v6, v6, v6
	v_pk_fma_f32 v[4:5], v[48:49], v[4:5], v[102:103] op_sel:[1,0,0]
	v_max_f32_e32 v21, 0, v6
	v_max_f32_e32 v6, v23, v23
	v_max_f32_e32 v7, v7, v7
	v_pk_fma_f32 v[4:5], v[50:51], v[20:21], v[4:5] op_sel_hi:[0,1,1]
	v_max_f32_e32 v6, 0, v6
	v_max_f32_e32 v7, 0, v7
	v_mov_b32_e32 v20, v51
	v_pk_fma_f32 v[4:5], v[20:21], v[6:7], v[4:5] op_sel_hi:[0,1,1]
	v_mov_b32_e32 v6, v5
	v_max_f32_e32 v5, v24, v24
	v_max_f32_e32 v20, 0, v5
	v_max_f32_e32 v5, v8, v8
	v_max_f32_e32 v21, 0, v5
	v_max_f32_e32 v5, v25, v25
	v_max_f32_e32 v8, 0, v5
	v_max_f32_e32 v5, v9, v9
	v_pk_fma_f32 v[20:21], v[44:45], v[20:21], 0 op_sel_hi:[0,1,0]
	v_max_f32_e32 v9, 0, v5
	v_max_f32_e32 v5, v26, v26
	v_pk_fma_f32 v[8:9], v[44:45], v[8:9], v[20:21] op_sel:[1,0,0]
	v_max_f32_e32 v20, 0, v5
	v_max_f32_e32 v5, v10, v10
	v_max_f32_e32 v21, 0, v5
	v_max_f32_e32 v5, v27, v27
	v_max_f32_e32 v10, 0, v5
	v_max_f32_e32 v5, v11, v11
	v_pk_fma_f32 v[8:9], v[46:47], v[20:21], v[8:9] op_sel_hi:[0,1,1]
	v_max_f32_e32 v11, 0, v5
	v_mov_b32_e32 v20, v47
	v_pk_fma_f32 v[8:9], v[20:21], v[10:11], v[8:9] op_sel_hi:[0,1,1]
	v_mov_b32_e32 v7, v9
	s_nop 1
	v_permlane32_swap_b32_e32 v8, v7
	v_permlane32_swap_b32_e32 v4, v6
	v_mov_b32_e32 v5, v8
	v_pk_add_f32 v[4:5], v[4:5], v[6:7]
	v_max_f32_e32 v6, v28, v28
	v_max_f32_e32 v7, v12, v12
	v_max_f32_e32 v6, 0, v6
	v_max_f32_e32 v7, 0, v7
	v_max_f32_e32 v8, v29, v29
	v_max_f32_e32 v9, v13, v13
	v_pk_fma_f32 v[6:7], v[40:41], v[6:7], 0 op_sel_hi:[0,1,0]
	v_max_f32_e32 v8, 0, v8
	v_max_f32_e32 v9, 0, v9
	v_pk_fma_f32 v[6:7], v[40:41], v[8:9], v[6:7] op_sel:[1,0,0]
	v_max_f32_e32 v8, v30, v30
	v_max_f32_e32 v9, v14, v14
	v_max_f32_e32 v8, 0, v8
	v_max_f32_e32 v9, 0, v9
	v_pk_fma_f32 v[6:7], v[42:43], v[8:9], v[6:7] op_sel_hi:[0,1,1]
	v_max_f32_e32 v8, v31, v31
	v_max_f32_e32 v9, v15, v15
	v_max_f32_e32 v8, 0, v8
	v_max_f32_e32 v9, 0, v9
	v_mov_b32_e32 v10, v43
	v_pk_fma_f32 v[6:7], v[10:11], v[8:9], v[6:7] op_sel_hi:[0,1,1]
	v_mov_b32_e32 v8, v7
	v_max_f32_e32 v7, v32, v32
	v_max_f32_e32 v10, 0, v7
	v_max_f32_e32 v7, v16, v16
	v_max_f32_e32 v11, 0, v7
	v_max_f32_e32 v7, v33, v33
	v_max_f32_e32 v12, 0, v7
	v_max_f32_e32 v7, v17, v17
	v_pk_fma_f32 v[10:11], v[36:37], v[10:11], 0 op_sel_hi:[0,1,0]
	v_max_f32_e32 v13, 0, v7
	v_max_f32_e32 v7, v34, v34
	v_pk_fma_f32 v[10:11], v[36:37], v[12:13], v[10:11] op_sel:[1,0,0]
	v_max_f32_e32 v12, 0, v7
	v_max_f32_e32 v7, v18, v18
	v_max_f32_e32 v13, 0, v7
	v_max_f32_e32 v7, v35, v35
	v_pk_fma_f32 v[10:11], v[38:39], v[12:13], v[10:11] op_sel_hi:[0,1,1]
	v_max_f32_e32 v12, 0, v7
	v_max_f32_e32 v7, v19, v19
	v_max_f32_e32 v13, 0, v7
	v_mov_b32_e32 v14, v39
	v_pk_fma_f32 v[10:11], v[14:15], v[12:13], v[10:11] op_sel_hi:[0,1,1]
	v_mov_b32_e32 v9, v11
	s_nop 1
	v_permlane32_swap_b32_e32 v10, v9
	v_permlane32_swap_b32_e32 v6, v8
	v_mov_b32_e32 v7, v10
	v_pk_add_f32 v[6:7], v[6:7], v[8:9]
	v_pk_add_f32 v[4:5], v[4:5], 0 op_sel_hi:[1,0]
	v_pk_add_f32 v[6:7], v[6:7], 0 op_sel_hi:[1,0]
	v_cmp_gt_i32_e64 s[4:5], 0, v4
	v_cmp_gt_i32_e64 s[8:9], 0, v5
	v_cmp_gt_i32_e64 s[12:13], 0, v6
	v_cmp_gt_i32_e64 s[16:17], 0, v7
	s_and_saveexec_b64 s[20:21], s[0:1]
	s_cbranch_execz .LBB0_725
	v_mad_u32_u24 v8, v209, s57, v2
	s_waitcnt vmcnt(0)
	ds_write_b128 v8, v[68:71] offset:16384
	ds_write_b128 v8, v[72:75] offset:17536
	ds_write_b128 v8, v[76:79] offset:18688
	ds_write_b128 v8, v[80:83] offset:19840
	ds_write_b128 v8, v[84:87] offset:20992
	ds_write_b128 v8, v[88:91] offset:22144
	ds_write_b128 v8, v[92:95] offset:23296
	ds_write_b128 v8, v[96:99] offset:24448

; #define MFMA32(a, b, c) __builtin_amdgcn_mfma_f32_32x32x16_bf16((a), (b), (c), 0, 0, 0)
; DI void topk_job(const Params& p, int b, int t0, char* lds) {
;     ...
; #pragma unroll
;     for (int i = 0; i < 17; ++i) {
;       const int c = 1 + w + 8 * i;
;       if (c <= cmax) {
;         const bool more = c + 8 <= cmax;
;         if (more) {
;           const u16* kp = ikb + (size_t)(c + 8) * 64 * 64;
; #pragma unroll
;           for (int j = 0; j < 8; ++j) st[j] = *(const u32x4*)(kp + (size_t)j * 8 * 64);
;         }
;         bf16x8 b0[4], b1[4];
; #pragma unroll
;         for (int ks = 0; ks < 4; ++ks) {
;           b0[ks] = *(const bf16x8*)(wb + r * 144 + ks * 32 + h * 16);
;           b1[ks] = *(const bf16x8*)(wb + (32 + r) * 144 + ks * 32 + h * 16);
;         }
;         __builtin_amdgcn_sched_barrier(0);
;         f32x16 a0, a1;
; #pragma unroll
;         for (int e = 0; e < 16; ++e) { a0[e] = 0.f; a1[e] = 0.f; }
; #pragma unroll
;         for (int ks = 0; ks < 4; ++ks) { a0 = MFMA32(af[ks], b0[ks], a0); a1 = MFMA32(af[ks], b1[ks], a1); }
;         const int key = c * 64 + lane;
; #pragma unroll
;         for (int qi = 0; qi < 4; ++qi) {
;           f32x2 pp2 = {0.f, 0.f};
; #pragma unroll
;           for (int e = 0; e < 4; ++e) {
;             const f32x2 rl = {fmaxf(a0[4 * qi + e], 0.f), fmaxf(a1[4 * qi + e], 0.f)};
;             const f32x2 wv = {iw[qi][e], iw[qi][e]};
;             pp2 += rl * wv;
;           }
;           const float p0 = pp2[0], p1 = pp2[1];
;           const u32x2 sw = __builtin_amdgcn_permlane32_swap(__float_as_uint(p0), __float_as_uint(p1), false, false);
;           float mine = __uint_as_float(sw[0]) + __uint_as_float(sw[1]);
;           mine += 0.0f;
;           unsigned u = __float_as_uint(mine);
;           u = (u & 0x80000000u) ? ~u : (u | 0x80000000u);
;           if (key > t0 + qi || key < LEAD) u = 0u;
;           sc[i][qi] = u;
;         }
;         if (more) {
; #pragma unroll
;           for (int j = 0; j < 8; ++j) *(u32x4*)(wb + (lrow + 8 * j) * 144 + lpc * 16) = st[j];
;         }
.LBB0_729:
	s_or_b64 exec, exec, s[2:3]
	ds_read_b128 v[4:7], v210 offset:16384
	ds_read_b128 v[102:105], v210 offset:16416
	s_waitcnt vmcnt(8)
	ds_read_b128 v[8:11], v210 offset:20992
	ds_read_b128 v[212:215], v210 offset:21024
	ds_read_b128 v[216:219], v210 offset:16448
	ds_read_b128 v[220:223], v210 offset:16480
	ds_read_b128 v[224:227], v210 offset:21056
	ds_read_b128 v[228:231], v210 offset:21088
	s_waitcnt lgkmcnt(7)
	v_mfma_f32_32x32x16_bf16 v[20:35], v[64:67], v[4:7], 0
	s_sub_i32 s2, 0x209d, s23
	s_sub_i32 s10, 0x209e, s23
	s_waitcnt lgkmcnt(5)
	v_mfma_f32_32x32x16_bf16 v[4:19], v[64:67], v[8:11], 0
	v_mfma_f32_32x32x16_bf16 v[20:35], v[60:63], v[102:105], v[20:35]
	v_lshl_or_b32 v104, v110, 6, v101
	v_cmp_gt_i32_e32 vcc, s25, v104
	v_cmp_lt_i32_e64 s[6:7], s24, v104
	v_cmp_lt_i32_e64 s[2:3], s2, v104
	v_cmp_lt_i32_e64 s[14:15], s10, v104
	v_cmp_lt_i32_e64 s[10:11], s22, v104
	s_waitcnt lgkmcnt(4)
	v_mfma_f32_32x32x16_bf16 v[4:19], v[60:63], v[212:215], v[4:19]
	s_waitcnt lgkmcnt(3)
	v_mfma_f32_32x32x16_bf16 v[20:35], v[56:59], v[216:219], v[20:35]
	s_waitcnt lgkmcnt(1)
	v_mfma_f32_32x32x16_bf16 v[4:19], v[56:59], v[224:227], v[4:19]
	v_mfma_f32_32x32x16_bf16 v[20:35], v[52:55], v[220:223], v[20:35]
	s_waitcnt lgkmcnt(0)
	v_mfma_f32_32x32x16_bf16 v[4:19], v[52:55], v[228:231], v[4:19]
	s_nop 9
	v_max_f32_e32 v20, v20, v20
	v_max_f32_e32 v102, 0, v20
	v_max_f32_e32 v20, v22, v22
	v_max_f32_e32 v20, 0, v20
	v_max_f32_e32 v4, v4, v4
	v_max_f32_e32 v103, 0, v4
	v_max_f32_e32 v4, v21, v21
	v_max_f32_e32 v5, v5, v5
	v_pk_fma_f32 v[102:103], v[48:49], v[102:103], 0 op_sel_hi:[0,1,0]
	v_max_f32_e32 v4, 0, v4
	v_max_f32_e32 v5, 0, v5
	v_max_f32_e32 v6, v6, v6
	v_pk_fma_f32 v[4:5], v[48:49], v[4:5], v[102:103] op_sel:[1,0,0]
	v_max_f32_e32 v21, 0, v6
	v_max_f32_e32 v6, v23, v23
	v_max_f32_e32 v7, v7, v7
	v_pk_fma_f32 v[4:5], v[50:51], v[20:21], v[4:5] op_sel_hi:[0,1,1]
	v_max_f32_e32 v6, 0, v6
	v_max_f32_e32 v7, 0, v7
	v_mov_b32_e32 v20, v51
	v_pk_fma_f32 v[4:5], v[20:21], v[6:7], v[4:5] op_sel_hi:[0,1,1]
	v_mov_b32_e32 v6, v5
	v_max_f32_e32 v5, v24, v24
	v_max_f32_e32 v20, 0, v5
	v_max_f32_e32 v5, v8, v8
	v_max_f32_e32 v21, 0, v5
	v_max_f32_e32 v5, v25, v25
	v_max_f32_e32 v8, 0, v5
	v_max_f32_e32 v5, v9, v9
	v_pk_fma_f32 v[20:21], v[44:45], v[20:21], 0 op_sel_hi:[0,1,0]
	v_max_f32_e32 v9, 0, v5
	v_max_f32_e32 v5, v26, v26
	v_pk_fma_f32 v[8:9], v[44:45], v[8:9], v[20:21] op_sel:[1,0,0]
	v_max_f32_e32 v20, 0, v5
	v_max_f32_e32 v5, v10, v10
	v_max_f32_e32 v21, 0, v5
	v_max_f32_e32 v5, v27, v27
	v_max_f32_e32 v10, 0, v5
	v_max_f32_e32 v5, v11, v11
	v_pk_fma_f32 v[8:9], v[46:47], v[20:21], v[8:9] op_sel_hi:[0,1,1]
	v_max_f32_e32 v11, 0, v5
	v_mov_b32_e32 v20, v47
	v_pk_fma_f32 v[8:9], v[20:21], v[10:11], v[8:9] op_sel_hi:[0,1,1]
	v_mov_b32_e32 v7, v9
	s_nop 1
	v_permlane32_swap_b32_e32 v8, v7
	v_permlane32_swap_b32_e32 v4, v6
	v_mov_b32_e32 v5, v8
	v_pk_add_f32 v[4:5], v[4:5], v[6:7]
	v_max_f32_e32 v6, v28, v28
	v_max_f32_e32 v7, v12, v12
	v_max_f32_e32 v6, 0, v6
	v_max_f32_e32 v7, 0, v7
	v_max_f32_e32 v8, v29, v29
	v_max_f32_e32 v9, v13, v13
	v_pk_fma_f32 v[6:7], v[40:41], v[6:7], 0 op_sel_hi:[0,1,0]
	v_max_f32_e32 v8, 0, v8
	v_max_f32_e32 v9, 0, v9
	v_pk_fma_f32 v[6:7], v[40:41], v[8:9], v[6:7] op_sel:[1,0,0]
	v_max_f32_e32 v8, v30, v30
	v_max_f32_e32 v9, v14, v14
	v_max_f32_e32 v8, 0, v8
	v_max_f32_e32 v9, 0, v9
	v_pk_fma_f32 v[6:7], v[42:43], v[8:9], v[6:7] op_sel_hi:[0,1,1]
	v_max_f32_e32 v8, v31, v31
	v_max_f32_e32 v9, v15, v15
	v_max_f32_e32 v8, 0, v8
	v_max_f32_e32 v9, 0, v9
	v_mov_b32_e32 v10, v43
	v_pk_fma_f32 v[6:7], v[10:11], v[8:9], v[6:7] op_sel_hi:[0,1,1]
	v_mov_b32_e32 v8, v7
	v_max_f32_e32 v7, v32, v32
	v_max_f32_e32 v10, 0, v7
	v_max_f32_e32 v7, v16, v16
	v_max_f32_e32 v11, 0, v7
	v_max_f32_e32 v7, v33, v33
	v_max_f32_e32 v12, 0, v7
	v_max_f32_e32 v7, v17, v17
	v_pk_fma_f32 v[10:11], v[36:37], v[10:11], 0 op_sel_hi:[0,1,0]
	v_max_f32_e32 v13, 0, v7
	v_max_f32_e32 v7, v34, v34
	v_pk_fma_f32 v[10:11], v[36:37], v[12:13], v[10:11] op_sel:[1,0,0]
	v_max_f32_e32 v12, 0, v7
	v_max_f32_e32 v7, v18, v18
	v_max_f32_e32 v13, 0, v7
	v_max_f32_e32 v7, v35, v35
	v_pk_fma_f32 v[10:11], v[38:39], v[12:13], v[10:11] op_sel_hi:[0,1,1]
	v_max_f32_e32 v12, 0, v7
	v_max_f32_e32 v7, v19, v19
	v_max_f32_e32 v13, 0, v7
	v_mov_b32_e32 v14, v39
	v_pk_fma_f32 v[10:11], v[14:15], v[12:13], v[10:11] op_sel_hi:[0,1,1]
	v_mov_b32_e32 v9, v11
	s_nop 1
	v_permlane32_swap_b32_e32 v10, v9
	v_permlane32_swap_b32_e32 v6, v8
	v_mov_b32_e32 v7, v10
	v_pk_add_f32 v[6:7], v[6:7], v[8:9]
	v_pk_add_f32 v[4:5], v[4:5], 0 op_sel_hi:[1,0]
	v_pk_add_f32 v[6:7], v[6:7], 0 op_sel_hi:[1,0]
	v_cmp_gt_i32_e64 s[4:5], 0, v4
	v_cmp_gt_i32_e64 s[8:9], 0, v5
	v_cmp_gt_i32_e64 s[12:13], 0, v6
	v_cmp_gt_i32_e64 s[16:17], 0, v7
	s_and_saveexec_b64 s[20:21], s[0:1]
	s_cbranch_execz .LBB0_731
	v_mad_u32_u24 v8, v209, s57, v2
	s_waitcnt vmcnt(0)
	ds_write_b128 v8, v[68:71] offset:16384
	ds_write_b128 v8, v[72:75] offset:17536
	ds_write_b128 v8, v[76:79] offset:18688
	ds_write_b128 v8, v[80:83] offset:19840
	ds_write_b128 v8, v[84:87] offset:20992
	ds_write_b128 v8, v[88:91] offset:22144
	ds_write_b128 v8, v[92:95] offset:23296
	ds_write_b128 v8, v[96:99] offset:24448

; #define MFMA32(a, b, c) __builtin_amdgcn_mfma_f32_32x32x16_bf16((a), (b), (c), 0, 0, 0)
; DI void topk_job(const Params& p, int b, int t0, char* lds) {
;     ...
; #pragma unroll
;     for (int i = 0; i < 17; ++i) {
;       const int c = 1 + w + 8 * i;
;       if (c <= cmax) {
;         const bool more = c + 8 <= cmax;
;         if (more) {
;           const u16* kp = ikb + (size_t)(c + 8) * 64 * 64;
; #pragma unroll
;           for (int j = 0; j < 8; ++j) st[j] = *(const u32x4*)(kp + (size_t)j * 8 * 64);
;         }
;         bf16x8 b0[4], b1[4];
; #pragma unroll
;         for (int ks = 0; ks < 4; ++ks) {
;           b0[ks] = *(const bf16x8*)(wb + r * 144 + ks * 32 + h * 16);
;           b1[ks] = *(const bf16x8*)(wb + (32 + r) * 144 + ks * 32 + h * 16);
;         }
;         __builtin_amdgcn_sched_barrier(0);
;         f32x16 a0, a1;
; #pragma unroll
;         for (int e = 0; e < 16; ++e) { a0[e] = 0.f; a1[e] = 0.f; }
; #pragma unroll
;         for (int ks = 0; ks < 4; ++ks) { a0 = MFMA32(af[ks], b0[ks], a0); a1 = MFMA32(af[ks], b1[ks], a1); }
;         const int key = c * 64 + lane;
; #pragma unroll
;         for (int qi = 0; qi < 4; ++qi) {
;           f32x2 pp2 = {0.f, 0.f};
; #pragma unroll
;           for (int e = 0; e < 4; ++e) {
;             const f32x2 rl = {fmaxf(a0[4 * qi + e], 0.f), fmaxf(a1[4 * qi + e], 0.f)};
;             const f32x2 wv = {iw[qi][e], iw[qi][e]};
;             pp2 += rl * wv;
;           }
;           const float p0 = pp2[0], p1 = pp2[1];
;           const u32x2 sw = __builtin_amdgcn_permlane32_swap(__float_as_uint(p0), __float_as_uint(p1), false, false);
;           float mine = __uint_as_float(sw[0]) + __uint_as_float(sw[1]);
;           mine += 0.0f;
;           unsigned u = __float_as_uint(mine);
;           u = (u & 0x80000000u) ? ~u : (u | 0x80000000u);
;           if (key > t0 + qi || key < LEAD) u = 0u;
;           sc[i][qi] = u;
;         }
;         if (more) {
; #pragma unroll
;           for (int j = 0; j < 8; ++j) *(u32x4*)(wb + (lrow + 8 * j) * 144 + lpc * 16) = st[j];
;         }
.LBB0_735:
	s_or_b64 exec, exec, s[2:3]
	ds_read_b128 v[4:7], v210 offset:16384
	ds_read_b128 v[102:105], v210 offset:16416
	s_waitcnt vmcnt(8)
	ds_read_b128 v[8:11], v210 offset:20992
	ds_read_b128 v[212:215], v210 offset:21024
	ds_read_b128 v[216:219], v210 offset:16448
	ds_read_b128 v[220:223], v210 offset:16480
	ds_read_b128 v[224:227], v210 offset:21056
	ds_read_b128 v[228:231], v210 offset:21088
	s_waitcnt lgkmcnt(7)
	v_mfma_f32_32x32x16_bf16 v[20:35], v[64:67], v[4:7], 0
	s_sub_i32 s2, 0x209d, s23
	s_sub_i32 s10, 0x209e, s23
	s_waitcnt lgkmcnt(5)
	v_mfma_f32_32x32x16_bf16 v[4:19], v[64:67], v[8:11], 0
	v_mfma_f32_32x32x16_bf16 v[20:35], v[60:63], v[102:105], v[20:35]
	v_lshl_or_b32 v104, v108, 6, v101
	v_cmp_gt_i32_e32 vcc, s25, v104
	v_cmp_lt_i32_e64 s[6:7], s24, v104
	v_cmp_lt_i32_e64 s[2:3], s2, v104
	v_cmp_lt_i32_e64 s[14:15], s10, v104
	v_cmp_lt_i32_e64 s[10:11], s22, v104
	s_waitcnt lgkmcnt(4)
	v_mfma_f32_32x32x16_bf16 v[4:19], v[60:63], v[212:215], v[4:19]
	s_waitcnt lgkmcnt(3)
	v_mfma_f32_32x32x16_bf16 v[20:35], v[56:59], v[216:219], v[20:35]
	s_waitcnt lgkmcnt(1)
	v_mfma_f32_32x32x16_bf16 v[4:19], v[56:59], v[224:227], v[4:19]
	v_mfma_f32_32x32x16_bf16 v[20:35], v[52:55], v[220:223], v[20:35]
	s_waitcnt lgkmcnt(0)
	v_mfma_f32_32x32x16_bf16 v[4:19], v[52:55], v[228:231], v[4:19]
	s_nop 9
	v_max_f32_e32 v20, v20, v20
	v_max_f32_e32 v102, 0, v20
	v_max_f32_e32 v20, v22, v22
	v_max_f32_e32 v20, 0, v20
	v_max_f32_e32 v4, v4, v4
	v_max_f32_e32 v103, 0, v4
	v_max_f32_e32 v4, v21, v21
	v_max_f32_e32 v5, v5, v5
	v_pk_fma_f32 v[102:103], v[48:49], v[102:103], 0 op_sel_hi:[0,1,0]
	v_max_f32_e32 v4, 0, v4
	v_max_f32_e32 v5, 0, v5
	v_max_f32_e32 v6, v6, v6
	v_pk_fma_f32 v[4:5], v[48:49], v[4:5], v[102:103] op_sel:[1,0,0]
	v_max_f32_e32 v21, 0, v6
	v_max_f32_e32 v6, v23, v23
	v_max_f32_e32 v7, v7, v7
	v_pk_fma_f32 v[4:5], v[50:51], v[20:21], v[4:5] op_sel_hi:[0,1,1]
	v_max_f32_e32 v6, 0, v6
	v_max_f32_e32 v7, 0, v7
	v_mov_b32_e32 v20, v51
	v_pk_fma_f32 v[4:5], v[20:21], v[6:7], v[4:5] op_sel_hi:[0,1,1]
	v_mov_b32_e32 v6, v5
	v_max_f32_e32 v5, v24, v24
	v_max_f32_e32 v20, 0, v5
	v_max_f32_e32 v5, v8, v8
	v_max_f32_e32 v21, 0, v5
	v_max_f32_e32 v5, v25, v25
	v_max_f32_e32 v8, 0, v5
	v_max_f32_e32 v5, v9, v9
	v_pk_fma_f32 v[20:21], v[44:45], v[20:21], 0 op_sel_hi:[0,1,0]
	v_max_f32_e32 v9, 0, v5
	v_max_f32_e32 v5, v26, v26
	v_pk_fma_f32 v[8:9], v[44:45], v[8:9], v[20:21] op_sel:[1,0,0]
	v_max_f32_e32 v20, 0, v5
	v_max_f32_e32 v5, v10, v10
	v_max_f32_e32 v21, 0, v5
	v_max_f32_e32 v5, v27, v27
	v_max_f32_e32 v10, 0, v5
	v_max_f32_e32 v5, v11, v11
	v_pk_fma_f32 v[8:9], v[46:47], v[20:21], v[8:9] op_sel_hi:[0,1,1]
	v_max_f32_e32 v11, 0, v5
	v_mov_b32_e32 v20, v47
	v_pk_fma_f32 v[8:9], v[20:21], v[10:11], v[8:9] op_sel_hi:[0,1,1]
	v_mov_b32_e32 v7, v9
	s_nop 1
	v_permlane32_swap_b32_e32 v8, v7
	v_permlane32_swap_b32_e32 v4, v6
	v_mov_b32_e32 v5, v8
	v_pk_add_f32 v[4:5], v[4:5], v[6:7]
	v_max_f32_e32 v6, v28, v28
	v_max_f32_e32 v7, v12, v12
	v_max_f32_e32 v6, 0, v6
	v_max_f32_e32 v7, 0, v7
	v_max_f32_e32 v8, v29, v29
	v_max_f32_e32 v9, v13, v13
	v_pk_fma_f32 v[6:7], v[40:41], v[6:7], 0 op_sel_hi:[0,1,0]
	v_max_f32_e32 v8, 0, v8
	v_max_f32_e32 v9, 0, v9
	v_pk_fma_f32 v[6:7], v[40:41], v[8:9], v[6:7] op_sel:[1,0,0]
	v_max_f32_e32 v8, v30, v30
	v_max_f32_e32 v9, v14, v14
	v_max_f32_e32 v8, 0, v8
	v_max_f32_e32 v9, 0, v9
	v_pk_fma_f32 v[6:7], v[42:43], v[8:9], v[6:7] op_sel_hi:[0,1,1]
	v_max_f32_e32 v8, v31, v31
	v_max_f32_e32 v9, v15, v15
	v_max_f32_e32 v8, 0, v8
	v_max_f32_e32 v9, 0, v9
	v_mov_b32_e32 v10, v43
	v_pk_fma_f32 v[6:7], v[10:11], v[8:9], v[6:7] op_sel_hi:[0,1,1]
	v_mov_b32_e32 v8, v7
	v_max_f32_e32 v7, v32, v32
	v_max_f32_e32 v10, 0, v7
	v_max_f32_e32 v7, v16, v16
	v_max_f32_e32 v11, 0, v7
	v_max_f32_e32 v7, v33, v33
	v_max_f32_e32 v12, 0, v7
	v_max_f32_e32 v7, v17, v17
	v_pk_fma_f32 v[10:11], v[36:37], v[10:11], 0 op_sel_hi:[0,1,0]
	v_max_f32_e32 v13, 0, v7
	v_max_f32_e32 v7, v34, v34
	v_pk_fma_f32 v[10:11], v[36:37], v[12:13], v[10:11] op_sel:[1,0,0]
	v_max_f32_e32 v12, 0, v7
	v_max_f32_e32 v7, v18, v18
	v_max_f32_e32 v13, 0, v7
	v_max_f32_e32 v7, v35, v35
	v_pk_fma_f32 v[10:11], v[38:39], v[12:13], v[10:11] op_sel_hi:[0,1,1]
	v_max_f32_e32 v12, 0, v7
	v_max_f32_e32 v7, v19, v19
	v_max_f32_e32 v13, 0, v7
	v_mov_b32_e32 v14, v39
	v_pk_fma_f32 v[10:11], v[14:15], v[12:13], v[10:11] op_sel_hi:[0,1,1]
	v_mov_b32_e32 v9, v11
	s_nop 1
	v_permlane32_swap_b32_e32 v10, v9
	v_permlane32_swap_b32_e32 v6, v8
	v_mov_b32_e32 v7, v10
	v_pk_add_f32 v[6:7], v[6:7], v[8:9]
	v_pk_add_f32 v[4:5], v[4:5], 0 op_sel_hi:[1,0]
	v_pk_add_f32 v[6:7], v[6:7], 0 op_sel_hi:[1,0]
	v_cmp_gt_i32_e64 s[4:5], 0, v4
	v_cmp_gt_i32_e64 s[8:9], 0, v5
	v_cmp_gt_i32_e64 s[12:13], 0, v6
	v_cmp_gt_i32_e64 s[16:17], 0, v7
	s_and_saveexec_b64 s[20:21], s[0:1]
	s_cbranch_execz .LBB0_737
	v_mad_u32_u24 v8, v209, s57, v2
	s_waitcnt vmcnt(0)
	ds_write_b128 v8, v[68:71] offset:16384
	ds_write_b128 v8, v[72:75] offset:17536
	ds_write_b128 v8, v[76:79] offset:18688
	ds_write_b128 v8, v[80:83] offset:19840
	ds_write_b128 v8, v[84:87] offset:20992
	ds_write_b128 v8, v[88:91] offset:22144
	ds_write_b128 v8, v[92:95] offset:23296
	ds_write_b128 v8, v[96:99] offset:24448

; #define MFMA32(a, b, c) __builtin_amdgcn_mfma_f32_32x32x16_bf16((a), (b), (c), 0, 0, 0)
; DI void topk_job(const Params& p, int b, int t0, char* lds) {
;     ...
; #pragma unroll
;     for (int i = 0; i < 17; ++i) {
;       const int c = 1 + w + 8 * i;
;       if (c <= cmax) {
;         const bool more = c + 8 <= cmax;
;         if (more) {
;           const u16* kp = ikb + (size_t)(c + 8) * 64 * 64;
; #pragma unroll
;           for (int j = 0; j < 8; ++j) st[j] = *(const u32x4*)(kp + (size_t)j * 8 * 64);
;         }
;         bf16x8 b0[4], b1[4];
; #pragma unroll
;         for (int ks = 0; ks < 4; ++ks) {
;           b0[ks] = *(const bf16x8*)(wb + r * 144 + ks * 32 + h * 16);
;           b1[ks] = *(const bf16x8*)(wb + (32 + r) * 144 + ks * 32 + h * 16);
;         }
;         __builtin_amdgcn_sched_barrier(0);
;         f32x16 a0, a1;
; #pragma unroll
;         for (int e = 0; e < 16; ++e) { a0[e] = 0.f; a1[e] = 0.f; }
; #pragma unroll
;         for (int ks = 0; ks < 4; ++ks) { a0 = MFMA32(af[ks], b0[ks], a0); a1 = MFMA32(af[ks], b1[ks], a1); }
;         const int key = c * 64 + lane;
; #pragma unroll
;         for (int qi = 0; qi < 4; ++qi) {
;           f32x2 pp2 = {0.f, 0.f};
; #pragma unroll
;           for (int e = 0; e < 4; ++e) {
;             const f32x2 rl = {fmaxf(a0[4 * qi + e], 0.f), fmaxf(a1[4 * qi + e], 0.f)};
;             const f32x2 wv = {iw[qi][e], iw[qi][e]};
;             pp2 += rl * wv;
;           }
;           const float p0 = pp2[0], p1 = pp2[1];
;           const u32x2 sw = __builtin_amdgcn_permlane32_swap(__float_as_uint(p0), __float_as_uint(p1), false, false);
;           float mine = __uint_as_float(sw[0]) + __uint_as_float(sw[1]);
;           mine += 0.0f;
;           unsigned u = __float_as_uint(mine);
;           u = (u & 0x80000000u) ? ~u : (u | 0x80000000u);
;           if (key > t0 + qi || key < LEAD) u = 0u;
;           sc[i][qi] = u;
;         }
;         if (more) {
; #pragma unroll
;           for (int j = 0; j < 8; ++j) *(u32x4*)(wb + (lrow + 8 * j) * 144 + lpc * 16) = st[j];
;         }
.LBB0_741:
	s_or_b64 exec, exec, s[2:3]
	ds_read_b128 v[4:7], v210 offset:16384
	ds_read_b128 v[212:215], v210 offset:16416
	s_waitcnt vmcnt(8)
	ds_read_b128 v[8:11], v210 offset:20992
	ds_read_b128 v[216:219], v210 offset:21024
	ds_read_b128 v[220:223], v210 offset:16448
	ds_read_b128 v[224:227], v210 offset:16480
	ds_read_b128 v[228:231], v210 offset:21056
	ds_read_b128 v[232:235], v210 offset:21088
	s_waitcnt lgkmcnt(7)
	v_mfma_f32_32x32x16_bf16 v[20:35], v[64:67], v[4:7], 0
	v_lshl_or_b32 v105, v106, 6, v101
	s_sub_i32 s2, 0x209d, s23
	s_sub_i32 s10, 0x209e, s23
	v_cmp_gt_i32_e32 vcc, s25, v105
	v_cmp_lt_i32_e64 s[6:7], s24, v105
	v_cmp_lt_i32_e64 s[2:3], s2, v105
	v_cmp_lt_i32_e64 s[14:15], s10, v105
	s_waitcnt lgkmcnt(5)
	v_mfma_f32_32x32x16_bf16 v[4:19], v[64:67], v[8:11], 0
	v_cmp_lt_i32_e64 s[10:11], s22, v105
	v_mfma_f32_32x32x16_bf16 v[20:35], v[60:63], v[212:215], v[20:35]
	s_waitcnt lgkmcnt(4)
	v_mfma_f32_32x32x16_bf16 v[4:19], v[60:63], v[216:219], v[4:19]
	s_waitcnt lgkmcnt(3)
	v_mfma_f32_32x32x16_bf16 v[20:35], v[56:59], v[220:223], v[20:35]
	s_waitcnt lgkmcnt(1)
	v_mfma_f32_32x32x16_bf16 v[4:19], v[56:59], v[228:231], v[4:19]
	v_mfma_f32_32x32x16_bf16 v[20:35], v[52:55], v[224:227], v[20:35]
	s_waitcnt lgkmcnt(0)
	v_mfma_f32_32x32x16_bf16 v[4:19], v[52:55], v[232:235], v[4:19]
	s_nop 9
	v_max_f32_e32 v20, v20, v20
	v_max_f32_e32 v102, 0, v20
	v_max_f32_e32 v20, v22, v22
	v_max_f32_e32 v20, 0, v20
	v_max_f32_e32 v4, v4, v4
	v_max_f32_e32 v103, 0, v4
	v_max_f32_e32 v4, v21, v21
	v_max_f32_e32 v5, v5, v5
	v_pk_fma_f32 v[102:103], v[48:49], v[102:103], 0 op_sel_hi:[0,1,0]
	v_max_f32_e32 v4, 0, v4
	v_max_f32_e32 v5, 0, v5
	v_max_f32_e32 v6, v6, v6
	v_pk_fma_f32 v[4:5], v[48:49], v[4:5], v[102:103] op_sel:[1,0,0]
	v_max_f32_e32 v21, 0, v6
	v_max_f32_e32 v6, v23, v23
	v_max_f32_e32 v7, v7, v7
	v_pk_fma_f32 v[4:5], v[50:51], v[20:21], v[4:5] op_sel_hi:[0,1,1]
	v_max_f32_e32 v6, 0, v6
	v_max_f32_e32 v7, 0, v7
	v_mov_b32_e32 v20, v51
	v_pk_fma_f32 v[4:5], v[20:21], v[6:7], v[4:5] op_sel_hi:[0,1,1]
	v_mov_b32_e32 v6, v5
	v_max_f32_e32 v5, v24, v24
	v_max_f32_e32 v20, 0, v5
	v_max_f32_e32 v5, v8, v8
	v_max_f32_e32 v21, 0, v5
	v_max_f32_e32 v5, v25, v25
	v_max_f32_e32 v8, 0, v5
	v_max_f32_e32 v5, v9, v9
	v_pk_fma_f32 v[20:21], v[44:45], v[20:21], 0 op_sel_hi:[0,1,0]
	v_max_f32_e32 v9, 0, v5
	v_max_f32_e32 v5, v26, v26
	v_pk_fma_f32 v[8:9], v[44:45], v[8:9], v[20:21] op_sel:[1,0,0]
	v_max_f32_e32 v20, 0, v5
	v_max_f32_e32 v5, v10, v10
	v_max_f32_e32 v21, 0, v5
	v_max_f32_e32 v5, v27, v27
	v_max_f32_e32 v10, 0, v5
	v_max_f32_e32 v5, v11, v11
	v_pk_fma_f32 v[8:9], v[46:47], v[20:21], v[8:9] op_sel_hi:[0,1,1]
	v_max_f32_e32 v11, 0, v5
	v_mov_b32_e32 v20, v47
	v_pk_fma_f32 v[8:9], v[20:21], v[10:11], v[8:9] op_sel_hi:[0,1,1]
	v_mov_b32_e32 v7, v9
	s_nop 1
	v_permlane32_swap_b32_e32 v8, v7
	v_permlane32_swap_b32_e32 v4, v6
	v_mov_b32_e32 v5, v8
	v_pk_add_f32 v[4:5], v[4:5], v[6:7]
	v_max_f32_e32 v6, v28, v28
	v_max_f32_e32 v7, v12, v12
	v_max_f32_e32 v6, 0, v6
	v_max_f32_e32 v7, 0, v7
	v_max_f32_e32 v8, v29, v29
	v_max_f32_e32 v9, v13, v13
	v_pk_fma_f32 v[6:7], v[40:41], v[6:7], 0 op_sel_hi:[0,1,0]
	v_max_f32_e32 v8, 0, v8
	v_max_f32_e32 v9, 0, v9
	v_pk_fma_f32 v[6:7], v[40:41], v[8:9], v[6:7] op_sel:[1,0,0]
	v_max_f32_e32 v8, v30, v30
	v_max_f32_e32 v9, v14, v14
	v_max_f32_e32 v8, 0, v8
	v_max_f32_e32 v9, 0, v9
	v_pk_fma_f32 v[6:7], v[42:43], v[8:9], v[6:7] op_sel_hi:[0,1,1]
	v_max_f32_e32 v8, v31, v31
	v_max_f32_e32 v9, v15, v15
	v_max_f32_e32 v8, 0, v8
	v_max_f32_e32 v9, 0, v9
	v_mov_b32_e32 v10, v43
	v_pk_fma_f32 v[6:7], v[10:11], v[8:9], v[6:7] op_sel_hi:[0,1,1]
	v_mov_b32_e32 v8, v7
	v_max_f32_e32 v7, v32, v32
	v_max_f32_e32 v10, 0, v7
	v_max_f32_e32 v7, v16, v16
	v_max_f32_e32 v11, 0, v7
	v_max_f32_e32 v7, v33, v33
	v_max_f32_e32 v12, 0, v7
	v_max_f32_e32 v7, v17, v17
	v_pk_fma_f32 v[10:11], v[36:37], v[10:11], 0 op_sel_hi:[0,1,0]
	v_max_f32_e32 v13, 0, v7
	v_max_f32_e32 v7, v34, v34
	v_pk_fma_f32 v[10:11], v[36:37], v[12:13], v[10:11] op_sel:[1,0,0]
	v_max_f32_e32 v12, 0, v7
	v_max_f32_e32 v7, v18, v18
	v_max_f32_e32 v13, 0, v7
	v_max_f32_e32 v7, v35, v35
	v_pk_fma_f32 v[10:11], v[38:39], v[12:13], v[10:11] op_sel_hi:[0,1,1]
	v_max_f32_e32 v12, 0, v7
	v_max_f32_e32 v7, v19, v19
	v_max_f32_e32 v13, 0, v7
	v_mov_b32_e32 v14, v39
	v_pk_fma_f32 v[10:11], v[14:15], v[12:13], v[10:11] op_sel_hi:[0,1,1]
	v_mov_b32_e32 v9, v11
	s_nop 1
	v_permlane32_swap_b32_e32 v10, v9
	v_permlane32_swap_b32_e32 v6, v8
	v_mov_b32_e32 v7, v10
	v_pk_add_f32 v[6:7], v[6:7], v[8:9]
	v_pk_add_f32 v[4:5], v[4:5], 0 op_sel_hi:[1,0]
	v_pk_add_f32 v[6:7], v[6:7], 0 op_sel_hi:[1,0]
	v_cmp_gt_i32_e64 s[4:5], 0, v4
	v_cmp_gt_i32_e64 s[8:9], 0, v5
	v_cmp_gt_i32_e64 s[12:13], 0, v6
	v_cmp_gt_i32_e64 s[16:17], 0, v7
	s_and_saveexec_b64 s[20:21], s[0:1]
	s_cbranch_execz .LBB0_743
	v_mad_u32_u24 v8, v209, s57, v2
	s_waitcnt vmcnt(0)
	ds_write_b128 v8, v[68:71] offset:16384
	ds_write_b128 v8, v[72:75] offset:17536
	ds_write_b128 v8, v[76:79] offset:18688
	ds_write_b128 v8, v[80:83] offset:19840
	ds_write_b128 v8, v[84:87] offset:20992
	ds_write_b128 v8, v[88:91] offset:22144
	ds_write_b128 v8, v[92:95] offset:23296
	ds_write_b128 v8, v[96:99] offset:24448

; #define MFMA32(a, b, c) __builtin_amdgcn_mfma_f32_32x32x16_bf16((a), (b), (c), 0, 0, 0)
; DI void topk_job(const Params& p, int b, int t0, char* lds) {
;     ...
; #pragma unroll
;     for (int i = 0; i < 17; ++i) {
;       const int c = 1 + w + 8 * i;
;       if (c <= cmax) {
;         const bool more = c + 8 <= cmax;
;         if (more) {
;           const u16* kp = ikb + (size_t)(c + 8) * 64 * 64;
; #pragma unroll
;           for (int j = 0; j < 8; ++j) st[j] = *(const u32x4*)(kp + (size_t)j * 8 * 64);
;         }
;         bf16x8 b0[4], b1[4];
; #pragma unroll
;         for (int ks = 0; ks < 4; ++ks) {
;           b0[ks] = *(const bf16x8*)(wb + r * 144 + ks * 32 + h * 16);
;           b1[ks] = *(const bf16x8*)(wb + (32 + r) * 144 + ks * 32 + h * 16);
;         }
;         __builtin_amdgcn_sched_barrier(0);
;         f32x16 a0, a1;
; #pragma unroll
;         for (int e = 0; e < 16; ++e) { a0[e] = 0.f; a1[e] = 0.f; }
; #pragma unroll
;         for (int ks = 0; ks < 4; ++ks) { a0 = MFMA32(af[ks], b0[ks], a0); a1 = MFMA32(af[ks], b1[ks], a1); }
;         const int key = c * 64 + lane;
; #pragma unroll
;         for (int qi = 0; qi < 4; ++qi) {
;           f32x2 pp2 = {0.f, 0.f};
; #pragma unroll
;           for (int e = 0; e < 4; ++e) {
;             const f32x2 rl = {fmaxf(a0[4 * qi + e], 0.f), fmaxf(a1[4 * qi + e], 0.f)};
;             const f32x2 wv = {iw[qi][e], iw[qi][e]};
;             pp2 += rl * wv;
;           }
;           const float p0 = pp2[0], p1 = pp2[1];
;           const u32x2 sw = __builtin_amdgcn_permlane32_swap(__float_as_uint(p0), __float_as_uint(p1), false, false);
;           float mine = __uint_as_float(sw[0]) + __uint_as_float(sw[1]);
;           mine += 0.0f;
;           unsigned u = __float_as_uint(mine);
;           u = (u & 0x80000000u) ? ~u : (u | 0x80000000u);
;           if (key > t0 + qi || key < LEAD) u = 0u;
;           sc[i][qi] = u;
;         }
;         if (more) {
; #pragma unroll
;           for (int j = 0; j < 8; ++j) *(u32x4*)(wb + (lrow + 8 * j) * 144 + lpc * 16) = st[j];
;         }
.LBB0_747:
	s_or_b64 exec, exec, s[2:3]
	ds_read_b128 v[4:7], v210 offset:16384
	ds_read_b128 v[212:215], v210 offset:16416
	s_waitcnt vmcnt(8)
	ds_read_b128 v[8:11], v210 offset:20992
	ds_read_b128 v[216:219], v210 offset:21024
	ds_read_b128 v[220:223], v210 offset:16448
	ds_read_b128 v[224:227], v210 offset:16480
	ds_read_b128 v[228:231], v210 offset:21056
	ds_read_b128 v[232:235], v210 offset:21088
	s_waitcnt lgkmcnt(7)
	v_mfma_f32_32x32x16_bf16 v[20:35], v[64:67], v[4:7], 0
	v_lshl_or_b32 v103, v104, 6, v101
	s_sub_i32 s2, 0x209d, s23
	s_sub_i32 s10, 0x209e, s23
	v_cmp_gt_i32_e32 vcc, s25, v103
	v_cmp_lt_i32_e64 s[6:7], s24, v103
	v_cmp_lt_i32_e64 s[2:3], s2, v103
	v_cmp_lt_i32_e64 s[14:15], s10, v103
	s_waitcnt lgkmcnt(5)
	v_mfma_f32_32x32x16_bf16 v[4:19], v[64:67], v[8:11], 0
	v_cmp_lt_i32_e64 s[10:11], s22, v103
	v_mfma_f32_32x32x16_bf16 v[20:35], v[60:63], v[212:215], v[20:35]
	s_waitcnt lgkmcnt(4)
	v_mfma_f32_32x32x16_bf16 v[4:19], v[60:63], v[216:219], v[4:19]
	s_waitcnt lgkmcnt(3)
	v_mfma_f32_32x32x16_bf16 v[20:35], v[56:59], v[220:223], v[20:35]
	s_waitcnt lgkmcnt(1)
	v_mfma_f32_32x32x16_bf16 v[4:19], v[56:59], v[228:231], v[4:19]
	v_mfma_f32_32x32x16_bf16 v[20:35], v[52:55], v[224:227], v[20:35]
	s_waitcnt lgkmcnt(0)
	v_mfma_f32_32x32x16_bf16 v[4:19], v[52:55], v[232:235], v[4:19]
	s_nop 9
	v_max_f32_e32 v20, v20, v20
	v_max_f32_e32 v212, 0, v20
	v_max_f32_e32 v20, v22, v22
	v_max_f32_e32 v20, 0, v20
	v_max_f32_e32 v4, v4, v4
	v_max_f32_e32 v213, 0, v4
	v_max_f32_e32 v4, v21, v21
	v_max_f32_e32 v5, v5, v5
	v_pk_fma_f32 v[212:213], v[48:49], v[212:213], 0 op_sel_hi:[0,1,0]
	v_max_f32_e32 v4, 0, v4
	v_max_f32_e32 v5, 0, v5
	v_max_f32_e32 v6, v6, v6
	v_pk_fma_f32 v[4:5], v[48:49], v[4:5], v[212:213] op_sel:[1,0,0]
	v_max_f32_e32 v21, 0, v6
	v_max_f32_e32 v6, v23, v23
	v_max_f32_e32 v7, v7, v7
	v_pk_fma_f32 v[4:5], v[50:51], v[20:21], v[4:5] op_sel_hi:[0,1,1]
	v_max_f32_e32 v6, 0, v6
	v_max_f32_e32 v7, 0, v7
	v_mov_b32_e32 v20, v51
	v_pk_fma_f32 v[4:5], v[20:21], v[6:7], v[4:5] op_sel_hi:[0,1,1]
	v_mov_b32_e32 v6, v5
	v_max_f32_e32 v5, v24, v24
	v_max_f32_e32 v20, 0, v5
	v_max_f32_e32 v5, v8, v8
	v_max_f32_e32 v21, 0, v5
	v_max_f32_e32 v5, v25, v25
	v_max_f32_e32 v8, 0, v5
	v_max_f32_e32 v5, v9, v9
	v_pk_fma_f32 v[20:21], v[44:45], v[20:21], 0 op_sel_hi:[0,1,0]
	v_max_f32_e32 v9, 0, v5
	v_max_f32_e32 v5, v26, v26
	v_pk_fma_f32 v[8:9], v[44:45], v[8:9], v[20:21] op_sel:[1,0,0]
	v_max_f32_e32 v20, 0, v5
	v_max_f32_e32 v5, v10, v10
	v_max_f32_e32 v21, 0, v5
	v_max_f32_e32 v5, v27, v27
	v_max_f32_e32 v10, 0, v5
	v_max_f32_e32 v5, v11, v11
	v_pk_fma_f32 v[8:9], v[46:47], v[20:21], v[8:9] op_sel_hi:[0,1,1]
	v_max_f32_e32 v11, 0, v5
	v_mov_b32_e32 v20, v47
	v_pk_fma_f32 v[8:9], v[20:21], v[10:11], v[8:9] op_sel_hi:[0,1,1]
	v_mov_b32_e32 v7, v9
	s_nop 1
	v_permlane32_swap_b32_e32 v8, v7
	v_permlane32_swap_b32_e32 v4, v6
	v_mov_b32_e32 v5, v8
	v_pk_add_f32 v[4:5], v[4:5], v[6:7]
	v_max_f32_e32 v6, v28, v28
	v_max_f32_e32 v7, v12, v12
	v_max_f32_e32 v6, 0, v6
	v_max_f32_e32 v7, 0, v7
	v_max_f32_e32 v8, v29, v29
	v_max_f32_e32 v9, v13, v13
	v_pk_fma_f32 v[6:7], v[40:41], v[6:7], 0 op_sel_hi:[0,1,0]
	v_max_f32_e32 v8, 0, v8
	v_max_f32_e32 v9, 0, v9
	v_pk_fma_f32 v[6:7], v[40:41], v[8:9], v[6:7] op_sel:[1,0,0]
	v_max_f32_e32 v8, v30, v30
	v_max_f32_e32 v9, v14, v14
	v_max_f32_e32 v8, 0, v8
	v_max_f32_e32 v9, 0, v9
	v_pk_fma_f32 v[6:7], v[42:43], v[8:9], v[6:7] op_sel_hi:[0,1,1]
	v_max_f32_e32 v8, v31, v31
	v_max_f32_e32 v9, v15, v15
	v_max_f32_e32 v8, 0, v8
	v_max_f32_e32 v9, 0, v9
	v_mov_b32_e32 v10, v43
	v_pk_fma_f32 v[6:7], v[10:11], v[8:9], v[6:7] op_sel_hi:[0,1,1]
	v_mov_b32_e32 v8, v7
	v_max_f32_e32 v7, v32, v32
	v_max_f32_e32 v10, 0, v7
	v_max_f32_e32 v7, v16, v16
	v_max_f32_e32 v11, 0, v7
	v_max_f32_e32 v7, v33, v33
	v_max_f32_e32 v12, 0, v7
	v_max_f32_e32 v7, v17, v17
	v_pk_fma_f32 v[10:11], v[36:37], v[10:11], 0 op_sel_hi:[0,1,0]
	v_max_f32_e32 v13, 0, v7
	v_max_f32_e32 v7, v34, v34
	v_pk_fma_f32 v[10:11], v[36:37], v[12:13], v[10:11] op_sel:[1,0,0]
	v_max_f32_e32 v12, 0, v7
	v_max_f32_e32 v7, v18, v18
	v_max_f32_e32 v13, 0, v7
	v_max_f32_e32 v7, v35, v35
	v_pk_fma_f32 v[10:11], v[38:39], v[12:13], v[10:11] op_sel_hi:[0,1,1]
	v_max_f32_e32 v12, 0, v7
	v_max_f32_e32 v7, v19, v19
	v_max_f32_e32 v13, 0, v7
	v_mov_b32_e32 v14, v39
	v_pk_fma_f32 v[10:11], v[14:15], v[12:13], v[10:11] op_sel_hi:[0,1,1]
	v_mov_b32_e32 v9, v11
	s_nop 1
	v_permlane32_swap_b32_e32 v10, v9
	v_permlane32_swap_b32_e32 v6, v8
	v_mov_b32_e32 v7, v10
	v_pk_add_f32 v[6:7], v[6:7], v[8:9]
	v_pk_add_f32 v[4:5], v[4:5], 0 op_sel_hi:[1,0]
	v_pk_add_f32 v[6:7], v[6:7], 0 op_sel_hi:[1,0]
	v_cmp_gt_i32_e64 s[4:5], 0, v4
	v_cmp_gt_i32_e64 s[8:9], 0, v5
	v_cmp_gt_i32_e64 s[12:13], 0, v6
	v_cmp_gt_i32_e64 s[16:17], 0, v7
	s_and_saveexec_b64 s[20:21], s[0:1]
	s_cbranch_execz .LBB0_749
	v_mad_u32_u24 v8, v209, s57, v2
	s_waitcnt vmcnt(0)
	ds_write_b128 v8, v[68:71] offset:16384
	ds_write_b128 v8, v[72:75] offset:17536
	ds_write_b128 v8, v[76:79] offset:18688
	ds_write_b128 v8, v[80:83] offset:19840
	ds_write_b128 v8, v[84:87] offset:20992
	ds_write_b128 v8, v[88:91] offset:22144
	ds_write_b128 v8, v[92:95] offset:23296
	ds_write_b128 v8, v[96:99] offset:24448

; #define MFMA32(a, b, c) __builtin_amdgcn_mfma_f32_32x32x16_bf16((a), (b), (c), 0, 0, 0)
; DI void topk_job(const Params& p, int b, int t0, char* lds) {
;     ...
; #pragma unroll
;     for (int i = 0; i < 17; ++i) {
;       const int c = 1 + w + 8 * i;
;       if (c <= cmax) {
;         const bool more = c + 8 <= cmax;
;         if (more) {
;           const u16* kp = ikb + (size_t)(c + 8) * 64 * 64;
; #pragma unroll
;           for (int j = 0; j < 8; ++j) st[j] = *(const u32x4*)(kp + (size_t)j * 8 * 64);
;         }
;         bf16x8 b0[4], b1[4];
; #pragma unroll
;         for (int ks = 0; ks < 4; ++ks) {
;           b0[ks] = *(const bf16x8*)(wb + r * 144 + ks * 32 + h * 16);
;           b1[ks] = *(const bf16x8*)(wb + (32 + r) * 144 + ks * 32 + h * 16);
;         }
;         __builtin_amdgcn_sched_barrier(0);
;         f32x16 a0, a1;
; #pragma unroll
;         for (int e = 0; e < 16; ++e) { a0[e] = 0.f; a1[e] = 0.f; }
; #pragma unroll
;         for (int ks = 0; ks < 4; ++ks) { a0 = MFMA32(af[ks], b0[ks], a0); a1 = MFMA32(af[ks], b1[ks], a1); }
;         const int key = c * 64 + lane;
; #pragma unroll
;         for (int qi = 0; qi < 4; ++qi) {
;           f32x2 pp2 = {0.f, 0.f};
; #pragma unroll
;           for (int e = 0; e < 4; ++e) {
;             const f32x2 rl = {fmaxf(a0[4 * qi + e], 0.f), fmaxf(a1[4 * qi + e], 0.f)};
;             const f32x2 wv = {iw[qi][e], iw[qi][e]};
;             pp2 += rl * wv;
;           }
;           const float p0 = pp2[0], p1 = pp2[1];
;           const u32x2 sw = __builtin_amdgcn_permlane32_swap(__float_as_uint(p0), __float_as_uint(p1), false, false);
;           float mine = __uint_as_float(sw[0]) + __uint_as_float(sw[1]);
;           mine += 0.0f;
;           unsigned u = __float_as_uint(mine);
;           u = (u & 0x80000000u) ? ~u : (u | 0x80000000u);
;           if (key > t0 + qi || key < LEAD) u = 0u;
;           sc[i][qi] = u;
;         }
;         if (more) {
; #pragma unroll
;           for (int j = 0; j < 8; ++j) *(u32x4*)(wb + (lrow + 8 * j) * 144 + lpc * 16) = st[j];
;         }
.LBB0_753:
	s_or_b64 exec, exec, s[2:3]
	ds_read_b128 v[4:7], v210 offset:16384
	ds_read_b128 v[212:215], v210 offset:16416
	ds_read_b128 v[8:11], v210 offset:20992
	ds_read_b128 v[216:219], v210 offset:21024
	ds_read_b128 v[220:223], v210 offset:16448
	ds_read_b128 v[224:227], v210 offset:16480
	ds_read_b128 v[228:231], v210 offset:21056
	ds_read_b128 v[232:235], v210 offset:21088
	s_waitcnt lgkmcnt(7)
	v_mfma_f32_32x32x16_bf16 v[20:35], v[64:67], v[4:7], 0
	s_sub_i32 s2, 0x209d, s23
	s_sub_i32 s10, 0x209e, s23
	s_waitcnt lgkmcnt(5)
	v_mfma_f32_32x32x16_bf16 v[4:19], v[64:67], v[8:11], 0
	v_mfma_f32_32x32x16_bf16 v[20:35], v[60:63], v[212:215], v[20:35]
	s_waitcnt lgkmcnt(4)
	v_mfma_f32_32x32x16_bf16 v[4:19], v[60:63], v[216:219], v[4:19]
	s_waitcnt lgkmcnt(3)
	v_mfma_f32_32x32x16_bf16 v[20:35], v[56:59], v[220:223], v[20:35]
	s_waitcnt lgkmcnt(1)
	v_mfma_f32_32x32x16_bf16 v[4:19], v[56:59], v[228:231], v[4:19]
	v_lshl_or_b32 v56, v102, 6, v101
	v_cmp_gt_i32_e32 vcc, s25, v56
	v_cmp_lt_i32_e64 s[6:7], s24, v56
	v_cmp_lt_i32_e64 s[2:3], s2, v56
	v_cmp_lt_i32_e64 s[14:15], s10, v56
	v_cmp_lt_i32_e64 s[10:11], s22, v56
	v_mfma_f32_32x32x16_bf16 v[20:35], v[52:55], v[224:227], v[20:35]
	s_waitcnt lgkmcnt(0)
	v_mfma_f32_32x32x16_bf16 v[4:19], v[52:55], v[232:235], v[4:19]
	s_nop 9
	v_max_f32_e32 v0, v20, v20
	v_max_f32_e32 v0, 0, v0
	v_max_f32_e32 v1, v4, v4
	v_max_f32_e32 v1, 0, v1
	v_max_f32_e32 v4, v21, v21
	v_max_f32_e32 v5, v5, v5
	v_pk_fma_f32 v[0:1], v[48:49], v[0:1], 0 op_sel_hi:[0,1,0]
	v_max_f32_e32 v4, 0, v4
	v_max_f32_e32 v5, 0, v5
	v_pk_fma_f32 v[0:1], v[48:49], v[4:5], v[0:1] op_sel:[1,0,0]
	v_max_f32_e32 v4, v22, v22
	v_max_f32_e32 v5, v6, v6
	v_max_f32_e32 v4, 0, v4
	v_max_f32_e32 v5, 0, v5
	v_pk_fma_f32 v[0:1], v[50:51], v[4:5], v[0:1] op_sel_hi:[0,1,1]
	v_max_f32_e32 v4, v23, v23
	v_max_f32_e32 v5, v7, v7
	v_max_f32_e32 v4, 0, v4
	v_max_f32_e32 v5, 0, v5
	v_mov_b32_e32 v6, v51
	v_pk_fma_f32 v[0:1], v[6:7], v[4:5], v[0:1] op_sel_hi:[0,1,1]
	v_mov_b32_e32 v4, v1
	v_max_f32_e32 v1, v24, v24
	v_max_f32_e32 v6, 0, v1
	v_max_f32_e32 v1, v8, v8
	v_max_f32_e32 v7, 0, v1
	v_max_f32_e32 v1, v25, v25
	v_max_f32_e32 v8, 0, v1
	v_max_f32_e32 v1, v9, v9
	v_pk_fma_f32 v[6:7], v[44:45], v[6:7], 0 op_sel_hi:[0,1,0]
	v_max_f32_e32 v9, 0, v1
	v_max_f32_e32 v1, v26, v26
	v_pk_fma_f32 v[6:7], v[44:45], v[8:9], v[6:7] op_sel:[1,0,0]
	v_max_f32_e32 v8, 0, v1
	v_max_f32_e32 v1, v10, v10
	v_max_f32_e32 v9, 0, v1
	v_max_f32_e32 v1, v27, v27
	v_pk_fma_f32 v[6:7], v[46:47], v[8:9], v[6:7] op_sel_hi:[0,1,1]
	v_max_f32_e32 v8, 0, v1
	v_max_f32_e32 v1, v11, v11
	v_max_f32_e32 v9, 0, v1
	v_mov_b32_e32 v10, v47
	v_pk_fma_f32 v[6:7], v[10:11], v[8:9], v[6:7] op_sel_hi:[0,1,1]
	v_mov_b32_e32 v5, v7
	s_nop 1
	v_permlane32_swap_b32_e32 v6, v5
	v_permlane32_swap_b32_e32 v0, v4
	v_mov_b32_e32 v1, v6
	v_pk_add_f32 v[0:1], v[0:1], v[4:5]
	v_max_f32_e32 v4, v28, v28
	v_max_f32_e32 v5, v12, v12
	v_max_f32_e32 v4, 0, v4
	v_max_f32_e32 v5, 0, v5
	v_max_f32_e32 v6, v29, v29
	v_max_f32_e32 v7, v13, v13
	v_pk_fma_f32 v[4:5], v[40:41], v[4:5], 0 op_sel_hi:[0,1,0]
	v_max_f32_e32 v6, 0, v6
	v_max_f32_e32 v7, 0, v7
	v_pk_fma_f32 v[4:5], v[40:41], v[6:7], v[4:5] op_sel:[1,0,0]
	v_max_f32_e32 v6, v30, v30
	v_max_f32_e32 v7, v14, v14
	v_max_f32_e32 v6, 0, v6
	v_max_f32_e32 v7, 0, v7
	v_pk_fma_f32 v[4:5], v[42:43], v[6:7], v[4:5] op_sel_hi:[0,1,1]
	v_max_f32_e32 v6, v31, v31
	v_max_f32_e32 v7, v15, v15
	v_max_f32_e32 v6, 0, v6
	v_max_f32_e32 v7, 0, v7
	v_mov_b32_e32 v8, v43
	v_pk_fma_f32 v[4:5], v[8:9], v[6:7], v[4:5] op_sel_hi:[0,1,1]
	v_mov_b32_e32 v6, v5
	v_max_f32_e32 v5, v32, v32
	v_max_f32_e32 v8, 0, v5
	v_max_f32_e32 v5, v16, v16
	v_max_f32_e32 v9, 0, v5
	v_max_f32_e32 v5, v33, v33
	v_max_f32_e32 v10, 0, v5
	v_max_f32_e32 v5, v17, v17
	v_pk_fma_f32 v[8:9], v[36:37], v[8:9], 0 op_sel_hi:[0,1,0]
	v_max_f32_e32 v11, 0, v5
	v_max_f32_e32 v5, v34, v34
	v_pk_fma_f32 v[8:9], v[36:37], v[10:11], v[8:9] op_sel:[1,0,0]
	v_max_f32_e32 v10, 0, v5
	v_max_f32_e32 v5, v18, v18
	v_max_f32_e32 v11, 0, v5
	v_max_f32_e32 v5, v35, v35
	v_pk_fma_f32 v[8:9], v[38:39], v[10:11], v[8:9] op_sel_hi:[0,1,1]
	v_max_f32_e32 v10, 0, v5
	v_max_f32_e32 v5, v19, v19
	v_max_f32_e32 v11, 0, v5
	v_mov_b32_e32 v12, v39
	v_pk_fma_f32 v[8:9], v[12:13], v[10:11], v[8:9] op_sel_hi:[0,1,1]
	v_mov_b32_e32 v7, v9
	s_nop 1
	v_permlane32_swap_b32_e32 v8, v7
	v_permlane32_swap_b32_e32 v4, v6
	v_mov_b32_e32 v5, v8
	v_pk_add_f32 v[4:5], v[4:5], v[6:7]
	v_pk_add_f32 v[0:1], v[0:1], 0 op_sel_hi:[1,0]
	v_pk_add_f32 v[4:5], v[4:5], 0 op_sel_hi:[1,0]
	v_cmp_gt_i32_e64 s[4:5], 0, v0
	v_cmp_gt_i32_e64 s[8:9], 0, v1
	v_cmp_gt_i32_e64 s[12:13], 0, v4
	v_cmp_gt_i32_e64 s[16:17], 0, v5
	s_and_saveexec_b64 s[20:21], s[0:1]
	s_cbranch_execz .LBB0_755
	v_mad_u32_u24 v2, v209, s57, v2
	ds_write_b128 v2, v[68:71] offset:16384
	ds_write_b128 v2, v[72:75] offset:17536
	ds_write_b128 v2, v[76:79] offset:18688
	ds_write_b128 v2, v[80:83] offset:19840
	ds_write_b128 v2, v[84:87] offset:20992
	ds_write_b128 v2, v[88:91] offset:22144
	ds_write_b128 v2, v[92:95] offset:23296
	ds_write_b128 v2, v[96:99] offset:24448

; DI void topk_job(const Params& p, int b, int t0, char* lds) {
;     ...
;   unsigned T[4];
;   {
;     unsigned* hist = (unsigned*)(lds + 16384);
;     int* sel = (int*)(lds + 512);
;     unsigned pref[4] = {0u, 0u, 0u, 0u};
;     int chi[4] = {0, 0, 0, 0};
;     bool few[4] = {false, false, false, false};
;     __syncthreads();
;     bool small = false;
;     int nb[4] = {0, 0, 0, 0};
; #pragma unroll
;     for (int pass = 0; pass < 3; ++pass) {
;       if (pass == 2) {
;         small = true;
; #pragma unroll
;         for (int q = 0; q < 4; ++q) small = small && (few[q] || nb[q] <= 64);
;         if (small) break;
;       }
;       {
;         const u32x4 z = {0u, 0u, 0u, 0u};
; #pragma unroll
;         for (int j = 0; j < 8; ++j) ((u32x4*)hist)[tid + 512 * j] = z;
;       }
;       __syncthreads();
; #pragma unroll
;       for (int i = 0; i < 17; ++i) {
; #pragma unroll
;         for (int q = 0; q < 4; ++q) {
;           const unsigned u = sc[i][q];
;           bool part; unsigned bin;
;           if (pass == 0) { part = (u != 0u); bin = (u >> 22) + (lane & 3) * 1024; }
;           else if (pass == 1) { part = (u != 0u) && ((u >> 22) == pref[q]) && !few[q]; bin = ((u >> 12) & 1023u) + (lane & 3) * 1024; }
;           else { part = (u != 0u) && ((u >> 12) == pref[q]) && !few[q]; bin = u & 4095u; }
;           if (part) atomicAdd(hist + q * 4096 + bin, 1u);
;         }
;       }
.LBB0_756:
	v_writelane_b32 v237, s46, 9
	s_nop 1
	v_writelane_b32 v237, s47, 10
	v_writelane_b32 v237, s44, 11
	s_nop 1
	v_writelane_b32 v237, s45, 12
	v_writelane_b32 v237, s42, 13
	s_nop 1
	v_writelane_b32 v237, s43, 14
	v_writelane_b32 v237, s40, 15
	s_nop 1
	v_writelane_b32 v237, s41, 16
	v_writelane_b32 v237, s36, 17
	s_nop 1
	v_writelane_b32 v237, s37, 18
	v_writelane_b32 v237, s34, 19
	s_nop 1
	v_writelane_b32 v237, s35, 20
	v_writelane_b32 v237, s30, 21
	s_nop 1
	v_writelane_b32 v237, s31, 22
	v_writelane_b32 v237, s28, 23
	s_nop 1
	v_writelane_b32 v237, s29, 24
	s_or_b64 exec, exec, s[18:19]
	s_waitcnt vmcnt(0) lgkmcnt(0)
	v_lshrrev_b32_e32 v0, 6, v100
	s_mov_b32 s3, s90
	v_readfirstlane_b32 s2, v0
	s_lshl_b32 s4, s87, 1
	s_and_b32 s4, s4, 0x3ffc
	s_sub_i32 s4, 0x209c, s4
	s_bitcmp1_b32 s87, 0
	s_cselect_b32 s5, 0x2100, 0
	s_add_i32 s4, s4, s5
	v_readlane_b32 s6, v240, 13
	v_readlane_b32 s7, v240, 14
	s_lshl_b32 s5, s4, 9
	s_add_u32 s40, s6, s5
	s_addc_u32 s41, s7, 0
	s_add_u32 s42, s40, 0x200
	s_addc_u32 s43, s41, 0
	s_add_u32 s44, s42, 0x200
	s_addc_u32 s45, s43, 0
	s_add_u32 s46, s44, 0x200
	s_addc_u32 s47, s45, 0
	s_mov_b32 s16, 0x55555555
	s_mov_b32 s17, 0x55555555
	s_mov_b32 s18, 0x33333333
	s_mov_b32 s19, 0x33333333
	s_mov_b32 s20, 0xf0f0f0f
	s_mov_b32 s21, 0xf0f0f0f
	s_mov_b32 s22, 0xff00ff
	s_mov_b32 s23, 0xff00ff
	s_mov_b32 s24, 0xffff
	s_mov_b32 s25, 0xffff
	s_mov_b32 s26, 0xffffffff
	s_mov_b32 s27, 0
	v_mov_b32_e32 v20, 1
	v_and_b32_e32 v0, 3, v101
	v_lshlrev_b32_e32 v0, 12, v0
	v_add_u32_e32 v21, 0x4000, v0
	v_add_u32_e32 v25, 0x14000, v0
	v_mov_b32_e32 v29, 0x4000
	v_add_u32_e32 v22, 0x8000, v0
	v_add_u32_e32 v26, 0x18000, v0
	v_mov_b32_e32 v30, 0x8000
	v_add_u32_e32 v23, 0xc000, v0
	v_add_u32_e32 v27, 0x1c000, v0
	v_mov_b32_e32 v31, 0xc000
	v_add_u32_e32 v24, 0x10000, v0
	v_add_u32_e32 v28, 0x20000, v0
	v_mov_b32_e32 v32, 0x10000
	s_movk_i32 s85, 0x100
	s_mov_b32 s56, 0
	s_mov_b32 s58, 0
	s_barrier
	v_mov_b32_e32 v4, 0
	v_mov_b32_e32 v5, 0
	v_mov_b32_e32 v6, 0
	v_mov_b32_e32 v7, 0
	v_lshlrev_b32_e32 v0, 4, v100
	v_add_u32_e32 v0, 0x4000, v0
	v_add_u32_e32 v1, 0x10000, v0
	ds_write_b128 v0, v[4:7]
	ds_write_b128 v0, v[4:7] offset:8192
	ds_write_b128 v0, v[4:7] offset:16384
	ds_write_b128 v0, v[4:7] offset:24576
	ds_write_b128 v0, v[4:7] offset:32768
	ds_write_b128 v0, v[4:7] offset:40960
	ds_write_b128 v0, v[4:7] offset:49152
	ds_write_b128 v0, v[4:7] offset:57344
	ds_write_b128 v1, v[4:7]
	ds_write_b128 v1, v[4:7] offset:8192
	ds_write_b128 v1, v[4:7] offset:16384
	ds_write_b128 v1, v[4:7] offset:24576
	ds_write_b128 v1, v[4:7] offset:32768
	ds_write_b128 v1, v[4:7] offset:40960
	ds_write_b128 v1, v[4:7] offset:49152
	ds_write_b128 v1, v[4:7] offset:57344
	s_waitcnt lgkmcnt(0)
	s_barrier
	s_add_i32 s28, s2, 1
	s_cmp_gt_u32 s28, s3
	s_cbranch_scc1 .Ltk_p0_done_1
	v_lshrrev_b32_e32 v0, 22, v208
	v_lshl_add_u32 v0, v0, 2, v21
	ds_add_u32 v0, v20
	v_lshrrev_b32_e32 v1, 22, v175
	v_lshl_add_u32 v1, v1, 2, v22
	ds_add_u32 v1, v20
	v_lshrrev_b32_e32 v4, 22, v161
	v_lshl_add_u32 v4, v4, 2, v23
	ds_add_u32 v4, v20
	v_lshrrev_b32_e32 v5, 22, v138
	v_lshl_add_u32 v5, v5, 2, v24
	ds_add_u32 v5, v20
	s_add_i32 s28, s28, 8
	s_cmp_gt_u32 s28, s3
	s_cbranch_scc1 .Ltk_p0_done_1
	v_lshrrev_b32_e32 v0, 22, v207
	v_lshl_add_u32 v0, v0, 2, v21
	ds_add_u32 v0, v20
	v_lshrrev_b32_e32 v1, 22, v173
	v_lshl_add_u32 v1, v1, 2, v22
	ds_add_u32 v1, v20
	v_lshrrev_b32_e32 v4, 22, v159
	v_lshl_add_u32 v4, v4, 2, v23
	ds_add_u32 v4, v20
	v_lshrrev_b32_e32 v5, 22, v135
	v_lshl_add_u32 v5, v5, 2, v24
	ds_add_u32 v5, v20
	s_add_i32 s28, s28, 8
	s_cmp_gt_u32 s28, s3
	s_cbranch_scc1 .Ltk_p0_done_1
	v_lshrrev_b32_e32 v0, 22, v187
	v_lshl_add_u32 v0, v0, 2, v21
	ds_add_u32 v0, v20
	v_lshrrev_b32_e32 v1, 22, v172
	v_lshl_add_u32 v1, v1, 2, v22
	ds_add_u32 v1, v20
	v_lshrrev_b32_e32 v4, 22, v158
	v_lshl_add_u32 v4, v4, 2, v23
	ds_add_u32 v4, v20
	v_lshrrev_b32_e32 v5, 22, v133
	v_lshl_add_u32 v5, v5, 2, v24
	ds_add_u32 v5, v20
	s_add_i32 s28, s28, 8
	s_cmp_gt_u32 s28, s3
	s_cbranch_scc1 .Ltk_p0_done_1
	v_lshrrev_b32_e32 v0, 22, v186
	v_lshl_add_u32 v0, v0, 2, v21
	ds_add_u32 v0, v20
	v_lshrrev_b32_e32 v1, 22, v171
	v_lshl_add_u32 v1, v1, 2, v22
	ds_add_u32 v1, v20
	v_lshrrev_b32_e32 v4, 22, v153
	v_lshl_add_u32 v4, v4, 2, v23
	ds_add_u32 v4, v20
	v_lshrrev_b32_e32 v5, 22, v129
	v_lshl_add_u32 v5, v5, 2, v24
	ds_add_u32 v5, v20
	s_add_i32 s28, s28, 8
	s_cmp_gt_u32 s28, s3
	s_cbranch_scc1 .Ltk_p0_done_1
	v_lshrrev_b32_e32 v0, 22, v185
	v_lshl_add_u32 v0, v0, 2, v21
	ds_add_u32 v0, v20
	v_lshrrev_b32_e32 v1, 22, v170
	v_lshl_add_u32 v1, v1, 2, v22
	ds_add_u32 v1, v20
	v_lshrrev_b32_e32 v4, 22, v150
	v_lshl_add_u32 v4, v4, 2, v23
	ds_add_u32 v4, v20
	v_lshrrev_b32_e32 v5, 22, v127
	v_lshl_add_u32 v5, v5, 2, v24
	ds_add_u32 v5, v20
	s_add_i32 s28, s28, 8
	s_cmp_gt_u32 s28, s3
	s_cbranch_scc1 .Ltk_p0_done_1
	v_lshrrev_b32_e32 v0, 22, v184
	v_lshl_add_u32 v0, v0, 2, v21
	ds_add_u32 v0, v20
	v_lshrrev_b32_e32 v1, 22, v168
	v_lshl_add_u32 v1, v1, 2, v22
	ds_add_u32 v1, v20
	v_lshrrev_b32_e32 v4, 22, v149
	v_lshl_add_u32 v4, v4, 2, v23
	ds_add_u32 v4, v20
	v_lshrrev_b32_e32 v5, 22, v125
	v_lshl_add_u32 v5, v5, 2, v24
	ds_add_u32 v5, v20
	s_add_i32 s28, s28, 8
	s_cmp_gt_u32 s28, s3
	s_cbranch_scc1 .Ltk_p0_done_1
	v_lshrrev_b32_e32 v0, 22, v183
	v_lshl_add_u32 v0, v0, 2, v21
	ds_add_u32 v0, v20
	v_lshrrev_b32_e32 v1, 22, v167
	v_lshl_add_u32 v1, v1, 2, v22
	ds_add_u32 v1, v20
	v_lshrrev_b32_e32 v4, 22, v147
	v_lshl_add_u32 v4, v4, 2, v23
	ds_add_u32 v4, v20
	v_lshrrev_b32_e32 v5, 22, v123
	v_lshl_add_u32 v5, v5, 2, v24
	ds_add_u32 v5, v20
	s_add_i32 s28, s28, 8
	s_cmp_gt_u32 s28, s3
	s_cbranch_scc1 .Ltk_p0_done_1
; DI void topk_job(const Params& p, int b, int t0, char* lds) {
;     ...
; #pragma unroll
;       for (int i = 0; i < 17; ++i) {
; #pragma unroll
;         for (int q = 0; q < 4; ++q) {
;           const unsigned u = sc[i][q];
;           bool part; unsigned bin;
;           if (pass == 0) { part = (u != 0u); bin = (u >> 22) + (lane & 3) * 1024; }
;           else if (pass == 1) { part = (u != 0u) && ((u >> 22) == pref[q]) && !few[q]; bin = ((u >> 12) & 1023u) + (lane & 3) * 1024; }
;           else { part = (u != 0u) && ((u >> 12) == pref[q]) && !few[q]; bin = u & 4095u; }
;           if (part) atomicAdd(hist + q * 4096 + bin, 1u);
;         }
;       }
;       __syncthreads();
;       if (w < 4) {
;         const int q = w;
;         const unsigned* hq = hist + q * 4096;
;         const int need = 256 - chi[q];
;         int G = 0;
;         if (pass < 2) {
; #pragma unroll
;           for (int rep = 0; rep < 4; ++rep)
; #pragma unroll
;             for (int j = 0; j < 16; ++j) G += (int)hq[rep * 1024 + 16 * lane + ((j + lane) & 15)];
	v_lshrrev_b32_e32 v0, 22, v182
	v_lshl_add_u32 v0, v0, 2, v21
	ds_add_u32 v0, v20
	v_lshrrev_b32_e32 v1, 22, v166
	v_lshl_add_u32 v1, v1, 2, v22
	ds_add_u32 v1, v20
	v_lshrrev_b32_e32 v4, 22, v146
	v_lshl_add_u32 v4, v4, 2, v23
	ds_add_u32 v4, v20
	v_lshrrev_b32_e32 v5, 22, v121
	v_lshl_add_u32 v5, v5, 2, v24
	ds_add_u32 v5, v20
	s_add_i32 s28, s28, 8
	s_cmp_gt_u32 s28, s3
	s_cbranch_scc1 .Ltk_p0_done_1
	v_lshrrev_b32_e32 v0, 22, v181
	v_lshl_add_u32 v0, v0, 2, v21
	ds_add_u32 v0, v20
	v_lshrrev_b32_e32 v1, 22, v165
	v_lshl_add_u32 v1, v1, 2, v22
	ds_add_u32 v1, v20
	v_lshrrev_b32_e32 v4, 22, v145
	v_lshl_add_u32 v4, v4, 2, v23
	ds_add_u32 v4, v20
	v_lshrrev_b32_e32 v5, 22, v119
	v_lshl_add_u32 v5, v5, 2, v24
	ds_add_u32 v5, v20
	s_add_i32 s28, s28, 8
	s_cmp_gt_u32 s28, s3
	s_cbranch_scc1 .Ltk_p0_done_1
	v_lshrrev_b32_e32 v0, 22, v180
	v_lshl_add_u32 v0, v0, 2, v21
	ds_add_u32 v0, v20
	v_lshrrev_b32_e32 v1, 22, v164
	v_lshl_add_u32 v1, v1, 2, v22
	ds_add_u32 v1, v20
	v_lshrrev_b32_e32 v4, 22, v143
	v_lshl_add_u32 v4, v4, 2, v23
	ds_add_u32 v4, v20
	v_lshrrev_b32_e32 v5, 22, v115
	v_lshl_add_u32 v5, v5, 2, v24
	ds_add_u32 v5, v20
	s_add_i32 s28, s28, 8
	s_cmp_gt_u32 s28, s3
	s_cbranch_scc1 .Ltk_p0_done_1
	v_lshrrev_b32_e32 v0, 22, v179
	v_lshl_add_u32 v0, v0, 2, v21
	ds_add_u32 v0, v20
	v_lshrrev_b32_e32 v1, 22, v163
	v_lshl_add_u32 v1, v1, 2, v22
	ds_add_u32 v1, v20
	v_lshrrev_b32_e32 v4, 22, v142
	v_lshl_add_u32 v4, v4, 2, v23
	ds_add_u32 v4, v20
	v_lshrrev_b32_e32 v5, 22, v113
	v_lshl_add_u32 v5, v5, 2, v24
	ds_add_u32 v5, v20
	s_add_i32 s28, s28, 8
	s_cmp_gt_u32 s28, s3
	s_cbranch_scc1 .Ltk_p0_done_1
	v_lshrrev_b32_e32 v0, 22, v178
	v_lshl_add_u32 v0, v0, 2, v21
	ds_add_u32 v0, v20
	v_lshrrev_b32_e32 v1, 22, v162
	v_lshl_add_u32 v1, v1, 2, v22
	ds_add_u32 v1, v20
	v_lshrrev_b32_e32 v4, 22, v141
	v_lshl_add_u32 v4, v4, 2, v23
	ds_add_u32 v4, v20
	v_lshrrev_b32_e32 v5, 22, v111
	v_lshl_add_u32 v5, v5, 2, v24
	ds_add_u32 v5, v20
	s_add_i32 s28, s28, 8
	s_cmp_gt_u32 s28, s3
	s_cbranch_scc1 .Ltk_p0_done_1
	v_lshrrev_b32_e32 v0, 22, v177
	v_lshl_add_u32 v0, v0, 2, v21
	ds_add_u32 v0, v20
	v_lshrrev_b32_e32 v1, 22, v160
	v_lshl_add_u32 v1, v1, 2, v22
	ds_add_u32 v1, v20
	v_lshrrev_b32_e32 v4, 22, v140
	v_lshl_add_u32 v4, v4, 2, v23
	ds_add_u32 v4, v20
	v_lshrrev_b32_e32 v5, 22, v109
	v_lshl_add_u32 v5, v5, 2, v24
	ds_add_u32 v5, v20
	s_add_i32 s28, s28, 8
	s_cmp_gt_u32 s28, s3
	s_cbranch_scc1 .Ltk_p0_done_1
	v_lshrrev_b32_e32 v0, 22, v176
	v_lshl_add_u32 v0, v0, 2, v21
	ds_add_u32 v0, v20
	v_lshrrev_b32_e32 v1, 22, v151
	v_lshl_add_u32 v1, v1, 2, v22
	ds_add_u32 v1, v20
	v_lshrrev_b32_e32 v4, 22, v139
	v_lshl_add_u32 v4, v4, 2, v23
	ds_add_u32 v4, v20
	v_lshrrev_b32_e32 v5, 22, v107
	v_lshl_add_u32 v5, v5, 2, v24
	ds_add_u32 v5, v20
	s_add_i32 s28, s28, 8
	s_cmp_gt_u32 s28, s3
	s_cbranch_scc1 .Ltk_p0_done_1
	v_lshrrev_b32_e32 v0, 22, v174
	v_lshl_add_u32 v0, v0, 2, v21
	ds_add_u32 v0, v20
	v_lshrrev_b32_e32 v1, 22, v148
	v_lshl_add_u32 v1, v1, 2, v22
	ds_add_u32 v1, v20
	v_lshrrev_b32_e32 v4, 22, v131
	v_lshl_add_u32 v4, v4, 2, v23
	ds_add_u32 v4, v20
	v_lshrrev_b32_e32 v5, 22, v105
	v_lshl_add_u32 v5, v5, 2, v24
	ds_add_u32 v5, v20
	s_add_i32 s28, s28, 8
	s_cmp_gt_u32 s28, s3
	s_cbranch_scc1 .Ltk_p0_done_1
	v_lshrrev_b32_e32 v0, 22, v169
	v_lshl_add_u32 v0, v0, 2, v21
	ds_add_u32 v0, v20
	v_lshrrev_b32_e32 v1, 22, v144
	v_lshl_add_u32 v1, v1, 2, v22
	ds_add_u32 v1, v20
	v_lshrrev_b32_e32 v4, 22, v117
	v_lshl_add_u32 v4, v4, 2, v23
	ds_add_u32 v4, v20
	v_lshrrev_b32_e32 v5, 22, v103
	v_lshl_add_u32 v5, v5, 2, v24
	ds_add_u32 v5, v20
	s_add_i32 s28, s28, 8
	s_cmp_gt_u32 s28, s3
	s_cbranch_scc1 .Ltk_p0_done_1
	v_lshrrev_b32_e32 v0, 22, v19
	v_lshl_add_u32 v0, v0, 2, v21
	ds_add_u32 v0, v20
	v_lshrrev_b32_e32 v1, 22, v18
	v_lshl_add_u32 v1, v1, 2, v22
	ds_add_u32 v1, v20
	v_lshrrev_b32_e32 v4, 22, v17
	v_lshl_add_u32 v4, v4, 2, v23
	ds_add_u32 v4, v20
	v_lshrrev_b32_e32 v5, 22, v16
	v_lshl_add_u32 v5, v5, 2, v24
	ds_add_u32 v5, v20
.Ltk_p0_done_1:
	s_waitcnt lgkmcnt(0)
	s_barrier
	s_cmp_gt_u32 s2, 3
	s_cbranch_scc1 .Ltk_scan_end_2
	s_lshl_b32 s84, s2, 14
	s_add_i32 s84, s84, 0x4000
	s_cmp_eq_u32 s56, 1
	s_cbranch_scc1 .Ltk_scan_few_3
	v_lshlrev_b32_e32 v0, 12, v101
	v_add_u32_e32 v0, s84, v0
	s_mov_b64 exec, 15
	ds_write_b32 v0, v3
	s_mov_b64 exec, -1
	v_lshlrev_b32_e32 v33, 6, v101
	v_add_u32_e32 v33, s84, v33
	v_mov_b32_e32 v66, 0
	v_add_u32_e32 v0, 0, v101
	v_and_b32_e32 v0, 15, v0
	v_lshl_add_u32 v34, v0, 2, v33
	v_add_u32_e32 v0, 1, v101
	v_and_b32_e32 v0, 15, v0
	v_lshl_add_u32 v35, v0, 2, v33
	v_add_u32_e32 v0, 2, v101
	v_and_b32_e32 v0, 15, v0
	v_lshl_add_u32 v36, v0, 2, v33
	v_add_u32_e32 v0, 3, v101
	v_and_b32_e32 v0, 15, v0
	v_lshl_add_u32 v37, v0, 2, v33
	v_add_u32_e32 v0, 4, v101
	v_and_b32_e32 v0, 15, v0
	v_lshl_add_u32 v38, v0, 2, v33
	v_add_u32_e32 v0, 5, v101
	v_and_b32_e32 v0, 15, v0
	v_lshl_add_u32 v39, v0, 2, v33
	v_add_u32_e32 v0, 6, v101
	v_and_b32_e32 v0, 15, v0
	v_lshl_add_u32 v40, v0, 2, v33
	v_add_u32_e32 v0, 7, v101
	v_and_b32_e32 v0, 15, v0
	v_lshl_add_u32 v41, v0, 2, v33
	v_add_u32_e32 v0, 8, v101
	v_and_b32_e32 v0, 15, v0
	v_lshl_add_u32 v42, v0, 2, v33
	v_add_u32_e32 v0, 9, v101
	v_and_b32_e32 v0, 15, v0
	v_lshl_add_u32 v43, v0, 2, v33
	v_add_u32_e32 v0, 10, v101
	v_and_b32_e32 v0, 15, v0
	v_lshl_add_u32 v44, v0, 2, v33
	v_add_u32_e32 v0, 11, v101
	v_and_b32_e32 v0, 15, v0
	v_lshl_add_u32 v45, v0, 2, v33
	v_add_u32_e32 v0, 12, v101
	v_and_b32_e32 v0, 15, v0
	v_lshl_add_u32 v46, v0, 2, v33
	v_add_u32_e32 v0, 13, v101
	v_and_b32_e32 v0, 15, v0
	v_lshl_add_u32 v47, v0, 2, v33
	v_add_u32_e32 v0, 14, v101
	v_and_b32_e32 v0, 15, v0
	v_lshl_add_u32 v48, v0, 2, v33
	v_add_u32_e32 v0, 15, v101
	v_and_b32_e32 v0, 15, v0
	v_lshl_add_u32 v49, v0, 2, v33
	ds_read_b32 v50, v34
	ds_read_b32 v51, v35
	ds_read_b32 v52, v36
	ds_read_b32 v53, v37
	ds_read_b32 v54, v38
	ds_read_b32 v55, v39
	ds_read_b32 v56, v40
	ds_read_b32 v57, v41
	ds_read_b32 v58, v42
	ds_read_b32 v59, v43
	ds_read_b32 v60, v44
	ds_read_b32 v61, v45
	ds_read_b32 v62, v46
	ds_read_b32 v63, v47
	ds_read_b32 v64, v48
	ds_read_b32 v65, v49
	s_waitcnt lgkmcnt(0)
; DI void topk_job(const Params& p, int b, int t0, char* lds) {
;     ...
;         if (pass < 2) {
; #pragma unroll
;           for (int rep = 0; rep < 4; ++rep)
; #pragma unroll
;             for (int j = 0; j < 16; ++j) G += (int)hq[rep * 1024 + 16 * lane + ((j + lane) & 15)];
;         } else {
; #pragma unroll 8
;           for (int j = 0; j < 64; ++j) G += (int)hq[64 * lane + ((j + lane) & 63)];
;         }
;         int S = G;
;         { int tt; S = wscan<false>(S, lane, tt); }
;         const unsigned long long mk = __ballot(S >= need);
;         int B = 0, cg2 = 0, fw = 0, nbin = 0;
;         if (mk == 0ull) {
;           fw = 1;
;         } else {
;           const int ks = 63 - __clzll(mk);
;           const int above = (ks < 63) ? __builtin_amdgcn_readlane(S, ks + 1) : 0;
;           int hh;
;           if (pass < 2) {
;             hh = 0;
;             if (lane < 16) hh = (int)(hq[16 * ks + lane] + hq[1024 + 16 * ks + lane] + hq[2048 + 16 * ks + lane] + hq[3072 + 16 * ks + lane]);
;           } else {
;             hh = (int)hq[64 * ks + lane];
;           }
;           int s2 = hh;
;           { int tt; s2 = wscan<false>(s2, lane, tt); }
;           const unsigned long long m2 = __ballot(above + s2 >= need);
;           const int Ls = 63 - __clzll(m2);
;           B = (pass < 2 ? 16 : 64) * ks + Ls;
;           nbin = __builtin_amdgcn_readlane(hh, Ls);
;           cg2 = above + __builtin_amdgcn_readlane(s2, Ls) - nbin;
;         }
;         if (lane == 0) { sel[q * 4 + 0] = B; sel[q * 4 + 1] = chi[q] + cg2; sel[q * 4 + 2] = fw; sel[q * 4 + 3] = nbin; }
;       }
;       __syncthreads();
; #pragma unroll
;       for (int q = 0; q < 4; ++q) {
;         if (!few[q]) {
;           pref[q] = (pref[q] << (pass < 2 ? 10 : 12)) | (unsigned)sel[q * 4 + 0];
;           chi[q] = sel[q * 4 + 1];
;           nb[q] = sel[q * 4 + 3];
;           if (pass == 0) few[q] = sel[q * 4 + 2] != 0;
	v_add3_u32 v66, v66, v50, v51
	v_add3_u32 v66, v66, v52, v53
	v_add3_u32 v66, v66, v54, v55
	v_add3_u32 v66, v66, v56, v57
	v_add3_u32 v66, v66, v58, v59
	v_add3_u32 v66, v66, v60, v61
	v_add3_u32 v66, v66, v62, v63
	v_add3_u32 v66, v66, v64, v65
	ds_read_b32 v50, v34 offset:4096
	ds_read_b32 v51, v35 offset:4096
	ds_read_b32 v52, v36 offset:4096
	ds_read_b32 v53, v37 offset:4096
	ds_read_b32 v54, v38 offset:4096
	ds_read_b32 v55, v39 offset:4096
	ds_read_b32 v56, v40 offset:4096
	ds_read_b32 v57, v41 offset:4096
	ds_read_b32 v58, v42 offset:4096
	ds_read_b32 v59, v43 offset:4096
	ds_read_b32 v60, v44 offset:4096
	ds_read_b32 v61, v45 offset:4096
	ds_read_b32 v62, v46 offset:4096
	ds_read_b32 v63, v47 offset:4096
	ds_read_b32 v64, v48 offset:4096
	ds_read_b32 v65, v49 offset:4096
	s_waitcnt lgkmcnt(0)
	v_add3_u32 v66, v66, v50, v51
	v_add3_u32 v66, v66, v52, v53
	v_add3_u32 v66, v66, v54, v55
	v_add3_u32 v66, v66, v56, v57
	v_add3_u32 v66, v66, v58, v59
	v_add3_u32 v66, v66, v60, v61
	v_add3_u32 v66, v66, v62, v63
	v_add3_u32 v66, v66, v64, v65
	ds_read_b32 v50, v34 offset:8192
	ds_read_b32 v51, v35 offset:8192
	ds_read_b32 v52, v36 offset:8192
	ds_read_b32 v53, v37 offset:8192
	ds_read_b32 v54, v38 offset:8192
	ds_read_b32 v55, v39 offset:8192
	ds_read_b32 v56, v40 offset:8192
	ds_read_b32 v57, v41 offset:8192
	ds_read_b32 v58, v42 offset:8192
	ds_read_b32 v59, v43 offset:8192
	ds_read_b32 v60, v44 offset:8192
	ds_read_b32 v61, v45 offset:8192
	ds_read_b32 v62, v46 offset:8192
	ds_read_b32 v63, v47 offset:8192
	ds_read_b32 v64, v48 offset:8192
	ds_read_b32 v65, v49 offset:8192
	s_waitcnt lgkmcnt(0)
	v_add3_u32 v66, v66, v50, v51
	v_add3_u32 v66, v66, v52, v53
	v_add3_u32 v66, v66, v54, v55
	v_add3_u32 v66, v66, v56, v57
	v_add3_u32 v66, v66, v58, v59
	v_add3_u32 v66, v66, v60, v61
	v_add3_u32 v66, v66, v62, v63
	v_add3_u32 v66, v66, v64, v65
	ds_read_b32 v50, v34 offset:12288
	ds_read_b32 v51, v35 offset:12288
	ds_read_b32 v52, v36 offset:12288
	ds_read_b32 v53, v37 offset:12288
	ds_read_b32 v54, v38 offset:12288
	ds_read_b32 v55, v39 offset:12288
	ds_read_b32 v56, v40 offset:12288
	ds_read_b32 v57, v41 offset:12288
	ds_read_b32 v58, v42 offset:12288
	ds_read_b32 v59, v43 offset:12288
	ds_read_b32 v60, v44 offset:12288
	ds_read_b32 v61, v45 offset:12288
	ds_read_b32 v62, v46 offset:12288
	ds_read_b32 v63, v47 offset:12288
	ds_read_b32 v64, v48 offset:12288
	ds_read_b32 v65, v49 offset:12288
	s_waitcnt lgkmcnt(0)
	v_add3_u32 v66, v66, v50, v51
	v_add3_u32 v66, v66, v52, v53
	v_add3_u32 v66, v66, v54, v55
	v_add3_u32 v66, v66, v56, v57
	v_add3_u32 v66, v66, v58, v59
	v_add3_u32 v66, v66, v60, v61
	v_add3_u32 v66, v66, v62, v63
	v_add3_u32 v66, v66, v64, v65
	s_nop 1
	v_add_u32_dpp v68, v66, v66 quad_perm:[1,0,3,2] row_mask:0xf bank_mask:0xf bound_ctrl:1
	v_cndmask_b32_e64 v67, v66, v68, s[16:17]
	s_nop 1
	v_mov_b32_dpp v69, v68 quad_perm:[2,3,0,1] row_mask:0xf bank_mask:0xf bound_ctrl:1
	v_add_u32_e32 v68, v68, v69
	v_cndmask_b32_e64 v70, 0, v69, s[18:19]
	v_add_u32_e32 v67, v67, v70
	s_nop 0
	v_mov_b32_dpp v69, v68 row_half_mirror row_mask:0xf bank_mask:0xf bound_ctrl:1
	v_add_u32_e32 v68, v68, v69
	v_cndmask_b32_e64 v70, 0, v69, s[20:21]
	v_add_u32_e32 v67, v67, v70
	s_nop 0
	v_mov_b32_dpp v69, v68 row_mirror row_mask:0xf bank_mask:0xf bound_ctrl:1
	v_add_u32_e32 v68, v68, v69
	v_cndmask_b32_e64 v70, 0, v69, s[22:23]
	v_add_u32_e32 v67, v67, v70
	v_mov_b32_e32 v71, v68
	v_mov_b32_e32 v72, v68
	s_nop 1
	v_permlane16_swap_b32_e32 v71, v72
	v_cndmask_b32_e64 v69, v71, v72, s[24:25]
	v_add_u32_e32 v68, v68, v69
	v_cndmask_b32_e64 v70, 0, v69, s[24:25]
	v_add_u32_e32 v67, v67, v70
	v_mov_b32_e32 v71, v68
	v_mov_b32_e32 v72, v68
	s_nop 1
	v_permlane32_swap_b32_e32 v71, v72
	v_cndmask_b32_e64 v69, v71, v72, s[26:27]
	v_cndmask_b32_e64 v70, 0, v69, s[26:27]
	v_add_u32_e32 v67, v67, v70
	v_cmp_le_u32_e64 s[30:31], s85, v67
	s_cmp_eq_u64 s[30:31], 0
	s_cbranch_scc1 .Ltk_scan_few_3
	s_flbit_i32_b64 s88, s[30:31]
	s_sub_i32 s88, 63, s88
	s_mov_b32 s90, 0
	s_cmp_eq_u32 s88, 63
	s_cbranch_scc1 .Ltk_noabove_5
	s_add_i32 s4, s88, 1
	s_nop 0
	v_readlane_b32 s90, v67, s4
.Ltk_noabove_5:
	s_lshl_b32 s4, s88, 6
	s_add_i32 s4, s4, s84
	v_lshlrev_b32_e32 v0, 2, v101
	v_add_u32_e32 v0, s4, v0
	ds_read_b32 v50, v0
	ds_read_b32 v51, v0 offset:4096
	ds_read_b32 v52, v0 offset:8192
	ds_read_b32 v53, v0 offset:12288
	s_waitcnt lgkmcnt(0)
	v_add3_u32 v73, v50, v51, v52
	v_add_u32_e32 v73, v73, v53
	v_cmp_gt_u32_e32 vcc, 16, v101
	s_nop 1
	v_cndmask_b32_e32 v73, 0, v73, vcc
	s_nop 1
	v_add_u32_dpp v68, v73, v73 quad_perm:[1,0,3,2] row_mask:0xf bank_mask:0xf bound_ctrl:1
	v_cndmask_b32_e64 v74, v73, v68, s[16:17]
	s_nop 1
	v_mov_b32_dpp v69, v68 quad_perm:[2,3,0,1] row_mask:0xf bank_mask:0xf bound_ctrl:1
	v_add_u32_e32 v68, v68, v69
	v_cndmask_b32_e64 v70, 0, v69, s[18:19]
	v_add_u32_e32 v74, v74, v70
	s_nop 0
	v_mov_b32_dpp v69, v68 row_half_mirror row_mask:0xf bank_mask:0xf bound_ctrl:1
	v_add_u32_e32 v68, v68, v69
	v_cndmask_b32_e64 v70, 0, v69, s[20:21]
	v_add_u32_e32 v74, v74, v70
	s_nop 0
	v_mov_b32_dpp v69, v68 row_mirror row_mask:0xf bank_mask:0xf bound_ctrl:1
	v_add_u32_e32 v68, v68, v69
	v_cndmask_b32_e64 v70, 0, v69, s[22:23]
	v_add_u32_e32 v74, v74, v70
	v_mov_b32_e32 v71, v68
	v_mov_b32_e32 v72, v68
	s_nop 1
	v_permlane16_swap_b32_e32 v71, v72
	v_cndmask_b32_e64 v69, v71, v72, s[24:25]
	v_add_u32_e32 v68, v68, v69
	v_cndmask_b32_e64 v70, 0, v69, s[24:25]
	v_add_u32_e32 v74, v74, v70
	v_mov_b32_e32 v71, v68
	v_mov_b32_e32 v72, v68
	s_nop 1
	v_permlane32_swap_b32_e32 v71, v72
	v_cndmask_b32_e64 v69, v71, v72, s[26:27]
	v_cndmask_b32_e64 v70, 0, v69, s[26:27]
	v_add_u32_e32 v74, v74, v70
	v_add_u32_e32 v0, s90, v74
	v_cmp_le_u32_e64 s[30:31], s85, v0
	s_flbit_i32_b64 s4, s[30:31]
	s_sub_i32 s4, 63, s4
	s_nop 0
	v_readlane_b32 s5, v73, s4
	v_readlane_b32 s60, v74, s4
	s_lshl_b32 s62, s88, 4
	s_add_i32 s62, s62, s4
	s_add_i32 s60, s60, s90
	s_sub_i32 s60, s60, s5
	s_sub_i32 s85, s85, s60
	s_lshl_b32 s58, s58, 10
	s_or_b32 s58, s58, s62
	s_mov_b32 s62, s58
	s_branch .Ltk_scan_wr_4
; DI void topk_job(const Params& p, int b, int t0, char* lds) {
;     ...
;       {
;         const u32x4 z = {0u, 0u, 0u, 0u};
; #pragma unroll
;         for (int j = 0; j < 8; ++j) ((u32x4*)hist)[tid + 512 * j] = z;
;       }
;       __syncthreads();
; #pragma unroll
;       for (int i = 0; i < 17; ++i) {
; #pragma unroll
;         for (int q = 0; q < 4; ++q) {
;           const unsigned u = sc[i][q];
;           bool part; unsigned bin;
;           if (pass == 0) { part = (u != 0u); bin = (u >> 22) + (lane & 3) * 1024; }
;           else if (pass == 1) { part = (u != 0u) && ((u >> 22) == pref[q]) && !few[q]; bin = ((u >> 12) & 1023u) + (lane & 3) * 1024; }
;           else { part = (u != 0u) && ((u >> 12) == pref[q]) && !few[q]; bin = u & 4095u; }
;           if (part) atomicAdd(hist + q * 4096 + bin, 1u);
;         }
;       }
;     ...
;         if (lane == 0) { sel[q * 4 + 0] = B; sel[q * 4 + 1] = chi[q] + cg2; sel[q * 4 + 2] = fw; sel[q * 4 + 3] = nbin; }
;       }
;       __syncthreads();
; #pragma unroll
;       for (int q = 0; q < 4; ++q) {
;         if (!few[q]) {
;           pref[q] = (pref[q] << (pass < 2 ? 10 : 12)) | (unsigned)sel[q * 4 + 0];
;           chi[q] = sel[q * 4 + 1];
;           nb[q] = sel[q * 4 + 3];
;           if (pass == 0) few[q] = sel[q * 4 + 2] != 0;
.Ltk_scan_few_3:
	s_mov_b32 s56, 1
	s_mov_b32 s62, -1
.Ltk_scan_wr_4:
	v_mov_b32_e32 v4, s62
	v_mov_b32_e32 v5, s56
	v_mov_b32_e32 v0, 0x200
	v_lshl_add_u32 v0, s2, 3, v0
	s_mov_b64 exec, 1
	ds_write_b64 v0, v[4:5]
	s_mov_b64 exec, -1
.Ltk_scan_end_2:
	s_waitcnt lgkmcnt(0)
	s_barrier
	ds_read_b128 v[4:7], v3 offset:512
	ds_read_b128 v[8:11], v3 offset:528
	s_waitcnt lgkmcnt(0)
	v_readfirstlane_b32 s8, v4
	v_readfirstlane_b32 s9, v6
	v_readfirstlane_b32 s10, v8
	v_readfirstlane_b32 s11, v10
	v_mov_b32_e32 v4, 0
	v_mov_b32_e32 v5, 0
	v_mov_b32_e32 v6, 0
	v_mov_b32_e32 v7, 0
	v_lshlrev_b32_e32 v0, 4, v100
	v_add_u32_e32 v0, 0x4000, v0
	ds_write_b128 v0, v[4:7]
	ds_write_b128 v0, v[4:7] offset:8192
	ds_write_b128 v0, v[4:7] offset:16384
	ds_write_b128 v0, v[4:7] offset:24576
	ds_write_b128 v0, v[4:7] offset:32768
	ds_write_b128 v0, v[4:7] offset:40960
	ds_write_b128 v0, v[4:7] offset:49152
	ds_write_b128 v0, v[4:7] offset:57344
	s_add_i32 s28, s2, 1
	s_cmp_gt_u32 s28, s3
	s_cbranch_scc1 .Ltk_p1_done_6
	v_lshrrev_b32_e32 v0, 22, v208
	v_cmp_eq_u32_e32 vcc, s8, v0
	v_bfe_u32 v8, v208, 12, 10
	v_lshl_add_u32 v8, v8, 2, v25
	s_mov_b64 exec, vcc
	ds_add_u32 v8, v20
	s_mov_b64 exec, -1
	v_lshrrev_b32_e32 v1, 22, v175
	v_cmp_eq_u32_e32 vcc, s9, v1
	v_bfe_u32 v9, v175, 12, 10
	v_lshl_add_u32 v9, v9, 2, v26
	s_mov_b64 exec, vcc
	ds_add_u32 v9, v20
	s_mov_b64 exec, -1
	v_lshrrev_b32_e32 v4, 22, v161
	v_cmp_eq_u32_e32 vcc, s10, v4
	v_bfe_u32 v10, v161, 12, 10
	v_lshl_add_u32 v10, v10, 2, v27
	s_mov_b64 exec, vcc
	ds_add_u32 v10, v20
	s_mov_b64 exec, -1
	v_lshrrev_b32_e32 v5, 22, v138
	v_cmp_eq_u32_e32 vcc, s11, v5
	v_bfe_u32 v11, v138, 12, 10
	v_lshl_add_u32 v11, v11, 2, v28
	s_mov_b64 exec, vcc
	ds_add_u32 v11, v20
	s_mov_b64 exec, -1
	s_add_i32 s28, s28, 8
	s_cmp_gt_u32 s28, s3
	s_cbranch_scc1 .Ltk_p1_done_6
	v_lshrrev_b32_e32 v0, 22, v207
	v_cmp_eq_u32_e32 vcc, s8, v0
	v_bfe_u32 v8, v207, 12, 10
	v_lshl_add_u32 v8, v8, 2, v25
	s_mov_b64 exec, vcc
	ds_add_u32 v8, v20
	s_mov_b64 exec, -1
	v_lshrrev_b32_e32 v1, 22, v173
	v_cmp_eq_u32_e32 vcc, s9, v1
	v_bfe_u32 v9, v173, 12, 10
	v_lshl_add_u32 v9, v9, 2, v26
	s_mov_b64 exec, vcc
	ds_add_u32 v9, v20
	s_mov_b64 exec, -1
	v_lshrrev_b32_e32 v4, 22, v159
	v_cmp_eq_u32_e32 vcc, s10, v4
	v_bfe_u32 v10, v159, 12, 10
	v_lshl_add_u32 v10, v10, 2, v27
	s_mov_b64 exec, vcc
	ds_add_u32 v10, v20
	s_mov_b64 exec, -1
	v_lshrrev_b32_e32 v5, 22, v135
	v_cmp_eq_u32_e32 vcc, s11, v5
	v_bfe_u32 v11, v135, 12, 10
	v_lshl_add_u32 v11, v11, 2, v28
	s_mov_b64 exec, vcc
	ds_add_u32 v11, v20
	s_mov_b64 exec, -1
	s_add_i32 s28, s28, 8
	s_cmp_gt_u32 s28, s3
	s_cbranch_scc1 .Ltk_p1_done_6
	v_lshrrev_b32_e32 v0, 22, v187
	v_cmp_eq_u32_e32 vcc, s8, v0
	v_bfe_u32 v8, v187, 12, 10
	v_lshl_add_u32 v8, v8, 2, v25
	s_mov_b64 exec, vcc
	ds_add_u32 v8, v20
	s_mov_b64 exec, -1
	v_lshrrev_b32_e32 v1, 22, v172
	v_cmp_eq_u32_e32 vcc, s9, v1
	v_bfe_u32 v9, v172, 12, 10
	v_lshl_add_u32 v9, v9, 2, v26
	s_mov_b64 exec, vcc
	ds_add_u32 v9, v20
	s_mov_b64 exec, -1
	v_lshrrev_b32_e32 v4, 22, v158
	v_cmp_eq_u32_e32 vcc, s10, v4
	v_bfe_u32 v10, v158, 12, 10
	v_lshl_add_u32 v10, v10, 2, v27
	s_mov_b64 exec, vcc
	ds_add_u32 v10, v20
	s_mov_b64 exec, -1
	v_lshrrev_b32_e32 v5, 22, v133
	v_cmp_eq_u32_e32 vcc, s11, v5
	v_bfe_u32 v11, v133, 12, 10
	v_lshl_add_u32 v11, v11, 2, v28
	s_mov_b64 exec, vcc
	ds_add_u32 v11, v20
	s_mov_b64 exec, -1
	s_add_i32 s28, s28, 8
	s_cmp_gt_u32 s28, s3
	s_cbranch_scc1 .Ltk_p1_done_6
	v_lshrrev_b32_e32 v0, 22, v186
	v_cmp_eq_u32_e32 vcc, s8, v0
	v_bfe_u32 v8, v186, 12, 10
	v_lshl_add_u32 v8, v8, 2, v25
	s_mov_b64 exec, vcc
	ds_add_u32 v8, v20
	s_mov_b64 exec, -1
	v_lshrrev_b32_e32 v1, 22, v171
	v_cmp_eq_u32_e32 vcc, s9, v1
	v_bfe_u32 v9, v171, 12, 10
	v_lshl_add_u32 v9, v9, 2, v26
	s_mov_b64 exec, vcc
	ds_add_u32 v9, v20
	s_mov_b64 exec, -1
	v_lshrrev_b32_e32 v4, 22, v153
	v_cmp_eq_u32_e32 vcc, s10, v4
	v_bfe_u32 v10, v153, 12, 10
	v_lshl_add_u32 v10, v10, 2, v27
	s_mov_b64 exec, vcc
	ds_add_u32 v10, v20
	s_mov_b64 exec, -1
	v_lshrrev_b32_e32 v5, 22, v129
	v_cmp_eq_u32_e32 vcc, s11, v5
	v_bfe_u32 v11, v129, 12, 10
	v_lshl_add_u32 v11, v11, 2, v28
	s_mov_b64 exec, vcc
	ds_add_u32 v11, v20
	s_mov_b64 exec, -1
	s_add_i32 s28, s28, 8
	s_cmp_gt_u32 s28, s3
	s_cbranch_scc1 .Ltk_p1_done_6
	v_lshrrev_b32_e32 v0, 22, v185
	v_cmp_eq_u32_e32 vcc, s8, v0
	v_bfe_u32 v8, v185, 12, 10
	v_lshl_add_u32 v8, v8, 2, v25
	s_mov_b64 exec, vcc
	ds_add_u32 v8, v20
	s_mov_b64 exec, -1
	v_lshrrev_b32_e32 v1, 22, v170
	v_cmp_eq_u32_e32 vcc, s9, v1
	v_bfe_u32 v9, v170, 12, 10
	v_lshl_add_u32 v9, v9, 2, v26
	s_mov_b64 exec, vcc
	ds_add_u32 v9, v20
	s_mov_b64 exec, -1
	v_lshrrev_b32_e32 v4, 22, v150
	v_cmp_eq_u32_e32 vcc, s10, v4
	v_bfe_u32 v10, v150, 12, 10
	v_lshl_add_u32 v10, v10, 2, v27
	s_mov_b64 exec, vcc
	ds_add_u32 v10, v20
	s_mov_b64 exec, -1
	v_lshrrev_b32_e32 v5, 22, v127
	v_cmp_eq_u32_e32 vcc, s11, v5
	v_bfe_u32 v11, v127, 12, 10
	v_lshl_add_u32 v11, v11, 2, v28
	s_mov_b64 exec, vcc
	ds_add_u32 v11, v20
	s_mov_b64 exec, -1
	s_add_i32 s28, s28, 8
	s_cmp_gt_u32 s28, s3
	s_cbranch_scc1 .Ltk_p1_done_6
	v_lshrrev_b32_e32 v0, 22, v184
	v_cmp_eq_u32_e32 vcc, s8, v0
	v_bfe_u32 v8, v184, 12, 10
	v_lshl_add_u32 v8, v8, 2, v25
	s_mov_b64 exec, vcc
	ds_add_u32 v8, v20
	s_mov_b64 exec, -1
	v_lshrrev_b32_e32 v1, 22, v168
	v_cmp_eq_u32_e32 vcc, s9, v1
	v_bfe_u32 v9, v168, 12, 10
	v_lshl_add_u32 v9, v9, 2, v26
	s_mov_b64 exec, vcc
	ds_add_u32 v9, v20
	s_mov_b64 exec, -1
	v_lshrrev_b32_e32 v4, 22, v149
	v_cmp_eq_u32_e32 vcc, s10, v4
	v_bfe_u32 v10, v149, 12, 10
	v_lshl_add_u32 v10, v10, 2, v27
	s_mov_b64 exec, vcc
	ds_add_u32 v10, v20
	s_mov_b64 exec, -1
	v_lshrrev_b32_e32 v5, 22, v125
	v_cmp_eq_u32_e32 vcc, s11, v5
	v_bfe_u32 v11, v125, 12, 10
	v_lshl_add_u32 v11, v11, 2, v28
	s_mov_b64 exec, vcc
	ds_add_u32 v11, v20
	s_mov_b64 exec, -1
	s_add_i32 s28, s28, 8
	s_cmp_gt_u32 s28, s3
	s_cbranch_scc1 .Ltk_p1_done_6
; DI void topk_job(const Params& p, int b, int t0, char* lds) {
;     ...
; #pragma unroll
;       for (int i = 0; i < 17; ++i) {
; #pragma unroll
;         for (int q = 0; q < 4; ++q) {
;           const unsigned u = sc[i][q];
;           bool part; unsigned bin;
;           if (pass == 0) { part = (u != 0u); bin = (u >> 22) + (lane & 3) * 1024; }
;           else if (pass == 1) { part = (u != 0u) && ((u >> 22) == pref[q]) && !few[q]; bin = ((u >> 12) & 1023u) + (lane & 3) * 1024; }
;           else { part = (u != 0u) && ((u >> 12) == pref[q]) && !few[q]; bin = u & 4095u; }
;           if (part) atomicAdd(hist + q * 4096 + bin, 1u);
;         }
;       }
	v_lshrrev_b32_e32 v0, 22, v183
	v_cmp_eq_u32_e32 vcc, s8, v0
	v_bfe_u32 v8, v183, 12, 10
	v_lshl_add_u32 v8, v8, 2, v25
	s_mov_b64 exec, vcc
	ds_add_u32 v8, v20
	s_mov_b64 exec, -1
	v_lshrrev_b32_e32 v1, 22, v167
	v_cmp_eq_u32_e32 vcc, s9, v1
	v_bfe_u32 v9, v167, 12, 10
	v_lshl_add_u32 v9, v9, 2, v26
	s_mov_b64 exec, vcc
	ds_add_u32 v9, v20
	s_mov_b64 exec, -1
	v_lshrrev_b32_e32 v4, 22, v147
	v_cmp_eq_u32_e32 vcc, s10, v4
	v_bfe_u32 v10, v147, 12, 10
	v_lshl_add_u32 v10, v10, 2, v27
	s_mov_b64 exec, vcc
	ds_add_u32 v10, v20
	s_mov_b64 exec, -1
	v_lshrrev_b32_e32 v5, 22, v123
	v_cmp_eq_u32_e32 vcc, s11, v5
	v_bfe_u32 v11, v123, 12, 10
	v_lshl_add_u32 v11, v11, 2, v28
	s_mov_b64 exec, vcc
	ds_add_u32 v11, v20
	s_mov_b64 exec, -1
	s_add_i32 s28, s28, 8
	s_cmp_gt_u32 s28, s3
	s_cbranch_scc1 .Ltk_p1_done_6
	v_lshrrev_b32_e32 v0, 22, v182
	v_cmp_eq_u32_e32 vcc, s8, v0
	v_bfe_u32 v8, v182, 12, 10
	v_lshl_add_u32 v8, v8, 2, v25
	s_mov_b64 exec, vcc
	ds_add_u32 v8, v20
	s_mov_b64 exec, -1
	v_lshrrev_b32_e32 v1, 22, v166
	v_cmp_eq_u32_e32 vcc, s9, v1
	v_bfe_u32 v9, v166, 12, 10
	v_lshl_add_u32 v9, v9, 2, v26
	s_mov_b64 exec, vcc
	ds_add_u32 v9, v20
	s_mov_b64 exec, -1
	v_lshrrev_b32_e32 v4, 22, v146
	v_cmp_eq_u32_e32 vcc, s10, v4
	v_bfe_u32 v10, v146, 12, 10
	v_lshl_add_u32 v10, v10, 2, v27
	s_mov_b64 exec, vcc
	ds_add_u32 v10, v20
	s_mov_b64 exec, -1
	v_lshrrev_b32_e32 v5, 22, v121
	v_cmp_eq_u32_e32 vcc, s11, v5
	v_bfe_u32 v11, v121, 12, 10
	v_lshl_add_u32 v11, v11, 2, v28
	s_mov_b64 exec, vcc
	ds_add_u32 v11, v20
	s_mov_b64 exec, -1
	s_add_i32 s28, s28, 8
	s_cmp_gt_u32 s28, s3
	s_cbranch_scc1 .Ltk_p1_done_6
	v_lshrrev_b32_e32 v0, 22, v181
	v_cmp_eq_u32_e32 vcc, s8, v0
	v_bfe_u32 v8, v181, 12, 10
	v_lshl_add_u32 v8, v8, 2, v25
	s_mov_b64 exec, vcc
	ds_add_u32 v8, v20
	s_mov_b64 exec, -1
	v_lshrrev_b32_e32 v1, 22, v165
	v_cmp_eq_u32_e32 vcc, s9, v1
	v_bfe_u32 v9, v165, 12, 10
	v_lshl_add_u32 v9, v9, 2, v26
	s_mov_b64 exec, vcc
	ds_add_u32 v9, v20
	s_mov_b64 exec, -1
	v_lshrrev_b32_e32 v4, 22, v145
	v_cmp_eq_u32_e32 vcc, s10, v4
	v_bfe_u32 v10, v145, 12, 10
	v_lshl_add_u32 v10, v10, 2, v27
	s_mov_b64 exec, vcc
	ds_add_u32 v10, v20
	s_mov_b64 exec, -1
	v_lshrrev_b32_e32 v5, 22, v119
	v_cmp_eq_u32_e32 vcc, s11, v5
	v_bfe_u32 v11, v119, 12, 10
	v_lshl_add_u32 v11, v11, 2, v28
	s_mov_b64 exec, vcc
	ds_add_u32 v11, v20
	s_mov_b64 exec, -1
	s_add_i32 s28, s28, 8
	s_cmp_gt_u32 s28, s3
	s_cbranch_scc1 .Ltk_p1_done_6
	v_lshrrev_b32_e32 v0, 22, v180
	v_cmp_eq_u32_e32 vcc, s8, v0
	v_bfe_u32 v8, v180, 12, 10
	v_lshl_add_u32 v8, v8, 2, v25
	s_mov_b64 exec, vcc
	ds_add_u32 v8, v20
	s_mov_b64 exec, -1
	v_lshrrev_b32_e32 v1, 22, v164
	v_cmp_eq_u32_e32 vcc, s9, v1
	v_bfe_u32 v9, v164, 12, 10
	v_lshl_add_u32 v9, v9, 2, v26
	s_mov_b64 exec, vcc
	ds_add_u32 v9, v20
	s_mov_b64 exec, -1
	v_lshrrev_b32_e32 v4, 22, v143
	v_cmp_eq_u32_e32 vcc, s10, v4
	v_bfe_u32 v10, v143, 12, 10
	v_lshl_add_u32 v10, v10, 2, v27
	s_mov_b64 exec, vcc
	ds_add_u32 v10, v20
	s_mov_b64 exec, -1
	v_lshrrev_b32_e32 v5, 22, v115
	v_cmp_eq_u32_e32 vcc, s11, v5
	v_bfe_u32 v11, v115, 12, 10
	v_lshl_add_u32 v11, v11, 2, v28
	s_mov_b64 exec, vcc
	ds_add_u32 v11, v20
	s_mov_b64 exec, -1
	s_add_i32 s28, s28, 8
	s_cmp_gt_u32 s28, s3
	s_cbranch_scc1 .Ltk_p1_done_6
	v_lshrrev_b32_e32 v0, 22, v179
	v_cmp_eq_u32_e32 vcc, s8, v0
	v_bfe_u32 v8, v179, 12, 10
	v_lshl_add_u32 v8, v8, 2, v25
	s_mov_b64 exec, vcc
	ds_add_u32 v8, v20
	s_mov_b64 exec, -1
	v_lshrrev_b32_e32 v1, 22, v163
	v_cmp_eq_u32_e32 vcc, s9, v1
	v_bfe_u32 v9, v163, 12, 10
	v_lshl_add_u32 v9, v9, 2, v26
	s_mov_b64 exec, vcc
	ds_add_u32 v9, v20
	s_mov_b64 exec, -1
	v_lshrrev_b32_e32 v4, 22, v142
	v_cmp_eq_u32_e32 vcc, s10, v4
	v_bfe_u32 v10, v142, 12, 10
	v_lshl_add_u32 v10, v10, 2, v27
	s_mov_b64 exec, vcc
	ds_add_u32 v10, v20
	s_mov_b64 exec, -1
	v_lshrrev_b32_e32 v5, 22, v113
	v_cmp_eq_u32_e32 vcc, s11, v5
	v_bfe_u32 v11, v113, 12, 10
	v_lshl_add_u32 v11, v11, 2, v28
	s_mov_b64 exec, vcc
	ds_add_u32 v11, v20
	s_mov_b64 exec, -1
	s_add_i32 s28, s28, 8
	s_cmp_gt_u32 s28, s3
	s_cbranch_scc1 .Ltk_p1_done_6
	v_lshrrev_b32_e32 v0, 22, v178
	v_cmp_eq_u32_e32 vcc, s8, v0
	v_bfe_u32 v8, v178, 12, 10
	v_lshl_add_u32 v8, v8, 2, v25
	s_mov_b64 exec, vcc
	ds_add_u32 v8, v20
	s_mov_b64 exec, -1
	v_lshrrev_b32_e32 v1, 22, v162
	v_cmp_eq_u32_e32 vcc, s9, v1
	v_bfe_u32 v9, v162, 12, 10
	v_lshl_add_u32 v9, v9, 2, v26
	s_mov_b64 exec, vcc
	ds_add_u32 v9, v20
	s_mov_b64 exec, -1
	v_lshrrev_b32_e32 v4, 22, v141
	v_cmp_eq_u32_e32 vcc, s10, v4
	v_bfe_u32 v10, v141, 12, 10
	v_lshl_add_u32 v10, v10, 2, v27
	s_mov_b64 exec, vcc
	ds_add_u32 v10, v20
	s_mov_b64 exec, -1
	v_lshrrev_b32_e32 v5, 22, v111
	v_cmp_eq_u32_e32 vcc, s11, v5
	v_bfe_u32 v11, v111, 12, 10
	v_lshl_add_u32 v11, v11, 2, v28
	s_mov_b64 exec, vcc
	ds_add_u32 v11, v20
	s_mov_b64 exec, -1
	s_add_i32 s28, s28, 8
	s_cmp_gt_u32 s28, s3
	s_cbranch_scc1 .Ltk_p1_done_6
	v_lshrrev_b32_e32 v0, 22, v177
	v_cmp_eq_u32_e32 vcc, s8, v0
	v_bfe_u32 v8, v177, 12, 10
	v_lshl_add_u32 v8, v8, 2, v25
	s_mov_b64 exec, vcc
	ds_add_u32 v8, v20
	s_mov_b64 exec, -1
	v_lshrrev_b32_e32 v1, 22, v160
	v_cmp_eq_u32_e32 vcc, s9, v1
	v_bfe_u32 v9, v160, 12, 10
	v_lshl_add_u32 v9, v9, 2, v26
	s_mov_b64 exec, vcc
	ds_add_u32 v9, v20
	s_mov_b64 exec, -1
	v_lshrrev_b32_e32 v4, 22, v140
	v_cmp_eq_u32_e32 vcc, s10, v4
	v_bfe_u32 v10, v140, 12, 10
	v_lshl_add_u32 v10, v10, 2, v27
	s_mov_b64 exec, vcc
	ds_add_u32 v10, v20
	s_mov_b64 exec, -1
	v_lshrrev_b32_e32 v5, 22, v109
	v_cmp_eq_u32_e32 vcc, s11, v5
	v_bfe_u32 v11, v109, 12, 10
	v_lshl_add_u32 v11, v11, 2, v28
	s_mov_b64 exec, vcc
	ds_add_u32 v11, v20
	s_mov_b64 exec, -1
	s_add_i32 s28, s28, 8
	s_cmp_gt_u32 s28, s3
	s_cbranch_scc1 .Ltk_p1_done_6
; DI void topk_job(const Params& p, int b, int t0, char* lds) {
;     ...
; #pragma unroll
;       for (int i = 0; i < 17; ++i) {
; #pragma unroll
;         for (int q = 0; q < 4; ++q) {
;           const unsigned u = sc[i][q];
;           bool part; unsigned bin;
;           if (pass == 0) { part = (u != 0u); bin = (u >> 22) + (lane & 3) * 1024; }
;           else if (pass == 1) { part = (u != 0u) && ((u >> 22) == pref[q]) && !few[q]; bin = ((u >> 12) & 1023u) + (lane & 3) * 1024; }
;           else { part = (u != 0u) && ((u >> 12) == pref[q]) && !few[q]; bin = u & 4095u; }
;           if (part) atomicAdd(hist + q * 4096 + bin, 1u);
;         }
;       }
	v_lshrrev_b32_e32 v0, 22, v176
	v_cmp_eq_u32_e32 vcc, s8, v0
	v_bfe_u32 v8, v176, 12, 10
	v_lshl_add_u32 v8, v8, 2, v25
	s_mov_b64 exec, vcc
	ds_add_u32 v8, v20
	s_mov_b64 exec, -1
	v_lshrrev_b32_e32 v1, 22, v151
	v_cmp_eq_u32_e32 vcc, s9, v1
	v_bfe_u32 v9, v151, 12, 10
	v_lshl_add_u32 v9, v9, 2, v26
	s_mov_b64 exec, vcc
	ds_add_u32 v9, v20
	s_mov_b64 exec, -1
	v_lshrrev_b32_e32 v4, 22, v139
	v_cmp_eq_u32_e32 vcc, s10, v4
	v_bfe_u32 v10, v139, 12, 10
	v_lshl_add_u32 v10, v10, 2, v27
	s_mov_b64 exec, vcc
	ds_add_u32 v10, v20
	s_mov_b64 exec, -1
	v_lshrrev_b32_e32 v5, 22, v107
	v_cmp_eq_u32_e32 vcc, s11, v5
	v_bfe_u32 v11, v107, 12, 10
	v_lshl_add_u32 v11, v11, 2, v28
	s_mov_b64 exec, vcc
	ds_add_u32 v11, v20
	s_mov_b64 exec, -1
	s_add_i32 s28, s28, 8
	s_cmp_gt_u32 s28, s3
	s_cbranch_scc1 .Ltk_p1_done_6
	v_lshrrev_b32_e32 v0, 22, v174
	v_cmp_eq_u32_e32 vcc, s8, v0
	v_bfe_u32 v8, v174, 12, 10
	v_lshl_add_u32 v8, v8, 2, v25
	s_mov_b64 exec, vcc
	ds_add_u32 v8, v20
	s_mov_b64 exec, -1
	v_lshrrev_b32_e32 v1, 22, v148
	v_cmp_eq_u32_e32 vcc, s9, v1
	v_bfe_u32 v9, v148, 12, 10
	v_lshl_add_u32 v9, v9, 2, v26
	s_mov_b64 exec, vcc
	ds_add_u32 v9, v20
	s_mov_b64 exec, -1
	v_lshrrev_b32_e32 v4, 22, v131
	v_cmp_eq_u32_e32 vcc, s10, v4
	v_bfe_u32 v10, v131, 12, 10
	v_lshl_add_u32 v10, v10, 2, v27
	s_mov_b64 exec, vcc
	ds_add_u32 v10, v20
	s_mov_b64 exec, -1
	v_lshrrev_b32_e32 v5, 22, v105
	v_cmp_eq_u32_e32 vcc, s11, v5
	v_bfe_u32 v11, v105, 12, 10
	v_lshl_add_u32 v11, v11, 2, v28
	s_mov_b64 exec, vcc
	ds_add_u32 v11, v20
	s_mov_b64 exec, -1
	s_add_i32 s28, s28, 8
	s_cmp_gt_u32 s28, s3
	s_cbranch_scc1 .Ltk_p1_done_6
	v_lshrrev_b32_e32 v0, 22, v169
	v_cmp_eq_u32_e32 vcc, s8, v0
	v_bfe_u32 v8, v169, 12, 10
	v_lshl_add_u32 v8, v8, 2, v25
	s_mov_b64 exec, vcc
	ds_add_u32 v8, v20
	s_mov_b64 exec, -1
	v_lshrrev_b32_e32 v1, 22, v144
	v_cmp_eq_u32_e32 vcc, s9, v1
	v_bfe_u32 v9, v144, 12, 10
	v_lshl_add_u32 v9, v9, 2, v26
	s_mov_b64 exec, vcc
	ds_add_u32 v9, v20
	s_mov_b64 exec, -1
	v_lshrrev_b32_e32 v4, 22, v117
	v_cmp_eq_u32_e32 vcc, s10, v4
	v_bfe_u32 v10, v117, 12, 10
	v_lshl_add_u32 v10, v10, 2, v27
	s_mov_b64 exec, vcc
	ds_add_u32 v10, v20
	s_mov_b64 exec, -1
	v_lshrrev_b32_e32 v5, 22, v103
	v_cmp_eq_u32_e32 vcc, s11, v5
	v_bfe_u32 v11, v103, 12, 10
	v_lshl_add_u32 v11, v11, 2, v28
	s_mov_b64 exec, vcc
	ds_add_u32 v11, v20
	s_mov_b64 exec, -1
	s_add_i32 s28, s28, 8
	s_cmp_gt_u32 s28, s3
	s_cbranch_scc1 .Ltk_p1_done_6
	v_lshrrev_b32_e32 v0, 22, v19
	v_cmp_eq_u32_e32 vcc, s8, v0
	v_bfe_u32 v8, v19, 12, 10
	v_lshl_add_u32 v8, v8, 2, v25
	s_mov_b64 exec, vcc
	ds_add_u32 v8, v20
	s_mov_b64 exec, -1
	v_lshrrev_b32_e32 v1, 22, v18
	v_cmp_eq_u32_e32 vcc, s9, v1
	v_bfe_u32 v9, v18, 12, 10
	v_lshl_add_u32 v9, v9, 2, v26
	s_mov_b64 exec, vcc
	ds_add_u32 v9, v20
	s_mov_b64 exec, -1
	v_lshrrev_b32_e32 v4, 22, v17
	v_cmp_eq_u32_e32 vcc, s10, v4
	v_bfe_u32 v10, v17, 12, 10
	v_lshl_add_u32 v10, v10, 2, v27
	s_mov_b64 exec, vcc
	ds_add_u32 v10, v20
	s_mov_b64 exec, -1
	v_lshrrev_b32_e32 v5, 22, v16
	v_cmp_eq_u32_e32 vcc, s11, v5
	v_bfe_u32 v11, v16, 12, 10
	v_lshl_add_u32 v11, v11, 2, v28
	s_mov_b64 exec, vcc
	ds_add_u32 v11, v20
	s_mov_b64 exec, -1
; DI void topk_job(const Params& p, int b, int t0, char* lds) {
;     ...
;       __syncthreads();
;       if (w < 4) {
;         const int q = w;
;         const unsigned* hq = hist + q * 4096;
;         const int need = 256 - chi[q];
;         int G = 0;
;         if (pass < 2) {
; #pragma unroll
;           for (int rep = 0; rep < 4; ++rep)
; #pragma unroll
;             for (int j = 0; j < 16; ++j) G += (int)hq[rep * 1024 + 16 * lane + ((j + lane) & 15)];
;         } else {
; #pragma unroll 8
;           for (int j = 0; j < 64; ++j) G += (int)hq[64 * lane + ((j + lane) & 63)];
;         }
;         int S = G;
;         { int tt; S = wscan<false>(S, lane, tt); }
;         const unsigned long long mk = __ballot(S >= need);
;         int B = 0, cg2 = 0, fw = 0, nbin = 0;
;         if (mk == 0ull) {
;           fw = 1;
;         } else {
;           const int ks = 63 - __clzll(mk);
;           const int above = (ks < 63) ? __builtin_amdgcn_readlane(S, ks + 1) : 0;
;           int hh;
;           if (pass < 2) {
;             hh = 0;
;             if (lane < 16) hh = (int)(hq[16 * ks + lane] + hq[1024 + 16 * ks + lane] + hq[2048 + 16 * ks + lane] + hq[3072 + 16 * ks + lane]);
;           } else {
;             hh = (int)hq[64 * ks + lane];
;           }
;           int s2 = hh;
;           { int tt; s2 = wscan<false>(s2, lane, tt); }
.Ltk_p1_done_6:
	s_waitcnt lgkmcnt(0)
	s_barrier
	s_cmp_gt_u32 s2, 3
	s_cbranch_scc1 .Ltk_scan_end_7
	s_lshl_b32 s84, s2, 14
	s_add_i32 s84, s84, 0x14000
	s_cmp_eq_u32 s56, 1
	s_cbranch_scc1 .Ltk_scan_few_8
	v_lshlrev_b32_e32 v33, 6, v101
	v_add_u32_e32 v33, s84, v33
	v_mov_b32_e32 v66, 0
	v_add_u32_e32 v0, 0, v101
	v_and_b32_e32 v0, 15, v0
	v_lshl_add_u32 v34, v0, 2, v33
	v_add_u32_e32 v0, 1, v101
	v_and_b32_e32 v0, 15, v0
	v_lshl_add_u32 v35, v0, 2, v33
	v_add_u32_e32 v0, 2, v101
	v_and_b32_e32 v0, 15, v0
	v_lshl_add_u32 v36, v0, 2, v33
	v_add_u32_e32 v0, 3, v101
	v_and_b32_e32 v0, 15, v0
	v_lshl_add_u32 v37, v0, 2, v33
	v_add_u32_e32 v0, 4, v101
	v_and_b32_e32 v0, 15, v0
	v_lshl_add_u32 v38, v0, 2, v33
	v_add_u32_e32 v0, 5, v101
	v_and_b32_e32 v0, 15, v0
	v_lshl_add_u32 v39, v0, 2, v33
	v_add_u32_e32 v0, 6, v101
	v_and_b32_e32 v0, 15, v0
	v_lshl_add_u32 v40, v0, 2, v33
	v_add_u32_e32 v0, 7, v101
	v_and_b32_e32 v0, 15, v0
	v_lshl_add_u32 v41, v0, 2, v33
	v_add_u32_e32 v0, 8, v101
	v_and_b32_e32 v0, 15, v0
	v_lshl_add_u32 v42, v0, 2, v33
	v_add_u32_e32 v0, 9, v101
	v_and_b32_e32 v0, 15, v0
	v_lshl_add_u32 v43, v0, 2, v33
	v_add_u32_e32 v0, 10, v101
	v_and_b32_e32 v0, 15, v0
	v_lshl_add_u32 v44, v0, 2, v33
	v_add_u32_e32 v0, 11, v101
	v_and_b32_e32 v0, 15, v0
	v_lshl_add_u32 v45, v0, 2, v33
	v_add_u32_e32 v0, 12, v101
	v_and_b32_e32 v0, 15, v0
	v_lshl_add_u32 v46, v0, 2, v33
	v_add_u32_e32 v0, 13, v101
	v_and_b32_e32 v0, 15, v0
	v_lshl_add_u32 v47, v0, 2, v33
	v_add_u32_e32 v0, 14, v101
	v_and_b32_e32 v0, 15, v0
	v_lshl_add_u32 v48, v0, 2, v33
	v_add_u32_e32 v0, 15, v101
	v_and_b32_e32 v0, 15, v0
	v_lshl_add_u32 v49, v0, 2, v33
	ds_read_b32 v50, v34
	ds_read_b32 v51, v35
	ds_read_b32 v52, v36
	ds_read_b32 v53, v37
	ds_read_b32 v54, v38
	ds_read_b32 v55, v39
	ds_read_b32 v56, v40
	ds_read_b32 v57, v41
	ds_read_b32 v58, v42
	ds_read_b32 v59, v43
	ds_read_b32 v60, v44
	ds_read_b32 v61, v45
	ds_read_b32 v62, v46
	ds_read_b32 v63, v47
	ds_read_b32 v64, v48
	ds_read_b32 v65, v49
	s_waitcnt lgkmcnt(0)
	v_add3_u32 v66, v66, v50, v51
	v_add3_u32 v66, v66, v52, v53
	v_add3_u32 v66, v66, v54, v55
	v_add3_u32 v66, v66, v56, v57
	v_add3_u32 v66, v66, v58, v59
	v_add3_u32 v66, v66, v60, v61
	v_add3_u32 v66, v66, v62, v63
	v_add3_u32 v66, v66, v64, v65
	ds_read_b32 v50, v34 offset:4096
	ds_read_b32 v51, v35 offset:4096
	ds_read_b32 v52, v36 offset:4096
	ds_read_b32 v53, v37 offset:4096
	ds_read_b32 v54, v38 offset:4096
	ds_read_b32 v55, v39 offset:4096
	ds_read_b32 v56, v40 offset:4096
	ds_read_b32 v57, v41 offset:4096
	ds_read_b32 v58, v42 offset:4096
	ds_read_b32 v59, v43 offset:4096
	ds_read_b32 v60, v44 offset:4096
	ds_read_b32 v61, v45 offset:4096
	ds_read_b32 v62, v46 offset:4096
	ds_read_b32 v63, v47 offset:4096
	ds_read_b32 v64, v48 offset:4096
	ds_read_b32 v65, v49 offset:4096
	s_waitcnt lgkmcnt(0)
	v_add3_u32 v66, v66, v50, v51
	v_add3_u32 v66, v66, v52, v53
	v_add3_u32 v66, v66, v54, v55
	v_add3_u32 v66, v66, v56, v57
	v_add3_u32 v66, v66, v58, v59
	v_add3_u32 v66, v66, v60, v61
	v_add3_u32 v66, v66, v62, v63
	v_add3_u32 v66, v66, v64, v65
	ds_read_b32 v50, v34 offset:8192
	ds_read_b32 v51, v35 offset:8192
	ds_read_b32 v52, v36 offset:8192
	ds_read_b32 v53, v37 offset:8192
	ds_read_b32 v54, v38 offset:8192
	ds_read_b32 v55, v39 offset:8192
	ds_read_b32 v56, v40 offset:8192
	ds_read_b32 v57, v41 offset:8192
	ds_read_b32 v58, v42 offset:8192
	ds_read_b32 v59, v43 offset:8192
	ds_read_b32 v60, v44 offset:8192
	ds_read_b32 v61, v45 offset:8192
	ds_read_b32 v62, v46 offset:8192
	ds_read_b32 v63, v47 offset:8192
	ds_read_b32 v64, v48 offset:8192
	ds_read_b32 v65, v49 offset:8192
	s_waitcnt lgkmcnt(0)
	v_add3_u32 v66, v66, v50, v51
	v_add3_u32 v66, v66, v52, v53
	v_add3_u32 v66, v66, v54, v55
	v_add3_u32 v66, v66, v56, v57
	v_add3_u32 v66, v66, v58, v59
	v_add3_u32 v66, v66, v60, v61
	v_add3_u32 v66, v66, v62, v63
	v_add3_u32 v66, v66, v64, v65
	ds_read_b32 v50, v34 offset:12288
	ds_read_b32 v51, v35 offset:12288
	ds_read_b32 v52, v36 offset:12288
	ds_read_b32 v53, v37 offset:12288
	ds_read_b32 v54, v38 offset:12288
	ds_read_b32 v55, v39 offset:12288
	ds_read_b32 v56, v40 offset:12288
	ds_read_b32 v57, v41 offset:12288
	ds_read_b32 v58, v42 offset:12288
	ds_read_b32 v59, v43 offset:12288
	ds_read_b32 v60, v44 offset:12288
	ds_read_b32 v61, v45 offset:12288
	ds_read_b32 v62, v46 offset:12288
	ds_read_b32 v63, v47 offset:12288
	ds_read_b32 v64, v48 offset:12288
	ds_read_b32 v65, v49 offset:12288
	s_waitcnt lgkmcnt(0)
	v_add3_u32 v66, v66, v50, v51
	v_add3_u32 v66, v66, v52, v53
	v_add3_u32 v66, v66, v54, v55
	v_add3_u32 v66, v66, v56, v57
	v_add3_u32 v66, v66, v58, v59
	v_add3_u32 v66, v66, v60, v61
	v_add3_u32 v66, v66, v62, v63
	v_add3_u32 v66, v66, v64, v65
	s_nop 1
	v_add_u32_dpp v68, v66, v66 quad_perm:[1,0,3,2] row_mask:0xf bank_mask:0xf bound_ctrl:1
	v_cndmask_b32_e64 v67, v66, v68, s[16:17]
	s_nop 1
	v_mov_b32_dpp v69, v68 quad_perm:[2,3,0,1] row_mask:0xf bank_mask:0xf bound_ctrl:1
	v_add_u32_e32 v68, v68, v69
	v_cndmask_b32_e64 v70, 0, v69, s[18:19]
	v_add_u32_e32 v67, v67, v70
	s_nop 0
	v_mov_b32_dpp v69, v68 row_half_mirror row_mask:0xf bank_mask:0xf bound_ctrl:1
	v_add_u32_e32 v68, v68, v69
	v_cndmask_b32_e64 v70, 0, v69, s[20:21]
	v_add_u32_e32 v67, v67, v70
	s_nop 0
	v_mov_b32_dpp v69, v68 row_mirror row_mask:0xf bank_mask:0xf bound_ctrl:1
	v_add_u32_e32 v68, v68, v69
	v_cndmask_b32_e64 v70, 0, v69, s[22:23]
	v_add_u32_e32 v67, v67, v70
	v_mov_b32_e32 v71, v68
	v_mov_b32_e32 v72, v68
	s_nop 1
	v_permlane16_swap_b32_e32 v71, v72
	v_cndmask_b32_e64 v69, v71, v72, s[24:25]
	v_add_u32_e32 v68, v68, v69
	v_cndmask_b32_e64 v70, 0, v69, s[24:25]
	v_add_u32_e32 v67, v67, v70
	v_mov_b32_e32 v71, v68
	v_mov_b32_e32 v72, v68
	s_nop 1
	v_permlane32_swap_b32_e32 v71, v72
	v_cndmask_b32_e64 v69, v71, v72, s[26:27]
	v_cndmask_b32_e64 v70, 0, v69, s[26:27]
	v_add_u32_e32 v67, v67, v70
	v_cmp_le_u32_e64 s[30:31], s85, v67
	s_cmp_eq_u64 s[30:31], 0
	s_cbranch_scc1 .Ltk_scan_few_8
	s_flbit_i32_b64 s88, s[30:31]
	s_sub_i32 s88, 63, s88
	s_mov_b32 s90, 0
	s_cmp_eq_u32 s88, 63
	s_cbranch_scc1 .Ltk_noabove_10
	s_add_i32 s4, s88, 1
	s_nop 0
	v_readlane_b32 s90, v67, s4

; DI void topk_job(const Params& p, int b, int t0, char* lds) {
;     ...
; #pragma unroll
;       for (int i = 0; i < 17; ++i) {
; #pragma unroll
;         for (int q = 0; q < 4; ++q) {
;           const unsigned u = sc[i][q];
;           bool part; unsigned bin;
;           if (pass == 0) { part = (u != 0u); bin = (u >> 22) + (lane & 3) * 1024; }
;           else if (pass == 1) { part = (u != 0u) && ((u >> 22) == pref[q]) && !few[q]; bin = ((u >> 12) & 1023u) + (lane & 3) * 1024; }
;           else { part = (u != 0u) && ((u >> 12) == pref[q]) && !few[q]; bin = u & 4095u; }
;           if (part) atomicAdd(hist + q * 4096 + bin, 1u);
;         }
;       }
;     ...
;       for (int q = 0; q < 4; ++q) {
;         if (!few[q]) {
;           pref[q] = (pref[q] << (pass < 2 ? 10 : 12)) | (unsigned)sel[q * 4 + 0];
;           chi[q] = sel[q * 4 + 1];
;           nb[q] = sel[q * 4 + 3];
;           if (pass == 0) few[q] = sel[q * 4 + 2] != 0;
.Ltk_scan_end_7:
	s_waitcnt lgkmcnt(0)
	s_barrier
	ds_read_b128 v[4:7], v3 offset:512
	ds_read_b128 v[8:11], v3 offset:528
	s_waitcnt lgkmcnt(0)
	v_readfirstlane_b32 s8, v4
	v_readfirstlane_b32 s9, v6
	v_readfirstlane_b32 s10, v8
	v_readfirstlane_b32 s11, v10
	s_add_i32 s28, s2, 1
	s_cmp_gt_u32 s28, s3
	s_cbranch_scc1 .Ltk_p2_done_11
	v_lshrrev_b32_e32 v0, 12, v208
	v_cmp_eq_u32_e32 vcc, s8, v0
	v_and_b32_e32 v8, 0xfff, v208
	v_lshl_add_u32 v8, v8, 2, v29
	s_mov_b64 exec, vcc
	ds_add_u32 v8, v20
	s_mov_b64 exec, -1
	v_lshrrev_b32_e32 v1, 12, v175
	v_cmp_eq_u32_e32 vcc, s9, v1
	v_and_b32_e32 v9, 0xfff, v175
	v_lshl_add_u32 v9, v9, 2, v30
	s_mov_b64 exec, vcc
	ds_add_u32 v9, v20
	s_mov_b64 exec, -1
	v_lshrrev_b32_e32 v4, 12, v161
	v_cmp_eq_u32_e32 vcc, s10, v4
	v_and_b32_e32 v10, 0xfff, v161
	v_lshl_add_u32 v10, v10, 2, v31
	s_mov_b64 exec, vcc
	ds_add_u32 v10, v20
	s_mov_b64 exec, -1
	v_lshrrev_b32_e32 v5, 12, v138
	v_cmp_eq_u32_e32 vcc, s11, v5
	v_and_b32_e32 v11, 0xfff, v138
	v_lshl_add_u32 v11, v11, 2, v32
	s_mov_b64 exec, vcc
	ds_add_u32 v11, v20
	s_mov_b64 exec, -1
	s_add_i32 s28, s28, 8
	s_cmp_gt_u32 s28, s3
	s_cbranch_scc1 .Ltk_p2_done_11
	v_lshrrev_b32_e32 v0, 12, v207
	v_cmp_eq_u32_e32 vcc, s8, v0
	v_and_b32_e32 v8, 0xfff, v207
	v_lshl_add_u32 v8, v8, 2, v29
	s_mov_b64 exec, vcc
	ds_add_u32 v8, v20
	s_mov_b64 exec, -1
	v_lshrrev_b32_e32 v1, 12, v173
	v_cmp_eq_u32_e32 vcc, s9, v1
	v_and_b32_e32 v9, 0xfff, v173
	v_lshl_add_u32 v9, v9, 2, v30
	s_mov_b64 exec, vcc
	ds_add_u32 v9, v20
	s_mov_b64 exec, -1
	v_lshrrev_b32_e32 v4, 12, v159
	v_cmp_eq_u32_e32 vcc, s10, v4
	v_and_b32_e32 v10, 0xfff, v159
	v_lshl_add_u32 v10, v10, 2, v31
	s_mov_b64 exec, vcc
	ds_add_u32 v10, v20
	s_mov_b64 exec, -1
	v_lshrrev_b32_e32 v5, 12, v135
	v_cmp_eq_u32_e32 vcc, s11, v5
	v_and_b32_e32 v11, 0xfff, v135
	v_lshl_add_u32 v11, v11, 2, v32
	s_mov_b64 exec, vcc
	ds_add_u32 v11, v20
	s_mov_b64 exec, -1
	s_add_i32 s28, s28, 8
	s_cmp_gt_u32 s28, s3
	s_cbranch_scc1 .Ltk_p2_done_11
	v_lshrrev_b32_e32 v0, 12, v187
	v_cmp_eq_u32_e32 vcc, s8, v0
	v_and_b32_e32 v8, 0xfff, v187
	v_lshl_add_u32 v8, v8, 2, v29
	s_mov_b64 exec, vcc
	ds_add_u32 v8, v20
	s_mov_b64 exec, -1
	v_lshrrev_b32_e32 v1, 12, v172
	v_cmp_eq_u32_e32 vcc, s9, v1
	v_and_b32_e32 v9, 0xfff, v172
	v_lshl_add_u32 v9, v9, 2, v30
	s_mov_b64 exec, vcc
	ds_add_u32 v9, v20
	s_mov_b64 exec, -1
	v_lshrrev_b32_e32 v4, 12, v158
	v_cmp_eq_u32_e32 vcc, s10, v4
	v_and_b32_e32 v10, 0xfff, v158
	v_lshl_add_u32 v10, v10, 2, v31
	s_mov_b64 exec, vcc
	ds_add_u32 v10, v20
	s_mov_b64 exec, -1
	v_lshrrev_b32_e32 v5, 12, v133
	v_cmp_eq_u32_e32 vcc, s11, v5
	v_and_b32_e32 v11, 0xfff, v133
	v_lshl_add_u32 v11, v11, 2, v32
	s_mov_b64 exec, vcc
	ds_add_u32 v11, v20
	s_mov_b64 exec, -1
	s_add_i32 s28, s28, 8
	s_cmp_gt_u32 s28, s3
	s_cbranch_scc1 .Ltk_p2_done_11
	v_lshrrev_b32_e32 v0, 12, v186
	v_cmp_eq_u32_e32 vcc, s8, v0
	v_and_b32_e32 v8, 0xfff, v186
	v_lshl_add_u32 v8, v8, 2, v29
	s_mov_b64 exec, vcc
	ds_add_u32 v8, v20
	s_mov_b64 exec, -1
	v_lshrrev_b32_e32 v1, 12, v171
	v_cmp_eq_u32_e32 vcc, s9, v1
	v_and_b32_e32 v9, 0xfff, v171
	v_lshl_add_u32 v9, v9, 2, v30
	s_mov_b64 exec, vcc
	ds_add_u32 v9, v20
	s_mov_b64 exec, -1
	v_lshrrev_b32_e32 v4, 12, v153
	v_cmp_eq_u32_e32 vcc, s10, v4
	v_and_b32_e32 v10, 0xfff, v153
	v_lshl_add_u32 v10, v10, 2, v31
	s_mov_b64 exec, vcc
	ds_add_u32 v10, v20
	s_mov_b64 exec, -1
	v_lshrrev_b32_e32 v5, 12, v129
	v_cmp_eq_u32_e32 vcc, s11, v5
	v_and_b32_e32 v11, 0xfff, v129
	v_lshl_add_u32 v11, v11, 2, v32
	s_mov_b64 exec, vcc
	ds_add_u32 v11, v20
	s_mov_b64 exec, -1
	s_add_i32 s28, s28, 8
	s_cmp_gt_u32 s28, s3
	s_cbranch_scc1 .Ltk_p2_done_11
	v_lshrrev_b32_e32 v0, 12, v185
	v_cmp_eq_u32_e32 vcc, s8, v0
	v_and_b32_e32 v8, 0xfff, v185
	v_lshl_add_u32 v8, v8, 2, v29
	s_mov_b64 exec, vcc
	ds_add_u32 v8, v20
	s_mov_b64 exec, -1
	v_lshrrev_b32_e32 v1, 12, v170
	v_cmp_eq_u32_e32 vcc, s9, v1
	v_and_b32_e32 v9, 0xfff, v170
	v_lshl_add_u32 v9, v9, 2, v30
	s_mov_b64 exec, vcc
	ds_add_u32 v9, v20
	s_mov_b64 exec, -1
	v_lshrrev_b32_e32 v4, 12, v150
	v_cmp_eq_u32_e32 vcc, s10, v4
	v_and_b32_e32 v10, 0xfff, v150
	v_lshl_add_u32 v10, v10, 2, v31
	s_mov_b64 exec, vcc
	ds_add_u32 v10, v20
	s_mov_b64 exec, -1
	v_lshrrev_b32_e32 v5, 12, v127
	v_cmp_eq_u32_e32 vcc, s11, v5
	v_and_b32_e32 v11, 0xfff, v127
	v_lshl_add_u32 v11, v11, 2, v32
	s_mov_b64 exec, vcc
	ds_add_u32 v11, v20
	s_mov_b64 exec, -1
	s_add_i32 s28, s28, 8
	s_cmp_gt_u32 s28, s3
	s_cbranch_scc1 .Ltk_p2_done_11
	v_lshrrev_b32_e32 v0, 12, v184
	v_cmp_eq_u32_e32 vcc, s8, v0
	v_and_b32_e32 v8, 0xfff, v184
	v_lshl_add_u32 v8, v8, 2, v29
	s_mov_b64 exec, vcc
	ds_add_u32 v8, v20
	s_mov_b64 exec, -1
	v_lshrrev_b32_e32 v1, 12, v168
	v_cmp_eq_u32_e32 vcc, s9, v1
	v_and_b32_e32 v9, 0xfff, v168
	v_lshl_add_u32 v9, v9, 2, v30
	s_mov_b64 exec, vcc
	ds_add_u32 v9, v20
	s_mov_b64 exec, -1
	v_lshrrev_b32_e32 v4, 12, v149
	v_cmp_eq_u32_e32 vcc, s10, v4
	v_and_b32_e32 v10, 0xfff, v149
	v_lshl_add_u32 v10, v10, 2, v31
	s_mov_b64 exec, vcc
	ds_add_u32 v10, v20
	s_mov_b64 exec, -1
	v_lshrrev_b32_e32 v5, 12, v125
	v_cmp_eq_u32_e32 vcc, s11, v5
	v_and_b32_e32 v11, 0xfff, v125
	v_lshl_add_u32 v11, v11, 2, v32
	s_mov_b64 exec, vcc
	ds_add_u32 v11, v20
	s_mov_b64 exec, -1
	s_add_i32 s28, s28, 8
	s_cmp_gt_u32 s28, s3
	s_cbranch_scc1 .Ltk_p2_done_11
; DI void topk_job(const Params& p, int b, int t0, char* lds) {
;     ...
; #pragma unroll
;       for (int i = 0; i < 17; ++i) {
; #pragma unroll
;         for (int q = 0; q < 4; ++q) {
;           const unsigned u = sc[i][q];
;           bool part; unsigned bin;
;           if (pass == 0) { part = (u != 0u); bin = (u >> 22) + (lane & 3) * 1024; }
;           else if (pass == 1) { part = (u != 0u) && ((u >> 22) == pref[q]) && !few[q]; bin = ((u >> 12) & 1023u) + (lane & 3) * 1024; }
;           else { part = (u != 0u) && ((u >> 12) == pref[q]) && !few[q]; bin = u & 4095u; }
;           if (part) atomicAdd(hist + q * 4096 + bin, 1u);
;         }
;       }
	v_lshrrev_b32_e32 v0, 12, v183
	v_cmp_eq_u32_e32 vcc, s8, v0
	v_and_b32_e32 v8, 0xfff, v183
	v_lshl_add_u32 v8, v8, 2, v29
	s_mov_b64 exec, vcc
	ds_add_u32 v8, v20
	s_mov_b64 exec, -1
	v_lshrrev_b32_e32 v1, 12, v167
	v_cmp_eq_u32_e32 vcc, s9, v1
	v_and_b32_e32 v9, 0xfff, v167
	v_lshl_add_u32 v9, v9, 2, v30
	s_mov_b64 exec, vcc
	ds_add_u32 v9, v20
	s_mov_b64 exec, -1
	v_lshrrev_b32_e32 v4, 12, v147
	v_cmp_eq_u32_e32 vcc, s10, v4
	v_and_b32_e32 v10, 0xfff, v147
	v_lshl_add_u32 v10, v10, 2, v31
	s_mov_b64 exec, vcc
	ds_add_u32 v10, v20
	s_mov_b64 exec, -1
	v_lshrrev_b32_e32 v5, 12, v123
	v_cmp_eq_u32_e32 vcc, s11, v5
	v_and_b32_e32 v11, 0xfff, v123
	v_lshl_add_u32 v11, v11, 2, v32
	s_mov_b64 exec, vcc
	ds_add_u32 v11, v20
	s_mov_b64 exec, -1
	s_add_i32 s28, s28, 8
	s_cmp_gt_u32 s28, s3
	s_cbranch_scc1 .Ltk_p2_done_11
	v_lshrrev_b32_e32 v0, 12, v182
	v_cmp_eq_u32_e32 vcc, s8, v0
	v_and_b32_e32 v8, 0xfff, v182
	v_lshl_add_u32 v8, v8, 2, v29
	s_mov_b64 exec, vcc
	ds_add_u32 v8, v20
	s_mov_b64 exec, -1
	v_lshrrev_b32_e32 v1, 12, v166
	v_cmp_eq_u32_e32 vcc, s9, v1
	v_and_b32_e32 v9, 0xfff, v166
	v_lshl_add_u32 v9, v9, 2, v30
	s_mov_b64 exec, vcc
	ds_add_u32 v9, v20
	s_mov_b64 exec, -1
	v_lshrrev_b32_e32 v4, 12, v146
	v_cmp_eq_u32_e32 vcc, s10, v4
	v_and_b32_e32 v10, 0xfff, v146
	v_lshl_add_u32 v10, v10, 2, v31
	s_mov_b64 exec, vcc
	ds_add_u32 v10, v20
	s_mov_b64 exec, -1
	v_lshrrev_b32_e32 v5, 12, v121
	v_cmp_eq_u32_e32 vcc, s11, v5
	v_and_b32_e32 v11, 0xfff, v121
	v_lshl_add_u32 v11, v11, 2, v32
	s_mov_b64 exec, vcc
	ds_add_u32 v11, v20
	s_mov_b64 exec, -1
	s_add_i32 s28, s28, 8
	s_cmp_gt_u32 s28, s3
	s_cbranch_scc1 .Ltk_p2_done_11
	v_lshrrev_b32_e32 v0, 12, v181
	v_cmp_eq_u32_e32 vcc, s8, v0
	v_and_b32_e32 v8, 0xfff, v181
	v_lshl_add_u32 v8, v8, 2, v29
	s_mov_b64 exec, vcc
	ds_add_u32 v8, v20
	s_mov_b64 exec, -1
	v_lshrrev_b32_e32 v1, 12, v165
	v_cmp_eq_u32_e32 vcc, s9, v1
	v_and_b32_e32 v9, 0xfff, v165
	v_lshl_add_u32 v9, v9, 2, v30
	s_mov_b64 exec, vcc
	ds_add_u32 v9, v20
	s_mov_b64 exec, -1
	v_lshrrev_b32_e32 v4, 12, v145
	v_cmp_eq_u32_e32 vcc, s10, v4
	v_and_b32_e32 v10, 0xfff, v145
	v_lshl_add_u32 v10, v10, 2, v31
	s_mov_b64 exec, vcc
	ds_add_u32 v10, v20
	s_mov_b64 exec, -1
	v_lshrrev_b32_e32 v5, 12, v119
	v_cmp_eq_u32_e32 vcc, s11, v5
	v_and_b32_e32 v11, 0xfff, v119
	v_lshl_add_u32 v11, v11, 2, v32
	s_mov_b64 exec, vcc
	ds_add_u32 v11, v20
	s_mov_b64 exec, -1
	s_add_i32 s28, s28, 8
	s_cmp_gt_u32 s28, s3
	s_cbranch_scc1 .Ltk_p2_done_11
	v_lshrrev_b32_e32 v0, 12, v180
	v_cmp_eq_u32_e32 vcc, s8, v0
	v_and_b32_e32 v8, 0xfff, v180
	v_lshl_add_u32 v8, v8, 2, v29
	s_mov_b64 exec, vcc
	ds_add_u32 v8, v20
	s_mov_b64 exec, -1
	v_lshrrev_b32_e32 v1, 12, v164
	v_cmp_eq_u32_e32 vcc, s9, v1
	v_and_b32_e32 v9, 0xfff, v164
	v_lshl_add_u32 v9, v9, 2, v30
	s_mov_b64 exec, vcc
	ds_add_u32 v9, v20
	s_mov_b64 exec, -1
	v_lshrrev_b32_e32 v4, 12, v143
	v_cmp_eq_u32_e32 vcc, s10, v4
	v_and_b32_e32 v10, 0xfff, v143
	v_lshl_add_u32 v10, v10, 2, v31
	s_mov_b64 exec, vcc
	ds_add_u32 v10, v20
	s_mov_b64 exec, -1
	v_lshrrev_b32_e32 v5, 12, v115
	v_cmp_eq_u32_e32 vcc, s11, v5
	v_and_b32_e32 v11, 0xfff, v115
	v_lshl_add_u32 v11, v11, 2, v32
	s_mov_b64 exec, vcc
	ds_add_u32 v11, v20
	s_mov_b64 exec, -1
	s_add_i32 s28, s28, 8
	s_cmp_gt_u32 s28, s3
	s_cbranch_scc1 .Ltk_p2_done_11
	v_lshrrev_b32_e32 v0, 12, v179
	v_cmp_eq_u32_e32 vcc, s8, v0
	v_and_b32_e32 v8, 0xfff, v179
	v_lshl_add_u32 v8, v8, 2, v29
	s_mov_b64 exec, vcc
	ds_add_u32 v8, v20
	s_mov_b64 exec, -1
	v_lshrrev_b32_e32 v1, 12, v163
	v_cmp_eq_u32_e32 vcc, s9, v1
	v_and_b32_e32 v9, 0xfff, v163
	v_lshl_add_u32 v9, v9, 2, v30
	s_mov_b64 exec, vcc
	ds_add_u32 v9, v20
	s_mov_b64 exec, -1
	v_lshrrev_b32_e32 v4, 12, v142
	v_cmp_eq_u32_e32 vcc, s10, v4
	v_and_b32_e32 v10, 0xfff, v142
	v_lshl_add_u32 v10, v10, 2, v31
	s_mov_b64 exec, vcc
	ds_add_u32 v10, v20
	s_mov_b64 exec, -1
	v_lshrrev_b32_e32 v5, 12, v113
	v_cmp_eq_u32_e32 vcc, s11, v5
	v_and_b32_e32 v11, 0xfff, v113
	v_lshl_add_u32 v11, v11, 2, v32
	s_mov_b64 exec, vcc
	ds_add_u32 v11, v20
	s_mov_b64 exec, -1
	s_add_i32 s28, s28, 8
	s_cmp_gt_u32 s28, s3
	s_cbranch_scc1 .Ltk_p2_done_11
	v_lshrrev_b32_e32 v0, 12, v178
	v_cmp_eq_u32_e32 vcc, s8, v0
	v_and_b32_e32 v8, 0xfff, v178
	v_lshl_add_u32 v8, v8, 2, v29
	s_mov_b64 exec, vcc
	ds_add_u32 v8, v20
	s_mov_b64 exec, -1
	v_lshrrev_b32_e32 v1, 12, v162
	v_cmp_eq_u32_e32 vcc, s9, v1
	v_and_b32_e32 v9, 0xfff, v162
	v_lshl_add_u32 v9, v9, 2, v30
	s_mov_b64 exec, vcc
	ds_add_u32 v9, v20
	s_mov_b64 exec, -1
	v_lshrrev_b32_e32 v4, 12, v141
	v_cmp_eq_u32_e32 vcc, s10, v4
	v_and_b32_e32 v10, 0xfff, v141
	v_lshl_add_u32 v10, v10, 2, v31
	s_mov_b64 exec, vcc
	ds_add_u32 v10, v20
	s_mov_b64 exec, -1
	v_lshrrev_b32_e32 v5, 12, v111
	v_cmp_eq_u32_e32 vcc, s11, v5
	v_and_b32_e32 v11, 0xfff, v111
	v_lshl_add_u32 v11, v11, 2, v32
	s_mov_b64 exec, vcc
	ds_add_u32 v11, v20
	s_mov_b64 exec, -1
	s_add_i32 s28, s28, 8
	s_cmp_gt_u32 s28, s3
	s_cbranch_scc1 .Ltk_p2_done_11
	v_lshrrev_b32_e32 v0, 12, v177
	v_cmp_eq_u32_e32 vcc, s8, v0
	v_and_b32_e32 v8, 0xfff, v177
	v_lshl_add_u32 v8, v8, 2, v29
	s_mov_b64 exec, vcc
	ds_add_u32 v8, v20
	s_mov_b64 exec, -1
	v_lshrrev_b32_e32 v1, 12, v160
	v_cmp_eq_u32_e32 vcc, s9, v1
	v_and_b32_e32 v9, 0xfff, v160
	v_lshl_add_u32 v9, v9, 2, v30
	s_mov_b64 exec, vcc
	ds_add_u32 v9, v20
	s_mov_b64 exec, -1
	v_lshrrev_b32_e32 v4, 12, v140
	v_cmp_eq_u32_e32 vcc, s10, v4
	v_and_b32_e32 v10, 0xfff, v140
	v_lshl_add_u32 v10, v10, 2, v31
	s_mov_b64 exec, vcc
	ds_add_u32 v10, v20
	s_mov_b64 exec, -1
	v_lshrrev_b32_e32 v5, 12, v109
	v_cmp_eq_u32_e32 vcc, s11, v5
	v_and_b32_e32 v11, 0xfff, v109
	v_lshl_add_u32 v11, v11, 2, v32
	s_mov_b64 exec, vcc
	ds_add_u32 v11, v20
	s_mov_b64 exec, -1
	s_add_i32 s28, s28, 8
	s_cmp_gt_u32 s28, s3
	s_cbranch_scc1 .Ltk_p2_done_11
; DI void topk_job(const Params& p, int b, int t0, char* lds) {
;     ...
; #pragma unroll
;       for (int i = 0; i < 17; ++i) {
; #pragma unroll
;         for (int q = 0; q < 4; ++q) {
;           const unsigned u = sc[i][q];
;           bool part; unsigned bin;
;           if (pass == 0) { part = (u != 0u); bin = (u >> 22) + (lane & 3) * 1024; }
;           else if (pass == 1) { part = (u != 0u) && ((u >> 22) == pref[q]) && !few[q]; bin = ((u >> 12) & 1023u) + (lane & 3) * 1024; }
;           else { part = (u != 0u) && ((u >> 12) == pref[q]) && !few[q]; bin = u & 4095u; }
;           if (part) atomicAdd(hist + q * 4096 + bin, 1u);
;         }
;       }
;       __syncthreads();
;       if (w < 4) {
;         const int q = w;
;         const unsigned* hq = hist + q * 4096;
;         const int need = 256 - chi[q];
;         int G = 0;
;         if (pass < 2) {
; #pragma unroll
;           for (int rep = 0; rep < 4; ++rep)
; #pragma unroll
;             for (int j = 0; j < 16; ++j) G += (int)hq[rep * 1024 + 16 * lane + ((j + lane) & 15)];
;         } else {
; #pragma unroll 8
;           for (int j = 0; j < 64; ++j) G += (int)hq[64 * lane + ((j + lane) & 63)];
;         }
;         int S = G;
	v_lshrrev_b32_e32 v0, 12, v176
	v_cmp_eq_u32_e32 vcc, s8, v0
	v_and_b32_e32 v8, 0xfff, v176
	v_lshl_add_u32 v8, v8, 2, v29
	s_mov_b64 exec, vcc
	ds_add_u32 v8, v20
	s_mov_b64 exec, -1
	v_lshrrev_b32_e32 v1, 12, v151
	v_cmp_eq_u32_e32 vcc, s9, v1
	v_and_b32_e32 v9, 0xfff, v151
	v_lshl_add_u32 v9, v9, 2, v30
	s_mov_b64 exec, vcc
	ds_add_u32 v9, v20
	s_mov_b64 exec, -1
	v_lshrrev_b32_e32 v4, 12, v139
	v_cmp_eq_u32_e32 vcc, s10, v4
	v_and_b32_e32 v10, 0xfff, v139
	v_lshl_add_u32 v10, v10, 2, v31
	s_mov_b64 exec, vcc
	ds_add_u32 v10, v20
	s_mov_b64 exec, -1
	v_lshrrev_b32_e32 v5, 12, v107
	v_cmp_eq_u32_e32 vcc, s11, v5
	v_and_b32_e32 v11, 0xfff, v107
	v_lshl_add_u32 v11, v11, 2, v32
	s_mov_b64 exec, vcc
	ds_add_u32 v11, v20
	s_mov_b64 exec, -1
	s_add_i32 s28, s28, 8
	s_cmp_gt_u32 s28, s3
	s_cbranch_scc1 .Ltk_p2_done_11
	v_lshrrev_b32_e32 v0, 12, v174
	v_cmp_eq_u32_e32 vcc, s8, v0
	v_and_b32_e32 v8, 0xfff, v174
	v_lshl_add_u32 v8, v8, 2, v29
	s_mov_b64 exec, vcc
	ds_add_u32 v8, v20
	s_mov_b64 exec, -1
	v_lshrrev_b32_e32 v1, 12, v148
	v_cmp_eq_u32_e32 vcc, s9, v1
	v_and_b32_e32 v9, 0xfff, v148
	v_lshl_add_u32 v9, v9, 2, v30
	s_mov_b64 exec, vcc
	ds_add_u32 v9, v20
	s_mov_b64 exec, -1
	v_lshrrev_b32_e32 v4, 12, v131
	v_cmp_eq_u32_e32 vcc, s10, v4
	v_and_b32_e32 v10, 0xfff, v131
	v_lshl_add_u32 v10, v10, 2, v31
	s_mov_b64 exec, vcc
	ds_add_u32 v10, v20
	s_mov_b64 exec, -1
	v_lshrrev_b32_e32 v5, 12, v105
	v_cmp_eq_u32_e32 vcc, s11, v5
	v_and_b32_e32 v11, 0xfff, v105
	v_lshl_add_u32 v11, v11, 2, v32
	s_mov_b64 exec, vcc
	ds_add_u32 v11, v20
	s_mov_b64 exec, -1
	s_add_i32 s28, s28, 8
	s_cmp_gt_u32 s28, s3
	s_cbranch_scc1 .Ltk_p2_done_11
	v_lshrrev_b32_e32 v0, 12, v169
	v_cmp_eq_u32_e32 vcc, s8, v0
	v_and_b32_e32 v8, 0xfff, v169
	v_lshl_add_u32 v8, v8, 2, v29
	s_mov_b64 exec, vcc
	ds_add_u32 v8, v20
	s_mov_b64 exec, -1
	v_lshrrev_b32_e32 v1, 12, v144
	v_cmp_eq_u32_e32 vcc, s9, v1
	v_and_b32_e32 v9, 0xfff, v144
	v_lshl_add_u32 v9, v9, 2, v30
	s_mov_b64 exec, vcc
	ds_add_u32 v9, v20
	s_mov_b64 exec, -1
	v_lshrrev_b32_e32 v4, 12, v117
	v_cmp_eq_u32_e32 vcc, s10, v4
	v_and_b32_e32 v10, 0xfff, v117
	v_lshl_add_u32 v10, v10, 2, v31
	s_mov_b64 exec, vcc
	ds_add_u32 v10, v20
	s_mov_b64 exec, -1
	v_lshrrev_b32_e32 v5, 12, v103
	v_cmp_eq_u32_e32 vcc, s11, v5
	v_and_b32_e32 v11, 0xfff, v103
	v_lshl_add_u32 v11, v11, 2, v32
	s_mov_b64 exec, vcc
	ds_add_u32 v11, v20
	s_mov_b64 exec, -1
	s_add_i32 s28, s28, 8
	s_cmp_gt_u32 s28, s3
	s_cbranch_scc1 .Ltk_p2_done_11
	v_lshrrev_b32_e32 v0, 12, v19
	v_cmp_eq_u32_e32 vcc, s8, v0
	v_and_b32_e32 v8, 0xfff, v19
	v_lshl_add_u32 v8, v8, 2, v29
	s_mov_b64 exec, vcc
	ds_add_u32 v8, v20
	s_mov_b64 exec, -1
	v_lshrrev_b32_e32 v1, 12, v18
	v_cmp_eq_u32_e32 vcc, s9, v1
	v_and_b32_e32 v9, 0xfff, v18
	v_lshl_add_u32 v9, v9, 2, v30
	s_mov_b64 exec, vcc
	ds_add_u32 v9, v20
	s_mov_b64 exec, -1
	v_lshrrev_b32_e32 v4, 12, v17
	v_cmp_eq_u32_e32 vcc, s10, v4
	v_and_b32_e32 v10, 0xfff, v17
	v_lshl_add_u32 v10, v10, 2, v31
	s_mov_b64 exec, vcc
	ds_add_u32 v10, v20
	s_mov_b64 exec, -1
	v_lshrrev_b32_e32 v5, 12, v16
	v_cmp_eq_u32_e32 vcc, s11, v5
	v_and_b32_e32 v11, 0xfff, v16
	v_lshl_add_u32 v11, v11, 2, v32
	s_mov_b64 exec, vcc
	ds_add_u32 v11, v20
	s_mov_b64 exec, -1
.Ltk_p2_done_11:
	s_waitcnt lgkmcnt(0)
	s_barrier
	s_cmp_gt_u32 s2, 3
	s_cbranch_scc1 .Ltk_scan_end_12
	s_lshl_b32 s84, s2, 14
	s_add_i32 s84, s84, 0x4000
	s_cmp_eq_u32 s56, 1
	s_cbranch_scc1 .Ltk_scan_few_13
	v_lshlrev_b32_e32 v33, 8, v101
	v_add_u32_e32 v33, s84, v33
	v_mov_b32_e32 v66, 0
	v_add_u32_e32 v0, 0, v101
	v_and_b32_e32 v0, 63, v0
	v_lshl_add_u32 v34, v0, 2, v33
	ds_read_b32 v50, v34
	v_add_u32_e32 v0, 1, v101
	v_and_b32_e32 v0, 63, v0
	v_lshl_add_u32 v35, v0, 2, v33
	ds_read_b32 v51, v35
	v_add_u32_e32 v0, 2, v101
	v_and_b32_e32 v0, 63, v0
	v_lshl_add_u32 v36, v0, 2, v33
	ds_read_b32 v52, v36
	v_add_u32_e32 v0, 3, v101
	v_and_b32_e32 v0, 63, v0
	v_lshl_add_u32 v37, v0, 2, v33
	ds_read_b32 v53, v37
	v_add_u32_e32 v0, 4, v101
	v_and_b32_e32 v0, 63, v0
	v_lshl_add_u32 v38, v0, 2, v33
	ds_read_b32 v54, v38
	v_add_u32_e32 v0, 5, v101
	v_and_b32_e32 v0, 63, v0
	v_lshl_add_u32 v39, v0, 2, v33
	ds_read_b32 v55, v39
	v_add_u32_e32 v0, 6, v101
	v_and_b32_e32 v0, 63, v0
	v_lshl_add_u32 v40, v0, 2, v33
	ds_read_b32 v56, v40
	v_add_u32_e32 v0, 7, v101
	v_and_b32_e32 v0, 63, v0
	v_lshl_add_u32 v41, v0, 2, v33
	ds_read_b32 v57, v41
	v_add_u32_e32 v0, 8, v101
	v_and_b32_e32 v0, 63, v0
	v_lshl_add_u32 v42, v0, 2, v33
	ds_read_b32 v58, v42
	v_add_u32_e32 v0, 9, v101
	v_and_b32_e32 v0, 63, v0
	v_lshl_add_u32 v43, v0, 2, v33
	ds_read_b32 v59, v43
	v_add_u32_e32 v0, 10, v101
	v_and_b32_e32 v0, 63, v0
	v_lshl_add_u32 v44, v0, 2, v33
	ds_read_b32 v60, v44
	v_add_u32_e32 v0, 11, v101
	v_and_b32_e32 v0, 63, v0
	v_lshl_add_u32 v45, v0, 2, v33
	ds_read_b32 v61, v45
	v_add_u32_e32 v0, 12, v101
	v_and_b32_e32 v0, 63, v0
	v_lshl_add_u32 v46, v0, 2, v33
	ds_read_b32 v62, v46
	v_add_u32_e32 v0, 13, v101
	v_and_b32_e32 v0, 63, v0
	v_lshl_add_u32 v47, v0, 2, v33
	ds_read_b32 v63, v47
	v_add_u32_e32 v0, 14, v101
	v_and_b32_e32 v0, 63, v0
	v_lshl_add_u32 v48, v0, 2, v33
	ds_read_b32 v64, v48
	v_add_u32_e32 v0, 15, v101
	v_and_b32_e32 v0, 63, v0
	v_lshl_add_u32 v49, v0, 2, v33
	ds_read_b32 v65, v49
	s_waitcnt lgkmcnt(0)
; DI void topk_job(const Params& p, int b, int t0, char* lds) {
;     ...
;         } else {
; #pragma unroll 8
;           for (int j = 0; j < 64; ++j) G += (int)hq[64 * lane + ((j + lane) & 63)];
;         }
	v_add3_u32 v66, v66, v50, v51
	v_add3_u32 v66, v66, v52, v53
	v_add3_u32 v66, v66, v54, v55
	v_add3_u32 v66, v66, v56, v57
	v_add3_u32 v66, v66, v58, v59
	v_add3_u32 v66, v66, v60, v61
	v_add3_u32 v66, v66, v62, v63
	v_add3_u32 v66, v66, v64, v65
	v_add_u32_e32 v0, 16, v101
	v_and_b32_e32 v0, 63, v0
	v_lshl_add_u32 v34, v0, 2, v33
	ds_read_b32 v50, v34
	v_add_u32_e32 v0, 17, v101
	v_and_b32_e32 v0, 63, v0
	v_lshl_add_u32 v35, v0, 2, v33
	ds_read_b32 v51, v35
	v_add_u32_e32 v0, 18, v101
	v_and_b32_e32 v0, 63, v0
	v_lshl_add_u32 v36, v0, 2, v33
	ds_read_b32 v52, v36
	v_add_u32_e32 v0, 19, v101
	v_and_b32_e32 v0, 63, v0
	v_lshl_add_u32 v37, v0, 2, v33
	ds_read_b32 v53, v37
	v_add_u32_e32 v0, 20, v101
	v_and_b32_e32 v0, 63, v0
	v_lshl_add_u32 v38, v0, 2, v33
	ds_read_b32 v54, v38
	v_add_u32_e32 v0, 21, v101
	v_and_b32_e32 v0, 63, v0
	v_lshl_add_u32 v39, v0, 2, v33
	ds_read_b32 v55, v39
	v_add_u32_e32 v0, 22, v101
	v_and_b32_e32 v0, 63, v0
	v_lshl_add_u32 v40, v0, 2, v33
	ds_read_b32 v56, v40
	v_add_u32_e32 v0, 23, v101
	v_and_b32_e32 v0, 63, v0
	v_lshl_add_u32 v41, v0, 2, v33
	ds_read_b32 v57, v41
	v_add_u32_e32 v0, 24, v101
	v_and_b32_e32 v0, 63, v0
	v_lshl_add_u32 v42, v0, 2, v33
	ds_read_b32 v58, v42
	v_add_u32_e32 v0, 25, v101
	v_and_b32_e32 v0, 63, v0
	v_lshl_add_u32 v43, v0, 2, v33
	ds_read_b32 v59, v43
	v_add_u32_e32 v0, 26, v101
	v_and_b32_e32 v0, 63, v0
	v_lshl_add_u32 v44, v0, 2, v33
	ds_read_b32 v60, v44
	v_add_u32_e32 v0, 27, v101
	v_and_b32_e32 v0, 63, v0
	v_lshl_add_u32 v45, v0, 2, v33
	ds_read_b32 v61, v45
	v_add_u32_e32 v0, 28, v101
	v_and_b32_e32 v0, 63, v0
	v_lshl_add_u32 v46, v0, 2, v33
	ds_read_b32 v62, v46
	v_add_u32_e32 v0, 29, v101
	v_and_b32_e32 v0, 63, v0
	v_lshl_add_u32 v47, v0, 2, v33
	ds_read_b32 v63, v47
	v_add_u32_e32 v0, 30, v101
	v_and_b32_e32 v0, 63, v0
	v_lshl_add_u32 v48, v0, 2, v33
	ds_read_b32 v64, v48
	v_add_u32_e32 v0, 31, v101
	v_and_b32_e32 v0, 63, v0
	v_lshl_add_u32 v49, v0, 2, v33
	ds_read_b32 v65, v49
	s_waitcnt lgkmcnt(0)
	v_add3_u32 v66, v66, v50, v51
	v_add3_u32 v66, v66, v52, v53
	v_add3_u32 v66, v66, v54, v55
	v_add3_u32 v66, v66, v56, v57
	v_add3_u32 v66, v66, v58, v59
	v_add3_u32 v66, v66, v60, v61
	v_add3_u32 v66, v66, v62, v63
	v_add3_u32 v66, v66, v64, v65
	v_add_u32_e32 v0, 32, v101
	v_and_b32_e32 v0, 63, v0
	v_lshl_add_u32 v34, v0, 2, v33
	ds_read_b32 v50, v34
	v_add_u32_e32 v0, 33, v101
	v_and_b32_e32 v0, 63, v0
	v_lshl_add_u32 v35, v0, 2, v33
	ds_read_b32 v51, v35
	v_add_u32_e32 v0, 34, v101
	v_and_b32_e32 v0, 63, v0
	v_lshl_add_u32 v36, v0, 2, v33
	ds_read_b32 v52, v36
	v_add_u32_e32 v0, 35, v101
	v_and_b32_e32 v0, 63, v0
	v_lshl_add_u32 v37, v0, 2, v33
	ds_read_b32 v53, v37
	v_add_u32_e32 v0, 36, v101
	v_and_b32_e32 v0, 63, v0
	v_lshl_add_u32 v38, v0, 2, v33
	ds_read_b32 v54, v38
	v_add_u32_e32 v0, 37, v101
	v_and_b32_e32 v0, 63, v0
	v_lshl_add_u32 v39, v0, 2, v33
	ds_read_b32 v55, v39
	v_add_u32_e32 v0, 38, v101
	v_and_b32_e32 v0, 63, v0
	v_lshl_add_u32 v40, v0, 2, v33
	ds_read_b32 v56, v40
	v_add_u32_e32 v0, 39, v101
	v_and_b32_e32 v0, 63, v0
	v_lshl_add_u32 v41, v0, 2, v33
	ds_read_b32 v57, v41
	v_add_u32_e32 v0, 40, v101
	v_and_b32_e32 v0, 63, v0
	v_lshl_add_u32 v42, v0, 2, v33
	ds_read_b32 v58, v42
	v_add_u32_e32 v0, 41, v101
	v_and_b32_e32 v0, 63, v0
	v_lshl_add_u32 v43, v0, 2, v33
	ds_read_b32 v59, v43
	v_add_u32_e32 v0, 42, v101
	v_and_b32_e32 v0, 63, v0
	v_lshl_add_u32 v44, v0, 2, v33
	ds_read_b32 v60, v44
	v_add_u32_e32 v0, 43, v101
	v_and_b32_e32 v0, 63, v0
	v_lshl_add_u32 v45, v0, 2, v33
	ds_read_b32 v61, v45
	v_add_u32_e32 v0, 44, v101
	v_and_b32_e32 v0, 63, v0
	v_lshl_add_u32 v46, v0, 2, v33
	ds_read_b32 v62, v46
	v_add_u32_e32 v0, 45, v101
	v_and_b32_e32 v0, 63, v0
	v_lshl_add_u32 v47, v0, 2, v33
	ds_read_b32 v63, v47
	v_add_u32_e32 v0, 46, v101
	v_and_b32_e32 v0, 63, v0
	v_lshl_add_u32 v48, v0, 2, v33
	ds_read_b32 v64, v48
	v_add_u32_e32 v0, 47, v101
	v_and_b32_e32 v0, 63, v0
	v_lshl_add_u32 v49, v0, 2, v33
	ds_read_b32 v65, v49
	s_waitcnt lgkmcnt(0)
; DI void topk_job(const Params& p, int b, int t0, char* lds) {
;     ...
;         } else {
; #pragma unroll 8
;           for (int j = 0; j < 64; ++j) G += (int)hq[64 * lane + ((j + lane) & 63)];
;         }
;         int S = G;
;         { int tt; S = wscan<false>(S, lane, tt); }
;         const unsigned long long mk = __ballot(S >= need);
;         int B = 0, cg2 = 0, fw = 0, nbin = 0;
;         if (mk == 0ull) {
;           fw = 1;
;         } else {
;           const int ks = 63 - __clzll(mk);
;           const int above = (ks < 63) ? __builtin_amdgcn_readlane(S, ks + 1) : 0;
;           int hh;
;           if (pass < 2) {
;             hh = 0;
;             if (lane < 16) hh = (int)(hq[16 * ks + lane] + hq[1024 + 16 * ks + lane] + hq[2048 + 16 * ks + lane] + hq[3072 + 16 * ks + lane]);
;           } else {
;             hh = (int)hq[64 * ks + lane];
;           }
;           int s2 = hh;
;           { int tt; s2 = wscan<false>(s2, lane, tt); }
;           const unsigned long long m2 = __ballot(above + s2 >= need);
;           const int Ls = 63 - __clzll(m2);
;           B = (pass < 2 ? 16 : 64) * ks + Ls;
;           nbin = __builtin_amdgcn_readlane(hh, Ls);
;           cg2 = above + __builtin_amdgcn_readlane(s2, Ls) - nbin;
;         }
;         if (lane == 0) { sel[q * 4 + 0] = B; sel[q * 4 + 1] = chi[q] + cg2; sel[q * 4 + 2] = fw; sel[q * 4 + 3] = nbin; }
;       }
;       __syncthreads();
; #pragma unroll
;       for (int q = 0; q < 4; ++q) {
;         if (!few[q]) {
;           pref[q] = (pref[q] << (pass < 2 ? 10 : 12)) | (unsigned)sel[q * 4 + 0];
;           chi[q] = sel[q * 4 + 1];
;           nb[q] = sel[q * 4 + 3];
;           if (pass == 0) few[q] = sel[q * 4 + 2] != 0;
	v_add3_u32 v66, v66, v50, v51
	v_add3_u32 v66, v66, v52, v53
	v_add3_u32 v66, v66, v54, v55
	v_add3_u32 v66, v66, v56, v57
	v_add3_u32 v66, v66, v58, v59
	v_add3_u32 v66, v66, v60, v61
	v_add3_u32 v66, v66, v62, v63
	v_add3_u32 v66, v66, v64, v65
	v_add_u32_e32 v0, 48, v101
	v_and_b32_e32 v0, 63, v0
	v_lshl_add_u32 v34, v0, 2, v33
	ds_read_b32 v50, v34
	v_add_u32_e32 v0, 49, v101
	v_and_b32_e32 v0, 63, v0
	v_lshl_add_u32 v35, v0, 2, v33
	ds_read_b32 v51, v35
	v_add_u32_e32 v0, 50, v101
	v_and_b32_e32 v0, 63, v0
	v_lshl_add_u32 v36, v0, 2, v33
	ds_read_b32 v52, v36
	v_add_u32_e32 v0, 51, v101
	v_and_b32_e32 v0, 63, v0
	v_lshl_add_u32 v37, v0, 2, v33
	ds_read_b32 v53, v37
	v_add_u32_e32 v0, 52, v101
	v_and_b32_e32 v0, 63, v0
	v_lshl_add_u32 v38, v0, 2, v33
	ds_read_b32 v54, v38
	v_add_u32_e32 v0, 53, v101
	v_and_b32_e32 v0, 63, v0
	v_lshl_add_u32 v39, v0, 2, v33
	ds_read_b32 v55, v39
	v_add_u32_e32 v0, 54, v101
	v_and_b32_e32 v0, 63, v0
	v_lshl_add_u32 v40, v0, 2, v33
	ds_read_b32 v56, v40
	v_add_u32_e32 v0, 55, v101
	v_and_b32_e32 v0, 63, v0
	v_lshl_add_u32 v41, v0, 2, v33
	ds_read_b32 v57, v41
	v_add_u32_e32 v0, 56, v101
	v_and_b32_e32 v0, 63, v0
	v_lshl_add_u32 v42, v0, 2, v33
	ds_read_b32 v58, v42
	v_add_u32_e32 v0, 57, v101
	v_and_b32_e32 v0, 63, v0
	v_lshl_add_u32 v43, v0, 2, v33
	ds_read_b32 v59, v43
	v_add_u32_e32 v0, 58, v101
	v_and_b32_e32 v0, 63, v0
	v_lshl_add_u32 v44, v0, 2, v33
	ds_read_b32 v60, v44
	v_add_u32_e32 v0, 59, v101
	v_and_b32_e32 v0, 63, v0
	v_lshl_add_u32 v45, v0, 2, v33
	ds_read_b32 v61, v45
	v_add_u32_e32 v0, 60, v101
	v_and_b32_e32 v0, 63, v0
	v_lshl_add_u32 v46, v0, 2, v33
	ds_read_b32 v62, v46
	v_add_u32_e32 v0, 61, v101
	v_and_b32_e32 v0, 63, v0
	v_lshl_add_u32 v47, v0, 2, v33
	ds_read_b32 v63, v47
	v_add_u32_e32 v0, 62, v101
	v_and_b32_e32 v0, 63, v0
	v_lshl_add_u32 v48, v0, 2, v33
	ds_read_b32 v64, v48
	v_add_u32_e32 v0, 63, v101
	v_and_b32_e32 v0, 63, v0
	v_lshl_add_u32 v49, v0, 2, v33
	ds_read_b32 v65, v49
	s_waitcnt lgkmcnt(0)
	v_add3_u32 v66, v66, v50, v51
	v_add3_u32 v66, v66, v52, v53
	v_add3_u32 v66, v66, v54, v55
	v_add3_u32 v66, v66, v56, v57
	v_add3_u32 v66, v66, v58, v59
	v_add3_u32 v66, v66, v60, v61
	v_add3_u32 v66, v66, v62, v63
	v_add3_u32 v66, v66, v64, v65
	s_nop 1
	v_add_u32_dpp v68, v66, v66 quad_perm:[1,0,3,2] row_mask:0xf bank_mask:0xf bound_ctrl:1
	v_cndmask_b32_e64 v67, v66, v68, s[16:17]
	s_nop 1
	v_mov_b32_dpp v69, v68 quad_perm:[2,3,0,1] row_mask:0xf bank_mask:0xf bound_ctrl:1
	v_add_u32_e32 v68, v68, v69
	v_cndmask_b32_e64 v70, 0, v69, s[18:19]
	v_add_u32_e32 v67, v67, v70
	s_nop 0
	v_mov_b32_dpp v69, v68 row_half_mirror row_mask:0xf bank_mask:0xf bound_ctrl:1
	v_add_u32_e32 v68, v68, v69
	v_cndmask_b32_e64 v70, 0, v69, s[20:21]
	v_add_u32_e32 v67, v67, v70
	s_nop 0
	v_mov_b32_dpp v69, v68 row_mirror row_mask:0xf bank_mask:0xf bound_ctrl:1
	v_add_u32_e32 v68, v68, v69
	v_cndmask_b32_e64 v70, 0, v69, s[22:23]
	v_add_u32_e32 v67, v67, v70
	v_mov_b32_e32 v71, v68
	v_mov_b32_e32 v72, v68
	s_nop 1
	v_permlane16_swap_b32_e32 v71, v72
	v_cndmask_b32_e64 v69, v71, v72, s[24:25]
	v_add_u32_e32 v68, v68, v69
	v_cndmask_b32_e64 v70, 0, v69, s[24:25]
	v_add_u32_e32 v67, v67, v70
	v_mov_b32_e32 v71, v68
	v_mov_b32_e32 v72, v68
	s_nop 1
	v_permlane32_swap_b32_e32 v71, v72
	v_cndmask_b32_e64 v69, v71, v72, s[26:27]
	v_cndmask_b32_e64 v70, 0, v69, s[26:27]
	v_add_u32_e32 v67, v67, v70
	v_cmp_le_u32_e64 s[30:31], s85, v67
	s_cmp_eq_u64 s[30:31], 0
	s_cbranch_scc1 .Ltk_scan_few_13
	s_flbit_i32_b64 s88, s[30:31]
	s_sub_i32 s88, 63, s88
	s_mov_b32 s90, 0
	s_cmp_eq_u32 s88, 63
	s_cbranch_scc1 .Ltk_noabove_15
	s_add_i32 s4, s88, 1
	s_nop 0
	v_readlane_b32 s90, v67, s4
.Ltk_noabove_15:
	s_lshl_b32 s4, s88, 8
	s_add_i32 s4, s4, s84
	v_lshlrev_b32_e32 v0, 2, v101
	v_add_u32_e32 v0, s4, v0
	ds_read_b32 v50, v0
	s_waitcnt lgkmcnt(0)
	v_mov_b32_e32 v73, v50
	s_nop 1
	v_add_u32_dpp v68, v73, v73 quad_perm:[1,0,3,2] row_mask:0xf bank_mask:0xf bound_ctrl:1
	v_cndmask_b32_e64 v74, v73, v68, s[16:17]
	s_nop 1
	v_mov_b32_dpp v69, v68 quad_perm:[2,3,0,1] row_mask:0xf bank_mask:0xf bound_ctrl:1
	v_add_u32_e32 v68, v68, v69
	v_cndmask_b32_e64 v70, 0, v69, s[18:19]
	v_add_u32_e32 v74, v74, v70
	s_nop 0
	v_mov_b32_dpp v69, v68 row_half_mirror row_mask:0xf bank_mask:0xf bound_ctrl:1
	v_add_u32_e32 v68, v68, v69
	v_cndmask_b32_e64 v70, 0, v69, s[20:21]
	v_add_u32_e32 v74, v74, v70
	s_nop 0
	v_mov_b32_dpp v69, v68 row_mirror row_mask:0xf bank_mask:0xf bound_ctrl:1
	v_add_u32_e32 v68, v68, v69
	v_cndmask_b32_e64 v70, 0, v69, s[22:23]
	v_add_u32_e32 v74, v74, v70
	v_mov_b32_e32 v71, v68
	v_mov_b32_e32 v72, v68
	s_nop 1
	v_permlane16_swap_b32_e32 v71, v72
	v_cndmask_b32_e64 v69, v71, v72, s[24:25]
	v_add_u32_e32 v68, v68, v69
	v_cndmask_b32_e64 v70, 0, v69, s[24:25]
	v_add_u32_e32 v74, v74, v70
	v_mov_b32_e32 v71, v68
	v_mov_b32_e32 v72, v68
	s_nop 1
	v_permlane32_swap_b32_e32 v71, v72
	v_cndmask_b32_e64 v69, v71, v72, s[26:27]
	v_cndmask_b32_e64 v70, 0, v69, s[26:27]
	v_add_u32_e32 v74, v74, v70
	v_add_u32_e32 v0, s90, v74
	v_cmp_le_u32_e64 s[30:31], s85, v0
	s_flbit_i32_b64 s4, s[30:31]
	s_sub_i32 s4, 63, s4
	s_nop 0
	v_readlane_b32 s5, v73, s4
	v_readlane_b32 s60, v74, s4
	s_lshl_b32 s62, s88, 6
	s_add_i32 s62, s62, s4
	s_add_i32 s60, s60, s90
	s_sub_i32 s60, s60, s5
	s_sub_i32 s85, s85, s60
	s_lshl_b32 s58, s58, 12
	s_or_b32 s58, s58, s62
	s_mov_b32 s62, s58
	s_branch .Ltk_scan_wr_14
.Ltk_scan_few_13:
	s_mov_b32 s56, 1
	s_mov_b32 s62, 0

; DI void topk_job(const Params& p, int b, int t0, char* lds) {
;     ...
;       for (int q = 0; q < 4; ++q) T[q] = few[q] ? 0u : pref[q];
;     }
;   }
;   unsigned* cntb = (unsigned*)mg;
;   unsigned* baseb = (unsigned*)bg;
; #pragma unroll
;   for (int i = 0; i < 17; ++i) {
;     const int c = 1 + w + 8 * i;
;     if (c <= cmax) {
;       unsigned mine = 0u;
; #pragma unroll
;       for (int q = 0; q < 4; ++q) {
;         const unsigned pk = (unsigned)__popcll(__ballot(sc[i][q] > T[q])) | ((unsigned)__popcll(__ballot(sc[i][q] == T[q])) << 16);
;         mine = (lane == q) ? pk : mine;
;       }
;       if (lane < 4) cntb[lane * 132 + c] = mine;
;     }
;   }
.Ltk_scan_end_12:
	s_waitcnt lgkmcnt(0)
	s_barrier
	ds_read_b128 v[4:7], v3 offset:512
	ds_read_b128 v[8:11], v3 offset:528
	s_waitcnt lgkmcnt(0)
	v_readfirstlane_b32 s12, v4
	v_readfirstlane_b32 s13, v6
	v_readfirstlane_b32 s14, v8
	v_readfirstlane_b32 s15, v10
	v_mov_b32_e32 v0, 0x220
	v_mul_u32_u24_e32 v10, v101, v0
	v_add_u32_e32 v10, 0x400, v10
	v_mov_b32_e32 v9, 0
	s_add_i32 s28, s2, 1
	s_cmp_gt_u32 s28, s3
	s_cbranch_scc1 .Ltk_cnt_done_16
	v_cmp_lt_u32_e64 s[68:69], s12, v208
	v_cmp_eq_u32_e64 s[70:71], s12, v208
	v_cmp_lt_u32_e64 s[72:73], s13, v175
	v_cmp_eq_u32_e64 s[74:75], s13, v175
	v_cmp_lt_u32_e64 s[76:77], s14, v161
	v_cmp_eq_u32_e64 s[78:79], s14, v161
	v_cmp_lt_u32_e64 s[80:81], s15, v138
	v_cmp_eq_u32_e64 s[82:83], s15, v138
	s_bcnt1_i32_b64 s4, s[68:69]
	s_bcnt1_i32_b64 s5, s[70:71]
	s_lshl_b32 s5, s5, 16
	s_or_b32 s4, s4, s5
	v_writelane_b32 v9, s4, 0
	s_bcnt1_i32_b64 s4, s[72:73]
	s_bcnt1_i32_b64 s5, s[74:75]
	s_lshl_b32 s5, s5, 16
	s_or_b32 s4, s4, s5
	v_writelane_b32 v9, s4, 1
	s_bcnt1_i32_b64 s4, s[76:77]
	s_bcnt1_i32_b64 s5, s[78:79]
	s_lshl_b32 s5, s5, 16
	s_or_b32 s4, s4, s5
	v_writelane_b32 v9, s4, 2
	s_bcnt1_i32_b64 s4, s[80:81]
	s_bcnt1_i32_b64 s5, s[82:83]
	s_lshl_b32 s5, s5, 16
	s_or_b32 s4, s4, s5
	v_writelane_b32 v9, s4, 3
	v_lshl_add_u32 v0, s28, 2, v10
	s_mov_b64 exec, 15
	ds_write_b32 v0, v9
	s_mov_b64 exec, -1
	s_add_i32 s28, s28, 8
	s_cmp_gt_u32 s28, s3
	s_cbranch_scc1 .Ltk_cnt_done_16
	v_cmp_lt_u32_e64 s[68:69], s12, v207
	v_cmp_eq_u32_e64 s[70:71], s12, v207
	v_cmp_lt_u32_e64 s[72:73], s13, v173
	v_cmp_eq_u32_e64 s[74:75], s13, v173
	v_cmp_lt_u32_e64 s[76:77], s14, v159
	v_cmp_eq_u32_e64 s[78:79], s14, v159
	v_cmp_lt_u32_e64 s[80:81], s15, v135
	v_cmp_eq_u32_e64 s[82:83], s15, v135
	s_bcnt1_i32_b64 s4, s[68:69]
	s_bcnt1_i32_b64 s5, s[70:71]
	s_lshl_b32 s5, s5, 16
	s_or_b32 s4, s4, s5
	v_writelane_b32 v9, s4, 0
	s_bcnt1_i32_b64 s4, s[72:73]
	s_bcnt1_i32_b64 s5, s[74:75]
	s_lshl_b32 s5, s5, 16
	s_or_b32 s4, s4, s5
	v_writelane_b32 v9, s4, 1
	s_bcnt1_i32_b64 s4, s[76:77]
	s_bcnt1_i32_b64 s5, s[78:79]
	s_lshl_b32 s5, s5, 16
	s_or_b32 s4, s4, s5
	v_writelane_b32 v9, s4, 2
	s_bcnt1_i32_b64 s4, s[80:81]
	s_bcnt1_i32_b64 s5, s[82:83]
	s_lshl_b32 s5, s5, 16
	s_or_b32 s4, s4, s5
	v_writelane_b32 v9, s4, 3
	v_lshl_add_u32 v0, s28, 2, v10
	s_mov_b64 exec, 15
	ds_write_b32 v0, v9
	s_mov_b64 exec, -1
	s_add_i32 s28, s28, 8
	s_cmp_gt_u32 s28, s3
	s_cbranch_scc1 .Ltk_cnt_done_16
	v_cmp_lt_u32_e64 s[68:69], s12, v187
	v_cmp_eq_u32_e64 s[70:71], s12, v187
	v_cmp_lt_u32_e64 s[72:73], s13, v172
	v_cmp_eq_u32_e64 s[74:75], s13, v172
	v_cmp_lt_u32_e64 s[76:77], s14, v158
	v_cmp_eq_u32_e64 s[78:79], s14, v158
	v_cmp_lt_u32_e64 s[80:81], s15, v133
	v_cmp_eq_u32_e64 s[82:83], s15, v133
	s_bcnt1_i32_b64 s4, s[68:69]
	s_bcnt1_i32_b64 s5, s[70:71]
	s_lshl_b32 s5, s5, 16
	s_or_b32 s4, s4, s5
	v_writelane_b32 v9, s4, 0
	s_bcnt1_i32_b64 s4, s[72:73]
	s_bcnt1_i32_b64 s5, s[74:75]
	s_lshl_b32 s5, s5, 16
	s_or_b32 s4, s4, s5
	v_writelane_b32 v9, s4, 1
	s_bcnt1_i32_b64 s4, s[76:77]
	s_bcnt1_i32_b64 s5, s[78:79]
	s_lshl_b32 s5, s5, 16
	s_or_b32 s4, s4, s5
	v_writelane_b32 v9, s4, 2
	s_bcnt1_i32_b64 s4, s[80:81]
	s_bcnt1_i32_b64 s5, s[82:83]
	s_lshl_b32 s5, s5, 16
	s_or_b32 s4, s4, s5
	v_writelane_b32 v9, s4, 3
	v_lshl_add_u32 v0, s28, 2, v10
	s_mov_b64 exec, 15
	ds_write_b32 v0, v9
	s_mov_b64 exec, -1
	s_add_i32 s28, s28, 8
	s_cmp_gt_u32 s28, s3
	s_cbranch_scc1 .Ltk_cnt_done_16
	v_cmp_lt_u32_e64 s[68:69], s12, v186
	v_cmp_eq_u32_e64 s[70:71], s12, v186
	v_cmp_lt_u32_e64 s[72:73], s13, v171
	v_cmp_eq_u32_e64 s[74:75], s13, v171
	v_cmp_lt_u32_e64 s[76:77], s14, v153
	v_cmp_eq_u32_e64 s[78:79], s14, v153
	v_cmp_lt_u32_e64 s[80:81], s15, v129
	v_cmp_eq_u32_e64 s[82:83], s15, v129
	s_bcnt1_i32_b64 s4, s[68:69]
	s_bcnt1_i32_b64 s5, s[70:71]
	s_lshl_b32 s5, s5, 16
	s_or_b32 s4, s4, s5
	v_writelane_b32 v9, s4, 0
	s_bcnt1_i32_b64 s4, s[72:73]
	s_bcnt1_i32_b64 s5, s[74:75]
	s_lshl_b32 s5, s5, 16
	s_or_b32 s4, s4, s5
	v_writelane_b32 v9, s4, 1
	s_bcnt1_i32_b64 s4, s[76:77]
	s_bcnt1_i32_b64 s5, s[78:79]
	s_lshl_b32 s5, s5, 16
	s_or_b32 s4, s4, s5
	v_writelane_b32 v9, s4, 2
	s_bcnt1_i32_b64 s4, s[80:81]
	s_bcnt1_i32_b64 s5, s[82:83]
	s_lshl_b32 s5, s5, 16
	s_or_b32 s4, s4, s5
	v_writelane_b32 v9, s4, 3
	v_lshl_add_u32 v0, s28, 2, v10
	s_mov_b64 exec, 15
	ds_write_b32 v0, v9
	s_mov_b64 exec, -1
	s_add_i32 s28, s28, 8
	s_cmp_gt_u32 s28, s3
	s_cbranch_scc1 .Ltk_cnt_done_16
	v_cmp_lt_u32_e64 s[68:69], s12, v185
	v_cmp_eq_u32_e64 s[70:71], s12, v185
	v_cmp_lt_u32_e64 s[72:73], s13, v170
	v_cmp_eq_u32_e64 s[74:75], s13, v170
	v_cmp_lt_u32_e64 s[76:77], s14, v150
	v_cmp_eq_u32_e64 s[78:79], s14, v150
	v_cmp_lt_u32_e64 s[80:81], s15, v127
	v_cmp_eq_u32_e64 s[82:83], s15, v127
	s_bcnt1_i32_b64 s4, s[68:69]
	s_bcnt1_i32_b64 s5, s[70:71]
	s_lshl_b32 s5, s5, 16
	s_or_b32 s4, s4, s5
	v_writelane_b32 v9, s4, 0
	s_bcnt1_i32_b64 s4, s[72:73]
	s_bcnt1_i32_b64 s5, s[74:75]
	s_lshl_b32 s5, s5, 16
	s_or_b32 s4, s4, s5
	v_writelane_b32 v9, s4, 1
	s_bcnt1_i32_b64 s4, s[76:77]
	s_bcnt1_i32_b64 s5, s[78:79]
	s_lshl_b32 s5, s5, 16
	s_or_b32 s4, s4, s5
	v_writelane_b32 v9, s4, 2
	s_bcnt1_i32_b64 s4, s[80:81]
	s_bcnt1_i32_b64 s5, s[82:83]
	s_lshl_b32 s5, s5, 16
	s_or_b32 s4, s4, s5
	v_writelane_b32 v9, s4, 3
	v_lshl_add_u32 v0, s28, 2, v10
	s_mov_b64 exec, 15
	ds_write_b32 v0, v9
	s_mov_b64 exec, -1
	s_add_i32 s28, s28, 8
	s_cmp_gt_u32 s28, s3
	s_cbranch_scc1 .Ltk_cnt_done_16
; DI void topk_job(const Params& p, int b, int t0, char* lds) {
;     ...
; #pragma unroll
;   for (int i = 0; i < 17; ++i) {
;     const int c = 1 + w + 8 * i;
;     if (c <= cmax) {
;       unsigned mine = 0u;
; #pragma unroll
;       for (int q = 0; q < 4; ++q) {
;         const unsigned pk = (unsigned)__popcll(__ballot(sc[i][q] > T[q])) | ((unsigned)__popcll(__ballot(sc[i][q] == T[q])) << 16);
;         mine = (lane == q) ? pk : mine;
;       }
;       if (lane < 4) cntb[lane * 132 + c] = mine;
;     }
;   }
	v_cmp_lt_u32_e64 s[68:69], s12, v184
	v_cmp_eq_u32_e64 s[70:71], s12, v184
	v_cmp_lt_u32_e64 s[72:73], s13, v168
	v_cmp_eq_u32_e64 s[74:75], s13, v168
	v_cmp_lt_u32_e64 s[76:77], s14, v149
	v_cmp_eq_u32_e64 s[78:79], s14, v149
	v_cmp_lt_u32_e64 s[80:81], s15, v125
	v_cmp_eq_u32_e64 s[82:83], s15, v125
	s_bcnt1_i32_b64 s4, s[68:69]
	s_bcnt1_i32_b64 s5, s[70:71]
	s_lshl_b32 s5, s5, 16
	s_or_b32 s4, s4, s5
	v_writelane_b32 v9, s4, 0
	s_bcnt1_i32_b64 s4, s[72:73]
	s_bcnt1_i32_b64 s5, s[74:75]
	s_lshl_b32 s5, s5, 16
	s_or_b32 s4, s4, s5
	v_writelane_b32 v9, s4, 1
	s_bcnt1_i32_b64 s4, s[76:77]
	s_bcnt1_i32_b64 s5, s[78:79]
	s_lshl_b32 s5, s5, 16
	s_or_b32 s4, s4, s5
	v_writelane_b32 v9, s4, 2
	s_bcnt1_i32_b64 s4, s[80:81]
	s_bcnt1_i32_b64 s5, s[82:83]
	s_lshl_b32 s5, s5, 16
	s_or_b32 s4, s4, s5
	v_writelane_b32 v9, s4, 3
	v_lshl_add_u32 v0, s28, 2, v10
	s_mov_b64 exec, 15
	ds_write_b32 v0, v9
	s_mov_b64 exec, -1
	s_add_i32 s28, s28, 8
	s_cmp_gt_u32 s28, s3
	s_cbranch_scc1 .Ltk_cnt_done_16
	v_cmp_lt_u32_e64 s[68:69], s12, v183
	v_cmp_eq_u32_e64 s[70:71], s12, v183
	v_cmp_lt_u32_e64 s[72:73], s13, v167
	v_cmp_eq_u32_e64 s[74:75], s13, v167
	v_cmp_lt_u32_e64 s[76:77], s14, v147
	v_cmp_eq_u32_e64 s[78:79], s14, v147
	v_cmp_lt_u32_e64 s[80:81], s15, v123
	v_cmp_eq_u32_e64 s[82:83], s15, v123
	s_bcnt1_i32_b64 s4, s[68:69]
	s_bcnt1_i32_b64 s5, s[70:71]
	s_lshl_b32 s5, s5, 16
	s_or_b32 s4, s4, s5
	v_writelane_b32 v9, s4, 0
	s_bcnt1_i32_b64 s4, s[72:73]
	s_bcnt1_i32_b64 s5, s[74:75]
	s_lshl_b32 s5, s5, 16
	s_or_b32 s4, s4, s5
	v_writelane_b32 v9, s4, 1
	s_bcnt1_i32_b64 s4, s[76:77]
	s_bcnt1_i32_b64 s5, s[78:79]
	s_lshl_b32 s5, s5, 16
	s_or_b32 s4, s4, s5
	v_writelane_b32 v9, s4, 2
	s_bcnt1_i32_b64 s4, s[80:81]
	s_bcnt1_i32_b64 s5, s[82:83]
	s_lshl_b32 s5, s5, 16
	s_or_b32 s4, s4, s5
	v_writelane_b32 v9, s4, 3
	v_lshl_add_u32 v0, s28, 2, v10
	s_mov_b64 exec, 15
	ds_write_b32 v0, v9
	s_mov_b64 exec, -1
	s_add_i32 s28, s28, 8
	s_cmp_gt_u32 s28, s3
	s_cbranch_scc1 .Ltk_cnt_done_16
	v_cmp_lt_u32_e64 s[68:69], s12, v182
	v_cmp_eq_u32_e64 s[70:71], s12, v182
	v_cmp_lt_u32_e64 s[72:73], s13, v166
	v_cmp_eq_u32_e64 s[74:75], s13, v166
	v_cmp_lt_u32_e64 s[76:77], s14, v146
	v_cmp_eq_u32_e64 s[78:79], s14, v146
	v_cmp_lt_u32_e64 s[80:81], s15, v121
	v_cmp_eq_u32_e64 s[82:83], s15, v121
	s_bcnt1_i32_b64 s4, s[68:69]
	s_bcnt1_i32_b64 s5, s[70:71]
	s_lshl_b32 s5, s5, 16
	s_or_b32 s4, s4, s5
	v_writelane_b32 v9, s4, 0
	s_bcnt1_i32_b64 s4, s[72:73]
	s_bcnt1_i32_b64 s5, s[74:75]
	s_lshl_b32 s5, s5, 16
	s_or_b32 s4, s4, s5
	v_writelane_b32 v9, s4, 1
	s_bcnt1_i32_b64 s4, s[76:77]
	s_bcnt1_i32_b64 s5, s[78:79]
	s_lshl_b32 s5, s5, 16
	s_or_b32 s4, s4, s5
	v_writelane_b32 v9, s4, 2
	s_bcnt1_i32_b64 s4, s[80:81]
	s_bcnt1_i32_b64 s5, s[82:83]
	s_lshl_b32 s5, s5, 16
	s_or_b32 s4, s4, s5
	v_writelane_b32 v9, s4, 3
	v_lshl_add_u32 v0, s28, 2, v10
	s_mov_b64 exec, 15
	ds_write_b32 v0, v9
	s_mov_b64 exec, -1
	s_add_i32 s28, s28, 8
	s_cmp_gt_u32 s28, s3
	s_cbranch_scc1 .Ltk_cnt_done_16
	v_cmp_lt_u32_e64 s[68:69], s12, v181
	v_cmp_eq_u32_e64 s[70:71], s12, v181
	v_cmp_lt_u32_e64 s[72:73], s13, v165
	v_cmp_eq_u32_e64 s[74:75], s13, v165
	v_cmp_lt_u32_e64 s[76:77], s14, v145
	v_cmp_eq_u32_e64 s[78:79], s14, v145
	v_cmp_lt_u32_e64 s[80:81], s15, v119
	v_cmp_eq_u32_e64 s[82:83], s15, v119
	s_bcnt1_i32_b64 s4, s[68:69]
	s_bcnt1_i32_b64 s5, s[70:71]
	s_lshl_b32 s5, s5, 16
	s_or_b32 s4, s4, s5
	v_writelane_b32 v9, s4, 0
	s_bcnt1_i32_b64 s4, s[72:73]
	s_bcnt1_i32_b64 s5, s[74:75]
	s_lshl_b32 s5, s5, 16
	s_or_b32 s4, s4, s5
	v_writelane_b32 v9, s4, 1
	s_bcnt1_i32_b64 s4, s[76:77]
	s_bcnt1_i32_b64 s5, s[78:79]
	s_lshl_b32 s5, s5, 16
	s_or_b32 s4, s4, s5
	v_writelane_b32 v9, s4, 2
	s_bcnt1_i32_b64 s4, s[80:81]
	s_bcnt1_i32_b64 s5, s[82:83]
	s_lshl_b32 s5, s5, 16
	s_or_b32 s4, s4, s5
	v_writelane_b32 v9, s4, 3
	v_lshl_add_u32 v0, s28, 2, v10
	s_mov_b64 exec, 15
	ds_write_b32 v0, v9
	s_mov_b64 exec, -1
	s_add_i32 s28, s28, 8
	s_cmp_gt_u32 s28, s3
	s_cbranch_scc1 .Ltk_cnt_done_16
	v_cmp_lt_u32_e64 s[68:69], s12, v180
	v_cmp_eq_u32_e64 s[70:71], s12, v180
	v_cmp_lt_u32_e64 s[72:73], s13, v164
	v_cmp_eq_u32_e64 s[74:75], s13, v164
	v_cmp_lt_u32_e64 s[76:77], s14, v143
	v_cmp_eq_u32_e64 s[78:79], s14, v143
	v_cmp_lt_u32_e64 s[80:81], s15, v115
	v_cmp_eq_u32_e64 s[82:83], s15, v115
	s_bcnt1_i32_b64 s4, s[68:69]
	s_bcnt1_i32_b64 s5, s[70:71]
	s_lshl_b32 s5, s5, 16
	s_or_b32 s4, s4, s5
	v_writelane_b32 v9, s4, 0
	s_bcnt1_i32_b64 s4, s[72:73]
	s_bcnt1_i32_b64 s5, s[74:75]
	s_lshl_b32 s5, s5, 16
	s_or_b32 s4, s4, s5
	v_writelane_b32 v9, s4, 1
	s_bcnt1_i32_b64 s4, s[76:77]
	s_bcnt1_i32_b64 s5, s[78:79]
	s_lshl_b32 s5, s5, 16
	s_or_b32 s4, s4, s5
	v_writelane_b32 v9, s4, 2
	s_bcnt1_i32_b64 s4, s[80:81]
	s_bcnt1_i32_b64 s5, s[82:83]
	s_lshl_b32 s5, s5, 16
	s_or_b32 s4, s4, s5
	v_writelane_b32 v9, s4, 3
	v_lshl_add_u32 v0, s28, 2, v10
	s_mov_b64 exec, 15
	ds_write_b32 v0, v9
	s_mov_b64 exec, -1
	s_add_i32 s28, s28, 8
	s_cmp_gt_u32 s28, s3
	s_cbranch_scc1 .Ltk_cnt_done_16
	v_cmp_lt_u32_e64 s[68:69], s12, v179
	v_cmp_eq_u32_e64 s[70:71], s12, v179
	v_cmp_lt_u32_e64 s[72:73], s13, v163
	v_cmp_eq_u32_e64 s[74:75], s13, v163
	v_cmp_lt_u32_e64 s[76:77], s14, v142
	v_cmp_eq_u32_e64 s[78:79], s14, v142
	v_cmp_lt_u32_e64 s[80:81], s15, v113
	v_cmp_eq_u32_e64 s[82:83], s15, v113
	s_bcnt1_i32_b64 s4, s[68:69]
	s_bcnt1_i32_b64 s5, s[70:71]
	s_lshl_b32 s5, s5, 16
	s_or_b32 s4, s4, s5
	v_writelane_b32 v9, s4, 0
	s_bcnt1_i32_b64 s4, s[72:73]
	s_bcnt1_i32_b64 s5, s[74:75]
	s_lshl_b32 s5, s5, 16
	s_or_b32 s4, s4, s5
	v_writelane_b32 v9, s4, 1
	s_bcnt1_i32_b64 s4, s[76:77]
	s_bcnt1_i32_b64 s5, s[78:79]
	s_lshl_b32 s5, s5, 16
	s_or_b32 s4, s4, s5
	v_writelane_b32 v9, s4, 2
	s_bcnt1_i32_b64 s4, s[80:81]
	s_bcnt1_i32_b64 s5, s[82:83]
	s_lshl_b32 s5, s5, 16
	s_or_b32 s4, s4, s5
	v_writelane_b32 v9, s4, 3
	v_lshl_add_u32 v0, s28, 2, v10
	s_mov_b64 exec, 15
	ds_write_b32 v0, v9
	s_mov_b64 exec, -1
	s_add_i32 s28, s28, 8
	s_cmp_gt_u32 s28, s3
	s_cbranch_scc1 .Ltk_cnt_done_16
; DI void topk_job(const Params& p, int b, int t0, char* lds) {
;     ...
; #pragma unroll
;   for (int i = 0; i < 17; ++i) {
;     const int c = 1 + w + 8 * i;
;     if (c <= cmax) {
;       unsigned mine = 0u;
; #pragma unroll
;       for (int q = 0; q < 4; ++q) {
;         const unsigned pk = (unsigned)__popcll(__ballot(sc[i][q] > T[q])) | ((unsigned)__popcll(__ballot(sc[i][q] == T[q])) << 16);
;         mine = (lane == q) ? pk : mine;
;       }
;       if (lane < 4) cntb[lane * 132 + c] = mine;
;     }
;   }
	v_cmp_lt_u32_e64 s[68:69], s12, v178
	v_cmp_eq_u32_e64 s[70:71], s12, v178
	v_cmp_lt_u32_e64 s[72:73], s13, v162
	v_cmp_eq_u32_e64 s[74:75], s13, v162
	v_cmp_lt_u32_e64 s[76:77], s14, v141
	v_cmp_eq_u32_e64 s[78:79], s14, v141
	v_cmp_lt_u32_e64 s[80:81], s15, v111
	v_cmp_eq_u32_e64 s[82:83], s15, v111
	s_bcnt1_i32_b64 s4, s[68:69]
	s_bcnt1_i32_b64 s5, s[70:71]
	s_lshl_b32 s5, s5, 16
	s_or_b32 s4, s4, s5
	v_writelane_b32 v9, s4, 0
	s_bcnt1_i32_b64 s4, s[72:73]
	s_bcnt1_i32_b64 s5, s[74:75]
	s_lshl_b32 s5, s5, 16
	s_or_b32 s4, s4, s5
	v_writelane_b32 v9, s4, 1
	s_bcnt1_i32_b64 s4, s[76:77]
	s_bcnt1_i32_b64 s5, s[78:79]
	s_lshl_b32 s5, s5, 16
	s_or_b32 s4, s4, s5
	v_writelane_b32 v9, s4, 2
	s_bcnt1_i32_b64 s4, s[80:81]
	s_bcnt1_i32_b64 s5, s[82:83]
	s_lshl_b32 s5, s5, 16
	s_or_b32 s4, s4, s5
	v_writelane_b32 v9, s4, 3
	v_lshl_add_u32 v0, s28, 2, v10
	s_mov_b64 exec, 15
	ds_write_b32 v0, v9
	s_mov_b64 exec, -1
	s_add_i32 s28, s28, 8
	s_cmp_gt_u32 s28, s3
	s_cbranch_scc1 .Ltk_cnt_done_16
	v_cmp_lt_u32_e64 s[68:69], s12, v177
	v_cmp_eq_u32_e64 s[70:71], s12, v177
	v_cmp_lt_u32_e64 s[72:73], s13, v160
	v_cmp_eq_u32_e64 s[74:75], s13, v160
	v_cmp_lt_u32_e64 s[76:77], s14, v140
	v_cmp_eq_u32_e64 s[78:79], s14, v140
	v_cmp_lt_u32_e64 s[80:81], s15, v109
	v_cmp_eq_u32_e64 s[82:83], s15, v109
	s_bcnt1_i32_b64 s4, s[68:69]
	s_bcnt1_i32_b64 s5, s[70:71]
	s_lshl_b32 s5, s5, 16
	s_or_b32 s4, s4, s5
	v_writelane_b32 v9, s4, 0
	s_bcnt1_i32_b64 s4, s[72:73]
	s_bcnt1_i32_b64 s5, s[74:75]
	s_lshl_b32 s5, s5, 16
	s_or_b32 s4, s4, s5
	v_writelane_b32 v9, s4, 1
	s_bcnt1_i32_b64 s4, s[76:77]
	s_bcnt1_i32_b64 s5, s[78:79]
	s_lshl_b32 s5, s5, 16
	s_or_b32 s4, s4, s5
	v_writelane_b32 v9, s4, 2
	s_bcnt1_i32_b64 s4, s[80:81]
	s_bcnt1_i32_b64 s5, s[82:83]
	s_lshl_b32 s5, s5, 16
	s_or_b32 s4, s4, s5
	v_writelane_b32 v9, s4, 3
	v_lshl_add_u32 v0, s28, 2, v10
	s_mov_b64 exec, 15
	ds_write_b32 v0, v9
	s_mov_b64 exec, -1
	s_add_i32 s28, s28, 8
	s_cmp_gt_u32 s28, s3
	s_cbranch_scc1 .Ltk_cnt_done_16
	v_cmp_lt_u32_e64 s[68:69], s12, v176
	v_cmp_eq_u32_e64 s[70:71], s12, v176
	v_cmp_lt_u32_e64 s[72:73], s13, v151
	v_cmp_eq_u32_e64 s[74:75], s13, v151
	v_cmp_lt_u32_e64 s[76:77], s14, v139
	v_cmp_eq_u32_e64 s[78:79], s14, v139
	v_cmp_lt_u32_e64 s[80:81], s15, v107
	v_cmp_eq_u32_e64 s[82:83], s15, v107
	s_bcnt1_i32_b64 s4, s[68:69]
	s_bcnt1_i32_b64 s5, s[70:71]
	s_lshl_b32 s5, s5, 16
	s_or_b32 s4, s4, s5
	v_writelane_b32 v9, s4, 0
	s_bcnt1_i32_b64 s4, s[72:73]
	s_bcnt1_i32_b64 s5, s[74:75]
	s_lshl_b32 s5, s5, 16
	s_or_b32 s4, s4, s5
	v_writelane_b32 v9, s4, 1
	s_bcnt1_i32_b64 s4, s[76:77]
	s_bcnt1_i32_b64 s5, s[78:79]
	s_lshl_b32 s5, s5, 16
	s_or_b32 s4, s4, s5
	v_writelane_b32 v9, s4, 2
	s_bcnt1_i32_b64 s4, s[80:81]
	s_bcnt1_i32_b64 s5, s[82:83]
	s_lshl_b32 s5, s5, 16
	s_or_b32 s4, s4, s5
	v_writelane_b32 v9, s4, 3
	v_lshl_add_u32 v0, s28, 2, v10
	s_mov_b64 exec, 15
	ds_write_b32 v0, v9
	s_mov_b64 exec, -1
	s_add_i32 s28, s28, 8
	s_cmp_gt_u32 s28, s3
	s_cbranch_scc1 .Ltk_cnt_done_16
	v_cmp_lt_u32_e64 s[68:69], s12, v174
	v_cmp_eq_u32_e64 s[70:71], s12, v174
	v_cmp_lt_u32_e64 s[72:73], s13, v148
	v_cmp_eq_u32_e64 s[74:75], s13, v148
	v_cmp_lt_u32_e64 s[76:77], s14, v131
	v_cmp_eq_u32_e64 s[78:79], s14, v131
	v_cmp_lt_u32_e64 s[80:81], s15, v105
	v_cmp_eq_u32_e64 s[82:83], s15, v105
	s_bcnt1_i32_b64 s4, s[68:69]
	s_bcnt1_i32_b64 s5, s[70:71]
	s_lshl_b32 s5, s5, 16
	s_or_b32 s4, s4, s5
	v_writelane_b32 v9, s4, 0
	s_bcnt1_i32_b64 s4, s[72:73]
	s_bcnt1_i32_b64 s5, s[74:75]
	s_lshl_b32 s5, s5, 16
	s_or_b32 s4, s4, s5
	v_writelane_b32 v9, s4, 1
	s_bcnt1_i32_b64 s4, s[76:77]
	s_bcnt1_i32_b64 s5, s[78:79]
	s_lshl_b32 s5, s5, 16
	s_or_b32 s4, s4, s5
	v_writelane_b32 v9, s4, 2
	s_bcnt1_i32_b64 s4, s[80:81]
	s_bcnt1_i32_b64 s5, s[82:83]
	s_lshl_b32 s5, s5, 16
	s_or_b32 s4, s4, s5
	v_writelane_b32 v9, s4, 3
	v_lshl_add_u32 v0, s28, 2, v10
	s_mov_b64 exec, 15
	ds_write_b32 v0, v9
	s_mov_b64 exec, -1
	s_add_i32 s28, s28, 8
	s_cmp_gt_u32 s28, s3
	s_cbranch_scc1 .Ltk_cnt_done_16
	v_cmp_lt_u32_e64 s[68:69], s12, v169
	v_cmp_eq_u32_e64 s[70:71], s12, v169
	v_cmp_lt_u32_e64 s[72:73], s13, v144
	v_cmp_eq_u32_e64 s[74:75], s13, v144
	v_cmp_lt_u32_e64 s[76:77], s14, v117
	v_cmp_eq_u32_e64 s[78:79], s14, v117
	v_cmp_lt_u32_e64 s[80:81], s15, v103
	v_cmp_eq_u32_e64 s[82:83], s15, v103
	s_bcnt1_i32_b64 s4, s[68:69]
	s_bcnt1_i32_b64 s5, s[70:71]
	s_lshl_b32 s5, s5, 16
	s_or_b32 s4, s4, s5
	v_writelane_b32 v9, s4, 0
	s_bcnt1_i32_b64 s4, s[72:73]
	s_bcnt1_i32_b64 s5, s[74:75]
	s_lshl_b32 s5, s5, 16
	s_or_b32 s4, s4, s5
	v_writelane_b32 v9, s4, 1
	s_bcnt1_i32_b64 s4, s[76:77]
	s_bcnt1_i32_b64 s5, s[78:79]
	s_lshl_b32 s5, s5, 16
	s_or_b32 s4, s4, s5
	v_writelane_b32 v9, s4, 2
	s_bcnt1_i32_b64 s4, s[80:81]
	s_bcnt1_i32_b64 s5, s[82:83]
	s_lshl_b32 s5, s5, 16
	s_or_b32 s4, s4, s5
	v_writelane_b32 v9, s4, 3
	v_lshl_add_u32 v0, s28, 2, v10
	s_mov_b64 exec, 15
	ds_write_b32 v0, v9
	s_mov_b64 exec, -1
	s_add_i32 s28, s28, 8
	s_cmp_gt_u32 s28, s3
	s_cbranch_scc1 .Ltk_cnt_done_16
	v_cmp_lt_u32_e64 s[68:69], s12, v19
	v_cmp_eq_u32_e64 s[70:71], s12, v19
	v_cmp_lt_u32_e64 s[72:73], s13, v18
	v_cmp_eq_u32_e64 s[74:75], s13, v18
	v_cmp_lt_u32_e64 s[76:77], s14, v17
	v_cmp_eq_u32_e64 s[78:79], s14, v17
	v_cmp_lt_u32_e64 s[80:81], s15, v16
	v_cmp_eq_u32_e64 s[82:83], s15, v16
	s_bcnt1_i32_b64 s4, s[68:69]
	s_bcnt1_i32_b64 s5, s[70:71]
	s_lshl_b32 s5, s5, 16
	s_or_b32 s4, s4, s5
	v_writelane_b32 v9, s4, 0
	s_bcnt1_i32_b64 s4, s[72:73]
	s_bcnt1_i32_b64 s5, s[74:75]
	s_lshl_b32 s5, s5, 16
	s_or_b32 s4, s4, s5
	v_writelane_b32 v9, s4, 1
	s_bcnt1_i32_b64 s4, s[76:77]
	s_bcnt1_i32_b64 s5, s[78:79]
	s_lshl_b32 s5, s5, 16
	s_or_b32 s4, s4, s5
	v_writelane_b32 v9, s4, 2
	s_bcnt1_i32_b64 s4, s[80:81]
	s_bcnt1_i32_b64 s5, s[82:83]
	s_lshl_b32 s5, s5, 16
	s_or_b32 s4, s4, s5
	v_writelane_b32 v9, s4, 3
	v_lshl_add_u32 v0, s28, 2, v10
	s_mov_b64 exec, 15
	ds_write_b32 v0, v9
	s_mov_b64 exec, -1
; template <int CTRL> DI int dpp_movi(int v) { return __builtin_amdgcn_mov_dpp(v, CTRL, 0xF, 0xF, true); }
; template <bool UP> DI int wscan(int v, int lane, int& total) {
;   int acc = v, tot = v, o;
;   o = dpp_movi<0xB1>(tot);  if (((lane & 1) != 0) == UP) acc += o;  tot += o;
;   o = dpp_movi<0x4E>(tot);  if (((lane & 2) != 0) == UP) acc += o;  tot += o;
;   o = dpp_movi<0x141>(tot); if (((lane & 4) != 0) == UP) acc += o;  tot += o;
;   o = dpp_movi<0x140>(tot); if (((lane & 8) != 0) == UP) acc += o;  tot += o;
;   u32x2 r = __builtin_amdgcn_permlane16_swap((unsigned)tot, (unsigned)tot, false, false);
;   o = (int)((lane & 16) ? r[0] : r[1]); if (((lane & 16) != 0) == UP) acc += o; tot += o;
;   r = __builtin_amdgcn_permlane32_swap((unsigned)tot, (unsigned)tot, false, false);
;   o = (int)((lane & 32) ? r[0] : r[1]); if (((lane & 32) != 0) == UP) acc += o; tot += o;
;   total = tot;
;   return acc;
; }
; DI void topk_job(const Params& p, int b, int t0, char* lds) {
;     ...
;   __syncthreads();
;   if (w < 4) {
;     const int q = w;
;     int cg_ = 0, ce_ = 0;
;     for (int base = 0; base <= cmax; base += 64) {
;       const int c = base + lane;
;       const bool in = (c >= 1) && (c <= cmax);
;       const unsigned cv = in ? cntb[q * 132 + c] : 0u;
;       const int v1 = (int)(cv & 0xffffu), v2 = (int)(cv >> 16);
;       int t1, t2;
;       const int i1 = wscan<true>(v1, lane, t1), i2 = wscan<true>(v2, lane, t2);
;       if (in) baseb[q * 132 + c] = (unsigned)(cg_ + i1 - v1) | ((unsigned)(ce_ + i2 - v2) << 16);
;       cg_ += t1;
;       ce_ += t2;
;     }
;     if (lane == 0) ng[q] = cg_;
;   }
.Ltk_cnt_done_16:
	s_waitcnt lgkmcnt(0)
	s_barrier
	s_cmp_gt_u32 s2, 3
	s_cbranch_scc1 .Ltk_pfx_end_17
	s_mul_i32 s4, s2, 0x220
	s_addk_i32 s4, 0x400
	v_mov_b32_e32 v11, s4
	s_mov_b32 s60, 0
	v_add_u32_e32 v0, 0, v101
	v_cmp_le_u32_e64 s[30:31], 1, v0
	v_cmp_ge_u32_e32 vcc, s3, v0
	s_and_b64 s[30:31], s[30:31], vcc
	v_lshl_add_u32 v1, v0, 2, v11
	v_mov_b32_e32 v4, 0
	s_mov_b64 exec, s[30:31]
	ds_read_b32 v4, v1
	s_mov_b64 exec, -1
	s_waitcnt lgkmcnt(0)
	s_nop 1
	v_add_u32_dpp v68, v4, v4 quad_perm:[1,0,3,2] row_mask:0xf bank_mask:0xf bound_ctrl:1
	v_cndmask_b32_e64 v67, v68, v4, s[16:17]
	s_nop 1
	v_mov_b32_dpp v69, v68 quad_perm:[2,3,0,1] row_mask:0xf bank_mask:0xf bound_ctrl:1
	v_add_u32_e32 v68, v68, v69
	v_cndmask_b32_e64 v70, v69, 0, s[18:19]
	v_add_u32_e32 v67, v67, v70
	s_nop 0
	v_mov_b32_dpp v69, v68 row_half_mirror row_mask:0xf bank_mask:0xf bound_ctrl:1
	v_add_u32_e32 v68, v68, v69
	v_cndmask_b32_e64 v70, v69, 0, s[20:21]
	v_add_u32_e32 v67, v67, v70
	s_nop 0
	v_mov_b32_dpp v69, v68 row_mirror row_mask:0xf bank_mask:0xf bound_ctrl:1
	v_add_u32_e32 v68, v68, v69
	v_cndmask_b32_e64 v70, v69, 0, s[22:23]
	v_add_u32_e32 v67, v67, v70
	v_mov_b32_e32 v71, v68
	v_mov_b32_e32 v72, v68
	s_nop 1
	v_permlane16_swap_b32_e32 v71, v72
	v_cndmask_b32_e64 v69, v71, v72, s[24:25]
	v_add_u32_e32 v68, v68, v69
	v_cndmask_b32_e64 v70, v69, 0, s[24:25]
	v_add_u32_e32 v67, v67, v70
	v_mov_b32_e32 v71, v68
	v_mov_b32_e32 v72, v68
	s_nop 1
	v_permlane32_swap_b32_e32 v71, v72
	v_cndmask_b32_e64 v69, v71, v72, s[26:27]
	v_cndmask_b32_e64 v70, v69, 0, s[26:27]
	v_add_u32_e32 v67, v67, v70
	v_sub_u32_e32 v5, v67, v4
	v_add_u32_e32 v5, s60, v5
	v_add_u32_e32 v1, 0xc00, v1
	s_mov_b64 exec, s[30:31]
	ds_write_b32 v1, v5
	s_mov_b64 exec, -1
	v_readlane_b32 s4, v67, 63
	s_add_i32 s60, s60, s4
	s_cmp_lt_u32 s3, 64
	s_cbranch_scc1 .Ltk_pfx_done_18
	v_add_u32_e32 v0, 64, v101
	v_cmp_le_u32_e64 s[30:31], 1, v0
	v_cmp_ge_u32_e32 vcc, s3, v0
	s_and_b64 s[30:31], s[30:31], vcc
	v_lshl_add_u32 v1, v0, 2, v11
	v_mov_b32_e32 v4, 0
	s_mov_b64 exec, s[30:31]
	ds_read_b32 v4, v1
	s_mov_b64 exec, -1
	s_waitcnt lgkmcnt(0)
	s_nop 1
	v_add_u32_dpp v68, v4, v4 quad_perm:[1,0,3,2] row_mask:0xf bank_mask:0xf bound_ctrl:1
	v_cndmask_b32_e64 v67, v68, v4, s[16:17]
	s_nop 1
	v_mov_b32_dpp v69, v68 quad_perm:[2,3,0,1] row_mask:0xf bank_mask:0xf bound_ctrl:1
	v_add_u32_e32 v68, v68, v69
	v_cndmask_b32_e64 v70, v69, 0, s[18:19]
	v_add_u32_e32 v67, v67, v70
	s_nop 0
	v_mov_b32_dpp v69, v68 row_half_mirror row_mask:0xf bank_mask:0xf bound_ctrl:1
	v_add_u32_e32 v68, v68, v69
	v_cndmask_b32_e64 v70, v69, 0, s[20:21]
	v_add_u32_e32 v67, v67, v70
	s_nop 0
	v_mov_b32_dpp v69, v68 row_mirror row_mask:0xf bank_mask:0xf bound_ctrl:1
	v_add_u32_e32 v68, v68, v69
	v_cndmask_b32_e64 v70, v69, 0, s[22:23]
	v_add_u32_e32 v67, v67, v70
	v_mov_b32_e32 v71, v68
	v_mov_b32_e32 v72, v68
	s_nop 1
	v_permlane16_swap_b32_e32 v71, v72
	v_cndmask_b32_e64 v69, v71, v72, s[24:25]
	v_add_u32_e32 v68, v68, v69
	v_cndmask_b32_e64 v70, v69, 0, s[24:25]
	v_add_u32_e32 v67, v67, v70
	v_mov_b32_e32 v71, v68
	v_mov_b32_e32 v72, v68
	s_nop 1
	v_permlane32_swap_b32_e32 v71, v72
	v_cndmask_b32_e64 v69, v71, v72, s[26:27]
	v_cndmask_b32_e64 v70, v69, 0, s[26:27]
	v_add_u32_e32 v67, v67, v70
	v_sub_u32_e32 v5, v67, v4
	v_add_u32_e32 v5, s60, v5
	v_add_u32_e32 v1, 0xc00, v1
	s_mov_b64 exec, s[30:31]
	ds_write_b32 v1, v5
	s_mov_b64 exec, -1
	v_readlane_b32 s4, v67, 63
	s_add_i32 s60, s60, s4
	s_cmp_lt_u32 s3, 128
	s_cbranch_scc1 .Ltk_pfx_done_18
	v_add_u32_e32 v0, 128, v101
	v_cmp_le_u32_e64 s[30:31], 1, v0
	v_cmp_ge_u32_e32 vcc, s3, v0
	s_and_b64 s[30:31], s[30:31], vcc
	v_lshl_add_u32 v1, v0, 2, v11
	v_mov_b32_e32 v4, 0
	s_mov_b64 exec, s[30:31]
	ds_read_b32 v4, v1
	s_mov_b64 exec, -1
	s_waitcnt lgkmcnt(0)
	s_nop 1
	v_add_u32_dpp v68, v4, v4 quad_perm:[1,0,3,2] row_mask:0xf bank_mask:0xf bound_ctrl:1
	v_cndmask_b32_e64 v67, v68, v4, s[16:17]
	s_nop 1
	v_mov_b32_dpp v69, v68 quad_perm:[2,3,0,1] row_mask:0xf bank_mask:0xf bound_ctrl:1
	v_add_u32_e32 v68, v68, v69
	v_cndmask_b32_e64 v70, v69, 0, s[18:19]
	v_add_u32_e32 v67, v67, v70
	s_nop 0
	v_mov_b32_dpp v69, v68 row_half_mirror row_mask:0xf bank_mask:0xf bound_ctrl:1
	v_add_u32_e32 v68, v68, v69
	v_cndmask_b32_e64 v70, v69, 0, s[20:21]
	v_add_u32_e32 v67, v67, v70
	s_nop 0
	v_mov_b32_dpp v69, v68 row_mirror row_mask:0xf bank_mask:0xf bound_ctrl:1
	v_add_u32_e32 v68, v68, v69
	v_cndmask_b32_e64 v70, v69, 0, s[22:23]
	v_add_u32_e32 v67, v67, v70
	v_mov_b32_e32 v71, v68
	v_mov_b32_e32 v72, v68
	s_nop 1
	v_permlane16_swap_b32_e32 v71, v72
	v_cndmask_b32_e64 v69, v71, v72, s[24:25]
	v_add_u32_e32 v68, v68, v69
	v_cndmask_b32_e64 v70, v69, 0, s[24:25]
	v_add_u32_e32 v67, v67, v70
	v_mov_b32_e32 v71, v68
	v_mov_b32_e32 v72, v68
	s_nop 1
	v_permlane32_swap_b32_e32 v71, v72
	v_cndmask_b32_e64 v69, v71, v72, s[26:27]
	v_cndmask_b32_e64 v70, v69, 0, s[26:27]
	v_add_u32_e32 v67, v67, v70
	v_sub_u32_e32 v5, v67, v4
	v_add_u32_e32 v5, s60, v5
	v_add_u32_e32 v1, 0xc00, v1
	s_mov_b64 exec, s[30:31]
	ds_write_b32 v1, v5
	s_mov_b64 exec, -1
	v_readlane_b32 s4, v67, 63
	s_add_i32 s60, s60, s4
.Ltk_pfx_done_18:
	s_and_b32 s60, s60, 0xffff
	v_mov_b32_e32 v4, s60
	v_mov_b32_e32 v0, 0x100
	v_lshl_add_u32 v0, s2, 2, v0
	s_mov_b64 exec, 1
	ds_write_b32 v0, v4
	s_mov_b64 exec, -1
; DI void topk_job(const Params& p, int b, int t0, char* lds) {
;     ...
;   __syncthreads();
;   const unsigned long long lt = (1ull << lane) - 1ull;
; #pragma unroll
;   for (int i = 0; i < 17; ++i) {
;     const int c = 1 + w + 8 * i;
;     if (c <= cmax) {
;       const int key = c * 64 + lane;
; #pragma unroll
;       for (int q = 0; q < 4; ++q) {
;         u16* out = p.IDX + (size_t)(b * PP + t0 + q) * 256;
;         const bool gt = sc[i][q] > T[q];
;         const bool eq = (sc[i][q] == T[q]) && (T[q] != 0u);
;         const unsigned long long m1 = __ballot(gt), m2 = __ballot(eq);
;         if ((m1 | m2) != 0ull) {
;           const unsigned bb = baseb[q * 132 + c];
;           if (gt) out[(int)(bb & 0xffffu) + __popcll(m1 & lt)] = (u16)key;
;           if (eq) { const int pos = ng[q] + (int)(bb >> 16) + __popcll(m2 & lt); if (pos < 256) out[pos] = (u16)key; }
;         }
;       }
;     }
;   }
.Ltk_pfx_end_17:
	s_waitcnt lgkmcnt(0)
	s_barrier
	ds_read_b128 v[4:7], v3 offset:256
	s_movk_i32 s84, 0x100
	s_waitcnt lgkmcnt(0)
	v_readfirstlane_b32 s48, v4
	v_readfirstlane_b32 s49, v5
	v_readfirstlane_b32 s50, v6
	v_readfirstlane_b32 s51, v7
	s_add_i32 s28, s2, 1
	s_cmp_gt_u32 s28, s3
	s_cbranch_scc1 .Ltk_scat_done_19
	s_lshl_b32 s29, s28, 2
	s_addk_i32 s29, 0x1000
	v_mov_b32_e32 v11, s29
	ds_read_b32 v12, v11
	ds_read_b32 v13, v11 offset:544
	ds_read_b32 v14, v11 offset:1088
	ds_read_b32 v15, v11 offset:1632
	v_lshl_add_u32 v6, s28, 6, v101
	v_cmp_lt_u32_e64 s[68:69], s12, v208
	v_cmp_eq_u32_e64 s[70:71], s12, v208
	s_cmp_lg_u32 s12, 0
	s_cselect_b64 s[70:71], s[70:71], 0
	v_mbcnt_lo_u32_b32 v7, s68, 0
	v_mbcnt_hi_u32_b32 v7, s69, v7
	v_mbcnt_lo_u32_b32 v8, s70, 0
	v_mbcnt_hi_u32_b32 v8, s71, v8
	s_waitcnt lgkmcnt(3)
	v_and_b32_e32 v0, 0xffff, v12
	v_add_lshl_u32 v0, v0, v7, 1
	v_lshrrev_b32_e32 v1, 16, v12
	v_add3_u32 v1, v1, v8, s48
	v_cmp_gt_u32_e64 s[72:73], s84, v1
	v_lshlrev_b32_e32 v1, 1, v1
	s_and_b64 s[70:71], s[70:71], s[72:73]
	s_mov_b64 exec, s[68:69]
	global_store_short v0, v6, s[40:41]
	s_mov_b64 exec, s[70:71]
	global_store_short v1, v6, s[40:41]
	s_mov_b64 exec, -1
	v_cmp_lt_u32_e64 s[68:69], s13, v175
	v_cmp_eq_u32_e64 s[70:71], s13, v175
	s_cmp_lg_u32 s13, 0
	s_cselect_b64 s[70:71], s[70:71], 0
	v_mbcnt_lo_u32_b32 v7, s68, 0
	v_mbcnt_hi_u32_b32 v7, s69, v7
	v_mbcnt_lo_u32_b32 v8, s70, 0
	v_mbcnt_hi_u32_b32 v8, s71, v8
	s_waitcnt lgkmcnt(2)
	v_and_b32_e32 v0, 0xffff, v13
	v_add_lshl_u32 v0, v0, v7, 1
	v_lshrrev_b32_e32 v1, 16, v13
	v_add3_u32 v1, v1, v8, s49
	v_cmp_gt_u32_e64 s[72:73], s84, v1
	v_lshlrev_b32_e32 v1, 1, v1
	s_and_b64 s[70:71], s[70:71], s[72:73]
	s_mov_b64 exec, s[68:69]
	global_store_short v0, v6, s[42:43]
	s_mov_b64 exec, s[70:71]
	global_store_short v1, v6, s[42:43]
	s_mov_b64 exec, -1
	v_cmp_lt_u32_e64 s[68:69], s14, v161
	v_cmp_eq_u32_e64 s[70:71], s14, v161
	s_cmp_lg_u32 s14, 0
	s_cselect_b64 s[70:71], s[70:71], 0
	v_mbcnt_lo_u32_b32 v7, s68, 0
	v_mbcnt_hi_u32_b32 v7, s69, v7
	v_mbcnt_lo_u32_b32 v8, s70, 0
	v_mbcnt_hi_u32_b32 v8, s71, v8
	s_waitcnt lgkmcnt(1)
	v_and_b32_e32 v0, 0xffff, v14
	v_add_lshl_u32 v0, v0, v7, 1
	v_lshrrev_b32_e32 v1, 16, v14
	v_add3_u32 v1, v1, v8, s50
	v_cmp_gt_u32_e64 s[72:73], s84, v1
	v_lshlrev_b32_e32 v1, 1, v1
	s_and_b64 s[70:71], s[70:71], s[72:73]
	s_mov_b64 exec, s[68:69]
	global_store_short v0, v6, s[44:45]
	s_mov_b64 exec, s[70:71]
	global_store_short v1, v6, s[44:45]
	s_mov_b64 exec, -1
	v_cmp_lt_u32_e64 s[68:69], s15, v138
	v_cmp_eq_u32_e64 s[70:71], s15, v138
	s_cmp_lg_u32 s15, 0
	s_cselect_b64 s[70:71], s[70:71], 0
	v_mbcnt_lo_u32_b32 v7, s68, 0
	v_mbcnt_hi_u32_b32 v7, s69, v7
	v_mbcnt_lo_u32_b32 v8, s70, 0
	v_mbcnt_hi_u32_b32 v8, s71, v8
	s_waitcnt lgkmcnt(0)
	v_and_b32_e32 v0, 0xffff, v15
	v_add_lshl_u32 v0, v0, v7, 1
	v_lshrrev_b32_e32 v1, 16, v15
	v_add3_u32 v1, v1, v8, s51
	v_cmp_gt_u32_e64 s[72:73], s84, v1
	v_lshlrev_b32_e32 v1, 1, v1
	s_and_b64 s[70:71], s[70:71], s[72:73]
	s_mov_b64 exec, s[68:69]
	global_store_short v0, v6, s[46:47]
	s_mov_b64 exec, s[70:71]
	global_store_short v1, v6, s[46:47]
	s_mov_b64 exec, -1
	s_add_i32 s28, s28, 8
	s_cmp_gt_u32 s28, s3
	s_cbranch_scc1 .Ltk_scat_done_19
	s_lshl_b32 s29, s28, 2
	s_addk_i32 s29, 0x1000
	v_mov_b32_e32 v11, s29
	ds_read_b32 v12, v11
	ds_read_b32 v13, v11 offset:544
	ds_read_b32 v14, v11 offset:1088
	ds_read_b32 v15, v11 offset:1632
	v_lshl_add_u32 v6, s28, 6, v101
	v_cmp_lt_u32_e64 s[68:69], s12, v207
	v_cmp_eq_u32_e64 s[70:71], s12, v207
	s_cmp_lg_u32 s12, 0
	s_cselect_b64 s[70:71], s[70:71], 0
	v_mbcnt_lo_u32_b32 v7, s68, 0
	v_mbcnt_hi_u32_b32 v7, s69, v7
	v_mbcnt_lo_u32_b32 v8, s70, 0
	v_mbcnt_hi_u32_b32 v8, s71, v8
	s_waitcnt lgkmcnt(3)
	v_and_b32_e32 v0, 0xffff, v12
	v_add_lshl_u32 v0, v0, v7, 1
	v_lshrrev_b32_e32 v1, 16, v12
	v_add3_u32 v1, v1, v8, s48
	v_cmp_gt_u32_e64 s[72:73], s84, v1
	v_lshlrev_b32_e32 v1, 1, v1
	s_and_b64 s[70:71], s[70:71], s[72:73]
	s_mov_b64 exec, s[68:69]
	global_store_short v0, v6, s[40:41]
	s_mov_b64 exec, s[70:71]
	global_store_short v1, v6, s[40:41]
	s_mov_b64 exec, -1
	v_cmp_lt_u32_e64 s[68:69], s13, v173
	v_cmp_eq_u32_e64 s[70:71], s13, v173
	s_cmp_lg_u32 s13, 0
	s_cselect_b64 s[70:71], s[70:71], 0
	v_mbcnt_lo_u32_b32 v7, s68, 0
	v_mbcnt_hi_u32_b32 v7, s69, v7
	v_mbcnt_lo_u32_b32 v8, s70, 0
	v_mbcnt_hi_u32_b32 v8, s71, v8
	s_waitcnt lgkmcnt(2)
	v_and_b32_e32 v0, 0xffff, v13
	v_add_lshl_u32 v0, v0, v7, 1
	v_lshrrev_b32_e32 v1, 16, v13
	v_add3_u32 v1, v1, v8, s49
	v_cmp_gt_u32_e64 s[72:73], s84, v1
	v_lshlrev_b32_e32 v1, 1, v1
	s_and_b64 s[70:71], s[70:71], s[72:73]
	s_mov_b64 exec, s[68:69]
	global_store_short v0, v6, s[42:43]
	s_mov_b64 exec, s[70:71]
	global_store_short v1, v6, s[42:43]
	s_mov_b64 exec, -1
	v_cmp_lt_u32_e64 s[68:69], s14, v159
	v_cmp_eq_u32_e64 s[70:71], s14, v159
	s_cmp_lg_u32 s14, 0
	s_cselect_b64 s[70:71], s[70:71], 0
	v_mbcnt_lo_u32_b32 v7, s68, 0
	v_mbcnt_hi_u32_b32 v7, s69, v7
	v_mbcnt_lo_u32_b32 v8, s70, 0
	v_mbcnt_hi_u32_b32 v8, s71, v8
	s_waitcnt lgkmcnt(1)
	v_and_b32_e32 v0, 0xffff, v14
	v_add_lshl_u32 v0, v0, v7, 1
	v_lshrrev_b32_e32 v1, 16, v14
	v_add3_u32 v1, v1, v8, s50
	v_cmp_gt_u32_e64 s[72:73], s84, v1
	v_lshlrev_b32_e32 v1, 1, v1
	s_and_b64 s[70:71], s[70:71], s[72:73]
	s_mov_b64 exec, s[68:69]
	global_store_short v0, v6, s[44:45]
	s_mov_b64 exec, s[70:71]
	global_store_short v1, v6, s[44:45]
	s_mov_b64 exec, -1
	v_cmp_lt_u32_e64 s[68:69], s15, v135
	v_cmp_eq_u32_e64 s[70:71], s15, v135
	s_cmp_lg_u32 s15, 0
	s_cselect_b64 s[70:71], s[70:71], 0
	v_mbcnt_lo_u32_b32 v7, s68, 0
	v_mbcnt_hi_u32_b32 v7, s69, v7
	v_mbcnt_lo_u32_b32 v8, s70, 0
	v_mbcnt_hi_u32_b32 v8, s71, v8
	s_waitcnt lgkmcnt(0)
	v_and_b32_e32 v0, 0xffff, v15
	v_add_lshl_u32 v0, v0, v7, 1
	v_lshrrev_b32_e32 v1, 16, v15
	v_add3_u32 v1, v1, v8, s51
	v_cmp_gt_u32_e64 s[72:73], s84, v1
	v_lshlrev_b32_e32 v1, 1, v1
	s_and_b64 s[70:71], s[70:71], s[72:73]
	s_mov_b64 exec, s[68:69]
	global_store_short v0, v6, s[46:47]
	s_mov_b64 exec, s[70:71]
	global_store_short v1, v6, s[46:47]
	s_mov_b64 exec, -1
	s_add_i32 s28, s28, 8
	s_cmp_gt_u32 s28, s3
	s_cbranch_scc1 .Ltk_scat_done_19
; DI void topk_job(const Params& p, int b, int t0, char* lds) {
;     ...
;   const unsigned long long lt = (1ull << lane) - 1ull;
; #pragma unroll
;   for (int i = 0; i < 17; ++i) {
;     const int c = 1 + w + 8 * i;
;     if (c <= cmax) {
;       const int key = c * 64 + lane;
; #pragma unroll
;       for (int q = 0; q < 4; ++q) {
;         u16* out = p.IDX + (size_t)(b * PP + t0 + q) * 256;
;         const bool gt = sc[i][q] > T[q];
;         const bool eq = (sc[i][q] == T[q]) && (T[q] != 0u);
;         const unsigned long long m1 = __ballot(gt), m2 = __ballot(eq);
;         if ((m1 | m2) != 0ull) {
;           const unsigned bb = baseb[q * 132 + c];
;           if (gt) out[(int)(bb & 0xffffu) + __popcll(m1 & lt)] = (u16)key;
;           if (eq) { const int pos = ng[q] + (int)(bb >> 16) + __popcll(m2 & lt); if (pos < 256) out[pos] = (u16)key; }
;         }
;       }
;     }
;   }
	s_lshl_b32 s29, s28, 2
	s_addk_i32 s29, 0x1000
	v_mov_b32_e32 v11, s29
	ds_read_b32 v12, v11
	ds_read_b32 v13, v11 offset:544
	ds_read_b32 v14, v11 offset:1088
	ds_read_b32 v15, v11 offset:1632
	v_lshl_add_u32 v6, s28, 6, v101
	v_cmp_lt_u32_e64 s[68:69], s12, v187
	v_cmp_eq_u32_e64 s[70:71], s12, v187
	s_cmp_lg_u32 s12, 0
	s_cselect_b64 s[70:71], s[70:71], 0
	v_mbcnt_lo_u32_b32 v7, s68, 0
	v_mbcnt_hi_u32_b32 v7, s69, v7
	v_mbcnt_lo_u32_b32 v8, s70, 0
	v_mbcnt_hi_u32_b32 v8, s71, v8
	s_waitcnt lgkmcnt(3)
	v_and_b32_e32 v0, 0xffff, v12
	v_add_lshl_u32 v0, v0, v7, 1
	v_lshrrev_b32_e32 v1, 16, v12
	v_add3_u32 v1, v1, v8, s48
	v_cmp_gt_u32_e64 s[72:73], s84, v1
	v_lshlrev_b32_e32 v1, 1, v1
	s_and_b64 s[70:71], s[70:71], s[72:73]
	s_mov_b64 exec, s[68:69]
	global_store_short v0, v6, s[40:41]
	s_mov_b64 exec, s[70:71]
	global_store_short v1, v6, s[40:41]
	s_mov_b64 exec, -1
	v_cmp_lt_u32_e64 s[68:69], s13, v172
	v_cmp_eq_u32_e64 s[70:71], s13, v172
	s_cmp_lg_u32 s13, 0
	s_cselect_b64 s[70:71], s[70:71], 0
	v_mbcnt_lo_u32_b32 v7, s68, 0
	v_mbcnt_hi_u32_b32 v7, s69, v7
	v_mbcnt_lo_u32_b32 v8, s70, 0
	v_mbcnt_hi_u32_b32 v8, s71, v8
	s_waitcnt lgkmcnt(2)
	v_and_b32_e32 v0, 0xffff, v13
	v_add_lshl_u32 v0, v0, v7, 1
	v_lshrrev_b32_e32 v1, 16, v13
	v_add3_u32 v1, v1, v8, s49
	v_cmp_gt_u32_e64 s[72:73], s84, v1
	v_lshlrev_b32_e32 v1, 1, v1
	s_and_b64 s[70:71], s[70:71], s[72:73]
	s_mov_b64 exec, s[68:69]
	global_store_short v0, v6, s[42:43]
	s_mov_b64 exec, s[70:71]
	global_store_short v1, v6, s[42:43]
	s_mov_b64 exec, -1
	v_cmp_lt_u32_e64 s[68:69], s14, v158
	v_cmp_eq_u32_e64 s[70:71], s14, v158
	s_cmp_lg_u32 s14, 0
	s_cselect_b64 s[70:71], s[70:71], 0
	v_mbcnt_lo_u32_b32 v7, s68, 0
	v_mbcnt_hi_u32_b32 v7, s69, v7
	v_mbcnt_lo_u32_b32 v8, s70, 0
	v_mbcnt_hi_u32_b32 v8, s71, v8
	s_waitcnt lgkmcnt(1)
	v_and_b32_e32 v0, 0xffff, v14
	v_add_lshl_u32 v0, v0, v7, 1
	v_lshrrev_b32_e32 v1, 16, v14
	v_add3_u32 v1, v1, v8, s50
	v_cmp_gt_u32_e64 s[72:73], s84, v1
	v_lshlrev_b32_e32 v1, 1, v1
	s_and_b64 s[70:71], s[70:71], s[72:73]
	s_mov_b64 exec, s[68:69]
	global_store_short v0, v6, s[44:45]
	s_mov_b64 exec, s[70:71]
	global_store_short v1, v6, s[44:45]
	s_mov_b64 exec, -1
	v_cmp_lt_u32_e64 s[68:69], s15, v133
	v_cmp_eq_u32_e64 s[70:71], s15, v133
	s_cmp_lg_u32 s15, 0
	s_cselect_b64 s[70:71], s[70:71], 0
	v_mbcnt_lo_u32_b32 v7, s68, 0
	v_mbcnt_hi_u32_b32 v7, s69, v7
	v_mbcnt_lo_u32_b32 v8, s70, 0
	v_mbcnt_hi_u32_b32 v8, s71, v8
	s_waitcnt lgkmcnt(0)
	v_and_b32_e32 v0, 0xffff, v15
	v_add_lshl_u32 v0, v0, v7, 1
	v_lshrrev_b32_e32 v1, 16, v15
	v_add3_u32 v1, v1, v8, s51
	v_cmp_gt_u32_e64 s[72:73], s84, v1
	v_lshlrev_b32_e32 v1, 1, v1
	s_and_b64 s[70:71], s[70:71], s[72:73]
	s_mov_b64 exec, s[68:69]
	global_store_short v0, v6, s[46:47]
	s_mov_b64 exec, s[70:71]
	global_store_short v1, v6, s[46:47]
	s_mov_b64 exec, -1
	s_add_i32 s28, s28, 8
	s_cmp_gt_u32 s28, s3
	s_cbranch_scc1 .Ltk_scat_done_19
	s_lshl_b32 s29, s28, 2
	s_addk_i32 s29, 0x1000
	v_mov_b32_e32 v11, s29
	ds_read_b32 v12, v11
	ds_read_b32 v13, v11 offset:544
	ds_read_b32 v14, v11 offset:1088
	ds_read_b32 v15, v11 offset:1632
	v_lshl_add_u32 v6, s28, 6, v101
	v_cmp_lt_u32_e64 s[68:69], s12, v186
	v_cmp_eq_u32_e64 s[70:71], s12, v186
	s_cmp_lg_u32 s12, 0
	s_cselect_b64 s[70:71], s[70:71], 0
	v_mbcnt_lo_u32_b32 v7, s68, 0
	v_mbcnt_hi_u32_b32 v7, s69, v7
	v_mbcnt_lo_u32_b32 v8, s70, 0
	v_mbcnt_hi_u32_b32 v8, s71, v8
	s_waitcnt lgkmcnt(3)
	v_and_b32_e32 v0, 0xffff, v12
	v_add_lshl_u32 v0, v0, v7, 1
	v_lshrrev_b32_e32 v1, 16, v12
	v_add3_u32 v1, v1, v8, s48
	v_cmp_gt_u32_e64 s[72:73], s84, v1
	v_lshlrev_b32_e32 v1, 1, v1
	s_and_b64 s[70:71], s[70:71], s[72:73]
	s_mov_b64 exec, s[68:69]
	global_store_short v0, v6, s[40:41]
	s_mov_b64 exec, s[70:71]
	global_store_short v1, v6, s[40:41]
	s_mov_b64 exec, -1
	v_cmp_lt_u32_e64 s[68:69], s13, v171
	v_cmp_eq_u32_e64 s[70:71], s13, v171
	s_cmp_lg_u32 s13, 0
	s_cselect_b64 s[70:71], s[70:71], 0
	v_mbcnt_lo_u32_b32 v7, s68, 0
	v_mbcnt_hi_u32_b32 v7, s69, v7
	v_mbcnt_lo_u32_b32 v8, s70, 0
	v_mbcnt_hi_u32_b32 v8, s71, v8
	s_waitcnt lgkmcnt(2)
	v_and_b32_e32 v0, 0xffff, v13
	v_add_lshl_u32 v0, v0, v7, 1
	v_lshrrev_b32_e32 v1, 16, v13
	v_add3_u32 v1, v1, v8, s49
	v_cmp_gt_u32_e64 s[72:73], s84, v1
	v_lshlrev_b32_e32 v1, 1, v1
	s_and_b64 s[70:71], s[70:71], s[72:73]
	s_mov_b64 exec, s[68:69]
	global_store_short v0, v6, s[42:43]
	s_mov_b64 exec, s[70:71]
	global_store_short v1, v6, s[42:43]
	s_mov_b64 exec, -1
	v_cmp_lt_u32_e64 s[68:69], s14, v153
	v_cmp_eq_u32_e64 s[70:71], s14, v153
	s_cmp_lg_u32 s14, 0
	s_cselect_b64 s[70:71], s[70:71], 0
	v_mbcnt_lo_u32_b32 v7, s68, 0
	v_mbcnt_hi_u32_b32 v7, s69, v7
	v_mbcnt_lo_u32_b32 v8, s70, 0
	v_mbcnt_hi_u32_b32 v8, s71, v8
	s_waitcnt lgkmcnt(1)
	v_and_b32_e32 v0, 0xffff, v14
	v_add_lshl_u32 v0, v0, v7, 1
	v_lshrrev_b32_e32 v1, 16, v14
	v_add3_u32 v1, v1, v8, s50
	v_cmp_gt_u32_e64 s[72:73], s84, v1
	v_lshlrev_b32_e32 v1, 1, v1
	s_and_b64 s[70:71], s[70:71], s[72:73]
	s_mov_b64 exec, s[68:69]
	global_store_short v0, v6, s[44:45]
	s_mov_b64 exec, s[70:71]
	global_store_short v1, v6, s[44:45]
	s_mov_b64 exec, -1
	v_cmp_lt_u32_e64 s[68:69], s15, v129
	v_cmp_eq_u32_e64 s[70:71], s15, v129
	s_cmp_lg_u32 s15, 0
	s_cselect_b64 s[70:71], s[70:71], 0
	v_mbcnt_lo_u32_b32 v7, s68, 0
	v_mbcnt_hi_u32_b32 v7, s69, v7
	v_mbcnt_lo_u32_b32 v8, s70, 0
	v_mbcnt_hi_u32_b32 v8, s71, v8
	s_waitcnt lgkmcnt(0)
	v_and_b32_e32 v0, 0xffff, v15
	v_add_lshl_u32 v0, v0, v7, 1
	v_lshrrev_b32_e32 v1, 16, v15
	v_add3_u32 v1, v1, v8, s51
	v_cmp_gt_u32_e64 s[72:73], s84, v1
	v_lshlrev_b32_e32 v1, 1, v1
	s_and_b64 s[70:71], s[70:71], s[72:73]
	s_mov_b64 exec, s[68:69]
	global_store_short v0, v6, s[46:47]
	s_mov_b64 exec, s[70:71]
	global_store_short v1, v6, s[46:47]
	s_mov_b64 exec, -1
	s_add_i32 s28, s28, 8
	s_cmp_gt_u32 s28, s3
	s_cbranch_scc1 .Ltk_scat_done_19
; DI void topk_job(const Params& p, int b, int t0, char* lds) {
;     ...
;   const unsigned long long lt = (1ull << lane) - 1ull;
; #pragma unroll
;   for (int i = 0; i < 17; ++i) {
;     const int c = 1 + w + 8 * i;
;     if (c <= cmax) {
;       const int key = c * 64 + lane;
; #pragma unroll
;       for (int q = 0; q < 4; ++q) {
;         u16* out = p.IDX + (size_t)(b * PP + t0 + q) * 256;
;         const bool gt = sc[i][q] > T[q];
;         const bool eq = (sc[i][q] == T[q]) && (T[q] != 0u);
;         const unsigned long long m1 = __ballot(gt), m2 = __ballot(eq);
;         if ((m1 | m2) != 0ull) {
;           const unsigned bb = baseb[q * 132 + c];
;           if (gt) out[(int)(bb & 0xffffu) + __popcll(m1 & lt)] = (u16)key;
;           if (eq) { const int pos = ng[q] + (int)(bb >> 16) + __popcll(m2 & lt); if (pos < 256) out[pos] = (u16)key; }
;         }
;       }
;     }
;   }
	s_lshl_b32 s29, s28, 2
	s_addk_i32 s29, 0x1000
	v_mov_b32_e32 v11, s29
	ds_read_b32 v12, v11
	ds_read_b32 v13, v11 offset:544
	ds_read_b32 v14, v11 offset:1088
	ds_read_b32 v15, v11 offset:1632
	v_lshl_add_u32 v6, s28, 6, v101
	v_cmp_lt_u32_e64 s[68:69], s12, v185
	v_cmp_eq_u32_e64 s[70:71], s12, v185
	s_cmp_lg_u32 s12, 0
	s_cselect_b64 s[70:71], s[70:71], 0
	v_mbcnt_lo_u32_b32 v7, s68, 0
	v_mbcnt_hi_u32_b32 v7, s69, v7
	v_mbcnt_lo_u32_b32 v8, s70, 0
	v_mbcnt_hi_u32_b32 v8, s71, v8
	s_waitcnt lgkmcnt(3)
	v_and_b32_e32 v0, 0xffff, v12
	v_add_lshl_u32 v0, v0, v7, 1
	v_lshrrev_b32_e32 v1, 16, v12
	v_add3_u32 v1, v1, v8, s48
	v_cmp_gt_u32_e64 s[72:73], s84, v1
	v_lshlrev_b32_e32 v1, 1, v1
	s_and_b64 s[70:71], s[70:71], s[72:73]
	s_mov_b64 exec, s[68:69]
	global_store_short v0, v6, s[40:41]
	s_mov_b64 exec, s[70:71]
	global_store_short v1, v6, s[40:41]
	s_mov_b64 exec, -1
	v_cmp_lt_u32_e64 s[68:69], s13, v170
	v_cmp_eq_u32_e64 s[70:71], s13, v170
	s_cmp_lg_u32 s13, 0
	s_cselect_b64 s[70:71], s[70:71], 0
	v_mbcnt_lo_u32_b32 v7, s68, 0
	v_mbcnt_hi_u32_b32 v7, s69, v7
	v_mbcnt_lo_u32_b32 v8, s70, 0
	v_mbcnt_hi_u32_b32 v8, s71, v8
	s_waitcnt lgkmcnt(2)
	v_and_b32_e32 v0, 0xffff, v13
	v_add_lshl_u32 v0, v0, v7, 1
	v_lshrrev_b32_e32 v1, 16, v13
	v_add3_u32 v1, v1, v8, s49
	v_cmp_gt_u32_e64 s[72:73], s84, v1
	v_lshlrev_b32_e32 v1, 1, v1
	s_and_b64 s[70:71], s[70:71], s[72:73]
	s_mov_b64 exec, s[68:69]
	global_store_short v0, v6, s[42:43]
	s_mov_b64 exec, s[70:71]
	global_store_short v1, v6, s[42:43]
	s_mov_b64 exec, -1
	v_cmp_lt_u32_e64 s[68:69], s14, v150
	v_cmp_eq_u32_e64 s[70:71], s14, v150
	s_cmp_lg_u32 s14, 0
	s_cselect_b64 s[70:71], s[70:71], 0
	v_mbcnt_lo_u32_b32 v7, s68, 0
	v_mbcnt_hi_u32_b32 v7, s69, v7
	v_mbcnt_lo_u32_b32 v8, s70, 0
	v_mbcnt_hi_u32_b32 v8, s71, v8
	s_waitcnt lgkmcnt(1)
	v_and_b32_e32 v0, 0xffff, v14
	v_add_lshl_u32 v0, v0, v7, 1
	v_lshrrev_b32_e32 v1, 16, v14
	v_add3_u32 v1, v1, v8, s50
	v_cmp_gt_u32_e64 s[72:73], s84, v1
	v_lshlrev_b32_e32 v1, 1, v1
	s_and_b64 s[70:71], s[70:71], s[72:73]
	s_mov_b64 exec, s[68:69]
	global_store_short v0, v6, s[44:45]
	s_mov_b64 exec, s[70:71]
	global_store_short v1, v6, s[44:45]
	s_mov_b64 exec, -1
	v_cmp_lt_u32_e64 s[68:69], s15, v127
	v_cmp_eq_u32_e64 s[70:71], s15, v127
	s_cmp_lg_u32 s15, 0
	s_cselect_b64 s[70:71], s[70:71], 0
	v_mbcnt_lo_u32_b32 v7, s68, 0
	v_mbcnt_hi_u32_b32 v7, s69, v7
	v_mbcnt_lo_u32_b32 v8, s70, 0
	v_mbcnt_hi_u32_b32 v8, s71, v8
	s_waitcnt lgkmcnt(0)
	v_and_b32_e32 v0, 0xffff, v15
	v_add_lshl_u32 v0, v0, v7, 1
	v_lshrrev_b32_e32 v1, 16, v15
	v_add3_u32 v1, v1, v8, s51
	v_cmp_gt_u32_e64 s[72:73], s84, v1
	v_lshlrev_b32_e32 v1, 1, v1
	s_and_b64 s[70:71], s[70:71], s[72:73]
	s_mov_b64 exec, s[68:69]
	global_store_short v0, v6, s[46:47]
	s_mov_b64 exec, s[70:71]
	global_store_short v1, v6, s[46:47]
	s_mov_b64 exec, -1
	s_add_i32 s28, s28, 8
	s_cmp_gt_u32 s28, s3
	s_cbranch_scc1 .Ltk_scat_done_19
	s_lshl_b32 s29, s28, 2
	s_addk_i32 s29, 0x1000
	v_mov_b32_e32 v11, s29
	ds_read_b32 v12, v11
	ds_read_b32 v13, v11 offset:544
	ds_read_b32 v14, v11 offset:1088
	ds_read_b32 v15, v11 offset:1632
	v_lshl_add_u32 v6, s28, 6, v101
	v_cmp_lt_u32_e64 s[68:69], s12, v184
	v_cmp_eq_u32_e64 s[70:71], s12, v184
	s_cmp_lg_u32 s12, 0
	s_cselect_b64 s[70:71], s[70:71], 0
	v_mbcnt_lo_u32_b32 v7, s68, 0
	v_mbcnt_hi_u32_b32 v7, s69, v7
	v_mbcnt_lo_u32_b32 v8, s70, 0
	v_mbcnt_hi_u32_b32 v8, s71, v8
	s_waitcnt lgkmcnt(3)
	v_and_b32_e32 v0, 0xffff, v12
	v_add_lshl_u32 v0, v0, v7, 1
	v_lshrrev_b32_e32 v1, 16, v12
	v_add3_u32 v1, v1, v8, s48
	v_cmp_gt_u32_e64 s[72:73], s84, v1
	v_lshlrev_b32_e32 v1, 1, v1
	s_and_b64 s[70:71], s[70:71], s[72:73]
	s_mov_b64 exec, s[68:69]
	global_store_short v0, v6, s[40:41]
	s_mov_b64 exec, s[70:71]
	global_store_short v1, v6, s[40:41]
	s_mov_b64 exec, -1
	v_cmp_lt_u32_e64 s[68:69], s13, v168
	v_cmp_eq_u32_e64 s[70:71], s13, v168
	s_cmp_lg_u32 s13, 0
	s_cselect_b64 s[70:71], s[70:71], 0
	v_mbcnt_lo_u32_b32 v7, s68, 0
	v_mbcnt_hi_u32_b32 v7, s69, v7
	v_mbcnt_lo_u32_b32 v8, s70, 0
	v_mbcnt_hi_u32_b32 v8, s71, v8
	s_waitcnt lgkmcnt(2)
	v_and_b32_e32 v0, 0xffff, v13
	v_add_lshl_u32 v0, v0, v7, 1
	v_lshrrev_b32_e32 v1, 16, v13
	v_add3_u32 v1, v1, v8, s49
	v_cmp_gt_u32_e64 s[72:73], s84, v1
	v_lshlrev_b32_e32 v1, 1, v1
	s_and_b64 s[70:71], s[70:71], s[72:73]
	s_mov_b64 exec, s[68:69]
	global_store_short v0, v6, s[42:43]
	s_mov_b64 exec, s[70:71]
	global_store_short v1, v6, s[42:43]
	s_mov_b64 exec, -1
	v_cmp_lt_u32_e64 s[68:69], s14, v149
	v_cmp_eq_u32_e64 s[70:71], s14, v149
	s_cmp_lg_u32 s14, 0
	s_cselect_b64 s[70:71], s[70:71], 0
	v_mbcnt_lo_u32_b32 v7, s68, 0
	v_mbcnt_hi_u32_b32 v7, s69, v7
	v_mbcnt_lo_u32_b32 v8, s70, 0
	v_mbcnt_hi_u32_b32 v8, s71, v8
	s_waitcnt lgkmcnt(1)
	v_and_b32_e32 v0, 0xffff, v14
	v_add_lshl_u32 v0, v0, v7, 1
	v_lshrrev_b32_e32 v1, 16, v14
	v_add3_u32 v1, v1, v8, s50
	v_cmp_gt_u32_e64 s[72:73], s84, v1
	v_lshlrev_b32_e32 v1, 1, v1
	s_and_b64 s[70:71], s[70:71], s[72:73]
	s_mov_b64 exec, s[68:69]
	global_store_short v0, v6, s[44:45]
	s_mov_b64 exec, s[70:71]
	global_store_short v1, v6, s[44:45]
	s_mov_b64 exec, -1
	v_cmp_lt_u32_e64 s[68:69], s15, v125
	v_cmp_eq_u32_e64 s[70:71], s15, v125
	s_cmp_lg_u32 s15, 0
	s_cselect_b64 s[70:71], s[70:71], 0
	v_mbcnt_lo_u32_b32 v7, s68, 0
	v_mbcnt_hi_u32_b32 v7, s69, v7
	v_mbcnt_lo_u32_b32 v8, s70, 0
	v_mbcnt_hi_u32_b32 v8, s71, v8
	s_waitcnt lgkmcnt(0)
	v_and_b32_e32 v0, 0xffff, v15
	v_add_lshl_u32 v0, v0, v7, 1
	v_lshrrev_b32_e32 v1, 16, v15
	v_add3_u32 v1, v1, v8, s51
	v_cmp_gt_u32_e64 s[72:73], s84, v1
	v_lshlrev_b32_e32 v1, 1, v1
	s_and_b64 s[70:71], s[70:71], s[72:73]
	s_mov_b64 exec, s[68:69]
	global_store_short v0, v6, s[46:47]
	s_mov_b64 exec, s[70:71]
	global_store_short v1, v6, s[46:47]
	s_mov_b64 exec, -1
	s_add_i32 s28, s28, 8
	s_cmp_gt_u32 s28, s3
	s_cbranch_scc1 .Ltk_scat_done_19
; DI void topk_job(const Params& p, int b, int t0, char* lds) {
;     ...
;   const unsigned long long lt = (1ull << lane) - 1ull;
; #pragma unroll
;   for (int i = 0; i < 17; ++i) {
;     const int c = 1 + w + 8 * i;
;     if (c <= cmax) {
;       const int key = c * 64 + lane;
; #pragma unroll
;       for (int q = 0; q < 4; ++q) {
;         u16* out = p.IDX + (size_t)(b * PP + t0 + q) * 256;
;         const bool gt = sc[i][q] > T[q];
;         const bool eq = (sc[i][q] == T[q]) && (T[q] != 0u);
;         const unsigned long long m1 = __ballot(gt), m2 = __ballot(eq);
;         if ((m1 | m2) != 0ull) {
;           const unsigned bb = baseb[q * 132 + c];
;           if (gt) out[(int)(bb & 0xffffu) + __popcll(m1 & lt)] = (u16)key;
;           if (eq) { const int pos = ng[q] + (int)(bb >> 16) + __popcll(m2 & lt); if (pos < 256) out[pos] = (u16)key; }
;         }
;       }
;     }
;   }
	s_lshl_b32 s29, s28, 2
	s_addk_i32 s29, 0x1000
	v_mov_b32_e32 v11, s29
	ds_read_b32 v12, v11
	ds_read_b32 v13, v11 offset:544
	ds_read_b32 v14, v11 offset:1088
	ds_read_b32 v15, v11 offset:1632
	v_lshl_add_u32 v6, s28, 6, v101
	v_cmp_lt_u32_e64 s[68:69], s12, v183
	v_cmp_eq_u32_e64 s[70:71], s12, v183
	s_cmp_lg_u32 s12, 0
	s_cselect_b64 s[70:71], s[70:71], 0
	v_mbcnt_lo_u32_b32 v7, s68, 0
	v_mbcnt_hi_u32_b32 v7, s69, v7
	v_mbcnt_lo_u32_b32 v8, s70, 0
	v_mbcnt_hi_u32_b32 v8, s71, v8
	s_waitcnt lgkmcnt(3)
	v_and_b32_e32 v0, 0xffff, v12
	v_add_lshl_u32 v0, v0, v7, 1
	v_lshrrev_b32_e32 v1, 16, v12
	v_add3_u32 v1, v1, v8, s48
	v_cmp_gt_u32_e64 s[72:73], s84, v1
	v_lshlrev_b32_e32 v1, 1, v1
	s_and_b64 s[70:71], s[70:71], s[72:73]
	s_mov_b64 exec, s[68:69]
	global_store_short v0, v6, s[40:41]
	s_mov_b64 exec, s[70:71]
	global_store_short v1, v6, s[40:41]
	s_mov_b64 exec, -1
	v_cmp_lt_u32_e64 s[68:69], s13, v167
	v_cmp_eq_u32_e64 s[70:71], s13, v167
	s_cmp_lg_u32 s13, 0
	s_cselect_b64 s[70:71], s[70:71], 0
	v_mbcnt_lo_u32_b32 v7, s68, 0
	v_mbcnt_hi_u32_b32 v7, s69, v7
	v_mbcnt_lo_u32_b32 v8, s70, 0
	v_mbcnt_hi_u32_b32 v8, s71, v8
	s_waitcnt lgkmcnt(2)
	v_and_b32_e32 v0, 0xffff, v13
	v_add_lshl_u32 v0, v0, v7, 1
	v_lshrrev_b32_e32 v1, 16, v13
	v_add3_u32 v1, v1, v8, s49
	v_cmp_gt_u32_e64 s[72:73], s84, v1
	v_lshlrev_b32_e32 v1, 1, v1
	s_and_b64 s[70:71], s[70:71], s[72:73]
	s_mov_b64 exec, s[68:69]
	global_store_short v0, v6, s[42:43]
	s_mov_b64 exec, s[70:71]
	global_store_short v1, v6, s[42:43]
	s_mov_b64 exec, -1
	v_cmp_lt_u32_e64 s[68:69], s14, v147
	v_cmp_eq_u32_e64 s[70:71], s14, v147
	s_cmp_lg_u32 s14, 0
	s_cselect_b64 s[70:71], s[70:71], 0
	v_mbcnt_lo_u32_b32 v7, s68, 0
	v_mbcnt_hi_u32_b32 v7, s69, v7
	v_mbcnt_lo_u32_b32 v8, s70, 0
	v_mbcnt_hi_u32_b32 v8, s71, v8
	s_waitcnt lgkmcnt(1)
	v_and_b32_e32 v0, 0xffff, v14
	v_add_lshl_u32 v0, v0, v7, 1
	v_lshrrev_b32_e32 v1, 16, v14
	v_add3_u32 v1, v1, v8, s50
	v_cmp_gt_u32_e64 s[72:73], s84, v1
	v_lshlrev_b32_e32 v1, 1, v1
	s_and_b64 s[70:71], s[70:71], s[72:73]
	s_mov_b64 exec, s[68:69]
	global_store_short v0, v6, s[44:45]
	s_mov_b64 exec, s[70:71]
	global_store_short v1, v6, s[44:45]
	s_mov_b64 exec, -1
	v_cmp_lt_u32_e64 s[68:69], s15, v123
	v_cmp_eq_u32_e64 s[70:71], s15, v123
	s_cmp_lg_u32 s15, 0
	s_cselect_b64 s[70:71], s[70:71], 0
	v_mbcnt_lo_u32_b32 v7, s68, 0
	v_mbcnt_hi_u32_b32 v7, s69, v7
	v_mbcnt_lo_u32_b32 v8, s70, 0
	v_mbcnt_hi_u32_b32 v8, s71, v8
	s_waitcnt lgkmcnt(0)
	v_and_b32_e32 v0, 0xffff, v15
	v_add_lshl_u32 v0, v0, v7, 1
	v_lshrrev_b32_e32 v1, 16, v15
	v_add3_u32 v1, v1, v8, s51
	v_cmp_gt_u32_e64 s[72:73], s84, v1
	v_lshlrev_b32_e32 v1, 1, v1
	s_and_b64 s[70:71], s[70:71], s[72:73]
	s_mov_b64 exec, s[68:69]
	global_store_short v0, v6, s[46:47]
	s_mov_b64 exec, s[70:71]
	global_store_short v1, v6, s[46:47]
	s_mov_b64 exec, -1
	s_add_i32 s28, s28, 8
	s_cmp_gt_u32 s28, s3
	s_cbranch_scc1 .Ltk_scat_done_19
	s_lshl_b32 s29, s28, 2
	s_addk_i32 s29, 0x1000
	v_mov_b32_e32 v11, s29
	ds_read_b32 v12, v11
	ds_read_b32 v13, v11 offset:544
	ds_read_b32 v14, v11 offset:1088
	ds_read_b32 v15, v11 offset:1632
	v_lshl_add_u32 v6, s28, 6, v101
	v_cmp_lt_u32_e64 s[68:69], s12, v182
	v_cmp_eq_u32_e64 s[70:71], s12, v182
	s_cmp_lg_u32 s12, 0
	s_cselect_b64 s[70:71], s[70:71], 0
	v_mbcnt_lo_u32_b32 v7, s68, 0
	v_mbcnt_hi_u32_b32 v7, s69, v7
	v_mbcnt_lo_u32_b32 v8, s70, 0
	v_mbcnt_hi_u32_b32 v8, s71, v8
	s_waitcnt lgkmcnt(3)
	v_and_b32_e32 v0, 0xffff, v12
	v_add_lshl_u32 v0, v0, v7, 1
	v_lshrrev_b32_e32 v1, 16, v12
	v_add3_u32 v1, v1, v8, s48
	v_cmp_gt_u32_e64 s[72:73], s84, v1
	v_lshlrev_b32_e32 v1, 1, v1
	s_and_b64 s[70:71], s[70:71], s[72:73]
	s_mov_b64 exec, s[68:69]
	global_store_short v0, v6, s[40:41]
	s_mov_b64 exec, s[70:71]
	global_store_short v1, v6, s[40:41]
	s_mov_b64 exec, -1
	v_cmp_lt_u32_e64 s[68:69], s13, v166
	v_cmp_eq_u32_e64 s[70:71], s13, v166
	s_cmp_lg_u32 s13, 0
	s_cselect_b64 s[70:71], s[70:71], 0
	v_mbcnt_lo_u32_b32 v7, s68, 0
	v_mbcnt_hi_u32_b32 v7, s69, v7
	v_mbcnt_lo_u32_b32 v8, s70, 0
	v_mbcnt_hi_u32_b32 v8, s71, v8
	s_waitcnt lgkmcnt(2)
	v_and_b32_e32 v0, 0xffff, v13
	v_add_lshl_u32 v0, v0, v7, 1
	v_lshrrev_b32_e32 v1, 16, v13
	v_add3_u32 v1, v1, v8, s49
	v_cmp_gt_u32_e64 s[72:73], s84, v1
	v_lshlrev_b32_e32 v1, 1, v1
	s_and_b64 s[70:71], s[70:71], s[72:73]
	s_mov_b64 exec, s[68:69]
	global_store_short v0, v6, s[42:43]
	s_mov_b64 exec, s[70:71]
	global_store_short v1, v6, s[42:43]
	s_mov_b64 exec, -1
	v_cmp_lt_u32_e64 s[68:69], s14, v146
	v_cmp_eq_u32_e64 s[70:71], s14, v146
	s_cmp_lg_u32 s14, 0
	s_cselect_b64 s[70:71], s[70:71], 0
	v_mbcnt_lo_u32_b32 v7, s68, 0
	v_mbcnt_hi_u32_b32 v7, s69, v7
	v_mbcnt_lo_u32_b32 v8, s70, 0
	v_mbcnt_hi_u32_b32 v8, s71, v8
	s_waitcnt lgkmcnt(1)
	v_and_b32_e32 v0, 0xffff, v14
	v_add_lshl_u32 v0, v0, v7, 1
	v_lshrrev_b32_e32 v1, 16, v14
	v_add3_u32 v1, v1, v8, s50
	v_cmp_gt_u32_e64 s[72:73], s84, v1
	v_lshlrev_b32_e32 v1, 1, v1
	s_and_b64 s[70:71], s[70:71], s[72:73]
	s_mov_b64 exec, s[68:69]
	global_store_short v0, v6, s[44:45]
	s_mov_b64 exec, s[70:71]
	global_store_short v1, v6, s[44:45]
	s_mov_b64 exec, -1
	v_cmp_lt_u32_e64 s[68:69], s15, v121
	v_cmp_eq_u32_e64 s[70:71], s15, v121
	s_cmp_lg_u32 s15, 0
	s_cselect_b64 s[70:71], s[70:71], 0
	v_mbcnt_lo_u32_b32 v7, s68, 0
	v_mbcnt_hi_u32_b32 v7, s69, v7
	v_mbcnt_lo_u32_b32 v8, s70, 0
	v_mbcnt_hi_u32_b32 v8, s71, v8
	s_waitcnt lgkmcnt(0)
	v_and_b32_e32 v0, 0xffff, v15
	v_add_lshl_u32 v0, v0, v7, 1
	v_lshrrev_b32_e32 v1, 16, v15
	v_add3_u32 v1, v1, v8, s51
	v_cmp_gt_u32_e64 s[72:73], s84, v1
	v_lshlrev_b32_e32 v1, 1, v1
	s_and_b64 s[70:71], s[70:71], s[72:73]
	s_mov_b64 exec, s[68:69]
	global_store_short v0, v6, s[46:47]
	s_mov_b64 exec, s[70:71]
	global_store_short v1, v6, s[46:47]
	s_mov_b64 exec, -1
	s_add_i32 s28, s28, 8
	s_cmp_gt_u32 s28, s3
	s_cbranch_scc1 .Ltk_scat_done_19
; DI void topk_job(const Params& p, int b, int t0, char* lds) {
;     ...
;   const unsigned long long lt = (1ull << lane) - 1ull;
; #pragma unroll
;   for (int i = 0; i < 17; ++i) {
;     const int c = 1 + w + 8 * i;
;     if (c <= cmax) {
;       const int key = c * 64 + lane;
; #pragma unroll
;       for (int q = 0; q < 4; ++q) {
;         u16* out = p.IDX + (size_t)(b * PP + t0 + q) * 256;
;         const bool gt = sc[i][q] > T[q];
;         const bool eq = (sc[i][q] == T[q]) && (T[q] != 0u);
;         const unsigned long long m1 = __ballot(gt), m2 = __ballot(eq);
;         if ((m1 | m2) != 0ull) {
;           const unsigned bb = baseb[q * 132 + c];
;           if (gt) out[(int)(bb & 0xffffu) + __popcll(m1 & lt)] = (u16)key;
;           if (eq) { const int pos = ng[q] + (int)(bb >> 16) + __popcll(m2 & lt); if (pos < 256) out[pos] = (u16)key; }
;         }
;       }
;     }
;   }
	s_lshl_b32 s29, s28, 2
	s_addk_i32 s29, 0x1000
	v_mov_b32_e32 v11, s29
	ds_read_b32 v12, v11
	ds_read_b32 v13, v11 offset:544
	ds_read_b32 v14, v11 offset:1088
	ds_read_b32 v15, v11 offset:1632
	v_lshl_add_u32 v6, s28, 6, v101
	v_cmp_lt_u32_e64 s[68:69], s12, v181
	v_cmp_eq_u32_e64 s[70:71], s12, v181
	s_cmp_lg_u32 s12, 0
	s_cselect_b64 s[70:71], s[70:71], 0
	v_mbcnt_lo_u32_b32 v7, s68, 0
	v_mbcnt_hi_u32_b32 v7, s69, v7
	v_mbcnt_lo_u32_b32 v8, s70, 0
	v_mbcnt_hi_u32_b32 v8, s71, v8
	s_waitcnt lgkmcnt(3)
	v_and_b32_e32 v0, 0xffff, v12
	v_add_lshl_u32 v0, v0, v7, 1
	v_lshrrev_b32_e32 v1, 16, v12
	v_add3_u32 v1, v1, v8, s48
	v_cmp_gt_u32_e64 s[72:73], s84, v1
	v_lshlrev_b32_e32 v1, 1, v1
	s_and_b64 s[70:71], s[70:71], s[72:73]
	s_mov_b64 exec, s[68:69]
	global_store_short v0, v6, s[40:41]
	s_mov_b64 exec, s[70:71]
	global_store_short v1, v6, s[40:41]
	s_mov_b64 exec, -1
	v_cmp_lt_u32_e64 s[68:69], s13, v165
	v_cmp_eq_u32_e64 s[70:71], s13, v165
	s_cmp_lg_u32 s13, 0
	s_cselect_b64 s[70:71], s[70:71], 0
	v_mbcnt_lo_u32_b32 v7, s68, 0
	v_mbcnt_hi_u32_b32 v7, s69, v7
	v_mbcnt_lo_u32_b32 v8, s70, 0
	v_mbcnt_hi_u32_b32 v8, s71, v8
	s_waitcnt lgkmcnt(2)
	v_and_b32_e32 v0, 0xffff, v13
	v_add_lshl_u32 v0, v0, v7, 1
	v_lshrrev_b32_e32 v1, 16, v13
	v_add3_u32 v1, v1, v8, s49
	v_cmp_gt_u32_e64 s[72:73], s84, v1
	v_lshlrev_b32_e32 v1, 1, v1
	s_and_b64 s[70:71], s[70:71], s[72:73]
	s_mov_b64 exec, s[68:69]
	global_store_short v0, v6, s[42:43]
	s_mov_b64 exec, s[70:71]
	global_store_short v1, v6, s[42:43]
	s_mov_b64 exec, -1
	v_cmp_lt_u32_e64 s[68:69], s14, v145
	v_cmp_eq_u32_e64 s[70:71], s14, v145
	s_cmp_lg_u32 s14, 0
	s_cselect_b64 s[70:71], s[70:71], 0
	v_mbcnt_lo_u32_b32 v7, s68, 0
	v_mbcnt_hi_u32_b32 v7, s69, v7
	v_mbcnt_lo_u32_b32 v8, s70, 0
	v_mbcnt_hi_u32_b32 v8, s71, v8
	s_waitcnt lgkmcnt(1)
	v_and_b32_e32 v0, 0xffff, v14
	v_add_lshl_u32 v0, v0, v7, 1
	v_lshrrev_b32_e32 v1, 16, v14
	v_add3_u32 v1, v1, v8, s50
	v_cmp_gt_u32_e64 s[72:73], s84, v1
	v_lshlrev_b32_e32 v1, 1, v1
	s_and_b64 s[70:71], s[70:71], s[72:73]
	s_mov_b64 exec, s[68:69]
	global_store_short v0, v6, s[44:45]
	s_mov_b64 exec, s[70:71]
	global_store_short v1, v6, s[44:45]
	s_mov_b64 exec, -1
	v_cmp_lt_u32_e64 s[68:69], s15, v119
	v_cmp_eq_u32_e64 s[70:71], s15, v119
	s_cmp_lg_u32 s15, 0
	s_cselect_b64 s[70:71], s[70:71], 0
	v_mbcnt_lo_u32_b32 v7, s68, 0
	v_mbcnt_hi_u32_b32 v7, s69, v7
	v_mbcnt_lo_u32_b32 v8, s70, 0
	v_mbcnt_hi_u32_b32 v8, s71, v8
	s_waitcnt lgkmcnt(0)
	v_and_b32_e32 v0, 0xffff, v15
	v_add_lshl_u32 v0, v0, v7, 1
	v_lshrrev_b32_e32 v1, 16, v15
	v_add3_u32 v1, v1, v8, s51
	v_cmp_gt_u32_e64 s[72:73], s84, v1
	v_lshlrev_b32_e32 v1, 1, v1
	s_and_b64 s[70:71], s[70:71], s[72:73]
	s_mov_b64 exec, s[68:69]
	global_store_short v0, v6, s[46:47]
	s_mov_b64 exec, s[70:71]
	global_store_short v1, v6, s[46:47]
	s_mov_b64 exec, -1
	s_add_i32 s28, s28, 8
	s_cmp_gt_u32 s28, s3
	s_cbranch_scc1 .Ltk_scat_done_19
	s_lshl_b32 s29, s28, 2
	s_addk_i32 s29, 0x1000
	v_mov_b32_e32 v11, s29
	ds_read_b32 v12, v11
	ds_read_b32 v13, v11 offset:544
	ds_read_b32 v14, v11 offset:1088
	ds_read_b32 v15, v11 offset:1632
	v_lshl_add_u32 v6, s28, 6, v101
	v_cmp_lt_u32_e64 s[68:69], s12, v180
	v_cmp_eq_u32_e64 s[70:71], s12, v180
	s_cmp_lg_u32 s12, 0
	s_cselect_b64 s[70:71], s[70:71], 0
	v_mbcnt_lo_u32_b32 v7, s68, 0
	v_mbcnt_hi_u32_b32 v7, s69, v7
	v_mbcnt_lo_u32_b32 v8, s70, 0
	v_mbcnt_hi_u32_b32 v8, s71, v8
	s_waitcnt lgkmcnt(3)
	v_and_b32_e32 v0, 0xffff, v12
	v_add_lshl_u32 v0, v0, v7, 1
	v_lshrrev_b32_e32 v1, 16, v12
	v_add3_u32 v1, v1, v8, s48
	v_cmp_gt_u32_e64 s[72:73], s84, v1
	v_lshlrev_b32_e32 v1, 1, v1
	s_and_b64 s[70:71], s[70:71], s[72:73]
	s_mov_b64 exec, s[68:69]
	global_store_short v0, v6, s[40:41]
	s_mov_b64 exec, s[70:71]
	global_store_short v1, v6, s[40:41]
	s_mov_b64 exec, -1
	v_cmp_lt_u32_e64 s[68:69], s13, v164
	v_cmp_eq_u32_e64 s[70:71], s13, v164
	s_cmp_lg_u32 s13, 0
	s_cselect_b64 s[70:71], s[70:71], 0
	v_mbcnt_lo_u32_b32 v7, s68, 0
	v_mbcnt_hi_u32_b32 v7, s69, v7
	v_mbcnt_lo_u32_b32 v8, s70, 0
	v_mbcnt_hi_u32_b32 v8, s71, v8
	s_waitcnt lgkmcnt(2)
	v_and_b32_e32 v0, 0xffff, v13
	v_add_lshl_u32 v0, v0, v7, 1
	v_lshrrev_b32_e32 v1, 16, v13
	v_add3_u32 v1, v1, v8, s49
	v_cmp_gt_u32_e64 s[72:73], s84, v1
	v_lshlrev_b32_e32 v1, 1, v1
	s_and_b64 s[70:71], s[70:71], s[72:73]
	s_mov_b64 exec, s[68:69]
	global_store_short v0, v6, s[42:43]
	s_mov_b64 exec, s[70:71]
	global_store_short v1, v6, s[42:43]
	s_mov_b64 exec, -1
	v_cmp_lt_u32_e64 s[68:69], s14, v143
	v_cmp_eq_u32_e64 s[70:71], s14, v143
	s_cmp_lg_u32 s14, 0
	s_cselect_b64 s[70:71], s[70:71], 0
	v_mbcnt_lo_u32_b32 v7, s68, 0
	v_mbcnt_hi_u32_b32 v7, s69, v7
	v_mbcnt_lo_u32_b32 v8, s70, 0
	v_mbcnt_hi_u32_b32 v8, s71, v8
	s_waitcnt lgkmcnt(1)
	v_and_b32_e32 v0, 0xffff, v14
	v_add_lshl_u32 v0, v0, v7, 1
	v_lshrrev_b32_e32 v1, 16, v14
	v_add3_u32 v1, v1, v8, s50
	v_cmp_gt_u32_e64 s[72:73], s84, v1
	v_lshlrev_b32_e32 v1, 1, v1
	s_and_b64 s[70:71], s[70:71], s[72:73]
	s_mov_b64 exec, s[68:69]
	global_store_short v0, v6, s[44:45]
	s_mov_b64 exec, s[70:71]
	global_store_short v1, v6, s[44:45]
	s_mov_b64 exec, -1
	v_cmp_lt_u32_e64 s[68:69], s15, v115
	v_cmp_eq_u32_e64 s[70:71], s15, v115
	s_cmp_lg_u32 s15, 0
	s_cselect_b64 s[70:71], s[70:71], 0
	v_mbcnt_lo_u32_b32 v7, s68, 0
	v_mbcnt_hi_u32_b32 v7, s69, v7
	v_mbcnt_lo_u32_b32 v8, s70, 0
	v_mbcnt_hi_u32_b32 v8, s71, v8
	s_waitcnt lgkmcnt(0)
	v_and_b32_e32 v0, 0xffff, v15
	v_add_lshl_u32 v0, v0, v7, 1
	v_lshrrev_b32_e32 v1, 16, v15
	v_add3_u32 v1, v1, v8, s51
	v_cmp_gt_u32_e64 s[72:73], s84, v1
	v_lshlrev_b32_e32 v1, 1, v1
	s_and_b64 s[70:71], s[70:71], s[72:73]
	s_mov_b64 exec, s[68:69]
	global_store_short v0, v6, s[46:47]
	s_mov_b64 exec, s[70:71]
	global_store_short v1, v6, s[46:47]
	s_mov_b64 exec, -1
	s_add_i32 s28, s28, 8
	s_cmp_gt_u32 s28, s3
	s_cbranch_scc1 .Ltk_scat_done_19
; DI void topk_job(const Params& p, int b, int t0, char* lds) {
;     ...
;   const unsigned long long lt = (1ull << lane) - 1ull;
; #pragma unroll
;   for (int i = 0; i < 17; ++i) {
;     const int c = 1 + w + 8 * i;
;     if (c <= cmax) {
;       const int key = c * 64 + lane;
; #pragma unroll
;       for (int q = 0; q < 4; ++q) {
;         u16* out = p.IDX + (size_t)(b * PP + t0 + q) * 256;
;         const bool gt = sc[i][q] > T[q];
;         const bool eq = (sc[i][q] == T[q]) && (T[q] != 0u);
;         const unsigned long long m1 = __ballot(gt), m2 = __ballot(eq);
;         if ((m1 | m2) != 0ull) {
;           const unsigned bb = baseb[q * 132 + c];
;           if (gt) out[(int)(bb & 0xffffu) + __popcll(m1 & lt)] = (u16)key;
;           if (eq) { const int pos = ng[q] + (int)(bb >> 16) + __popcll(m2 & lt); if (pos < 256) out[pos] = (u16)key; }
;         }
;       }
;     }
;   }
	s_lshl_b32 s29, s28, 2
	s_addk_i32 s29, 0x1000
	v_mov_b32_e32 v11, s29
	ds_read_b32 v12, v11
	ds_read_b32 v13, v11 offset:544
	ds_read_b32 v14, v11 offset:1088
	ds_read_b32 v15, v11 offset:1632
	v_lshl_add_u32 v6, s28, 6, v101
	v_cmp_lt_u32_e64 s[68:69], s12, v179
	v_cmp_eq_u32_e64 s[70:71], s12, v179
	s_cmp_lg_u32 s12, 0
	s_cselect_b64 s[70:71], s[70:71], 0
	v_mbcnt_lo_u32_b32 v7, s68, 0
	v_mbcnt_hi_u32_b32 v7, s69, v7
	v_mbcnt_lo_u32_b32 v8, s70, 0
	v_mbcnt_hi_u32_b32 v8, s71, v8
	s_waitcnt lgkmcnt(3)
	v_and_b32_e32 v0, 0xffff, v12
	v_add_lshl_u32 v0, v0, v7, 1
	v_lshrrev_b32_e32 v1, 16, v12
	v_add3_u32 v1, v1, v8, s48
	v_cmp_gt_u32_e64 s[72:73], s84, v1
	v_lshlrev_b32_e32 v1, 1, v1
	s_and_b64 s[70:71], s[70:71], s[72:73]
	s_mov_b64 exec, s[68:69]
	global_store_short v0, v6, s[40:41]
	s_mov_b64 exec, s[70:71]
	global_store_short v1, v6, s[40:41]
	s_mov_b64 exec, -1
	v_cmp_lt_u32_e64 s[68:69], s13, v163
	v_cmp_eq_u32_e64 s[70:71], s13, v163
	s_cmp_lg_u32 s13, 0
	s_cselect_b64 s[70:71], s[70:71], 0
	v_mbcnt_lo_u32_b32 v7, s68, 0
	v_mbcnt_hi_u32_b32 v7, s69, v7
	v_mbcnt_lo_u32_b32 v8, s70, 0
	v_mbcnt_hi_u32_b32 v8, s71, v8
	s_waitcnt lgkmcnt(2)
	v_and_b32_e32 v0, 0xffff, v13
	v_add_lshl_u32 v0, v0, v7, 1
	v_lshrrev_b32_e32 v1, 16, v13
	v_add3_u32 v1, v1, v8, s49
	v_cmp_gt_u32_e64 s[72:73], s84, v1
	v_lshlrev_b32_e32 v1, 1, v1
	s_and_b64 s[70:71], s[70:71], s[72:73]
	s_mov_b64 exec, s[68:69]
	global_store_short v0, v6, s[42:43]
	s_mov_b64 exec, s[70:71]
	global_store_short v1, v6, s[42:43]
	s_mov_b64 exec, -1
	v_cmp_lt_u32_e64 s[68:69], s14, v142
	v_cmp_eq_u32_e64 s[70:71], s14, v142
	s_cmp_lg_u32 s14, 0
	s_cselect_b64 s[70:71], s[70:71], 0
	v_mbcnt_lo_u32_b32 v7, s68, 0
	v_mbcnt_hi_u32_b32 v7, s69, v7
	v_mbcnt_lo_u32_b32 v8, s70, 0
	v_mbcnt_hi_u32_b32 v8, s71, v8
	s_waitcnt lgkmcnt(1)
	v_and_b32_e32 v0, 0xffff, v14
	v_add_lshl_u32 v0, v0, v7, 1
	v_lshrrev_b32_e32 v1, 16, v14
	v_add3_u32 v1, v1, v8, s50
	v_cmp_gt_u32_e64 s[72:73], s84, v1
	v_lshlrev_b32_e32 v1, 1, v1
	s_and_b64 s[70:71], s[70:71], s[72:73]
	s_mov_b64 exec, s[68:69]
	global_store_short v0, v6, s[44:45]
	s_mov_b64 exec, s[70:71]
	global_store_short v1, v6, s[44:45]
	s_mov_b64 exec, -1
	v_cmp_lt_u32_e64 s[68:69], s15, v113
	v_cmp_eq_u32_e64 s[70:71], s15, v113
	s_cmp_lg_u32 s15, 0
	s_cselect_b64 s[70:71], s[70:71], 0
	v_mbcnt_lo_u32_b32 v7, s68, 0
	v_mbcnt_hi_u32_b32 v7, s69, v7
	v_mbcnt_lo_u32_b32 v8, s70, 0
	v_mbcnt_hi_u32_b32 v8, s71, v8
	s_waitcnt lgkmcnt(0)
	v_and_b32_e32 v0, 0xffff, v15
	v_add_lshl_u32 v0, v0, v7, 1
	v_lshrrev_b32_e32 v1, 16, v15
	v_add3_u32 v1, v1, v8, s51
	v_cmp_gt_u32_e64 s[72:73], s84, v1
	v_lshlrev_b32_e32 v1, 1, v1
	s_and_b64 s[70:71], s[70:71], s[72:73]
	s_mov_b64 exec, s[68:69]
	global_store_short v0, v6, s[46:47]
	s_mov_b64 exec, s[70:71]
	global_store_short v1, v6, s[46:47]
	s_mov_b64 exec, -1
	s_add_i32 s28, s28, 8
	s_cmp_gt_u32 s28, s3
	s_cbranch_scc1 .Ltk_scat_done_19
	s_lshl_b32 s29, s28, 2
	s_addk_i32 s29, 0x1000
	v_mov_b32_e32 v11, s29
	ds_read_b32 v12, v11
	ds_read_b32 v13, v11 offset:544
	ds_read_b32 v14, v11 offset:1088
	ds_read_b32 v15, v11 offset:1632
	v_lshl_add_u32 v6, s28, 6, v101
	v_cmp_lt_u32_e64 s[68:69], s12, v178
	v_cmp_eq_u32_e64 s[70:71], s12, v178
	s_cmp_lg_u32 s12, 0
	s_cselect_b64 s[70:71], s[70:71], 0
	v_mbcnt_lo_u32_b32 v7, s68, 0
	v_mbcnt_hi_u32_b32 v7, s69, v7
	v_mbcnt_lo_u32_b32 v8, s70, 0
	v_mbcnt_hi_u32_b32 v8, s71, v8
	s_waitcnt lgkmcnt(3)
	v_and_b32_e32 v0, 0xffff, v12
	v_add_lshl_u32 v0, v0, v7, 1
	v_lshrrev_b32_e32 v1, 16, v12
	v_add3_u32 v1, v1, v8, s48
	v_cmp_gt_u32_e64 s[72:73], s84, v1
	v_lshlrev_b32_e32 v1, 1, v1
	s_and_b64 s[70:71], s[70:71], s[72:73]
	s_mov_b64 exec, s[68:69]
	global_store_short v0, v6, s[40:41]
	s_mov_b64 exec, s[70:71]
	global_store_short v1, v6, s[40:41]
	s_mov_b64 exec, -1
	v_cmp_lt_u32_e64 s[68:69], s13, v162
	v_cmp_eq_u32_e64 s[70:71], s13, v162
	s_cmp_lg_u32 s13, 0
	s_cselect_b64 s[70:71], s[70:71], 0
	v_mbcnt_lo_u32_b32 v7, s68, 0
	v_mbcnt_hi_u32_b32 v7, s69, v7
	v_mbcnt_lo_u32_b32 v8, s70, 0
	v_mbcnt_hi_u32_b32 v8, s71, v8
	s_waitcnt lgkmcnt(2)
	v_and_b32_e32 v0, 0xffff, v13
	v_add_lshl_u32 v0, v0, v7, 1
	v_lshrrev_b32_e32 v1, 16, v13
	v_add3_u32 v1, v1, v8, s49
	v_cmp_gt_u32_e64 s[72:73], s84, v1
	v_lshlrev_b32_e32 v1, 1, v1
	s_and_b64 s[70:71], s[70:71], s[72:73]
	s_mov_b64 exec, s[68:69]
	global_store_short v0, v6, s[42:43]
	s_mov_b64 exec, s[70:71]
	global_store_short v1, v6, s[42:43]
	s_mov_b64 exec, -1
	v_cmp_lt_u32_e64 s[68:69], s14, v141
	v_cmp_eq_u32_e64 s[70:71], s14, v141
	s_cmp_lg_u32 s14, 0
	s_cselect_b64 s[70:71], s[70:71], 0
	v_mbcnt_lo_u32_b32 v7, s68, 0
	v_mbcnt_hi_u32_b32 v7, s69, v7
	v_mbcnt_lo_u32_b32 v8, s70, 0
	v_mbcnt_hi_u32_b32 v8, s71, v8
	s_waitcnt lgkmcnt(1)
	v_and_b32_e32 v0, 0xffff, v14
	v_add_lshl_u32 v0, v0, v7, 1
	v_lshrrev_b32_e32 v1, 16, v14
	v_add3_u32 v1, v1, v8, s50
	v_cmp_gt_u32_e64 s[72:73], s84, v1
	v_lshlrev_b32_e32 v1, 1, v1
	s_and_b64 s[70:71], s[70:71], s[72:73]
	s_mov_b64 exec, s[68:69]
	global_store_short v0, v6, s[44:45]
	s_mov_b64 exec, s[70:71]
	global_store_short v1, v6, s[44:45]
	s_mov_b64 exec, -1
	v_cmp_lt_u32_e64 s[68:69], s15, v111
	v_cmp_eq_u32_e64 s[70:71], s15, v111
	s_cmp_lg_u32 s15, 0
	s_cselect_b64 s[70:71], s[70:71], 0
	v_mbcnt_lo_u32_b32 v7, s68, 0
	v_mbcnt_hi_u32_b32 v7, s69, v7
	v_mbcnt_lo_u32_b32 v8, s70, 0
	v_mbcnt_hi_u32_b32 v8, s71, v8
	s_waitcnt lgkmcnt(0)
	v_and_b32_e32 v0, 0xffff, v15
	v_add_lshl_u32 v0, v0, v7, 1
	v_lshrrev_b32_e32 v1, 16, v15
	v_add3_u32 v1, v1, v8, s51
	v_cmp_gt_u32_e64 s[72:73], s84, v1
	v_lshlrev_b32_e32 v1, 1, v1
	s_and_b64 s[70:71], s[70:71], s[72:73]
	s_mov_b64 exec, s[68:69]
	global_store_short v0, v6, s[46:47]
	s_mov_b64 exec, s[70:71]
	global_store_short v1, v6, s[46:47]
	s_mov_b64 exec, -1
	s_add_i32 s28, s28, 8
	s_cmp_gt_u32 s28, s3
	s_cbranch_scc1 .Ltk_scat_done_19
; DI void topk_job(const Params& p, int b, int t0, char* lds) {
;     ...
;   const unsigned long long lt = (1ull << lane) - 1ull;
; #pragma unroll
;   for (int i = 0; i < 17; ++i) {
;     const int c = 1 + w + 8 * i;
;     if (c <= cmax) {
;       const int key = c * 64 + lane;
; #pragma unroll
;       for (int q = 0; q < 4; ++q) {
;         u16* out = p.IDX + (size_t)(b * PP + t0 + q) * 256;
;         const bool gt = sc[i][q] > T[q];
;         const bool eq = (sc[i][q] == T[q]) && (T[q] != 0u);
;         const unsigned long long m1 = __ballot(gt), m2 = __ballot(eq);
;         if ((m1 | m2) != 0ull) {
;           const unsigned bb = baseb[q * 132 + c];
;           if (gt) out[(int)(bb & 0xffffu) + __popcll(m1 & lt)] = (u16)key;
;           if (eq) { const int pos = ng[q] + (int)(bb >> 16) + __popcll(m2 & lt); if (pos < 256) out[pos] = (u16)key; }
;         }
;       }
;     }
;   }
	s_lshl_b32 s29, s28, 2
	s_addk_i32 s29, 0x1000
	v_mov_b32_e32 v11, s29
	ds_read_b32 v12, v11
	ds_read_b32 v13, v11 offset:544
	ds_read_b32 v14, v11 offset:1088
	ds_read_b32 v15, v11 offset:1632
	v_lshl_add_u32 v6, s28, 6, v101
	v_cmp_lt_u32_e64 s[68:69], s12, v177
	v_cmp_eq_u32_e64 s[70:71], s12, v177
	s_cmp_lg_u32 s12, 0
	s_cselect_b64 s[70:71], s[70:71], 0
	v_mbcnt_lo_u32_b32 v7, s68, 0
	v_mbcnt_hi_u32_b32 v7, s69, v7
	v_mbcnt_lo_u32_b32 v8, s70, 0
	v_mbcnt_hi_u32_b32 v8, s71, v8
	s_waitcnt lgkmcnt(3)
	v_and_b32_e32 v0, 0xffff, v12
	v_add_lshl_u32 v0, v0, v7, 1
	v_lshrrev_b32_e32 v1, 16, v12
	v_add3_u32 v1, v1, v8, s48
	v_cmp_gt_u32_e64 s[72:73], s84, v1
	v_lshlrev_b32_e32 v1, 1, v1
	s_and_b64 s[70:71], s[70:71], s[72:73]
	s_mov_b64 exec, s[68:69]
	global_store_short v0, v6, s[40:41]
	s_mov_b64 exec, s[70:71]
	global_store_short v1, v6, s[40:41]
	s_mov_b64 exec, -1
	v_cmp_lt_u32_e64 s[68:69], s13, v160
	v_cmp_eq_u32_e64 s[70:71], s13, v160
	s_cmp_lg_u32 s13, 0
	s_cselect_b64 s[70:71], s[70:71], 0
	v_mbcnt_lo_u32_b32 v7, s68, 0
	v_mbcnt_hi_u32_b32 v7, s69, v7
	v_mbcnt_lo_u32_b32 v8, s70, 0
	v_mbcnt_hi_u32_b32 v8, s71, v8
	s_waitcnt lgkmcnt(2)
	v_and_b32_e32 v0, 0xffff, v13
	v_add_lshl_u32 v0, v0, v7, 1
	v_lshrrev_b32_e32 v1, 16, v13
	v_add3_u32 v1, v1, v8, s49
	v_cmp_gt_u32_e64 s[72:73], s84, v1
	v_lshlrev_b32_e32 v1, 1, v1
	s_and_b64 s[70:71], s[70:71], s[72:73]
	s_mov_b64 exec, s[68:69]
	global_store_short v0, v6, s[42:43]
	s_mov_b64 exec, s[70:71]
	global_store_short v1, v6, s[42:43]
	s_mov_b64 exec, -1
	v_cmp_lt_u32_e64 s[68:69], s14, v140
	v_cmp_eq_u32_e64 s[70:71], s14, v140
	s_cmp_lg_u32 s14, 0
	s_cselect_b64 s[70:71], s[70:71], 0
	v_mbcnt_lo_u32_b32 v7, s68, 0
	v_mbcnt_hi_u32_b32 v7, s69, v7
	v_mbcnt_lo_u32_b32 v8, s70, 0
	v_mbcnt_hi_u32_b32 v8, s71, v8
	s_waitcnt lgkmcnt(1)
	v_and_b32_e32 v0, 0xffff, v14
	v_add_lshl_u32 v0, v0, v7, 1
	v_lshrrev_b32_e32 v1, 16, v14
	v_add3_u32 v1, v1, v8, s50
	v_cmp_gt_u32_e64 s[72:73], s84, v1
	v_lshlrev_b32_e32 v1, 1, v1
	s_and_b64 s[70:71], s[70:71], s[72:73]
	s_mov_b64 exec, s[68:69]
	global_store_short v0, v6, s[44:45]
	s_mov_b64 exec, s[70:71]
	global_store_short v1, v6, s[44:45]
	s_mov_b64 exec, -1
	v_cmp_lt_u32_e64 s[68:69], s15, v109
	v_cmp_eq_u32_e64 s[70:71], s15, v109
	s_cmp_lg_u32 s15, 0
	s_cselect_b64 s[70:71], s[70:71], 0
	v_mbcnt_lo_u32_b32 v7, s68, 0
	v_mbcnt_hi_u32_b32 v7, s69, v7
	v_mbcnt_lo_u32_b32 v8, s70, 0
	v_mbcnt_hi_u32_b32 v8, s71, v8
	s_waitcnt lgkmcnt(0)
	v_and_b32_e32 v0, 0xffff, v15
	v_add_lshl_u32 v0, v0, v7, 1
	v_lshrrev_b32_e32 v1, 16, v15
	v_add3_u32 v1, v1, v8, s51
	v_cmp_gt_u32_e64 s[72:73], s84, v1
	v_lshlrev_b32_e32 v1, 1, v1
	s_and_b64 s[70:71], s[70:71], s[72:73]
	s_mov_b64 exec, s[68:69]
	global_store_short v0, v6, s[46:47]
	s_mov_b64 exec, s[70:71]
	global_store_short v1, v6, s[46:47]
	s_mov_b64 exec, -1
	s_add_i32 s28, s28, 8
	s_cmp_gt_u32 s28, s3
	s_cbranch_scc1 .Ltk_scat_done_19
	s_lshl_b32 s29, s28, 2
	s_addk_i32 s29, 0x1000
	v_mov_b32_e32 v11, s29
	ds_read_b32 v12, v11
	ds_read_b32 v13, v11 offset:544
	ds_read_b32 v14, v11 offset:1088
	ds_read_b32 v15, v11 offset:1632
	v_lshl_add_u32 v6, s28, 6, v101
	v_cmp_lt_u32_e64 s[68:69], s12, v176
	v_cmp_eq_u32_e64 s[70:71], s12, v176
	s_cmp_lg_u32 s12, 0
	s_cselect_b64 s[70:71], s[70:71], 0
	v_mbcnt_lo_u32_b32 v7, s68, 0
	v_mbcnt_hi_u32_b32 v7, s69, v7
	v_mbcnt_lo_u32_b32 v8, s70, 0
	v_mbcnt_hi_u32_b32 v8, s71, v8
	s_waitcnt lgkmcnt(3)
	v_and_b32_e32 v0, 0xffff, v12
	v_add_lshl_u32 v0, v0, v7, 1
	v_lshrrev_b32_e32 v1, 16, v12
	v_add3_u32 v1, v1, v8, s48
	v_cmp_gt_u32_e64 s[72:73], s84, v1
	v_lshlrev_b32_e32 v1, 1, v1
	s_and_b64 s[70:71], s[70:71], s[72:73]
	s_mov_b64 exec, s[68:69]
	global_store_short v0, v6, s[40:41]
	s_mov_b64 exec, s[70:71]
	global_store_short v1, v6, s[40:41]
	s_mov_b64 exec, -1
	v_cmp_lt_u32_e64 s[68:69], s13, v151
	v_cmp_eq_u32_e64 s[70:71], s13, v151
	s_cmp_lg_u32 s13, 0
	s_cselect_b64 s[70:71], s[70:71], 0
	v_mbcnt_lo_u32_b32 v7, s68, 0
	v_mbcnt_hi_u32_b32 v7, s69, v7
	v_mbcnt_lo_u32_b32 v8, s70, 0
	v_mbcnt_hi_u32_b32 v8, s71, v8
	s_waitcnt lgkmcnt(2)
	v_and_b32_e32 v0, 0xffff, v13
	v_add_lshl_u32 v0, v0, v7, 1
	v_lshrrev_b32_e32 v1, 16, v13
	v_add3_u32 v1, v1, v8, s49
	v_cmp_gt_u32_e64 s[72:73], s84, v1
	v_lshlrev_b32_e32 v1, 1, v1
	s_and_b64 s[70:71], s[70:71], s[72:73]
	s_mov_b64 exec, s[68:69]
	global_store_short v0, v6, s[42:43]
	s_mov_b64 exec, s[70:71]
	global_store_short v1, v6, s[42:43]
	s_mov_b64 exec, -1
	v_cmp_lt_u32_e64 s[68:69], s14, v139
	v_cmp_eq_u32_e64 s[70:71], s14, v139
	s_cmp_lg_u32 s14, 0
	s_cselect_b64 s[70:71], s[70:71], 0
	v_mbcnt_lo_u32_b32 v7, s68, 0
	v_mbcnt_hi_u32_b32 v7, s69, v7
	v_mbcnt_lo_u32_b32 v8, s70, 0
	v_mbcnt_hi_u32_b32 v8, s71, v8
	s_waitcnt lgkmcnt(1)
	v_and_b32_e32 v0, 0xffff, v14
	v_add_lshl_u32 v0, v0, v7, 1
	v_lshrrev_b32_e32 v1, 16, v14
	v_add3_u32 v1, v1, v8, s50
	v_cmp_gt_u32_e64 s[72:73], s84, v1
	v_lshlrev_b32_e32 v1, 1, v1
	s_and_b64 s[70:71], s[70:71], s[72:73]
	s_mov_b64 exec, s[68:69]
	global_store_short v0, v6, s[44:45]
	s_mov_b64 exec, s[70:71]
	global_store_short v1, v6, s[44:45]
	s_mov_b64 exec, -1
	v_cmp_lt_u32_e64 s[68:69], s15, v107
	v_cmp_eq_u32_e64 s[70:71], s15, v107
	s_cmp_lg_u32 s15, 0
	s_cselect_b64 s[70:71], s[70:71], 0
	v_mbcnt_lo_u32_b32 v7, s68, 0
	v_mbcnt_hi_u32_b32 v7, s69, v7
	v_mbcnt_lo_u32_b32 v8, s70, 0
	v_mbcnt_hi_u32_b32 v8, s71, v8
	s_waitcnt lgkmcnt(0)
	v_and_b32_e32 v0, 0xffff, v15
	v_add_lshl_u32 v0, v0, v7, 1
	v_lshrrev_b32_e32 v1, 16, v15
	v_add3_u32 v1, v1, v8, s51
	v_cmp_gt_u32_e64 s[72:73], s84, v1
	v_lshlrev_b32_e32 v1, 1, v1
	s_and_b64 s[70:71], s[70:71], s[72:73]
	s_mov_b64 exec, s[68:69]
	global_store_short v0, v6, s[46:47]
	s_mov_b64 exec, s[70:71]
	global_store_short v1, v6, s[46:47]
	s_mov_b64 exec, -1
	s_add_i32 s28, s28, 8
	s_cmp_gt_u32 s28, s3
	s_cbranch_scc1 .Ltk_scat_done_19
; DI void topk_job(const Params& p, int b, int t0, char* lds) {
;     ...
;   const unsigned long long lt = (1ull << lane) - 1ull;
; #pragma unroll
;   for (int i = 0; i < 17; ++i) {
;     const int c = 1 + w + 8 * i;
;     if (c <= cmax) {
;       const int key = c * 64 + lane;
; #pragma unroll
;       for (int q = 0; q < 4; ++q) {
;         u16* out = p.IDX + (size_t)(b * PP + t0 + q) * 256;
;         const bool gt = sc[i][q] > T[q];
;         const bool eq = (sc[i][q] == T[q]) && (T[q] != 0u);
;         const unsigned long long m1 = __ballot(gt), m2 = __ballot(eq);
;         if ((m1 | m2) != 0ull) {
;           const unsigned bb = baseb[q * 132 + c];
;           if (gt) out[(int)(bb & 0xffffu) + __popcll(m1 & lt)] = (u16)key;
;           if (eq) { const int pos = ng[q] + (int)(bb >> 16) + __popcll(m2 & lt); if (pos < 256) out[pos] = (u16)key; }
;         }
;       }
;     }
;   }
	s_lshl_b32 s29, s28, 2
	s_addk_i32 s29, 0x1000
	v_mov_b32_e32 v11, s29
	ds_read_b32 v12, v11
	ds_read_b32 v13, v11 offset:544
	ds_read_b32 v14, v11 offset:1088
	ds_read_b32 v15, v11 offset:1632
	v_lshl_add_u32 v6, s28, 6, v101
	v_cmp_lt_u32_e64 s[68:69], s12, v174
	v_cmp_eq_u32_e64 s[70:71], s12, v174
	s_cmp_lg_u32 s12, 0
	s_cselect_b64 s[70:71], s[70:71], 0
	v_mbcnt_lo_u32_b32 v7, s68, 0
	v_mbcnt_hi_u32_b32 v7, s69, v7
	v_mbcnt_lo_u32_b32 v8, s70, 0
	v_mbcnt_hi_u32_b32 v8, s71, v8
	s_waitcnt lgkmcnt(3)
	v_and_b32_e32 v0, 0xffff, v12
	v_add_lshl_u32 v0, v0, v7, 1
	v_lshrrev_b32_e32 v1, 16, v12
	v_add3_u32 v1, v1, v8, s48
	v_cmp_gt_u32_e64 s[72:73], s84, v1
	v_lshlrev_b32_e32 v1, 1, v1
	s_and_b64 s[70:71], s[70:71], s[72:73]
	s_mov_b64 exec, s[68:69]
	global_store_short v0, v6, s[40:41]
	s_mov_b64 exec, s[70:71]
	global_store_short v1, v6, s[40:41]
	s_mov_b64 exec, -1
	v_cmp_lt_u32_e64 s[68:69], s13, v148
	v_cmp_eq_u32_e64 s[70:71], s13, v148
	s_cmp_lg_u32 s13, 0
	s_cselect_b64 s[70:71], s[70:71], 0
	v_mbcnt_lo_u32_b32 v7, s68, 0
	v_mbcnt_hi_u32_b32 v7, s69, v7
	v_mbcnt_lo_u32_b32 v8, s70, 0
	v_mbcnt_hi_u32_b32 v8, s71, v8
	s_waitcnt lgkmcnt(2)
	v_and_b32_e32 v0, 0xffff, v13
	v_add_lshl_u32 v0, v0, v7, 1
	v_lshrrev_b32_e32 v1, 16, v13
	v_add3_u32 v1, v1, v8, s49
	v_cmp_gt_u32_e64 s[72:73], s84, v1
	v_lshlrev_b32_e32 v1, 1, v1
	s_and_b64 s[70:71], s[70:71], s[72:73]
	s_mov_b64 exec, s[68:69]
	global_store_short v0, v6, s[42:43]
	s_mov_b64 exec, s[70:71]
	global_store_short v1, v6, s[42:43]
	s_mov_b64 exec, -1
	v_cmp_lt_u32_e64 s[68:69], s14, v131
	v_cmp_eq_u32_e64 s[70:71], s14, v131
	s_cmp_lg_u32 s14, 0
	s_cselect_b64 s[70:71], s[70:71], 0
	v_mbcnt_lo_u32_b32 v7, s68, 0
	v_mbcnt_hi_u32_b32 v7, s69, v7
	v_mbcnt_lo_u32_b32 v8, s70, 0
	v_mbcnt_hi_u32_b32 v8, s71, v8
	s_waitcnt lgkmcnt(1)
	v_and_b32_e32 v0, 0xffff, v14
	v_add_lshl_u32 v0, v0, v7, 1
	v_lshrrev_b32_e32 v1, 16, v14
	v_add3_u32 v1, v1, v8, s50
	v_cmp_gt_u32_e64 s[72:73], s84, v1
	v_lshlrev_b32_e32 v1, 1, v1
	s_and_b64 s[70:71], s[70:71], s[72:73]
	s_mov_b64 exec, s[68:69]
	global_store_short v0, v6, s[44:45]
	s_mov_b64 exec, s[70:71]
	global_store_short v1, v6, s[44:45]
	s_mov_b64 exec, -1
	v_cmp_lt_u32_e64 s[68:69], s15, v105
	v_cmp_eq_u32_e64 s[70:71], s15, v105
	s_cmp_lg_u32 s15, 0
	s_cselect_b64 s[70:71], s[70:71], 0
	v_mbcnt_lo_u32_b32 v7, s68, 0
	v_mbcnt_hi_u32_b32 v7, s69, v7
	v_mbcnt_lo_u32_b32 v8, s70, 0
	v_mbcnt_hi_u32_b32 v8, s71, v8
	s_waitcnt lgkmcnt(0)
	v_and_b32_e32 v0, 0xffff, v15
	v_add_lshl_u32 v0, v0, v7, 1
	v_lshrrev_b32_e32 v1, 16, v15
	v_add3_u32 v1, v1, v8, s51
	v_cmp_gt_u32_e64 s[72:73], s84, v1
	v_lshlrev_b32_e32 v1, 1, v1
	s_and_b64 s[70:71], s[70:71], s[72:73]
	s_mov_b64 exec, s[68:69]
	global_store_short v0, v6, s[46:47]
	s_mov_b64 exec, s[70:71]
	global_store_short v1, v6, s[46:47]
	s_mov_b64 exec, -1
	s_add_i32 s28, s28, 8
	s_cmp_gt_u32 s28, s3
	s_cbranch_scc1 .Ltk_scat_done_19
	s_lshl_b32 s29, s28, 2
	s_addk_i32 s29, 0x1000
	v_mov_b32_e32 v11, s29
	ds_read_b32 v12, v11
	ds_read_b32 v13, v11 offset:544
	ds_read_b32 v14, v11 offset:1088
	ds_read_b32 v15, v11 offset:1632
	v_lshl_add_u32 v6, s28, 6, v101
	v_cmp_lt_u32_e64 s[68:69], s12, v169
	v_cmp_eq_u32_e64 s[70:71], s12, v169
	s_cmp_lg_u32 s12, 0
	s_cselect_b64 s[70:71], s[70:71], 0
	v_mbcnt_lo_u32_b32 v7, s68, 0
	v_mbcnt_hi_u32_b32 v7, s69, v7
	v_mbcnt_lo_u32_b32 v8, s70, 0
	v_mbcnt_hi_u32_b32 v8, s71, v8
	s_waitcnt lgkmcnt(3)
	v_and_b32_e32 v0, 0xffff, v12
	v_add_lshl_u32 v0, v0, v7, 1
	v_lshrrev_b32_e32 v1, 16, v12
	v_add3_u32 v1, v1, v8, s48
	v_cmp_gt_u32_e64 s[72:73], s84, v1
	v_lshlrev_b32_e32 v1, 1, v1
	s_and_b64 s[70:71], s[70:71], s[72:73]
	s_mov_b64 exec, s[68:69]
	global_store_short v0, v6, s[40:41]
	s_mov_b64 exec, s[70:71]
	global_store_short v1, v6, s[40:41]
	s_mov_b64 exec, -1
	v_cmp_lt_u32_e64 s[68:69], s13, v144
	v_cmp_eq_u32_e64 s[70:71], s13, v144
	s_cmp_lg_u32 s13, 0
	s_cselect_b64 s[70:71], s[70:71], 0
	v_mbcnt_lo_u32_b32 v7, s68, 0
	v_mbcnt_hi_u32_b32 v7, s69, v7
	v_mbcnt_lo_u32_b32 v8, s70, 0
	v_mbcnt_hi_u32_b32 v8, s71, v8
	s_waitcnt lgkmcnt(2)
	v_and_b32_e32 v0, 0xffff, v13
	v_add_lshl_u32 v0, v0, v7, 1
	v_lshrrev_b32_e32 v1, 16, v13
	v_add3_u32 v1, v1, v8, s49
	v_cmp_gt_u32_e64 s[72:73], s84, v1
	v_lshlrev_b32_e32 v1, 1, v1
	s_and_b64 s[70:71], s[70:71], s[72:73]
	s_mov_b64 exec, s[68:69]
	global_store_short v0, v6, s[42:43]
	s_mov_b64 exec, s[70:71]
	global_store_short v1, v6, s[42:43]
	s_mov_b64 exec, -1
	v_cmp_lt_u32_e64 s[68:69], s14, v117
	v_cmp_eq_u32_e64 s[70:71], s14, v117
	s_cmp_lg_u32 s14, 0
	s_cselect_b64 s[70:71], s[70:71], 0
	v_mbcnt_lo_u32_b32 v7, s68, 0
	v_mbcnt_hi_u32_b32 v7, s69, v7
	v_mbcnt_lo_u32_b32 v8, s70, 0
	v_mbcnt_hi_u32_b32 v8, s71, v8
	s_waitcnt lgkmcnt(1)
	v_and_b32_e32 v0, 0xffff, v14
	v_add_lshl_u32 v0, v0, v7, 1
	v_lshrrev_b32_e32 v1, 16, v14
	v_add3_u32 v1, v1, v8, s50
	v_cmp_gt_u32_e64 s[72:73], s84, v1
	v_lshlrev_b32_e32 v1, 1, v1
	s_and_b64 s[70:71], s[70:71], s[72:73]
	s_mov_b64 exec, s[68:69]
	global_store_short v0, v6, s[44:45]
	s_mov_b64 exec, s[70:71]
	global_store_short v1, v6, s[44:45]
	s_mov_b64 exec, -1
	v_cmp_lt_u32_e64 s[68:69], s15, v103
	v_cmp_eq_u32_e64 s[70:71], s15, v103
	s_cmp_lg_u32 s15, 0
	s_cselect_b64 s[70:71], s[70:71], 0
	v_mbcnt_lo_u32_b32 v7, s68, 0
	v_mbcnt_hi_u32_b32 v7, s69, v7
	v_mbcnt_lo_u32_b32 v8, s70, 0
	v_mbcnt_hi_u32_b32 v8, s71, v8
	s_waitcnt lgkmcnt(0)
	v_and_b32_e32 v0, 0xffff, v15
	v_add_lshl_u32 v0, v0, v7, 1
	v_lshrrev_b32_e32 v1, 16, v15
	v_add3_u32 v1, v1, v8, s51
	v_cmp_gt_u32_e64 s[72:73], s84, v1
	v_lshlrev_b32_e32 v1, 1, v1
	s_and_b64 s[70:71], s[70:71], s[72:73]
	s_mov_b64 exec, s[68:69]
	global_store_short v0, v6, s[46:47]
	s_mov_b64 exec, s[70:71]
	global_store_short v1, v6, s[46:47]
	s_mov_b64 exec, -1
	s_add_i32 s28, s28, 8
	s_cmp_gt_u32 s28, s3
	s_cbranch_scc1 .Ltk_scat_done_19
; DI void topk_job(const Params& p, int b, int t0, char* lds) {
;     ...
;   for (int i = 0; i < 17; ++i) {
;     const int c = 1 + w + 8 * i;
;     if (c <= cmax) {
;       const int key = c * 64 + lane;
; #pragma unroll
;       for (int q = 0; q < 4; ++q) {
;         u16* out = p.IDX + (size_t)(b * PP + t0 + q) * 256;
;         const bool gt = sc[i][q] > T[q];
;         const bool eq = (sc[i][q] == T[q]) && (T[q] != 0u);
;         const unsigned long long m1 = __ballot(gt), m2 = __ballot(eq);
;         if ((m1 | m2) != 0ull) {
;           const unsigned bb = baseb[q * 132 + c];
;           if (gt) out[(int)(bb & 0xffffu) + __popcll(m1 & lt)] = (u16)key;
;           if (eq) { const int pos = ng[q] + (int)(bb >> 16) + __popcll(m2 & lt); if (pos < 256) out[pos] = (u16)key; }
;         }
;       }
;     }
;   }
; #pragma unroll
;   for (int q = 0; q < 4; ++q) {
;     if (T[q] == 0u) {
;       u16* out = p.IDX + (size_t)(b * PP + t0 + q) * 256;
;       if (tid < 256 && tid >= ng[q]) out[tid] = (u16)0xFFFF;
;     }
;   }
	s_lshl_b32 s29, s28, 2
	s_addk_i32 s29, 0x1000
	v_mov_b32_e32 v11, s29
	ds_read_b32 v12, v11
	ds_read_b32 v13, v11 offset:544
	ds_read_b32 v14, v11 offset:1088
	ds_read_b32 v15, v11 offset:1632
	v_lshl_add_u32 v6, s28, 6, v101
	v_cmp_lt_u32_e64 s[68:69], s12, v19
	v_cmp_eq_u32_e64 s[70:71], s12, v19
	s_cmp_lg_u32 s12, 0
	s_cselect_b64 s[70:71], s[70:71], 0
	v_mbcnt_lo_u32_b32 v7, s68, 0
	v_mbcnt_hi_u32_b32 v7, s69, v7
	v_mbcnt_lo_u32_b32 v8, s70, 0
	v_mbcnt_hi_u32_b32 v8, s71, v8
	s_waitcnt lgkmcnt(3)
	v_and_b32_e32 v0, 0xffff, v12
	v_add_lshl_u32 v0, v0, v7, 1
	v_lshrrev_b32_e32 v1, 16, v12
	v_add3_u32 v1, v1, v8, s48
	v_cmp_gt_u32_e64 s[72:73], s84, v1
	v_lshlrev_b32_e32 v1, 1, v1
	s_and_b64 s[70:71], s[70:71], s[72:73]
	s_mov_b64 exec, s[68:69]
	global_store_short v0, v6, s[40:41]
	s_mov_b64 exec, s[70:71]
	global_store_short v1, v6, s[40:41]
	s_mov_b64 exec, -1
	v_cmp_lt_u32_e64 s[68:69], s13, v18
	v_cmp_eq_u32_e64 s[70:71], s13, v18
	s_cmp_lg_u32 s13, 0
	s_cselect_b64 s[70:71], s[70:71], 0
	v_mbcnt_lo_u32_b32 v7, s68, 0
	v_mbcnt_hi_u32_b32 v7, s69, v7
	v_mbcnt_lo_u32_b32 v8, s70, 0
	v_mbcnt_hi_u32_b32 v8, s71, v8
	s_waitcnt lgkmcnt(2)
	v_and_b32_e32 v0, 0xffff, v13
	v_add_lshl_u32 v0, v0, v7, 1
	v_lshrrev_b32_e32 v1, 16, v13
	v_add3_u32 v1, v1, v8, s49
	v_cmp_gt_u32_e64 s[72:73], s84, v1
	v_lshlrev_b32_e32 v1, 1, v1
	s_and_b64 s[70:71], s[70:71], s[72:73]
	s_mov_b64 exec, s[68:69]
	global_store_short v0, v6, s[42:43]
	s_mov_b64 exec, s[70:71]
	global_store_short v1, v6, s[42:43]
	s_mov_b64 exec, -1
	v_cmp_lt_u32_e64 s[68:69], s14, v17
	v_cmp_eq_u32_e64 s[70:71], s14, v17
	s_cmp_lg_u32 s14, 0
	s_cselect_b64 s[70:71], s[70:71], 0
	v_mbcnt_lo_u32_b32 v7, s68, 0
	v_mbcnt_hi_u32_b32 v7, s69, v7
	v_mbcnt_lo_u32_b32 v8, s70, 0
	v_mbcnt_hi_u32_b32 v8, s71, v8
	s_waitcnt lgkmcnt(1)
	v_and_b32_e32 v0, 0xffff, v14
	v_add_lshl_u32 v0, v0, v7, 1
	v_lshrrev_b32_e32 v1, 16, v14
	v_add3_u32 v1, v1, v8, s50
	v_cmp_gt_u32_e64 s[72:73], s84, v1
	v_lshlrev_b32_e32 v1, 1, v1
	s_and_b64 s[70:71], s[70:71], s[72:73]
	s_mov_b64 exec, s[68:69]
	global_store_short v0, v6, s[44:45]
	s_mov_b64 exec, s[70:71]
	global_store_short v1, v6, s[44:45]
	s_mov_b64 exec, -1
	v_cmp_lt_u32_e64 s[68:69], s15, v16
	v_cmp_eq_u32_e64 s[70:71], s15, v16
	s_cmp_lg_u32 s15, 0
	s_cselect_b64 s[70:71], s[70:71], 0
	v_mbcnt_lo_u32_b32 v7, s68, 0
	v_mbcnt_hi_u32_b32 v7, s69, v7
	v_mbcnt_lo_u32_b32 v8, s70, 0
	v_mbcnt_hi_u32_b32 v8, s71, v8
	s_waitcnt lgkmcnt(0)
	v_and_b32_e32 v0, 0xffff, v15
	v_add_lshl_u32 v0, v0, v7, 1
	v_lshrrev_b32_e32 v1, 16, v15
	v_add3_u32 v1, v1, v8, s51
	v_cmp_gt_u32_e64 s[72:73], s84, v1
	v_lshlrev_b32_e32 v1, 1, v1
	s_and_b64 s[70:71], s[70:71], s[72:73]
	s_mov_b64 exec, s[68:69]
	global_store_short v0, v6, s[46:47]
	s_mov_b64 exec, s[70:71]
	global_store_short v1, v6, s[46:47]
	s_mov_b64 exec, -1
.Ltk_scat_done_19:
	v_mov_b32_e32 v2, -1
	v_lshlrev_b32_e32 v0, 1, v100
	s_cmp_lg_u32 s12, 0
	s_cbranch_scc1 .Ltk_fill_20
	v_cmp_gt_u32_e64 s[68:69], s84, v100
	v_cmp_le_u32_e64 s[70:71], s48, v100
	s_and_b64 exec, s[68:69], s[70:71]
	global_store_short v0, v2, s[40:41]
	s_mov_b64 exec, -1
.Ltk_fill_20:
	s_cmp_lg_u32 s13, 0
	s_cbranch_scc1 .Ltk_fill_21
	v_cmp_gt_u32_e64 s[68:69], s84, v100
	v_cmp_le_u32_e64 s[70:71], s49, v100
	s_and_b64 exec, s[68:69], s[70:71]
	global_store_short v0, v2, s[42:43]
	s_mov_b64 exec, -1
.Ltk_fill_21:
	s_cmp_lg_u32 s14, 0
	s_cbranch_scc1 .Ltk_fill_22
	v_cmp_gt_u32_e64 s[68:69], s84, v100
	v_cmp_le_u32_e64 s[70:71], s50, v100
	s_and_b64 exec, s[68:69], s[70:71]
	global_store_short v0, v2, s[44:45]
	s_mov_b64 exec, -1
.Ltk_fill_22:
	s_cmp_lg_u32 s15, 0
	s_cbranch_scc1 .Ltk_fill_23
	v_cmp_gt_u32_e64 s[68:69], s84, v100
	v_cmp_le_u32_e64 s[70:71], s51, v100
	s_and_b64 exec, s[68:69], s[70:71]
	global_store_short v0, v2, s[46:47]
	s_mov_b64 exec, -1
.Ltk_fill_23:
	v_readlane_b32 s6, v240, 7
	v_readlane_b32 s7, v240, 8
	v_readlane_b32 s8, v240, 9
	v_readlane_b32 s9, v240, 10
	v_readlane_b32 s10, v240, 11
	v_readlane_b32 s11, v240, 12
	v_readlane_b32 s12, v240, 13
	v_readlane_b32 s13, v240, 14
	v_readlane_b32 s17, v240, 10
	v_readlane_b32 s20, v240, 13
	v_readlane_b32 s22, v240, 15
	v_readlane_b32 s23, v240, 16
	v_readlane_b32 s27, v238, 63
	v_readlane_b32 s34, v238, 57
	v_readlane_b32 s35, v238, 58
	v_readlane_b32 s36, v237, 2
	v_readlane_b32 s50, v238, 59
	v_readlane_b32 s91, v238, 41
	v_readlane_b32 s92, v238, 37
	v_readlane_b32 s93, v238, 38
	v_readlane_b32 s94, v238, 39
	v_readlane_b32 s95, v238, 40
	v_readlane_b32 s96, v238, 42
	s_movk_i32 s57, 0x90
	s_mov_b64 s[64:65], s[66:67]
	s_mov_b32 s89, 0x7f800000
	s_branch .LBB0_609
.LBB0_760:
.LBB0_761:
.LBB0_762:
.LBB0_763:
.LBB0_764:
.LBB0_765:
.LBB0_766:
.LBB0_767:
.LBB0_768:
.LBB0_769:
.LBB0_770:
.LBB0_771:
.LBB0_772:
.LBB0_773:
.LBB0_774:
.LBB0_775:
.LBB0_776:
.LBB0_777:
.LBB0_778:
	s_mov_b64 s[0:1], 0

; DI void topk_job(const Params& p, int b, int t0, char* lds) {
;     ...
; #pragma unroll
;       for (int i = 0; i < 17; ++i) {
; #pragma unroll
;         for (int q = 0; q < 4; ++q) {
;           const unsigned u = sc[i][q];
;           bool part; unsigned bin;
;           if (pass == 0) { part = (u != 0u); bin = (u >> 22) + (lane & 3) * 1024; }
;           else if (pass == 1) { part = (u != 0u) && ((u >> 22) == pref[q]) && !few[q]; bin = ((u >> 12) & 1023u) + (lane & 3) * 1024; }
;           else { part = (u != 0u) && ((u >> 12) == pref[q]) && !few[q]; bin = u & 4095u; }
;           if (part) atomicAdd(hist + q * 4096 + bin, 1u);
; DI void xcd_barrier(const XcdBarrier& b) {
;   asm volatile("s_waitcnt vmcnt(0)" ::: "memory");
;   __syncthreads();
;   if (threadIdx.x == 0) {
;     unsigned* bar = b.bar;
;     __builtin_amdgcn_s_waitcnt(0);
;     unsigned nloc = b.st[0], nx = b.st[1];
;     if (nloc == 0u) { xcd_barrier_complete(bar, b.x, nloc, nx); b.st[0] = nloc; b.st[1] = nx; }
.LBB0_822:
.LBB0_823:
.LBB0_824:
.LBB0_825:
.LBB0_826:
.LBB0_827:
.LBB0_828:
.LBB0_829:
.LBB0_830:
.LBB0_831:
.LBB0_832:
.LBB0_833:
.LBB0_834:
.LBB0_835:
.LBB0_836:
.LBB0_837:
.LBB0_838:
.LBB0_839:
.LBB0_840:
.LBB0_841:
.LBB0_842:
.LBB0_926:
.LBB0_927:
.LBB0_928:
.LBB0_929:
.LBB0_930:
.LBB0_936:
.LBB0_938:
.LBB0_939:
.LBB0_941:
.LBB0_943:
.LBB0_944:
.LBB0_945:
.LBB0_946:
.LBB0_948:
.LBB0_952:
.LBB0_955:
.LBB0_958:
.LBB0_961:
.LBB0_964:
.LBB0_967:
.LBB0_970:
.LBB0_973:
.LBB0_976:
.LBB0_979:
.LBB0_982:
.LBB0_985:
.LBB0_988:
.LBB0_991:
.LBB0_994:
.LBB0_997:
.LBB0_1000:
.LBB0_1003:
.LBB0_1006:
.LBB0_1009:
.LBB0_1012:
.LBB0_1015:
.LBB0_1018:
.LBB0_1021:
.LBB0_1024:
.LBB0_1027:
.LBB0_1030:
.LBB0_1033:
.LBB0_1036:
.LBB0_1039:
.LBB0_1042:
.LBB0_1045:
.LBB0_1048:
.LBB0_1051:
.LBB0_1054:
.LBB0_1057:
.LBB0_1060:
.LBB0_1063:
.LBB0_1066:
.LBB0_1069:
.LBB0_1072:
.LBB0_1075:
.LBB0_1078:
.LBB0_1081:
.LBB0_1084:
.LBB0_1087:
.LBB0_1090:
.LBB0_1093:
.LBB0_1096:
.LBB0_1099:
.LBB0_1102:
.LBB0_1105:
.LBB0_1108:
.LBB0_1111:
.LBB0_1114:
.LBB0_1117:
.LBB0_1120:
.LBB0_1123:
.LBB0_1126:
.LBB0_1129:
.LBB0_1132:
.LBB0_1135:
.LBB0_1138:
.LBB0_1141:
.LBB0_1144:
.LBB0_1147:
.LBB0_1150:
.LBB0_1153:
.LBB0_1157:
.LBB0_1159:
.LBB0_1160:
.LBB0_1162:
.LBB0_1164:
.LBB0_1165:
.LBB0_1166:
.LBB0_1167:
.LBB0_1168:
.LBB0_1169:
.LBB0_1170:
.LBB0_1174:
.LBB0_1177:
.LBB0_1180:
.LBB0_1183:
.LBB0_1186:
.LBB0_1189:
.LBB0_1192:
.LBB0_1195:
.LBB0_1198:
.LBB0_1201:
.LBB0_1204:
.LBB0_1207:
.LBB0_1210:
.LBB0_1213:
.LBB0_1216:
.LBB0_1219:
.LBB0_1222:
.LBB0_1225:
.LBB0_1228:
.LBB0_1231:
.LBB0_1234:
.LBB0_1237:
.LBB0_1240:
.LBB0_1243:
.LBB0_1246:
.LBB0_1249:
.LBB0_1252:
.LBB0_1255:
.LBB0_1258:
.LBB0_1261:
.LBB0_1264:
.LBB0_1267:
.LBB0_1270:
.LBB0_1273:
.LBB0_1276:
.LBB0_1279:
.LBB0_1282:
.LBB0_1285:
.LBB0_1288:
.LBB0_1291:
.LBB0_1294:
.LBB0_1297:
.LBB0_1300:
.LBB0_1303:
.LBB0_1306:
.LBB0_1309:
.LBB0_1312:
.LBB0_1315:
.LBB0_1318:
.LBB0_1321:
.LBB0_1324:
.LBB0_1327:
.LBB0_1330:
.LBB0_1333:
.LBB0_1336:
.LBB0_1339:
.LBB0_1342:
.LBB0_1345:
.LBB0_1348:
.LBB0_1351:
.LBB0_1354:
.LBB0_1357:
.LBB0_1360:
.LBB0_1363:
.LBB0_1366:
.LBB0_1369:
.LBB0_1372:
.LBB0_1375:
.LBB0_1378:
.LBB0_1380:
.LBB0_1382:
.LBB0_1384:
.LBB0_1387:
.LBB0_1388:
.LBB0_1390:
.LBB0_1392:
.LBB0_1393:
.LBB0_1394:
.LBB0_1395:
.LBB0_1396:
.LBB0_1397:
.LBB0_1398:
.LBB0_1399:
.LBB0_1406:
.LBB0_1410:
.LBB0_1414:
.LBB0_1418:
.LBB0_1422:
.LBB0_1426:
.LBB0_1430:
.LBB0_1434:
.LBB0_1438:
.LBB0_1442:
.LBB0_1446:
.LBB0_1450:
.LBB0_1454:
.LBB0_1458:
.LBB0_1462:
.LBB0_1466:
.LBB0_1470:
.LBB0_1474:
.LBB0_1478:
.LBB0_1482:
.LBB0_1486:
.LBB0_1490:
.LBB0_1494:
.LBB0_1498:
.LBB0_1502:
.LBB0_1506:
.LBB0_1510:
.LBB0_1514:
.LBB0_1518:
.LBB0_1522:
.LBB0_1526:
.LBB0_1530:
.LBB0_1534:
.LBB0_1538:
.LBB0_1542:
.LBB0_1546:
.LBB0_1550:
.LBB0_1554:
.LBB0_1558:
.LBB0_1562:
.LBB0_1566:
.LBB0_1570:
.LBB0_1574:
.LBB0_1578:
.LBB0_1582:
.LBB0_1586:
.LBB0_1590:
.LBB0_1594:
.LBB0_1598:
.LBB0_1602:
.LBB0_1606:
.LBB0_1610:
.LBB0_1614:
.LBB0_1618:
.LBB0_1622:
.LBB0_1626:
.LBB0_1630:
.LBB0_1634:
.LBB0_1638:
.LBB0_1642:
.LBB0_1646:
.LBB0_1650:
.LBB0_1654:
.LBB0_1658:
.LBB0_1662:
.LBB0_1666:
.LBB0_1670:
.LBB0_1674:
.LBB0_1680:
.LBB0_1682:
.LBB0_1683:
.LBB0_1684:
.LBB0_1685:
.LBB0_1686:
.LBB0_1688:
.LBB0_1689:
.LBB0_1691:
.LBB0_1693:
.LBB0_1694:
.LBB0_1695:
.LBB0_1696:
.LBB0_1697:
.LBB0_1698:
.LBB0_1699:
.LBB0_1702:
.LBB0_1705:
.LBB0_1708:
.LBB0_1711:
.LBB0_1714:
.LBB0_1717:
.LBB0_1720:
.LBB0_1723:
.LBB0_1726:
.LBB0_1729:
.LBB0_1732:
.LBB0_1735:
.LBB0_1738:
.LBB0_1741:
.LBB0_1744:
.LBB0_1747:
.LBB0_1750:
.LBB0_1752:
.LBB0_1753:
.LBB0_1757:
.LBB0_1759:
.LBB0_1763:
.LBB0_1766:
.LBB0_1767:
.LBB0_1770:
.LBB0_1773:
.LBB0_1774:
.LBB0_1777:
.LBB0_1780:
.LBB0_1781:
.LBB0_1784:
.LBB0_1787:
.LBB0_1791:
.LBB0_1794:
.LBB0_1795:
.LBB0_1798:
.LBB0_1801:
.LBB0_1802:
.LBB0_1805:
.LBB0_1808:
.LBB0_1809:
.LBB0_1812:
.LBB0_1815:
.LBB0_1819:
.LBB0_1822:
.LBB0_1823:
.LBB0_1826:
.LBB0_1829:
.LBB0_1830:
.LBB0_1833:
.LBB0_1836:
.LBB0_1837:
.LBB0_1840:
.LBB0_1843:
.LBB0_1847:
.LBB0_1850:
.LBB0_1851:
.LBB0_1854:
.LBB0_1857:
.LBB0_1858:
.LBB0_1861:
.LBB0_1864:
.LBB0_1865:
.LBB0_1868:
.LBB0_1871:
.LBB0_1875:
.LBB0_1878:
.LBB0_1879:
.LBB0_1882:
.LBB0_1885:
.LBB0_1886:
.LBB0_1889:
.LBB0_1892:
.LBB0_1893:
.LBB0_1896:
.LBB0_1899:
.LBB0_1903:
.LBB0_1906:
.LBB0_1907:
.LBB0_1910:
.LBB0_1913:
.LBB0_1914:
.LBB0_1917:
.LBB0_1920:
.LBB0_1921:
.LBB0_1924:
.LBB0_1927:
.LBB0_1931:
.LBB0_1934:
.LBB0_1935:
.LBB0_1938:
.LBB0_1941:
.LBB0_1942:
.LBB0_1945:
.LBB0_1948:
.LBB0_1949:
.LBB0_1952:
.LBB0_1955:
.LBB0_1959:
.LBB0_1962:
.LBB0_1963:
.LBB0_1966:
.LBB0_1969:
.LBB0_1970:
.LBB0_1973:
.LBB0_1976:
.LBB0_1977:
.LBB0_1980:
.LBB0_1983:
.LBB0_1987:
.LBB0_1990:
.LBB0_1991:
.LBB0_1994:
.LBB0_1997:
.LBB0_1998:
.LBB0_2001:
.LBB0_2004:
.LBB0_2005:
.LBB0_2008:
.LBB0_2011:
.LBB0_2015:
.LBB0_2018:
.LBB0_2019:
.LBB0_2022:
.LBB0_2025:
.LBB0_2026:
.LBB0_2029:
.LBB0_2032:
.LBB0_2033:
.LBB0_2036:
.LBB0_2039:
.LBB0_2043:
.LBB0_2046:
.LBB0_2047:
.LBB0_2050:
.LBB0_2053:
.LBB0_2054:
.LBB0_2057:
.LBB0_2060:
.LBB0_2061:
.LBB0_2064:
.LBB0_2067:
.LBB0_2071:
.LBB0_2074:
.LBB0_2075:
.LBB0_2078:
.LBB0_2081:
.LBB0_2082:
.LBB0_2085:
.LBB0_2088:
.LBB0_2089:
.LBB0_2092:
.LBB0_2095:
.LBB0_2099:
.LBB0_2102:
.LBB0_2103:
.LBB0_2106:
.LBB0_2109:
.LBB0_2110:
.LBB0_2113:
.LBB0_2116:
.LBB0_2117:
.LBB0_2120:
.LBB0_2123:
.LBB0_2127:
.LBB0_2130:
.LBB0_2131:
.LBB0_2134:
.LBB0_2137:
.LBB0_2138:
.LBB0_2141:
.LBB0_2144:
.LBB0_2145:
.LBB0_2148:
.LBB0_2151:
.LBB0_2155:
.LBB0_2158:
.LBB0_2159:
.LBB0_2162:
.LBB0_2165:
.LBB0_2166:
.LBB0_2169:
.LBB0_2172:
.LBB0_2173:
.LBB0_2176:
.LBB0_2179:
.LBB0_2183:
.LBB0_2186:
.LBB0_2187:
.LBB0_2190:
.LBB0_2193:
.LBB0_2194:
.LBB0_2197:
.LBB0_2200:
.LBB0_2201:
.LBB0_2204:
.LBB0_2207:
.LBB0_2211:
.LBB0_2214:
.LBB0_2215:
.LBB0_2218:
.LBB0_2221:
.LBB0_2222:
.LBB0_2225:
.LBB0_2228:
.LBB0_2229:
.LBB0_2232:
.LBB0_2235:
.LBB0_2238:
.LBB0_2241:
.LBB0_2244:
.LBB0_2247:
.LBB0_2248:
.LBB0_2249:
	s_waitcnt vmcnt(0)
	s_waitcnt lgkmcnt(0)
	s_barrier
	s_and_saveexec_b64 s[0:1], s[92:93]
	s_cbranch_execz .LBB0_2301
	s_add_i32 s11, 0, 0x24010
	s_mov_b64 s[2:3], src_shared_base
	s_cmp_lg_u32 s11, -1
	s_cselect_b32 s2, s11, 0
	s_cselect_b32 s4, s3, 0
	s_add_i32 s10, 0, 0x24014
	s_cmp_lg_u32 s10, -1
	v_mov_b32_e32 v0, s2
	v_mov_b32_e32 v1, s4
	s_cselect_b32 s2, s10, 0
	s_cselect_b32 s3, s3, 0
	s_waitcnt vmcnt(0) expcnt(0) lgkmcnt(0)
	flat_load_dword v2, v[0:1] sc0 sc1
	s_waitcnt vmcnt(0)
	v_mov_b32_e32 v0, s2
	v_mov_b32_e32 v1, s3
	flat_load_dword v0, v[0:1] sc0 sc1
	s_waitcnt vmcnt(0) lgkmcnt(0)
	v_cmp_eq_u32_e32 vcc, 0, v2
	s_and_saveexec_b64 s[2:3], vcc
	s_cbranch_execz .LBB0_2265
	s_mov_b32 s12, 1
	s_branch .LBB0_2253
